# replace ds_bpermute butterflies (wave/group sums, ssout reductions) with DPP and permlane16/32 swaps
# baseline (speedup 1.0000x reference)
; __device__ __forceinline__ void norm_row(const float* xrow, const float* g, bf16_t* orow, float* xcopy, int lane) {
;     f32x4 v[8]; float s = 0.f;
; #pragma unroll
;     for (int j = 0; j < 4; ++j) { v[2 * j] = ((const f32x4*)xrow)[2 * (lane + 64 * j)]; v[2 * j + 1] = ((const f32x4*)xrow)[2 * (lane + 64 * j) + 1]; }
; #pragma unroll
;     for (int j = 0; j < 8; ++j) s += (v[j][0] * v[j][0] + v[j][1] * v[j][1]) + (v[j][2] * v[j][2] + v[j][3] * v[j][3]);
;     if (xcopy) {
; #pragma unroll
;         for (int j = 0; j < 4; ++j) { ((f32x4*)xcopy)[2 * (lane + 64 * j)] = v[2 * j]; ((f32x4*)xcopy)[2 * (lane + 64 * j) + 1] = v[2 * j + 1]; } }
;     const float rinv = 1.0f / sqrtf(wave_sum(s) * (1.f / D) + EPS);
; __global__ void __launch_bounds__(NTHREADS, 2) fwd_megakernel(Params P) {
;     ...
;         _Pragma("unroll 1") for (int rp_ = 0; rp_ < REP_PREP; ++rp_) for (int row = gw; row < M; row += ngw) {
;             const float* xr = row < 8192 ? kp->in[I_XP] + (size_t)row * D : kp->in[I_XS] + (size_t)(row - 8192) * D;
;             norm_row(xr, kp->in[I_ATTN_NORM], H + (size_t)row * D, nullptr, lane);
.LBB0_34:
	v_lshl_add_u64 v[90:91], s[34:35], 0, v[26:27]
	v_add_co_u32_e32 v100, vcc, s38, v90
	s_nop 1
	global_load_dwordx4 v[108:111], v26, s[34:35]
	global_load_dwordx4 v[112:115], v26, s[34:35] offset:16
	global_load_dwordx4 v[116:119], v26, s[34:35] offset:2048
	global_load_dwordx4 v[120:123], v26, s[34:35] offset:2064
	v_addc_co_u32_e32 v101, vcc, 0, v91, vcc
	s_nop 1
	global_load_dwordx4 v[124:127], v[100:101], off
	v_lshl_add_u64 v[102:103], v[90:91], 0, s[28:29]
	global_load_dwordx4 v[128:131], v[102:103], off offset:16
	global_load_dwordx4 v[132:135], v[100:101], off offset:2048
	v_lshl_add_u64 v[104:105], v[90:91], 0, s[30:31]
	global_load_dwordx4 v[136:139], v[104:105], off offset:16
	global_load_dwordx4 v[140:143], v[28:29], off
	global_load_dwordx4 v[148:151], v[28:29], off offset:16
	global_load_dwordx4 v[152:155], v[30:31], off
	global_load_dwordx4 v[156:159], v[30:31], off offset:16
	global_load_dwordx4 v[160:163], v[32:33], off
	global_load_dwordx4 v[164:167], v[32:33], off offset:16
	global_load_dwordx4 v[168:171], v[34:35], off
	global_load_dwordx4 v[172:175], v[34:35], off offset:16
	v_lshl_add_u64 v[4:5], s[34:35], 0, v[26:27]
	v_add_co_u32_e32 v6, vcc, s38, v4
	s_waitcnt vmcnt(15)
	s_nop 0
	v_mov_b64_e32 v[46:47], v[108:109]
	v_mov_b64_e32 v[48:49], v[110:111]
	s_nop 1
	s_waitcnt vmcnt(14)
	s_nop 0
	v_mov_b64_e32 v[50:51], v[112:113]
	v_mov_b64_e32 v[52:53], v[114:115]
	s_nop 1
	s_waitcnt vmcnt(13)
	s_nop 0
	v_mov_b64_e32 v[20:21], v[116:117]
	v_mov_b64_e32 v[22:23], v[118:119]
	s_nop 1
	s_waitcnt vmcnt(12)
	s_nop 0
	v_mov_b64_e32 v[16:17], v[120:121]
	v_mov_b64_e32 v[18:19], v[122:123]
	s_nop 1
	v_addc_co_u32_e32 v7, vcc, 0, v5, vcc
	s_waitcnt vmcnt(11)
	s_nop 0
	v_mov_b64_e32 v[12:13], v[124:125]
	v_mov_b64_e32 v[14:15], v[126:127]
	s_nop 1
	v_lshl_add_u64 v[54:55], v[4:5], 0, s[28:29]
	s_waitcnt vmcnt(10)
	s_nop 0
	v_mov_b64_e32 v[8:9], v[128:129]
	v_mov_b64_e32 v[10:11], v[130:131]
	s_nop 1
	s_waitcnt vmcnt(9)
	s_nop 0
	v_mov_b64_e32 v[0:1], v[132:133]
	v_mov_b64_e32 v[2:3], v[134:135]
	s_nop 1
	v_lshl_add_u64 v[58:59], v[4:5], 0, s[30:31]
	s_waitcnt vmcnt(8)
	s_nop 0
	v_mov_b64_e32 v[4:5], v[136:137]
	v_mov_b64_e32 v[6:7], v[138:139]
	s_nop 1
	s_waitcnt vmcnt(7)
	s_nop 0
	v_mov_b64_e32 v[54:55], v[140:141]
	v_mov_b64_e32 v[56:57], v[142:143]
	s_nop 1
	s_lshl_b64 s[34:35], s[4:5], 12
	s_add_u32 s10, s10, s26
	s_addc_u32 s11, s11, s27
	s_add_u32 s16, s16, s18
	s_addc_u32 s17, s17, s19
	s_cmpk_gt_i32 s10, 0x3fff
	v_mul_f32_e32 v45, v47, v47
	v_mul_f32_e32 v58, v49, v49
	v_mul_f32_e32 v59, v51, v51
	v_mul_f32_e32 v60, v53, v53
	v_mul_f32_e32 v61, v21, v21
	v_mul_f32_e32 v62, v23, v23
	v_fmac_f32_e32 v45, v46, v46
	v_fmac_f32_e32 v58, v48, v48
	v_fmac_f32_e32 v59, v50, v50
	v_fmac_f32_e32 v60, v52, v52
	v_mul_f32_e32 v63, v17, v17
	v_mul_f32_e32 v64, v19, v19
	v_fmac_f32_e32 v61, v20, v20
	v_fmac_f32_e32 v62, v22, v22
	v_add_f32_e32 v45, v45, v58
	v_add_f32_e32 v58, v59, v60
	v_fmac_f32_e32 v63, v16, v16
	v_fmac_f32_e32 v64, v18, v18
	v_add_f32_e32 v59, v61, v62
	v_add_f32_e32 v45, v45, v58
	v_mul_f32_e32 v58, v13, v13
	v_mul_f32_e32 v61, v15, v15
	v_add_f32_e32 v60, v63, v64
	v_mul_f32_e32 v62, v9, v9
	v_mul_f32_e32 v63, v11, v11
	v_add_f32_e32 v45, v45, v59
	v_fmac_f32_e32 v58, v12, v12
	v_fmac_f32_e32 v61, v14, v14
	v_mul_f32_e32 v64, v1, v1
	v_mul_f32_e32 v65, v3, v3
	v_fmac_f32_e32 v62, v8, v8
	v_fmac_f32_e32 v63, v10, v10
	v_add_f32_e32 v45, v45, v60
	v_add_f32_e32 v58, v58, v61
	v_mul_f32_e32 v66, v5, v5
	v_mul_f32_e32 v67, v7, v7
	v_fmac_f32_e32 v64, v0, v0
	v_fmac_f32_e32 v65, v2, v2
	v_add_f32_e32 v59, v62, v63
	v_add_f32_e32 v45, v45, v58
	v_fmac_f32_e32 v66, v4, v4
	v_fmac_f32_e32 v67, v6, v6
	v_add_f32_e32 v60, v64, v65
	v_add_f32_e32 v45, v45, v59
	v_add_f32_e32 v61, v66, v67
	v_add_f32_e32 v45, v45, v60
	v_add_f32_e32 v45, v45, v61
	s_waitcnt vmcnt(6)
	s_nop 0
	v_mov_b64_e32 v[58:59], v[148:149]
	v_mov_b64_e32 v[60:61], v[150:151]
	s_nop 1
	s_nop 1
	v_mov_b32_dpp v62, v45 quad_perm:[1,0,3,2] row_mask:0xf bank_mask:0xf
	s_waitcnt lgkmcnt(0)
	v_add_f32_e32 v45, v45, v62
	s_nop 1
	v_mov_b32_dpp v62, v45 quad_perm:[2,3,0,1] row_mask:0xf bank_mask:0xf
	s_waitcnt lgkmcnt(0)
	v_add_f32_e32 v45, v45, v62
	s_nop 1
	v_mov_b32_dpp v62, v45 row_shl:4 row_mask:0xf bank_mask:0x5
	s_nop 1
	v_mov_b32_dpp v62, v45 row_shr:4 row_mask:0xf bank_mask:0xa
	s_waitcnt lgkmcnt(0)
	v_add_f32_e32 v45, v45, v62
	s_nop 1
	v_mov_b32_dpp v62, v45 row_ror:8 row_mask:0xf bank_mask:0xf
	s_waitcnt lgkmcnt(0)
; __device__ __forceinline__ unsigned cvt_pk_bf16(float lo, float hi) { unsigned r; asm volatile("v_cvt_pk_bf16_f32 %0, %1, %2" : "=v"(r) : "v"(lo), "v"(hi)); return r; }
; __device__ __forceinline__ void norm_row(const float* xrow, const float* g, bf16_t* orow, float* xcopy, int lane) {
;     ...
;     const float rinv = 1.0f / sqrtf(wave_sum(s) * (1.f / D) + EPS);
; #pragma unroll
;     for (int j = 0; j < 4; ++j) { const f32x4 g0 = ((const f32x4*)g)[2 * (lane + 64 * j)], g1 = ((const f32x4*)g)[2 * (lane + 64 * j) + 1]; const f32x4 a = v[2 * j], c = v[2 * j + 1];
;         u32x4 w; w.x = cvt_pk_bf16(a[0] * rinv * g0[0], a[1] * rinv * g0[1]); w.y = cvt_pk_bf16(a[2] * rinv * g0[2], a[3] * rinv * g0[3]);
;         w.z = cvt_pk_bf16(c[0] * rinv * g1[0], c[1] * rinv * g1[1]); w.w = cvt_pk_bf16(c[2] * rinv * g1[2], c[3] * rinv * g1[3]);
;         ((u32x4*)orow)[lane + 64 * j] = w; }
	v_add_f32_e32 v45, v45, v62
	v_mov_b32_e32 v62, v45
	s_nop 1
	v_permlane16_swap_b32_e32 v62, v45
	s_waitcnt lgkmcnt(0)
	v_add_f32_e32 v45, v45, v62
	v_mov_b32_e32 v62, v45
	s_nop 1
	v_permlane32_swap_b32_e32 v62, v45
	s_waitcnt lgkmcnt(0)
	v_add_f32_e32 v45, v45, v62
	v_fmamk_f32 v45, v45, 0x3a000000, v43
	v_mul_f32_e32 v62, 0x4f800000, v45
	v_cmp_gt_f32_e32 vcc, s39, v45
	s_nop 1
	v_cndmask_b32_e32 v45, v45, v62, vcc
	v_sqrt_f32_e32 v62, v45
	s_nop 0
	v_add_u32_e32 v63, -1, v62
	v_add_u32_e32 v64, 1, v62
	v_fma_f32 v65, -v63, v62, v45
	v_fma_f32 v66, -v64, v62, v45
	v_cmp_ge_f32_e64 s[4:5], 0, v65
	s_nop 1
	v_cndmask_b32_e64 v62, v62, v63, s[4:5]
	v_cmp_lt_f32_e64 s[4:5], 0, v66
	s_nop 1
	v_cndmask_b32_e64 v62, v62, v64, s[4:5]
	v_mul_f32_e32 v63, 0x37800000, v62
	v_cndmask_b32_e32 v62, v62, v63, vcc
	v_cmp_class_f32_e32 vcc, v45, v44
	s_nop 1
	v_cndmask_b32_e32 v45, v62, v45, vcc
	v_div_scale_f32 v64, s[4:5], v45, v45, 1.0
	v_rcp_f32_e32 v65, v64
	v_div_scale_f32 v66, vcc, 1.0, v45, 1.0
	v_lshl_add_u64 v[62:63], v[36:37], 0, s[34:35]
	v_fma_f32 v67, -v64, v65, 1.0
	v_fmac_f32_e32 v65, v67, v65
	v_mul_f32_e32 v67, v66, v65
	v_fma_f32 v68, -v64, v67, v66
	v_fmac_f32_e32 v67, v68, v65
	v_fma_f32 v64, -v64, v67, v66
	v_div_fmas_f32 v64, v64, v65, v67
	v_div_fixup_f32 v45, v64, v45, 1.0
	v_mul_f32_e32 v46, v46, v45
	v_mul_f32_e32 v47, v47, v45
	v_mul_f32_e32 v48, v48, v45
	v_mul_f32_e32 v49, v49, v45
	v_mul_f32_e32 v50, v50, v45
	v_mul_f32_e32 v51, v51, v45
	v_mul_f32_e32 v52, v52, v45
	v_mul_f32_e32 v53, v53, v45
	v_mul_f32_e32 v46, v54, v46
	v_mul_f32_e32 v47, v55, v47
	v_mul_f32_e32 v48, v56, v48
	v_mul_f32_e32 v49, v57, v49
	v_mul_f32_e32 v50, v58, v50
	v_mul_f32_e32 v51, v59, v51
	v_mul_f32_e32 v52, v60, v52
	v_mul_f32_e32 v53, v61, v53
	v_cvt_pk_bf16_f32 v46, v46, v47
	v_cvt_pk_bf16_f32 v47, v48, v49
	v_cvt_pk_bf16_f32 v48, v50, v51
	v_cvt_pk_bf16_f32 v49, v52, v53
	global_store_dwordx4 v[62:63], v[46:49], off
	s_waitcnt vmcnt(6)
	s_nop 0
	v_mov_b64_e32 v[46:47], v[152:153]
	v_mov_b64_e32 v[48:49], v[154:155]
	s_nop 1
	s_nop 0
	s_waitcnt vmcnt(5)
	s_nop 0
	v_mov_b64_e32 v[50:51], v[156:157]
	v_mov_b64_e32 v[52:53], v[158:159]
	s_nop 1
	v_mul_f32_e32 v19, v19, v45
	v_mul_f32_e32 v20, v20, v45
	v_mul_f32_e32 v21, v21, v45
	v_mul_f32_e32 v22, v22, v45
	v_mul_f32_e32 v23, v23, v45
	v_mul_f32_e32 v16, v16, v45
	v_mul_f32_e32 v17, v17, v45
	v_mul_f32_e32 v18, v18, v45
	v_mul_f32_e32 v11, v11, v45
	v_mul_f32_e32 v12, v12, v45
	v_mul_f32_e32 v13, v13, v45
	v_mul_f32_e32 v14, v14, v45
	v_mul_f32_e32 v15, v15, v45
	v_mul_f32_e32 v8, v8, v45
	v_mul_f32_e32 v9, v9, v45
	v_mul_f32_e32 v10, v10, v45
	v_mul_f32_e32 v0, v0, v45
	v_mul_f32_e32 v1, v1, v45
	v_mul_f32_e32 v2, v2, v45
	v_mul_f32_e32 v3, v3, v45
	v_mul_f32_e32 v4, v4, v45
	v_mul_f32_e32 v5, v5, v45
	v_mul_f32_e32 v6, v6, v45
	v_mul_f32_e32 v7, v7, v45
	v_mul_f32_e32 v20, v20, v46
	v_mul_f32_e32 v19, v19, v53
	v_mul_f32_e32 v21, v21, v47
	v_mul_f32_e32 v22, v22, v48
	v_mul_f32_e32 v23, v23, v49
	v_mul_f32_e32 v46, v16, v50
	v_mul_f32_e32 v47, v17, v51
	v_mul_f32_e32 v48, v18, v52
	v_cvt_pk_bf16_f32 v16, v20, v21
	v_cvt_pk_bf16_f32 v17, v22, v23
	v_cvt_pk_bf16_f32 v18, v46, v47
	v_cvt_pk_bf16_f32 v19, v48, v19
	global_store_dwordx4 v[62:63], v[16:19], off offset:1024
	s_waitcnt vmcnt(5)
	s_nop 0
	v_mov_b64_e32 v[16:17], v[160:161]
	v_mov_b64_e32 v[18:19], v[162:163]
	s_nop 1
	s_nop 0
	s_waitcnt vmcnt(4)
	s_nop 0
	v_mov_b64_e32 v[20:21], v[164:165]
	v_mov_b64_e32 v[22:23], v[166:167]
	s_nop 1
	v_mul_f32_e32 v12, v12, v16
	v_mul_f32_e32 v11, v11, v23
	v_mul_f32_e32 v13, v13, v17
	v_mul_f32_e32 v14, v14, v18
	v_mul_f32_e32 v15, v15, v19
	v_mul_f32_e32 v16, v8, v20
	v_mul_f32_e32 v17, v9, v21
	v_mul_f32_e32 v18, v10, v22
	v_cvt_pk_bf16_f32 v8, v12, v13
	v_cvt_pk_bf16_f32 v9, v14, v15
	v_cvt_pk_bf16_f32 v10, v16, v17
	v_cvt_pk_bf16_f32 v11, v18, v11
	global_store_dwordx4 v[62:63], v[8:11], off offset:2048
	s_waitcnt vmcnt(4)
	s_nop 0
	v_mov_b64_e32 v[8:9], v[168:169]
	v_mov_b64_e32 v[10:11], v[170:171]
	s_nop 1
	s_nop 0
	s_waitcnt vmcnt(3)
	s_nop 0
	v_mov_b64_e32 v[12:13], v[172:173]
	v_mov_b64_e32 v[14:15], v[174:175]
	s_nop 1
	v_mul_f32_e32 v0, v0, v8
	v_mul_f32_e32 v1, v1, v9
	v_mul_f32_e32 v2, v2, v10
	v_mul_f32_e32 v3, v3, v11
	v_mul_f32_e32 v4, v4, v12
	v_mul_f32_e32 v5, v5, v13
	v_mul_f32_e32 v6, v6, v14
	v_mul_f32_e32 v7, v7, v15
	v_cvt_pk_bf16_f32 v0, v0, v1
	v_cvt_pk_bf16_f32 v1, v2, v3
	v_cvt_pk_bf16_f32 v2, v4, v5
	v_cvt_pk_bf16_f32 v3, v6, v7
	global_store_dwordx4 v[62:63], v[0:3], off offset:3072
	s_cbranch_scc1 .LBB0_39

; __device__ __forceinline__ unsigned cvt_pk_bf16(float lo, float hi) { unsigned r; asm volatile("v_cvt_pk_bf16_f32 %0, %1, %2" : "=v"(r) : "v"(lo), "v"(hi)); return r; }
; __device__ __forceinline__ float bflo(unsigned w) { return __uint_as_float(w << 16); }
; __device__ __forceinline__ float bfhi(unsigned w) { return __uint_as_float(w & 0xffff0000u); }
; __device__ __forceinline__ float wave_sum(float v) {
; #pragma unroll
;     for (int o = 1; o < 64; o <<= 1) v += __shfl_xor(v, o);
;     return v;
; __global__ void __launch_bounds__(NTHREADS, 2) fwd_megakernel(Params P) {
;     ...
;             const bf16_t* z = Z + (size_t)tok * EV_INP; const int pos = tok_pos(tok);
;             { const u32x4 w = *(const u32x4*)(z + 8 * lane);
;               float v[8] = {bflo(w.x), bfhi(w.x), bflo(w.y), bfhi(w.y), bflo(w.z), bfhi(w.z), bflo(w.w), bfhi(w.w)}; float s = 0.f;
; #pragma unroll
;               for (int j = 0; j < 8; ++j) s += v[j] * v[j];
;               const float ri = 1.0f / sqrtf(wave_sum(s) * (1.f / 512.f) + EPS); const float* g = kp->in[I_QA_NORM] + 8 * lane;
;               u32x4 o; o.x = cvt_pk_bf16(v[0] * ri * g[0], v[1] * ri * g[1]); o.y = cvt_pk_bf16(v[2] * ri * g[2], v[3] * ri * g[3]); o.z = cvt_pk_bf16(v[4] * ri * g[4], v[5] * ri * g[5]); o.w = cvt_pk_bf16(v[6] * ri * g[6], v[7] * ri * g[7]);
;               *(u32x4*)(QN + (size_t)tok * 512 + 8 * lane) = o; }
;             { const u32x2 w = *(const u32x2*)(z + 512 + 4 * lane);
;               float v[4] = {bflo(w.x), bfhi(w.x), bflo(w.y), bfhi(w.y)}; const float s = (v[0] * v[0] + v[1] * v[1]) + (v[2] * v[2] + v[3] * v[3]);
;               const float ri = 1.0f / sqrtf(wave_sum(s) * (1.f / 256.f) + EPS); const float* g = kp->in[I_KVA_NORM] + 4 * lane;
;               u32x2 o; o.x = cvt_pk_bf16(v[0] * ri * g[0], v[1] * ri * g[1]); o.y = cvt_pk_bf16(v[2] * ri * g[2], v[3] * ri * g[3]);
;               *(u32x2*)(KVN + (size_t)tok * 256 + 4 * lane) = o; }
.LBB0_173:
	v_mov_b32_e32 v91, v1
	v_lshl_add_u64 v[100:101], s[30:31], 0, v[22:23]
	v_add_co_u32_e32 v102, vcc, 0xec00000, v100
	s_nop 1
	global_load_dwordx2 v[110:111], v[18:19], off
	v_addc_co_u32_e32 v103, vcc, 0, v101, vcc
	s_nop 1
	global_load_dwordx4 v[112:115], v[102:103], off
	s_cmpk_lt_i32 s70, 0x2000
	s_nop 0
	s_cselect_b32 s8, s63, 0x7ff
	s_nop 0
	s_and_b32 s8, s8, s70
	s_nop 0
	v_lshl_or_b32 v90, s8, 7, v58
	v_lshl_add_u64 v[108:109], s[36:37], 0, v[90:91]
	v_add_co_u32_e32 v108, vcc, s65, v108
	s_nop 1
	v_addc_co_u32_e32 v109, vcc, 0, v109, vcc
	s_nop 1
	v_lshl_add_u64 v[104:105], s[30:31], 0, v[24:25]
	v_lshl_add_u64 v[106:107], s[30:31], 0, v[20:21]
	global_load_dwordx2 v[116:117], v[18:19], off offset:8
	global_load_dwordx2 v[118:119], v[18:19], off offset:16
	global_load_dwordx2 v[120:121], v[18:19], off offset:24
	global_load_dwordx2 v[122:123], v[104:105], off
	global_load_dwordx2 v[124:125], v56, s[72:73]
	global_load_dwordx2 v[126:127], v56, s[72:73] offset:8
	global_load_ushort v80, v[106:107], off
	global_load_dword v82, v57, s[16:17]
	global_load_dword v84, v90, s[36:37]
	global_load_dword v86, v[108:109], off
	global_load_dwordx4 v[128:131], v[102:103], off offset:1664
	global_load_dwordx2 v[132:133], v59, s[18:19]
	global_load_dwordx2 v[134:135], v59, s[18:19] offset:8
	global_load_dwordx2 v[136:137], v59, s[18:19] offset:16
	global_load_dwordx2 v[138:139], v59, s[18:19] offset:24
	global_load_dwordx4 v[140:143], v[102:103], off offset:3712
	global_load_dwordx2 v[144:145], v59, s[52:53]
	global_load_dwordx2 v[146:147], v59, s[52:53] offset:8
	global_load_dwordx2 v[148:149], v59, s[52:53] offset:16
	global_load_dwordx2 v[150:151], v59, s[52:53] offset:24
	global_load_dwordx4 v[152:155], v[102:103], off offset:2688
	global_load_dwordx2 v[156:157], v59, s[18:19]
	global_load_dwordx2 v[158:159], v59, s[18:19] offset:8
	v_add_co_u32_e32 v100, vcc, s69, v100
	s_nop 1
	global_load_dwordx2 v[160:161], v59, s[18:19] offset:16
	v_addc_co_u32_e32 v101, vcc, 0, v101, vcc
	s_nop 1
	global_load_dwordx2 v[162:163], v59, s[18:19] offset:24
	global_load_dwordx4 v[164:167], v[100:101], off offset:640
	global_load_dwordx2 v[168:169], v59, s[52:53]
	global_load_dwordx2 v[170:171], v59, s[52:53] offset:8
	global_load_dwordx2 v[172:173], v59, s[52:53] offset:16
	global_load_dwordx2 v[174:175], v59, s[52:53] offset:24
	v_lshl_add_u64 v[34:35], s[30:31], 0, v[22:23]
	v_add_co_u32_e32 v38, vcc, 0xec00000, v34
	s_waitcnt vmcnt(31)
	s_nop 0
	v_mov_b64_e32 v[42:43], v[110:111]
	s_nop 1
	s_nop 0
	v_addc_co_u32_e32 v39, vcc, 0, v35, vcc
	s_waitcnt vmcnt(30)
	s_nop 0
	v_mov_b64_e32 v[66:67], v[112:113]
	v_mov_b64_e32 v[68:69], v[114:115]
	s_nop 1
	s_cmpk_lt_i32 s70, 0x2000
	s_cselect_b32 s8, s63, 0x7ff
	s_and_b32 s8, s8, s70
	v_lshl_or_b32 v0, s8, 7, v58
	v_lshl_add_u64 v[70:71], s[36:37], 0, v[0:1]
	v_add_co_u32_e32 v70, vcc, s65, v70
	v_lshl_add_u64 v[44:45], s[30:31], 0, v[26:27]
	s_nop 0
	v_addc_co_u32_e32 v71, vcc, 0, v71, vcc
	v_lshl_add_u64 v[46:47], s[30:31], 0, v[24:25]
	v_lshl_add_u64 v[48:49], s[30:31], 0, v[30:31]
	v_lshl_add_u64 v[50:51], s[30:31], 0, v[20:21]
	v_lshl_add_u64 v[52:53], s[30:31], 0, v[32:33]
	v_lshl_add_u64 v[40:41], s[30:31], 0, v[28:29]
	v_add_co_u32_e64 v36, s[6:7], s67, v40
	s_add_i32 s70, s70, s26
	v_lshl_add_u64 v[32:33], v[32:33], 0, s[12:13]
	v_lshl_add_u64 v[30:31], v[30:31], 0, s[42:43]
	v_lshl_add_u64 v[28:29], v[28:29], 0, s[44:45]
	v_lshl_add_u64 v[26:27], v[26:27], 0, s[28:29]
	v_lshl_add_u64 v[24:25], v[24:25], 0, s[46:47]
	v_lshl_add_u64 v[22:23], v[22:23], 0, s[46:47]
	v_lshl_add_u64 v[20:21], v[20:21], 0, s[46:47]
	s_cmpk_gt_i32 s70, 0x3fff
	v_and_b32_e32 v37, 0xffff0000, v66
	v_lshlrev_b32_e32 v17, 16, v66
	v_mul_f32_e32 v74, v37, v37
	v_lshlrev_b32_e32 v66, 16, v67
	v_fmac_f32_e32 v74, v17, v17
	v_and_b32_e32 v67, 0xffff0000, v67
	v_fmac_f32_e32 v74, v66, v66
	v_lshlrev_b32_e32 v72, 16, v68
	v_fmac_f32_e32 v74, v67, v67
	v_and_b32_e32 v68, 0xffff0000, v68
	v_fmac_f32_e32 v74, v72, v72
	v_lshlrev_b32_e32 v73, 16, v69
	v_fmac_f32_e32 v74, v68, v68
	v_and_b32_e32 v69, 0xffff0000, v69
	v_fmac_f32_e32 v74, v73, v73
	v_fmac_f32_e32 v74, v69, v69
	s_nop 1
	v_mov_b32_dpp v75, v74 quad_perm:[1,0,3,2] row_mask:0xf bank_mask:0xf
	s_waitcnt lgkmcnt(0)
	v_add_f32_e32 v74, v74, v75
	s_nop 1
	v_mov_b32_dpp v75, v74 quad_perm:[2,3,0,1] row_mask:0xf bank_mask:0xf
	s_waitcnt lgkmcnt(0)
	v_add_f32_e32 v74, v74, v75
	s_nop 1
	v_mov_b32_dpp v75, v74 row_shl:4 row_mask:0xf bank_mask:0x5
	s_nop 1
	v_mov_b32_dpp v75, v74 row_shr:4 row_mask:0xf bank_mask:0xa
	s_waitcnt lgkmcnt(0)
	v_add_f32_e32 v74, v74, v75
	s_nop 1
	v_mov_b32_dpp v75, v74 row_ror:8 row_mask:0xf bank_mask:0xf
	s_waitcnt lgkmcnt(0)
	v_add_f32_e32 v74, v74, v75
	v_mov_b32_e32 v75, v74
	s_nop 1
	v_permlane16_swap_b32_e32 v75, v74
	s_waitcnt lgkmcnt(0)
	v_add_f32_e32 v74, v74, v75
	v_mov_b32_e32 v75, v74
	s_nop 1
	v_permlane32_swap_b32_e32 v75, v74
	s_waitcnt lgkmcnt(0)
	v_add_f32_e32 v74, v74, v75
	v_fmamk_f32 v74, v74, 0x3b000000, v54
	v_mul_f32_e32 v75, 0x4f800000, v74
	v_cmp_gt_f32_e32 vcc, s64, v74
	s_nop 1
	v_cndmask_b32_e32 v74, v74, v75, vcc
	v_sqrt_f32_e32 v75, v74
	s_nop 0
	v_add_u32_e32 v76, -1, v75
	v_add_u32_e32 v77, 1, v75
	v_fma_f32 v78, -v76, v75, v74
	v_fma_f32 v79, -v77, v75, v74
	v_cmp_ge_f32_e64 s[8:9], 0, v78
	s_nop 1
	v_cndmask_b32_e64 v75, v75, v76, s[8:9]
	v_cmp_lt_f32_e64 s[8:9], 0, v79
	s_nop 1
	v_cndmask_b32_e64 v75, v75, v77, s[8:9]
	v_mul_f32_e32 v76, 0x37800000, v75
	v_cndmask_b32_e32 v75, v75, v76, vcc
	v_cmp_class_f32_e32 vcc, v74, v55
	s_nop 1
	v_cndmask_b32_e32 v74, v75, v74, vcc
	v_div_scale_f32 v75, s[8:9], v74, v74, 1.0
	v_rcp_f32_e32 v77, v75
	v_div_scale_f32 v76, vcc, 1.0, v74, 1.0
	v_fma_f32 v78, -v75, v77, 1.0
	v_fmac_f32_e32 v77, v78, v77
	v_mul_f32_e32 v78, v76, v77
	v_fma_f32 v79, -v75, v78, v76
	v_fmac_f32_e32 v78, v79, v77
	v_fma_f32 v75, -v75, v78, v76
	v_div_fmas_f32 v75, v75, v77, v78
	v_div_fixup_f32 v74, v75, v74, 1.0
	v_mul_f32_e32 v17, v74, v17
	v_mul_f32_e32 v37, v74, v37
	v_mul_f32_e32 v75, v74, v66
	v_mul_f32_e32 v17, v42, v17
	v_mul_f32_e32 v37, v43, v37
	v_cvt_pk_bf16_f32 v66, v17, v37
	s_waitcnt vmcnt(29)
; __device__ __forceinline__ unsigned cvt_pk_bf16(float lo, float hi) { unsigned r; asm volatile("v_cvt_pk_bf16_f32 %0, %1, %2" : "=v"(r) : "v"(lo), "v"(hi)); return r; }
; __device__ __forceinline__ float bf2f(unsigned short b) { return __uint_as_float(((unsigned)b) << 16); }
; __device__ __forceinline__ float bflo(unsigned w) { return __uint_as_float(w << 16); }
; __device__ __forceinline__ float bfhi(unsigned w) { return __uint_as_float(w & 0xffff0000u); }
; __device__ __forceinline__ unsigned short f2bf(float f) { return (unsigned short)(cvt_pk_bf16(f, 0.f) & 0xffffu); }
; __global__ void __launch_bounds__(NTHREADS, 2) fwd_megakernel(Params P) {
;     ...
;               u32x4 o; o.x = cvt_pk_bf16(v[0] * ri * g[0], v[1] * ri * g[1]); o.y = cvt_pk_bf16(v[2] * ri * g[2], v[3] * ri * g[3]); o.z = cvt_pk_bf16(v[4] * ri * g[4], v[5] * ri * g[5]); o.w = cvt_pk_bf16(v[6] * ri * g[6], v[7] * ri * g[7]);
;               *(u32x4*)(QN + (size_t)tok * 512 + 8 * lane) = o; }
;             { const u32x2 w = *(const u32x2*)(z + 512 + 4 * lane);
;               float v[4] = {bflo(w.x), bfhi(w.x), bflo(w.y), bfhi(w.y)}; const float s = (v[0] * v[0] + v[1] * v[1]) + (v[2] * v[2] + v[3] * v[3]);
;               const float ri = 1.0f / sqrtf(wave_sum(s) * (1.f / 256.f) + EPS); const float* g = kp->in[I_KVA_NORM] + 4 * lane;
;               u32x2 o; o.x = cvt_pk_bf16(v[0] * ri * g[0], v[1] * ri * g[1]); o.y = cvt_pk_bf16(v[2] * ri * g[2], v[3] * ri * g[3]);
;               *(u32x2*)(KVN + (size_t)tok * 256 + 4 * lane) = o; }
;             { const float v = bf2f(z[768 + lane]); const float ri = 1.0f / sqrtf(wave_sum(v * v) * (1.f / 64.f) + EPS);
;               const float y = v * ri * kp->in[I_KROPE_NORM][lane]; const float yp = __shfl_xor(y, 32);
;               const float c = ROPE64[pos * 32 + (lane & 31)], s = ROPE64[4096 * 32 + pos * 32 + (lane & 31)];
;               const float o = lane < 32 ? y * c - yp * s : y * c + yp * s;
;               KR[(size_t)tok * 64 + lane] = f2bf(o); }
	s_nop 0
	v_mov_b64_e32 v[42:43], v[116:117]
	s_nop 1
	v_mul_f32_e32 v67, v74, v67
	v_mul_f32_e32 v72, v74, v72
	v_mul_f32_e32 v68, v74, v68
	v_mul_f32_e32 v73, v74, v73
	v_mul_f32_e32 v69, v74, v69
	v_mul_f32_e32 v17, v42, v75
	v_mul_f32_e32 v37, v43, v67
	v_cvt_pk_bf16_f32 v67, v17, v37
	s_waitcnt vmcnt(28)
	s_nop 0
	v_mov_b64_e32 v[42:43], v[118:119]
	s_nop 1
	v_mul_f32_e32 v17, v72, v42
	v_mul_f32_e32 v37, v68, v43
	v_cvt_pk_bf16_f32 v68, v17, v37
	s_waitcnt vmcnt(27)
	s_nop 0
	v_mov_b64_e32 v[42:43], v[120:121]
	s_nop 1
	v_mul_f32_e32 v17, v73, v42
	v_mul_f32_e32 v37, v69, v43
	v_cvt_pk_bf16_f32 v69, v17, v37
	global_store_dwordx4 v[44:45], v[66:69], off
	s_waitcnt vmcnt(27)
	s_nop 0
	v_mov_b64_e32 v[42:43], v[122:123]
	s_nop 1
	s_load_dwordx2 s[72:73], s[10:11], 0x70
	s_load_dwordx4 s[16:19], s[10:11], 0x98
	s_load_dwordx2 s[52:53], s[10:11], 0xa8
	s_waitcnt lgkmcnt(0)
	s_waitcnt vmcnt(26)
	s_nop 0
	v_mov_b64_e32 v[44:45], v[124:125]
	s_nop 1
	v_lshlrev_b32_e32 v17, 16, v42
	v_and_b32_e32 v37, 0xffff0000, v42
	v_lshlrev_b32_e32 v42, 16, v43
	v_and_b32_e32 v43, 0xffff0000, v43
	v_mul_f32_e32 v46, v37, v37
	v_mul_f32_e32 v47, v43, v43
	v_fmac_f32_e32 v46, v17, v17
	v_fmac_f32_e32 v47, v42, v42
	v_add_f32_e32 v46, v46, v47
	s_nop 1
	v_mov_b32_dpp v47, v46 quad_perm:[1,0,3,2] row_mask:0xf bank_mask:0xf
	s_waitcnt lgkmcnt(0)
	v_add_f32_e32 v46, v46, v47
	s_nop 1
	v_mov_b32_dpp v47, v46 quad_perm:[2,3,0,1] row_mask:0xf bank_mask:0xf
	s_waitcnt lgkmcnt(0)
	v_add_f32_e32 v46, v46, v47
	s_nop 1
	v_mov_b32_dpp v47, v46 row_shl:4 row_mask:0xf bank_mask:0x5
	s_nop 1
	v_mov_b32_dpp v47, v46 row_shr:4 row_mask:0xf bank_mask:0xa
	s_waitcnt lgkmcnt(0)
	v_add_f32_e32 v46, v46, v47
	s_nop 1
	v_mov_b32_dpp v47, v46 row_ror:8 row_mask:0xf bank_mask:0xf
	s_waitcnt lgkmcnt(0)
	v_add_f32_e32 v46, v46, v47
	v_mov_b32_e32 v47, v46
	s_nop 1
	v_permlane16_swap_b32_e32 v47, v46
	s_waitcnt lgkmcnt(0)
	v_add_f32_e32 v46, v46, v47
	v_mov_b32_e32 v47, v46
	s_nop 1
	v_permlane32_swap_b32_e32 v47, v46
	s_waitcnt lgkmcnt(0)
	v_add_f32_e32 v46, v46, v47
	v_fmamk_f32 v46, v46, 0x3b800000, v54
	v_mul_f32_e32 v47, 0x4f800000, v46
	v_cmp_gt_f32_e32 vcc, s64, v46
	s_nop 1
	v_cndmask_b32_e32 v46, v46, v47, vcc
	v_sqrt_f32_e32 v47, v46
	s_nop 0
	v_add_u32_e32 v66, -1, v47
	v_add_u32_e32 v67, 1, v47
	v_fma_f32 v68, -v66, v47, v46
	v_fma_f32 v69, -v67, v47, v46
	v_cmp_ge_f32_e64 s[8:9], 0, v68
	s_nop 1
	v_cndmask_b32_e64 v47, v47, v66, s[8:9]
	v_cmp_lt_f32_e64 s[8:9], 0, v69
	s_nop 1
	v_cndmask_b32_e64 v47, v47, v67, s[8:9]
	v_mul_f32_e32 v66, 0x37800000, v47
	v_cndmask_b32_e32 v47, v47, v66, vcc
	v_cmp_class_f32_e32 vcc, v46, v55
	s_nop 1
	v_cndmask_b32_e32 v46, v47, v46, vcc
	v_div_scale_f32 v47, s[8:9], v46, v46, 1.0
	v_rcp_f32_e32 v67, v47
	v_div_scale_f32 v66, vcc, 1.0, v46, 1.0
	v_fma_f32 v68, -v47, v67, 1.0
	v_fmac_f32_e32 v67, v68, v67
	v_mul_f32_e32 v68, v66, v67
	v_fma_f32 v69, -v47, v68, v66
	v_fmac_f32_e32 v68, v69, v67
	v_fma_f32 v47, -v47, v68, v66
	v_div_fmas_f32 v47, v47, v67, v68
	v_div_fixup_f32 v46, v47, v46, 1.0
	v_mul_f32_e32 v17, v46, v17
	v_mul_f32_e32 v37, v46, v37
	v_mul_f32_e32 v47, v46, v42
	v_mul_f32_e32 v17, v44, v17
	v_mul_f32_e32 v37, v45, v37
	v_cvt_pk_bf16_f32 v42, v17, v37
	s_waitcnt vmcnt(25)
	s_nop 0
	v_mov_b64_e32 v[44:45], v[126:127]
	s_nop 1
	v_mul_f32_e32 v43, v46, v43
	v_mul_f32_e32 v17, v44, v47
	v_mul_f32_e32 v37, v45, v43
	v_cvt_pk_bf16_f32 v43, v17, v37
	global_store_dwordx2 v[48:49], v[42:43], off
	s_waitcnt vmcnt(25)
	s_nop 0
	v_mov_b32_e32 v17, v80
	s_nop 1
	s_waitcnt vmcnt(24)
	s_nop 0
	v_mov_b32_e32 v37, v82
	s_nop 1
	s_nop 0
	s_waitcnt vmcnt(23)
	s_nop 0
	v_mov_b32_e32 v0, v84
	s_nop 1
	s_nop 0
	s_waitcnt vmcnt(22)
	s_nop 0
	v_mov_b32_e32 v42, v86
	s_nop 1
	v_lshlrev_b32_e32 v17, 16, v17
	v_mul_f32_e32 v43, v17, v17
	ds_bpermute_b32 v43, v60, v43
	s_waitcnt lgkmcnt(0)
	v_fmac_f32_e32 v43, v17, v17
	s_nop 1
	v_mov_b32_dpp v44, v43 quad_perm:[2,3,0,1] row_mask:0xf bank_mask:0xf
	s_waitcnt lgkmcnt(0)
	v_add_f32_e32 v43, v43, v44
	s_nop 1
	v_mov_b32_dpp v44, v43 row_shl:4 row_mask:0xf bank_mask:0x5
	s_nop 1
	v_mov_b32_dpp v44, v43 row_shr:4 row_mask:0xf bank_mask:0xa
	s_waitcnt lgkmcnt(0)
	v_add_f32_e32 v43, v43, v44
	s_nop 1
	v_mov_b32_dpp v44, v43 row_ror:8 row_mask:0xf bank_mask:0xf
	s_waitcnt lgkmcnt(0)
	v_add_f32_e32 v43, v43, v44
	v_mov_b32_e32 v44, v43
	s_nop 1
	v_permlane16_swap_b32_e32 v44, v43
	s_waitcnt lgkmcnt(0)
	v_add_f32_e32 v43, v43, v44
	v_mov_b32_e32 v44, v43
	s_nop 1
	v_permlane32_swap_b32_e32 v44, v43
	s_waitcnt lgkmcnt(0)
	v_add_f32_e32 v43, v43, v44
	v_fmamk_f32 v43, v43, 0x3c800000, v54
	v_mul_f32_e32 v44, 0x4f800000, v43
	v_cmp_gt_f32_e32 vcc, s64, v43
	s_nop 1
	v_cndmask_b32_e32 v43, v43, v44, vcc
	v_sqrt_f32_e32 v44, v43
	s_nop 0
	v_add_u32_e32 v45, -1, v44
	v_add_u32_e32 v46, 1, v44
	v_fma_f32 v47, -v45, v44, v43
	v_fma_f32 v48, -v46, v44, v43
	v_cmp_ge_f32_e64 s[8:9], 0, v47
	s_nop 1
	v_cndmask_b32_e64 v44, v44, v45, s[8:9]
	v_cmp_lt_f32_e64 s[8:9], 0, v48
	s_nop 1
	v_cndmask_b32_e64 v44, v44, v46, s[8:9]
	v_mul_f32_e32 v45, 0x37800000, v44
	v_cndmask_b32_e32 v44, v44, v45, vcc
	v_cmp_class_f32_e32 vcc, v43, v55
	s_nop 1
	v_cndmask_b32_e32 v43, v44, v43, vcc
	v_div_scale_f32 v44, s[8:9], v43, v43, 1.0
	v_rcp_f32_e32 v46, v44
	v_div_scale_f32 v45, vcc, 1.0, v43, 1.0
	v_fma_f32 v47, -v44, v46, 1.0
	v_fmac_f32_e32 v46, v47, v46
	v_mul_f32_e32 v47, v45, v46
	v_fma_f32 v48, -v44, v47, v45
	v_fmac_f32_e32 v47, v48, v46
	v_fma_f32 v44, -v44, v47, v45
	v_div_fmas_f32 v44, v44, v46, v47
	v_div_fixup_f32 v43, v44, v43, 1.0
	v_mul_f32_e32 v17, v43, v17
	v_mul_f32_e32 v17, v37, v17
	ds_bpermute_b32 v37, v65, v17
	s_waitcnt lgkmcnt(0)
; __device__ __forceinline__ unsigned cvt_pk_bf16(float lo, float hi) { unsigned r; asm volatile("v_cvt_pk_bf16_f32 %0, %1, %2" : "=v"(r) : "v"(lo), "v"(hi)); return r; }
; __device__ __forceinline__ float bf2f(unsigned short b) { return __uint_as_float(((unsigned)b) << 16); }
; __device__ __forceinline__ float bflo(unsigned w) { return __uint_as_float(w << 16); }
; __device__ __forceinline__ float bfhi(unsigned w) { return __uint_as_float(w & 0xffff0000u); }
; __device__ __forceinline__ unsigned short f2bf(float f) { return (unsigned short)(cvt_pk_bf16(f, 0.f) & 0xffffu); }
; template <int W> __device__ __forceinline__ float group_sum(float v) {
; #pragma unroll
;     for (int o = 1; o < W; o <<= 1) v += __shfl_xor(v, o);
;     return v;
; }
; __global__ void __launch_bounds__(NTHREADS, 2) fwd_megakernel(Params P) {
;     ...
;             { const float v = bf2f(z[768 + lane]); const float ri = 1.0f / sqrtf(wave_sum(v * v) * (1.f / 64.f) + EPS);
;               const float y = v * ri * kp->in[I_KROPE_NORM][lane]; const float yp = __shfl_xor(y, 32);
;               const float c = ROPE64[pos * 32 + (lane & 31)], s = ROPE64[4096 * 32 + pos * 32 + (lane & 31)];
;               const float o = lane < 32 ? y * c - yp * s : y * c + yp * s;
;               KR[(size_t)tok * 64 + lane] = f2bf(o); }
; #pragma unroll
;             for (int p = 0; p < 2; ++p) {
;                 const int d0 = 8 * (lane & 15);
;                 { const u32x4 w = *(const u32x4*)(z + 832 + p * 512 + 8 * lane);
;                   float v[8] = {bflo(w.x), bfhi(w.x), bflo(w.y), bfhi(w.y), bflo(w.z), bfhi(w.z), bflo(w.w), bfhi(w.w)}; float s = 0.f;
; #pragma unroll
;                   for (int j = 0; j < 8; ++j) s += v[j] * v[j];
;                   const float ri = CNA / sqrtf(group_sum<16>(s) * (1.f / 128.f) + EPS); const float* g = kp->in[I_NAQ_NORM] + d0;
;                   u32x4 o; o.x = cvt_pk_bf16(v[0] * ri * g[0], v[1] * ri * g[1]); o.y = cvt_pk_bf16(v[2] * ri * g[2], v[3] * ri * g[3]); o.z = cvt_pk_bf16(v[4] * ri * g[4], v[5] * ri * g[5]); o.w = cvt_pk_bf16(v[6] * ri * g[6], v[7] * ri * g[7]);
;                   *(u32x4*)(NQ + (size_t)tok * 1024 + p * 512 + 8 * lane) = o; }
	v_mul_f32_e32 v37, v42, v37
	v_cndmask_b32_e64 v37, v37, -v37, s[4:5]
	v_fmac_f32_e32 v37, v0, v17
	v_cvt_pk_bf16_f32 v0, v37, v1
	global_store_short v[52:53], v0, off
	s_waitcnt vmcnt(22)
	s_nop 0
	v_mov_b64_e32 v[42:43], v[128:129]
	v_mov_b64_e32 v[44:45], v[130:131]
	s_nop 1
	s_waitcnt vmcnt(21)
	s_nop 0
	v_mov_b64_e32 v[46:47], v[132:133]
	s_nop 1
	v_and_b32_e32 v17, 0xffff0000, v42
	v_lshlrev_b32_e32 v0, 16, v42
	v_lshlrev_b32_e32 v37, 16, v43
	v_and_b32_e32 v42, 0xffff0000, v43
	v_lshlrev_b32_e32 v43, 16, v44
	v_and_b32_e32 v48, 0xffff0000, v44
	v_mul_f32_e32 v44, v17, v17
	v_fmac_f32_e32 v44, v0, v0
	v_fmac_f32_e32 v44, v37, v37
	v_fmac_f32_e32 v44, v42, v42
	v_fmac_f32_e32 v44, v43, v43
	v_lshlrev_b32_e32 v49, 16, v45
	v_fmac_f32_e32 v44, v48, v48
	v_and_b32_e32 v50, 0xffff0000, v45
	v_fmac_f32_e32 v44, v49, v49
	v_fmac_f32_e32 v44, v50, v50
	s_nop 1
	v_mov_b32_dpp v45, v44 quad_perm:[1,0,3,2] row_mask:0xf bank_mask:0xf
	s_waitcnt lgkmcnt(0)
	v_add_f32_e32 v44, v44, v45
	s_nop 1
	v_mov_b32_dpp v45, v44 quad_perm:[2,3,0,1] row_mask:0xf bank_mask:0xf
	s_waitcnt lgkmcnt(0)
	v_add_f32_e32 v44, v44, v45
	s_nop 1
	v_mov_b32_dpp v45, v44 row_shl:4 row_mask:0xf bank_mask:0x5
	s_nop 1
	v_mov_b32_dpp v45, v44 row_shr:4 row_mask:0xf bank_mask:0xa
	s_waitcnt lgkmcnt(0)
	v_add_f32_e32 v44, v44, v45
	s_nop 1
	v_mov_b32_dpp v45, v44 row_ror:8 row_mask:0xf bank_mask:0xf
	s_waitcnt lgkmcnt(0)
	v_add_f32_e32 v44, v44, v45
	v_fmamk_f32 v44, v44, 0x3c000000, v54
	v_mul_f32_e32 v45, 0x4f800000, v44
	v_cmp_gt_f32_e32 vcc, s64, v44
	s_nop 1
	v_cndmask_b32_e32 v44, v44, v45, vcc
	v_sqrt_f32_e32 v45, v44
	s_nop 0
	v_add_u32_e32 v51, -1, v45
	v_add_u32_e32 v52, 1, v45
	v_fma_f32 v53, -v51, v45, v44
	v_fma_f32 v66, -v52, v45, v44
	v_cmp_ge_f32_e64 s[8:9], 0, v53
	s_nop 1
	v_cndmask_b32_e64 v45, v45, v51, s[8:9]
	v_cmp_lt_f32_e64 s[8:9], 0, v66
	s_nop 1
	v_cndmask_b32_e64 v45, v45, v52, s[8:9]
	v_mul_f32_e32 v51, 0x37800000, v45
	v_cndmask_b32_e32 v45, v45, v51, vcc
	v_cmp_class_f32_e32 vcc, v44, v55
	s_nop 1
	v_cndmask_b32_e32 v44, v45, v44, vcc
	v_div_scale_f32 v45, s[8:9], v44, v44, s66
	v_rcp_f32_e32 v52, v45
	v_div_scale_f32 v51, vcc, s66, v44, s66
	v_fma_f32 v53, -v45, v52, 1.0
	v_fmac_f32_e32 v52, v53, v52
	v_mul_f32_e32 v53, v51, v52
	v_fma_f32 v66, -v45, v53, v51
	v_fmac_f32_e32 v53, v66, v52
	v_fma_f32 v45, -v45, v53, v51
	v_div_fmas_f32 v45, v45, v52, v53
	v_div_fixup_f32 v51, v45, v44, s66
	v_mul_f32_e32 v0, v51, v0
	v_mul_f32_e32 v17, v51, v17
	v_mul_f32_e32 v52, v51, v42
	v_mul_f32_e32 v0, v46, v0
	v_mul_f32_e32 v17, v47, v17
	v_cvt_pk_bf16_f32 v42, v0, v17
	s_waitcnt vmcnt(20)
	s_nop 0
	v_mov_b64_e32 v[44:45], v[134:135]
	s_nop 1
	v_mul_f32_e32 v37, v51, v37
	v_mul_f32_e32 v53, v51, v43
	v_mul_f32_e32 v0, v44, v37
	v_mul_f32_e32 v17, v45, v52
	v_cvt_pk_bf16_f32 v43, v0, v17
	s_waitcnt vmcnt(19)
	s_nop 0
	v_mov_b64_e32 v[44:45], v[136:137]
	s_nop 1
	v_mul_f32_e32 v0, v51, v48
	v_addc_co_u32_e64 v37, vcc, 0, v41, s[6:7]
	v_mul_f32_e32 v17, v53, v44
	v_mul_f32_e32 v0, v0, v45
	v_cvt_pk_bf16_f32 v44, v17, v0
	s_waitcnt vmcnt(18)
	s_nop 0
	v_mov_b64_e32 v[46:47], v[138:139]
	s_nop 1
	v_mul_f32_e32 v0, v51, v49
	v_mul_f32_e32 v17, v51, v50
	v_mul_f32_e32 v0, v0, v46
	v_mul_f32_e32 v17, v17, v47
	v_cvt_pk_bf16_f32 v45, v0, v17
	global_store_dwordx4 v[36:37], v[42:45], off
	s_waitcnt vmcnt(18)
	s_nop 0
	v_mov_b64_e32 v[42:43], v[140:141]
	v_mov_b64_e32 v[44:45], v[142:143]
	s_nop 1
	s_nop 0
	s_waitcnt vmcnt(17)
	s_nop 0
	v_mov_b64_e32 v[46:47], v[144:145]
	s_nop 1
	v_and_b32_e32 v17, 0xffff0000, v42
	v_lshlrev_b32_e32 v0, 16, v42
	v_mul_f32_e32 v42, v17, v17
	v_lshlrev_b32_e32 v48, 16, v43
	v_fmac_f32_e32 v42, v0, v0
	v_and_b32_e32 v43, 0xffff0000, v43
	v_fmac_f32_e32 v42, v48, v48
	v_lshlrev_b32_e32 v49, 16, v44
	v_fmac_f32_e32 v42, v43, v43
	v_and_b32_e32 v50, 0xffff0000, v44
	v_fmac_f32_e32 v42, v49, v49
	v_lshlrev_b32_e32 v51, 16, v45
	v_fmac_f32_e32 v42, v50, v50
	v_and_b32_e32 v52, 0xffff0000, v45
	v_fmac_f32_e32 v42, v51, v51
	v_fmac_f32_e32 v42, v52, v52
	s_nop 1
	v_mov_b32_dpp v44, v42 quad_perm:[1,0,3,2] row_mask:0xf bank_mask:0xf
	s_waitcnt lgkmcnt(0)
	v_add_f32_e32 v42, v42, v44
	s_nop 1
	v_mov_b32_dpp v44, v42 quad_perm:[2,3,0,1] row_mask:0xf bank_mask:0xf
	s_waitcnt lgkmcnt(0)
	v_add_f32_e32 v42, v42, v44
	s_nop 1
	v_mov_b32_dpp v44, v42 row_shl:4 row_mask:0xf bank_mask:0x5
	s_nop 1
	v_mov_b32_dpp v44, v42 row_shr:4 row_mask:0xf bank_mask:0xa
	s_waitcnt lgkmcnt(0)
	v_add_f32_e32 v42, v42, v44
	s_nop 1
	v_mov_b32_dpp v44, v42 row_ror:8 row_mask:0xf bank_mask:0xf
	s_waitcnt lgkmcnt(0)
	v_add_f32_e32 v42, v42, v44
	v_fmamk_f32 v42, v42, 0x3c000000, v54
	v_mul_f32_e32 v44, 0x4f800000, v42
	v_cmp_gt_f32_e32 vcc, s64, v42
	s_nop 1
	v_cndmask_b32_e32 v42, v42, v44, vcc
	v_sqrt_f32_e32 v44, v42
	s_nop 0
	v_add_u32_e32 v45, -1, v44
	v_add_u32_e32 v53, 1, v44
	v_fma_f32 v66, -v45, v44, v42
	v_fma_f32 v67, -v53, v44, v42
	v_cmp_ge_f32_e64 s[6:7], 0, v66
	s_nop 1
	v_cndmask_b32_e64 v44, v44, v45, s[6:7]
	v_cmp_lt_f32_e64 s[6:7], 0, v67
	s_nop 1
	v_cndmask_b32_e64 v44, v44, v53, s[6:7]
	v_mul_f32_e32 v45, 0x37800000, v44
	v_cndmask_b32_e32 v44, v44, v45, vcc
	v_cmp_class_f32_e32 vcc, v42, v55
	s_nop 1
	v_cndmask_b32_e32 v42, v44, v42, vcc
	v_div_scale_f32 v44, s[6:7], v42, v42, 1.0
	v_rcp_f32_e32 v53, v44
	v_div_scale_f32 v45, vcc, 1.0, v42, 1.0
	v_fma_f32 v66, -v44, v53, 1.0
	v_fmac_f32_e32 v53, v66, v53
	v_mul_f32_e32 v66, v45, v53
	v_fma_f32 v67, -v44, v66, v45
	v_fmac_f32_e32 v66, v67, v53
	v_fma_f32 v44, -v44, v66, v45
	v_div_fmas_f32 v44, v44, v53, v66
	v_div_fixup_f32 v53, v44, v42, 1.0
	v_mul_f32_e32 v0, v53, v0
	v_mul_f32_e32 v17, v53, v17
	v_mul_f32_e32 v0, v46, v0
	v_mul_f32_e32 v17, v47, v17
	v_cvt_pk_bf16_f32 v42, v0, v17
	s_waitcnt vmcnt(16)
; __device__ __forceinline__ unsigned cvt_pk_bf16(float lo, float hi) { unsigned r; asm volatile("v_cvt_pk_bf16_f32 %0, %1, %2" : "=v"(r) : "v"(lo), "v"(hi)); return r; }
; __device__ __forceinline__ float bflo(unsigned w) { return __uint_as_float(w << 16); }
; __device__ __forceinline__ float bfhi(unsigned w) { return __uint_as_float(w & 0xffff0000u); }
; __global__ void __launch_bounds__(NTHREADS, 2) fwd_megakernel(Params P) {
;     ...
;                   u32x4 o; o.x = cvt_pk_bf16(v[0] * ri * g[0], v[1] * ri * g[1]); o.y = cvt_pk_bf16(v[2] * ri * g[2], v[3] * ri * g[3]); o.z = cvt_pk_bf16(v[4] * ri * g[4], v[5] * ri * g[5]); o.w = cvt_pk_bf16(v[6] * ri * g[6], v[7] * ri * g[7]);
;                   *(u32x4*)(NQ + (size_t)tok * 1024 + p * 512 + 8 * lane) = o; }
;                 { const u32x4 w = *(const u32x4*)(z + 1856 + p * 512 + 8 * lane);
;                   float v[8] = {bflo(w.x), bfhi(w.x), bflo(w.y), bfhi(w.y), bflo(w.z), bfhi(w.z), bflo(w.w), bfhi(w.w)}; float s = 0.f;
; #pragma unroll
;                   for (int j = 0; j < 8; ++j) s += v[j] * v[j];
;                   const float ri = 1.0f / sqrtf(group_sum<16>(s) * (1.f / 128.f) + EPS); const float* g = kp->in[I_NAK_NORM] + d0;
;                   u32x4 o; o.x = cvt_pk_bf16(v[0] * ri * g[0], v[1] * ri * g[1]); o.y = cvt_pk_bf16(v[2] * ri * g[2], v[3] * ri * g[3]); o.z = cvt_pk_bf16(v[4] * ri * g[4], v[5] * ri * g[5]); o.w = cvt_pk_bf16(v[6] * ri * g[6], v[7] * ri * g[7]);
;                   *(u32x4*)(NK + (size_t)tok * 1024 + p * 512 + 8 * lane) = o; }
	s_nop 0
	v_mov_b64_e32 v[44:45], v[146:147]
	s_nop 1
	v_mul_f32_e32 v0, v53, v48
	v_mul_f32_e32 v17, v53, v43
	v_add_co_u32_e32 v40, vcc, s68, v40
	v_mul_f32_e32 v0, v44, v0
	v_mul_f32_e32 v17, v45, v17
	v_cvt_pk_bf16_f32 v43, v0, v17
	s_waitcnt vmcnt(15)
	s_nop 0
	v_mov_b64_e32 v[44:45], v[148:149]
	s_nop 1
	v_mul_f32_e32 v0, v53, v49
	v_mul_f32_e32 v17, v53, v50
	v_addc_co_u32_e32 v41, vcc, 0, v41, vcc
	v_mul_f32_e32 v0, v0, v44
	v_mul_f32_e32 v17, v17, v45
	v_cvt_pk_bf16_f32 v44, v0, v17
	s_waitcnt vmcnt(14)
	s_nop 0
	v_mov_b64_e32 v[46:47], v[150:151]
	s_nop 1
	v_mul_f32_e32 v0, v53, v51
	v_mul_f32_e32 v17, v53, v52
	v_mul_f32_e32 v0, v0, v46
	v_mul_f32_e32 v17, v17, v47
	v_cvt_pk_bf16_f32 v45, v0, v17
	global_store_dwordx4 v[40:41], v[42:45], off
	s_waitcnt vmcnt(14)
	s_nop 0
	v_mov_b64_e32 v[42:43], v[152:153]
	v_mov_b64_e32 v[44:45], v[154:155]
	s_nop 1
	s_nop 0
	s_waitcnt vmcnt(13)
	s_nop 0
	v_mov_b64_e32 v[38:39], v[156:157]
	s_nop 1
	v_and_b32_e32 v17, 0xffff0000, v42
	v_lshlrev_b32_e32 v0, 16, v42
	v_mul_f32_e32 v42, v17, v17
	v_lshlrev_b32_e32 v46, 16, v43
	v_fmac_f32_e32 v42, v0, v0
	v_and_b32_e32 v43, 0xffff0000, v43
	v_fmac_f32_e32 v42, v46, v46
	v_lshlrev_b32_e32 v47, 16, v44
	v_fmac_f32_e32 v42, v43, v43
	v_and_b32_e32 v44, 0xffff0000, v44
	v_fmac_f32_e32 v42, v47, v47
	v_lshlrev_b32_e32 v48, 16, v45
	v_fmac_f32_e32 v42, v44, v44
	v_and_b32_e32 v45, 0xffff0000, v45
	v_fmac_f32_e32 v42, v48, v48
	v_fmac_f32_e32 v42, v45, v45
	s_nop 1
	v_mov_b32_dpp v49, v42 quad_perm:[1,0,3,2] row_mask:0xf bank_mask:0xf
	s_waitcnt lgkmcnt(0)
	v_add_f32_e32 v42, v42, v49
	s_nop 1
	v_mov_b32_dpp v49, v42 quad_perm:[2,3,0,1] row_mask:0xf bank_mask:0xf
	s_waitcnt lgkmcnt(0)
	v_add_f32_e32 v42, v42, v49
	s_nop 1
	v_mov_b32_dpp v49, v42 row_shl:4 row_mask:0xf bank_mask:0x5
	s_nop 1
	v_mov_b32_dpp v49, v42 row_shr:4 row_mask:0xf bank_mask:0xa
	s_waitcnt lgkmcnt(0)
	v_add_f32_e32 v42, v42, v49
	s_nop 1
	v_mov_b32_dpp v49, v42 row_ror:8 row_mask:0xf bank_mask:0xf
	s_waitcnt lgkmcnt(0)
	v_add_f32_e32 v42, v42, v49
	v_fmamk_f32 v42, v42, 0x3c000000, v54
	v_mul_f32_e32 v49, 0x4f800000, v42
	v_cmp_gt_f32_e32 vcc, s64, v42
	s_nop 1
	v_cndmask_b32_e32 v42, v42, v49, vcc
	v_sqrt_f32_e32 v49, v42
	s_nop 0
	v_add_u32_e32 v50, -1, v49
	v_add_u32_e32 v51, 1, v49
	v_fma_f32 v52, -v50, v49, v42
	v_fma_f32 v53, -v51, v49, v42
	v_cmp_ge_f32_e64 s[6:7], 0, v52
	s_nop 1
	v_cndmask_b32_e64 v49, v49, v50, s[6:7]
	v_cmp_lt_f32_e64 s[6:7], 0, v53
	s_nop 1
	v_cndmask_b32_e64 v49, v49, v51, s[6:7]
	v_mul_f32_e32 v50, 0x37800000, v49
	v_cndmask_b32_e32 v49, v49, v50, vcc
	v_cmp_class_f32_e32 vcc, v42, v55
	s_nop 1
	v_cndmask_b32_e32 v42, v49, v42, vcc
	v_div_scale_f32 v49, s[6:7], v42, v42, s66
	v_rcp_f32_e32 v51, v49
	v_div_scale_f32 v50, vcc, s66, v42, s66
	v_fma_f32 v52, -v49, v51, 1.0
	v_fmac_f32_e32 v51, v52, v51
	v_mul_f32_e32 v52, v50, v51
	v_fma_f32 v53, -v49, v52, v50
	v_fmac_f32_e32 v52, v53, v51
	v_fma_f32 v49, -v49, v52, v50
	v_div_fmas_f32 v49, v49, v51, v52
	v_div_fixup_f32 v49, v49, v42, s66
	v_mul_f32_e32 v0, v49, v0
	v_mul_f32_e32 v17, v49, v17
	v_mul_f32_e32 v0, v38, v0
	v_mul_f32_e32 v17, v39, v17
	v_cvt_pk_bf16_f32 v42, v0, v17
	s_waitcnt vmcnt(12)
	s_nop 0
	v_mov_b64_e32 v[38:39], v[158:159]
	s_nop 1
	v_mul_f32_e32 v0, v49, v46
	v_mul_f32_e32 v17, v49, v43
	v_add_co_u32_e32 v34, vcc, s69, v34
	v_mul_f32_e32 v0, v38, v0
	v_mul_f32_e32 v17, v39, v17
	v_cvt_pk_bf16_f32 v43, v0, v17
	s_waitcnt vmcnt(11)
; __device__ __forceinline__ unsigned cvt_pk_bf16(float lo, float hi) { unsigned r; asm volatile("v_cvt_pk_bf16_f32 %0, %1, %2" : "=v"(r) : "v"(lo), "v"(hi)); return r; }
; __device__ __forceinline__ float bflo(unsigned w) { return __uint_as_float(w << 16); }
; __device__ __forceinline__ float bfhi(unsigned w) { return __uint_as_float(w & 0xffff0000u); }
; __global__ void __launch_bounds__(NTHREADS, 2) fwd_megakernel(Params P) {
;     ...
;                 { const u32x4 w = *(const u32x4*)(z + 1856 + p * 512 + 8 * lane);
;                   float v[8] = {bflo(w.x), bfhi(w.x), bflo(w.y), bfhi(w.y), bflo(w.z), bfhi(w.z), bflo(w.w), bfhi(w.w)}; float s = 0.f;
; #pragma unroll
;                   for (int j = 0; j < 8; ++j) s += v[j] * v[j];
;                   const float ri = 1.0f / sqrtf(group_sum<16>(s) * (1.f / 128.f) + EPS); const float* g = kp->in[I_NAK_NORM] + d0;
;                   u32x4 o; o.x = cvt_pk_bf16(v[0] * ri * g[0], v[1] * ri * g[1]); o.y = cvt_pk_bf16(v[2] * ri * g[2], v[3] * ri * g[3]); o.z = cvt_pk_bf16(v[4] * ri * g[4], v[5] * ri * g[5]); o.w = cvt_pk_bf16(v[6] * ri * g[6], v[7] * ri * g[7]);
;                   *(u32x4*)(NK + (size_t)tok * 1024 + p * 512 + 8 * lane) = o; }
;             }
;         }
	s_nop 0
	v_mov_b64_e32 v[38:39], v[160:161]
	s_nop 1
	v_mul_f32_e32 v0, v49, v47
	v_mul_f32_e32 v17, v49, v44
	v_addc_co_u32_e32 v35, vcc, 0, v35, vcc
	v_mul_f32_e32 v0, v0, v38
	v_mul_f32_e32 v17, v17, v39
	v_cvt_pk_bf16_f32 v44, v0, v17
	s_waitcnt vmcnt(10)
	s_nop 0
	v_mov_b64_e32 v[38:39], v[162:163]
	s_nop 1
	v_mul_f32_e32 v0, v49, v48
	v_mul_f32_e32 v17, v49, v45
	v_mul_f32_e32 v0, v0, v38
	v_mul_f32_e32 v17, v17, v39
	v_cvt_pk_bf16_f32 v45, v0, v17
	global_store_dwordx4 v[36:37], v[42:45], off offset:1024
	s_waitcnt vmcnt(10)
	s_nop 0
	v_mov_b64_e32 v[34:35], v[164:165]
	v_mov_b64_e32 v[36:37], v[166:167]
	s_nop 1
	s_nop 0
	s_waitcnt vmcnt(9)
	s_nop 0
	v_mov_b64_e32 v[38:39], v[168:169]
	s_nop 1
	v_and_b32_e32 v17, 0xffff0000, v34
	v_lshlrev_b32_e32 v0, 16, v34
	v_mul_f32_e32 v34, v17, v17
	v_lshlrev_b32_e32 v42, 16, v35
	v_fmac_f32_e32 v34, v0, v0
	v_and_b32_e32 v35, 0xffff0000, v35
	v_fmac_f32_e32 v34, v42, v42
	v_lshlrev_b32_e32 v43, 16, v36
	v_fmac_f32_e32 v34, v35, v35
	v_and_b32_e32 v44, 0xffff0000, v36
	v_fmac_f32_e32 v34, v43, v43
	v_lshlrev_b32_e32 v45, 16, v37
	v_fmac_f32_e32 v34, v44, v44
	v_and_b32_e32 v46, 0xffff0000, v37
	v_fmac_f32_e32 v34, v45, v45
	v_fmac_f32_e32 v34, v46, v46
	s_nop 1
	v_mov_b32_dpp v36, v34 quad_perm:[1,0,3,2] row_mask:0xf bank_mask:0xf
	s_waitcnt lgkmcnt(0)
	v_add_f32_e32 v34, v34, v36
	s_nop 1
	v_mov_b32_dpp v36, v34 quad_perm:[2,3,0,1] row_mask:0xf bank_mask:0xf
	s_waitcnt lgkmcnt(0)
	v_add_f32_e32 v34, v34, v36
	s_nop 1
	v_mov_b32_dpp v36, v34 row_shl:4 row_mask:0xf bank_mask:0x5
	s_nop 1
	v_mov_b32_dpp v36, v34 row_shr:4 row_mask:0xf bank_mask:0xa
	s_waitcnt lgkmcnt(0)
	v_add_f32_e32 v34, v34, v36
	s_nop 1
	v_mov_b32_dpp v36, v34 row_ror:8 row_mask:0xf bank_mask:0xf
	s_waitcnt lgkmcnt(0)
	v_add_f32_e32 v34, v34, v36
	v_fmamk_f32 v34, v34, 0x3c000000, v54
	v_mul_f32_e32 v36, 0x4f800000, v34
	v_cmp_gt_f32_e32 vcc, s64, v34
	s_nop 1
	v_cndmask_b32_e32 v34, v34, v36, vcc
	v_sqrt_f32_e32 v36, v34
	s_nop 0
	v_add_u32_e32 v37, -1, v36
	v_add_u32_e32 v47, 1, v36
	v_fma_f32 v48, -v37, v36, v34
	v_fma_f32 v49, -v47, v36, v34
	v_cmp_ge_f32_e64 s[6:7], 0, v48
	s_nop 1
	v_cndmask_b32_e64 v36, v36, v37, s[6:7]
	v_cmp_lt_f32_e64 s[6:7], 0, v49
	s_nop 1
	v_cndmask_b32_e64 v36, v36, v47, s[6:7]
	v_mul_f32_e32 v37, 0x37800000, v36
	v_cndmask_b32_e32 v36, v36, v37, vcc
	v_cmp_class_f32_e32 vcc, v34, v55
	s_nop 1
	v_cndmask_b32_e32 v34, v36, v34, vcc
	v_div_scale_f32 v36, s[6:7], v34, v34, 1.0
	v_rcp_f32_e32 v47, v36
	v_div_scale_f32 v37, vcc, 1.0, v34, 1.0
	v_fma_f32 v48, -v36, v47, 1.0
	v_fmac_f32_e32 v47, v48, v47
	v_mul_f32_e32 v48, v37, v47
	v_fma_f32 v49, -v36, v48, v37
	v_fmac_f32_e32 v48, v49, v47
	v_fma_f32 v36, -v36, v48, v37
	v_div_fmas_f32 v36, v36, v47, v48
	v_div_fixup_f32 v47, v36, v34, 1.0
	v_mul_f32_e32 v0, v47, v0
	v_mul_f32_e32 v17, v47, v17
	v_mul_f32_e32 v0, v38, v0
	v_mul_f32_e32 v17, v39, v17
	v_cvt_pk_bf16_f32 v34, v0, v17
	s_waitcnt vmcnt(8)
	s_nop 0
	v_mov_b64_e32 v[36:37], v[170:171]
	s_nop 1
	v_mul_f32_e32 v0, v47, v42
	v_mul_f32_e32 v17, v47, v35
	v_mul_f32_e32 v0, v36, v0
	v_mul_f32_e32 v17, v37, v17
	v_cvt_pk_bf16_f32 v35, v0, v17
	s_waitcnt vmcnt(7)
	s_nop 0
	v_mov_b64_e32 v[36:37], v[172:173]
	s_nop 1
	v_mul_f32_e32 v0, v47, v43
	v_mul_f32_e32 v17, v47, v44
	v_mul_f32_e32 v0, v0, v36
	v_mul_f32_e32 v17, v17, v37
	v_cvt_pk_bf16_f32 v36, v0, v17
	s_waitcnt vmcnt(6)
	s_nop 0
	v_mov_b64_e32 v[38:39], v[174:175]
	s_nop 1
	v_mul_f32_e32 v0, v47, v45
	v_mul_f32_e32 v17, v47, v46
	v_mul_f32_e32 v0, v0, v38
	v_mul_f32_e32 v17, v17, v39
	v_cvt_pk_bf16_f32 v37, v0, v17
	global_store_dwordx4 v[40:41], v[34:37], off offset:1024
	s_cbranch_scc0 .LBB0_173
	s_branch .LBB0_165

; __device__ __forceinline__ float bflo(unsigned w) { return __uint_as_float(w << 16); }
; __device__ __forceinline__ float bfhi(unsigned w) { return __uint_as_float(w & 0xffff0000u); }
; template <int W> __device__ __forceinline__ float group_sum(float v) {
; #pragma unroll
;     for (int o = 1; o < W; o <<= 1) v += __shfl_xor(v, o);
;     return v;
; }
; __global__ void __launch_bounds__(NTHREADS, 2) fwd_megakernel(Params P) {
;     ...
;         _Pragma("unroll 1") for (int rp_ = 0; rp_ < REP_PREP; ++rp_) for (int tok = gw; tok < M; tok += ngw) {
;             const int pos = tok_pos(tok);
;             const bf16_t* q = Q1 + (size_t)tok * 1536 + hq * 192; bf16_t* qo = QM + (size_t)tok * 1536 + hq * 192;
;             const bf16_t* k = KV1 + (size_t)tok * 2048 + hq * 256; bf16_t* ko = KM + (size_t)tok * 1536 + hq * 192;
;             const u32x4 qa = *(const u32x4*)(q + sl * 16), qb = *(const u32x4*)(q + sl * 16 + 8), qr = *(const u32x4*)(q + 128 + sl * 8);
;             const u32x4 ka = *(const u32x4*)(k + sl * 16), kb = *(const u32x4*)(k + sl * 16 + 8), krv = *(const u32x4*)(KR + (size_t)tok * 64 + sl * 8);
;             const f32x4 c0 = *(const f32x4*)(ROPE64 + pos * 32 + (sl & 3) * 8), c1 = *(const f32x4*)(ROPE64 + pos * 32 + (sl & 3) * 8 + 4);
;             const f32x4 s0 = *(const f32x4*)(ROPE64 + 4096 * 32 + pos * 32 + (sl & 3) * 8), s1 = *(const f32x4*)(ROPE64 + 4096 * 32 + pos * 32 + (sl & 3) * 8 + 4);
;             { float v[16] = {bflo(qa.x), bfhi(qa.x), bflo(qa.y), bfhi(qa.y), bflo(qa.z), bfhi(qa.z), bflo(qa.w), bfhi(qa.w), bflo(qb.x), bfhi(qb.x), bflo(qb.y), bfhi(qb.y), bflo(qb.z), bfhi(qb.z), bflo(qb.w), bfhi(qb.w)};
;               float ss = 0.f;
; #pragma unroll
;               for (int j = 0; j < 16; ++j) ss += v[j] * v[j];
;               const float ri = CM / sqrtf(group_sum<8>(ss) * (1.f / 128.f) + EPS);
.LBB0_314:
	v_lshl_add_u64 v[168:169], s[18:19], 0, v[70:71]
	v_lshl_add_u64 v[166:167], s[18:19], 0, v[72:73]
	v_add_co_u32_e32 v156, vcc, 0xec00000, v168
	s_nop 1
	s_cmpk_lt_i32 s65, 0x2000
	s_nop 0
	v_addc_co_u32_e32 v157, vcc, 0, v169, vcc
	s_nop 1
	s_cselect_b32 s8, s58, 0x7ff
	s_nop 0
	v_add_co_u32_e32 v160, vcc, s59, v166
	s_nop 1
	v_lshl_add_u64 v[150:151], s[18:19], 0, v[74:75]
	v_lshl_add_u64 v[154:155], v[168:169], 0, s[46:47]
	s_and_b32 s6, s8, s65
	s_nop 0
	global_load_dwordx4 v[172:175], v[156:157], off
	global_load_dwordx4 v[176:179], v[154:155], off offset:16
	v_addc_co_u32_e32 v161, vcc, 0, v167, vcc
	s_nop 1
	v_lshl_add_u64 v[158:159], v[150:151], 0, s[36:37]
	v_add_co_u32_e32 v150, vcc, s60, v150
	s_nop 1
	s_lshl_b32 s44, s6, 7
	s_nop 0
	global_load_dwordx4 v[180:183], v[160:161], off offset:256
	global_load_dwordx4 v[184:187], v[158:159], off offset:16
	v_lshl_add_u64 v[152:153], s[18:19], 0, v[76:77]
	v_addc_co_u32_e32 v151, vcc, 0, v151, vcc
	s_nop 1
	v_lshl_add_u64 v[162:163], v[58:59], 0, s[44:45]
	v_lshl_add_u64 v[164:165], v[60:61], 0, s[44:45]
	global_load_dwordx4 v[188:191], v[162:163], off
	global_load_dwordx4 v[192:195], v[164:165], off
	global_load_dwordx4 v[196:199], v[162:163], off offset:16
	global_load_dwordx4 v[204:207], v[164:165], off offset:16
	global_load_dwordx4 v[208:211], v[150:151], off
	global_load_dwordx4 v[212:215], v[152:153], off
	v_lshl_add_u64 v[80:81], s[18:19], 0, v[70:71]
	v_add_co_u32_e64 v84, s[6:7], s63, v80
	v_lshl_add_u64 v[78:79], s[18:19], 0, v[72:73]
	v_add_co_u32_e32 v46, vcc, 0xec00000, v80
	v_addc_co_u32_e64 v85, s[6:7], 0, v81, s[6:7]
	s_cmpk_lt_i32 s65, 0x2000
	v_add_co_u32_e64 v82, s[6:7], s63, v78
	v_addc_co_u32_e32 v47, vcc, 0, v81, vcc
	s_cselect_b32 s8, s58, 0x7ff
	v_addc_co_u32_e64 v83, s[6:7], 0, v79, s[6:7]
	v_add_co_u32_e32 v50, vcc, s59, v78
	v_lshl_add_u64 v[40:41], s[18:19], 0, v[74:75]
	v_lshl_add_u64 v[44:45], v[80:81], 0, s[46:47]
	s_and_b32 s6, s8, s65
	s_waitcnt vmcnt(9)
	s_nop 0
	v_mov_b64_e32 v[86:87], v[172:173]
	v_mov_b64_e32 v[88:89], v[174:175]
	s_nop 1
	s_waitcnt vmcnt(8)
	s_nop 0
	v_mov_b64_e32 v[94:95], v[176:177]
	v_mov_b64_e32 v[96:97], v[178:179]
	s_nop 1
	v_addc_co_u32_e32 v51, vcc, 0, v79, vcc
	v_lshl_add_u64 v[48:49], v[40:41], 0, s[36:37]
	v_add_co_u32_e32 v40, vcc, s60, v40
	s_lshl_b32 s44, s6, 7
	s_waitcnt vmcnt(7)
	s_nop 0
	v_mov_b64_e32 v[98:99], v[180:181]
	v_mov_b64_e32 v[100:101], v[182:183]
	s_nop 1
	s_waitcnt vmcnt(6)
	s_nop 0
	v_mov_b64_e32 v[102:103], v[184:185]
	v_mov_b64_e32 v[104:105], v[186:187]
	s_nop 1
	v_lshl_add_u64 v[42:43], s[18:19], 0, v[76:77]
	v_addc_co_u32_e32 v41, vcc, 0, v41, vcc
	v_lshl_add_u64 v[52:53], v[58:59], 0, s[44:45]
	v_lshl_add_u64 v[54:55], v[60:61], 0, s[44:45]
	s_waitcnt vmcnt(5)
	s_nop 0
	v_mov_b64_e32 v[44:45], v[188:189]
	v_mov_b64_e32 v[46:47], v[190:191]
	s_nop 1
	s_waitcnt vmcnt(4)
	s_nop 0
	v_mov_b64_e32 v[48:49], v[192:193]
	v_mov_b64_e32 v[50:51], v[194:195]
	s_nop 1
	s_waitcnt vmcnt(3)
	s_nop 0
	v_mov_b64_e32 v[106:107], v[196:197]
	v_mov_b64_e32 v[108:109], v[198:199]
	s_nop 1
	s_nop 0
	s_waitcnt vmcnt(2)
	s_nop 0
	v_mov_b64_e32 v[52:53], v[204:205]
	v_mov_b64_e32 v[54:55], v[206:207]
	s_nop 1
	s_nop 0
	s_waitcnt vmcnt(1)
	s_nop 0
	v_mov_b64_e32 v[110:111], v[208:209]
	v_mov_b64_e32 v[112:113], v[210:211]
	s_nop 1
	s_nop 0
	s_waitcnt vmcnt(0)
	s_nop 0
	v_mov_b64_e32 v[40:41], v[212:213]
	v_mov_b64_e32 v[42:43], v[214:215]
	s_nop 1
	s_add_i32 s65, s65, s26
	v_lshl_add_u64 v[76:77], v[76:77], 0, s[12:13]
	v_lshl_add_u64 v[74:75], v[74:75], 0, s[34:35]
	v_lshl_add_u64 v[72:73], v[72:73], 0, s[42:43]
	v_lshl_add_u64 v[70:71], v[70:71], 0, s[42:43]
	s_cmpk_gt_i32 s65, 0x3fff
	v_and_b32_e32 v115, 0xffff0000, v86
	v_lshlrev_b32_e32 v114, 16, v86
	v_mul_f32_e32 v128, v115, v115
	v_lshlrev_b32_e32 v116, 16, v87
	v_fmac_f32_e32 v128, v114, v114
	v_and_b32_e32 v117, 0xffff0000, v87
	v_lshlrev_b32_e32 v120, 16, v89
	v_and_b32_e32 v130, 0xffff0000, v98
	v_lshlrev_b32_e32 v129, 16, v98
	v_mul_f32_e32 v141, v130, v130
	v_and_b32_e32 v121, 0xffff0000, v89
	v_lshlrev_b32_e32 v131, 16, v99
	v_mov_b32_e32 v89, v54
	v_mov_b32_e32 v54, v109
	v_and_b32_e32 v109, 0xffff0000, v110
	v_fmac_f32_e32 v128, v116, v116
	v_fmac_f32_e32 v141, v129, v129
	v_lshlrev_b32_e32 v118, 16, v88
	v_and_b32_e32 v132, 0xffff0000, v99
	v_mov_b32_e32 v86, v46
	v_mov_b32_e32 v87, v50
	v_mov_b32_e32 v50, v47
	v_mov_b32_e32 v46, v106
	v_mov_b32_e32 v47, v52
	v_mov_b32_e32 v52, v107
	v_lshlrev_b32_e32 v107, 16, v110
	v_mul_f32_e32 v106, v109, v109
	v_fmac_f32_e32 v128, v117, v117
	v_fmac_f32_e32 v141, v131, v131
	v_and_b32_e32 v119, 0xffff0000, v88
	v_lshlrev_b32_e32 v133, 16, v100
	v_lshlrev_b32_e32 v142, 16, v111
	v_fmac_f32_e32 v106, v107, v107
	v_fmac_f32_e32 v128, v118, v118
	v_fmac_f32_e32 v141, v132, v132
	v_and_b32_e32 v134, 0xffff0000, v100
	v_lshlrev_b32_e32 v98, 16, v101
	v_and_b32_e32 v99, 0xffff0000, v101
	v_and_b32_e32 v111, 0xffff0000, v111
	v_fmac_f32_e32 v106, v142, v142
	v_fmac_f32_e32 v128, v119, v119
	v_fmac_f32_e32 v141, v133, v133
	v_pk_mul_f32 v[100:101], v[98:99], v[98:99]
	v_lshlrev_b32_e32 v143, 16, v112
	v_fmac_f32_e32 v106, v111, v111
	v_fmac_f32_e32 v128, v120, v120
	v_fmac_f32_e32 v141, v134, v134
	v_lshlrev_b32_e32 v122, 16, v94
	v_and_b32_e32 v144, 0xffff0000, v112
	v_fmac_f32_e32 v106, v143, v143
	v_fmac_f32_e32 v128, v121, v121
	v_add_f32_e32 v100, v141, v100
	v_and_b32_e32 v123, 0xffff0000, v94
	v_lshlrev_b32_e32 v145, 16, v113
	v_fmac_f32_e32 v106, v144, v144
	v_fmac_f32_e32 v128, v122, v122
	v_add_f32_e32 v100, v100, v101
	v_lshlrev_b32_e32 v124, 16, v95
	v_and_b32_e32 v113, 0xffff0000, v113
	v_fmac_f32_e32 v106, v145, v145
	v_fmac_f32_e32 v128, v123, v123
	s_nop 1
	v_mov_b32_dpp v101, v100 quad_perm:[1,0,3,2] row_mask:0xf bank_mask:0xf
	v_and_b32_e32 v125, 0xffff0000, v95
	v_lshlrev_b32_e32 v135, 16, v102
	v_fmac_f32_e32 v106, v113, v113
	v_fmac_f32_e32 v128, v124, v124
	v_lshlrev_b32_e32 v126, 16, v96
	v_and_b32_e32 v136, 0xffff0000, v102
	v_fmac_f32_e32 v106, v135, v135
	v_fmac_f32_e32 v128, v125, v125
	v_and_b32_e32 v127, 0xffff0000, v96
	v_lshlrev_b32_e32 v94, 16, v97
	v_and_b32_e32 v95, 0xffff0000, v97
	v_lshlrev_b32_e32 v137, 16, v103
	v_fmac_f32_e32 v106, v136, v136
	v_fmac_f32_e32 v128, v126, v126
	v_pk_mul_f32 v[96:97], v[94:95], v[94:95]
	v_and_b32_e32 v138, 0xffff0000, v103
	v_fmac_f32_e32 v106, v137, v137
	v_fmac_f32_e32 v128, v127, v127
	v_lshlrev_b32_e32 v139, 16, v104
	v_fmac_f32_e32 v106, v138, v138
	v_add_f32_e32 v96, v128, v96
	s_waitcnt lgkmcnt(0)
; __global__ void __launch_bounds__(NTHREADS, 2) fwd_megakernel(Params P) {
;     ...
;             { float v[16] = {bflo(qa.x), bfhi(qa.x), bflo(qa.y), bfhi(qa.y), bflo(qa.z), bfhi(qa.z), bflo(qa.w), bfhi(qa.w), bflo(qb.x), bfhi(qb.x), bflo(qb.y), bfhi(qb.y), bflo(qb.z), bfhi(qb.z), bflo(qb.w), bfhi(qb.w)};
;               float ss = 0.f;
; #pragma unroll
;               for (int j = 0; j < 16; ++j) ss += v[j] * v[j];
;               const float ri = CM / sqrtf(group_sum<8>(ss) * (1.f / 128.f) + EPS);
;               u32x4 o0, o1;
;               o0.x = cvt_pk_bf16(v[0] * ri * gqn[0], v[1] * ri * gqn[1]); o0.y = cvt_pk_bf16(v[2] * ri * gqn[2], v[3] * ri * gqn[3]); o0.z = cvt_pk_bf16(v[4] * ri * gqn[4], v[5] * ri * gqn[5]); o0.w = cvt_pk_bf16(v[6] * ri * gqn[6], v[7] * ri * gqn[7]);
;               o1.x = cvt_pk_bf16(v[8] * ri * gqn[8], v[9] * ri * gqn[9]); o1.y = cvt_pk_bf16(v[10] * ri * gqn[10], v[11] * ri * gqn[11]); o1.z = cvt_pk_bf16(v[12] * ri * gqn[12], v[13] * ri * gqn[13]); o1.w = cvt_pk_bf16(v[14] * ri * gqn[14], v[15] * ri * gqn[15]);
;               *(u32x4*)(qo + sl * 16) = o0; *(u32x4*)(qo + sl * 16 + 8) = o1; }
;             { float v[8] = {bflo(qr.x), bfhi(qr.x), bflo(qr.y), bfhi(qr.y), bflo(qr.z), bfhi(qr.z), bflo(qr.w), bfhi(qr.w)};
;               const float cc[8] = {c0[0], c0[1], c0[2], c0[3], c1[0], c1[1], c1[2], c1[3]}, sn[8] = {s0[0], s0[1], s0[2], s0[3], s1[0], s1[1], s1[2], s1[3]};
;               float ss = 0.f;
; #pragma unroll
;               for (int j = 0; j < 8; ++j) ss += v[j] * v[j];
;               const float ri = 1.0f / sqrtf(group_sum<8>(ss) * (1.f / 64.f) + EPS);
;               float o[8];
; #pragma unroll
;               for (int j = 0; j < 8; ++j) { const float y = v[j] * ri * gqr[j]; const float yp = __shfl_xor(y, 4); o[j] = (sl < 4 ? y * cc[j] - yp * sn[j] : y * cc[j] + yp * sn[j]) * CM; }
;               u32x4 w; w.x = cvt_pk_bf16(o[0], o[1]); w.y = cvt_pk_bf16(o[2], o[3]); w.z = cvt_pk_bf16(o[4], o[5]); w.w = cvt_pk_bf16(o[6], o[7]);
;               *(u32x4*)(qo + 128 + sl * 8) = w; }
;             { float v[16] = {bflo(ka.x), bfhi(ka.x), bflo(ka.y), bfhi(ka.y), bflo(ka.z), bfhi(ka.z), bflo(ka.w), bfhi(ka.w), bflo(kb.x), bfhi(kb.x), bflo(kb.y), bfhi(kb.y), bflo(kb.z), bfhi(kb.z), bflo(kb.w), bfhi(kb.w)};
;               float ss = 0.f;
; #pragma unroll
;               for (int j = 0; j < 16; ++j) ss += v[j] * v[j];
	v_add_f32_e32 v100, v100, v101
	v_and_b32_e32 v140, 0xffff0000, v104
	v_lshlrev_b32_e32 v102, 16, v105
	v_and_b32_e32 v103, 0xffff0000, v105
	v_fmac_f32_e32 v106, v139, v139
	v_add_f32_e32 v96, v96, v97
	s_nop 1
	v_mov_b32_dpp v97, v100 quad_perm:[2,3,0,1] row_mask:0xf bank_mask:0xf
	v_pk_mul_f32 v[104:105], v[102:103], v[102:103]
	v_fmac_f32_e32 v106, v140, v140
	s_nop 1
	v_mov_b32_dpp v101, v96 quad_perm:[1,0,3,2] row_mask:0xf bank_mask:0xf
	v_add_f32_e32 v104, v106, v104
	v_add_f32_e32 v104, v104, v105
	s_nop 1
	v_mov_b32_dpp v105, v104 quad_perm:[1,0,3,2] row_mask:0xf bank_mask:0xf
	s_waitcnt lgkmcnt(2)
	v_add_f32_e32 v97, v100, v97
	s_waitcnt lgkmcnt(1)
	v_add_f32_e32 v96, v96, v101
	s_nop 1
	v_mov_b32_dpp v100, v97 row_shl:4 row_mask:0xf bank_mask:0x5
	s_nop 1
	v_mov_b32_dpp v100, v97 row_shr:4 row_mask:0xf bank_mask:0xa
	s_nop 1
	v_mov_b32_dpp v101, v96 quad_perm:[2,3,0,1] row_mask:0xf bank_mask:0xf
	s_waitcnt lgkmcnt(2)
	v_add_f32_e32 v104, v104, v105
	s_nop 1
	v_mov_b32_dpp v105, v104 quad_perm:[2,3,0,1] row_mask:0xf bank_mask:0xf
	v_mov_b32_e32 v88, v108
	s_waitcnt lgkmcnt(2)
	v_add_f32_e32 v97, v97, v100
	s_waitcnt lgkmcnt(1)
	v_add_f32_e32 v96, v96, v101
	v_fmamk_f32 v97, v97, 0x3c800000, v90
	s_nop 1
	v_mov_b32_dpp v100, v96 row_shl:4 row_mask:0xf bank_mask:0x5
	s_nop 1
	v_mov_b32_dpp v100, v96 row_shr:4 row_mask:0xf bank_mask:0xa
	v_mul_f32_e32 v101, 0x4f800000, v97
	v_cmp_gt_f32_e32 vcc, s61, v97
	s_waitcnt lgkmcnt(0)
	v_add_f32_e32 v96, v96, v100
	v_cndmask_b32_e32 v97, v97, v101, vcc
	v_add_f32_e32 v101, v104, v105
	v_sqrt_f32_e32 v104, v97
	s_nop 1
	v_mov_b32_dpp v105, v101 row_shl:4 row_mask:0xf bank_mask:0x5
	s_nop 1
	v_mov_b32_dpp v105, v101 row_shr:4 row_mask:0xf bank_mask:0xa
	v_fmamk_f32 v96, v96, 0x3c000000, v90
	v_mul_f32_e32 v108, 0x4f800000, v96
	v_add_u32_e32 v100, -1, v104
	v_add_u32_e32 v106, 1, v104
	v_fma_f32 v110, -v100, v104, v97
	v_cmp_gt_f32_e64 s[6:7], s61, v96
	v_fma_f32 v112, -v106, v104, v97
	s_waitcnt lgkmcnt(0)
	v_add_f32_e32 v101, v101, v105
	v_cndmask_b32_e64 v96, v96, v108, s[6:7]
	v_cmp_ge_f32_e64 s[8:9], 0, v110
	v_fmamk_f32 v101, v101, 0x3c000000, v90
	v_mul_f32_e32 v105, 0x4f800000, v101
	v_cndmask_b32_e64 v100, v104, v100, s[8:9]
	v_cmp_lt_f32_e64 s[8:9], 0, v112
	v_sqrt_f32_e32 v104, v96
	s_nop 0
	v_cndmask_b32_e64 v100, v100, v106, s[8:9]
	v_cmp_gt_f32_e64 s[8:9], s61, v101
	v_mul_f32_e32 v106, 0x37800000, v100
	v_cndmask_b32_e32 v100, v100, v106, vcc
	v_cndmask_b32_e64 v101, v101, v105, s[8:9]
	v_sqrt_f32_e32 v105, v101
	v_cmp_class_f32_e32 vcc, v97, v91
	v_add_u32_e32 v106, 1, v104
	v_fma_f32 v128, -v106, v104, v96
	v_cndmask_b32_e32 v97, v100, v97, vcc
	v_add_u32_e32 v100, -1, v104
	v_fma_f32 v112, -v100, v104, v96
	v_cmp_ge_f32_e32 vcc, 0, v112
	v_div_scale_f32 v108, s[10:11], v97, v97, 1.0
	s_nop 0
	v_cndmask_b32_e32 v100, v104, v100, vcc
	v_add_u32_e32 v104, -1, v105
	v_cmp_lt_f32_e32 vcc, 0, v128
	v_rcp_f32_e32 v141, v108
	v_add_u32_e32 v112, 1, v105
	v_cndmask_b32_e32 v100, v100, v106, vcc
	v_fma_f32 v106, -v104, v105, v101
	v_fma_f32 v128, -v112, v105, v101
	v_cmp_ge_f32_e32 vcc, 0, v106
	v_mul_f32_e32 v146, 0x37800000, v100
	v_cndmask_b32_e64 v100, v100, v146, s[6:7]
	v_cndmask_b32_e32 v104, v105, v104, vcc
	v_cmp_lt_f32_e32 vcc, 0, v128
	v_fma_f32 v105, -v108, v141, 1.0
	v_div_scale_f32 v110, s[10:11], 1.0, v97, 1.0
	v_cndmask_b32_e32 v104, v104, v112, vcc
	v_cmp_class_f32_e32 vcc, v96, v91
	v_fmac_f32_e32 v141, v105, v141
	v_mul_f32_e32 v112, v110, v141
	v_cndmask_b32_e32 v96, v100, v96, vcc
	v_mul_f32_e32 v100, 0x37800000, v104
	v_div_scale_f32 v105, s[6:7], v96, v96, s62
	v_cndmask_b32_e64 v100, v104, v100, s[8:9]
	v_cmp_class_f32_e64 s[6:7], v101, v91
	v_rcp_f32_e32 v104, v105
	v_fma_f32 v128, -v108, v112, v110
	v_cndmask_b32_e64 v100, v100, v101, s[6:7]
	v_fmac_f32_e32 v112, v128, v141
	v_div_scale_f32 v101, s[6:7], v100, v100, 1.0
	v_fma_f32 v108, -v108, v112, v110
	v_rcp_f32_e32 v110, v101
	v_fma_f32 v146, -v105, v104, 1.0
	v_div_scale_f32 v106, vcc, s62, v96, s62
	v_fmac_f32_e32 v104, v146, v104
	v_mul_f32_e32 v146, v106, v104
	v_fma_f32 v147, -v101, v110, 1.0
	v_fma_f32 v148, -v105, v146, v106
	v_div_scale_f32 v128, s[6:7], 1.0, v100, 1.0
	v_fmac_f32_e32 v110, v147, v110
	v_fmac_f32_e32 v146, v148, v104
	v_mul_f32_e32 v147, v128, v110
	v_fma_f32 v105, -v105, v146, v106
	v_fma_f32 v106, -v101, v147, v128
	v_div_fmas_f32 v104, v105, v104, v146
	s_mov_b64 vcc, s[10:11]
	v_fmac_f32_e32 v147, v106, v110
	v_div_fixup_f32 v96, v104, v96, s62
	v_div_fmas_f32 v104, v108, v141, v112
	v_fma_f32 v101, -v101, v147, v128
	v_mul_f32_e32 v105, v96, v114
	v_mul_f32_e32 v106, v96, v115
	v_mul_f32_e32 v108, v96, v116
	v_mul_f32_e32 v112, v96, v117
	v_mul_f32_e32 v114, v96, v118
	v_mul_f32_e32 v115, v96, v119
	v_mul_f32_e32 v116, v96, v120
	v_mul_f32_e32 v117, v96, v121
	v_mul_f32_e32 v118, v96, v122
	v_mul_f32_e32 v119, v96, v123
	v_mul_f32_e32 v120, v96, v124
	v_mul_f32_e32 v121, v96, v125
	v_mul_f32_e32 v122, v96, v126
	v_mul_f32_e32 v123, v96, v127
	v_mul_f32_e32 v94, v96, v94
	v_mul_f32_e32 v95, v96, v95
	v_div_fixup_f32 v96, v104, v97, 1.0
	s_mov_b64 vcc, s[6:7]
	v_div_fmas_f32 v97, v101, v110, v147
	v_mul_f32_e32 v101, v0, v105
	v_mul_f32_e32 v105, v2, v108
	v_mul_f32_e32 v108, v4, v114
	v_mul_f32_e32 v110, v5, v115
	v_mul_f32_e32 v114, v7, v117
	v_mul_f32_e32 v115, v8, v118
	v_mul_f32_e32 v117, v10, v120
	v_mul_f32_e32 v118, v11, v121
	v_mul_f32_e32 v120, v13, v123
	v_mul_f32_e32 v123, v96, v129
	v_mul_f32_e32 v104, v1, v106
	v_mul_f32_e32 v106, v3, v112
	v_mul_f32_e32 v112, v6, v116
; __device__ __forceinline__ unsigned cvt_pk_bf16(float lo, float hi) { unsigned r; asm volatile("v_cvt_pk_bf16_f32 %0, %1, %2" : "=v"(r) : "v"(lo), "v"(hi)); return r; }
; __device__ __forceinline__ float bflo(unsigned w) { return __uint_as_float(w << 16); }
; __device__ __forceinline__ float bfhi(unsigned w) { return __uint_as_float(w & 0xffff0000u); }
; __global__ void __launch_bounds__(NTHREADS, 2) fwd_megakernel(Params P) {
;     ...
;               const float ri = 1.0f / sqrtf(group_sum<8>(ss) * (1.f / 64.f) + EPS);
;               float o[8];
; #pragma unroll
;               for (int j = 0; j < 8; ++j) { const float y = v[j] * ri * gqr[j]; const float yp = __shfl_xor(y, 4); o[j] = (sl < 4 ? y * cc[j] - yp * sn[j] : y * cc[j] + yp * sn[j]) * CM; }
;               u32x4 w; w.x = cvt_pk_bf16(o[0], o[1]); w.y = cvt_pk_bf16(o[2], o[3]); w.z = cvt_pk_bf16(o[4], o[5]); w.w = cvt_pk_bf16(o[6], o[7]);
;               *(u32x4*)(qo + 128 + sl * 8) = w; }
;             { float v[16] = {bflo(ka.x), bfhi(ka.x), bflo(ka.y), bfhi(ka.y), bflo(ka.z), bfhi(ka.z), bflo(ka.w), bfhi(ka.w), bflo(kb.x), bfhi(kb.x), bflo(kb.y), bfhi(kb.y), bflo(kb.z), bfhi(kb.z), bflo(kb.w), bfhi(kb.w)};
;               float ss = 0.f;
; #pragma unroll
;               for (int j = 0; j < 16; ++j) ss += v[j] * v[j];
;               const float ri = 1.0f / sqrtf(group_sum<8>(ss) * (1.f / 128.f) + EPS);
;               u32x4 o0, o1;
;               o0.x = cvt_pk_bf16(v[0] * ri * gkn[0], v[1] * ri * gkn[1]); o0.y = cvt_pk_bf16(v[2] * ri * gkn[2], v[3] * ri * gkn[3]); o0.z = cvt_pk_bf16(v[4] * ri * gkn[4], v[5] * ri * gkn[5]); o0.w = cvt_pk_bf16(v[6] * ri * gkn[6], v[7] * ri * gkn[7]);
;               o1.x = cvt_pk_bf16(v[8] * ri * gkn[8], v[9] * ri * gkn[9]); o1.y = cvt_pk_bf16(v[10] * ri * gkn[10], v[11] * ri * gkn[11]); o1.z = cvt_pk_bf16(v[12] * ri * gkn[12], v[13] * ri * gkn[13]); o1.w = cvt_pk_bf16(v[14] * ri * gkn[14], v[15] * ri * gkn[15]);
;               *(u32x4*)(ko + sl * 16) = o0; *(u32x4*)(ko + sl * 16 + 8) = o1; }
;             *(u32x4*)(ko + 128 + sl * 8) = krv;
	v_mul_f32_e32 v116, v9, v119
	v_mul_f32_e32 v119, v12, v122
	v_mul_f32_e32 v121, v14, v94
	v_mul_f32_e32 v122, v15, v95
	v_mul_f32_e32 v124, v96, v130
	v_mul_f32_e32 v125, v96, v131
	v_mul_f32_e32 v126, v96, v132
	v_mul_f32_e32 v127, v96, v133
	v_mul_f32_e32 v128, v96, v134
	v_mul_f32_e32 v129, v96, v98
	v_mul_f32_e32 v130, v96, v99
	v_div_fixup_f32 v131, v97, v100, 1.0
	v_cvt_pk_bf16_f32 v94, v101, v104
	v_cvt_pk_bf16_f32 v95, v105, v106
	v_cvt_pk_bf16_f32 v96, v108, v110
	v_cvt_pk_bf16_f32 v97, v112, v114
	v_cvt_pk_bf16_f32 v98, v115, v116
	v_cvt_pk_bf16_f32 v99, v117, v118
	v_mul_f32_e32 v118, v123, v32
	v_cvt_pk_bf16_f32 v100, v119, v120
	v_cvt_pk_bf16_f32 v101, v121, v122
	v_mul_f32_e32 v104, v124, v33
	v_mul_f32_e32 v106, v125, v34
	v_mul_f32_e32 v108, v126, v35
	v_mul_f32_e32 v110, v127, v36
	v_mul_f32_e32 v112, v128, v37
	global_store_dwordx4 v[84:85], v[94:97], off
	global_store_dwordx4 v[84:85], v[98:101], off offset:16
	s_nop 1
	v_mov_b32_dpp v84, v118 row_shl:4 row_mask:0xf bank_mask:0x5
	s_nop 1
	v_mov_b32_dpp v84, v118 row_shr:4 row_mask:0xf bank_mask:0xa
	v_mul_f32_e32 v114, v129, v38
	v_mul_f32_e32 v116, v130, v39
	v_mul_f32_e32 v119, v131, v107
	v_mul_f32_e32 v120, v131, v109
	v_mul_f32_e32 v122, v131, v111
	v_mul_f32_e32 v126, v131, v113
	s_nop 1
	v_mov_b32_dpp v105, v104 row_shl:4 row_mask:0xf bank_mask:0x5
	s_nop 1
	v_mov_b32_dpp v105, v104 row_shr:4 row_mask:0xf bank_mask:0xa
	s_nop 1
	v_mov_b32_dpp v107, v106 row_shl:4 row_mask:0xf bank_mask:0x5
	s_nop 1
	v_mov_b32_dpp v107, v106 row_shr:4 row_mask:0xf bank_mask:0xa
	s_nop 1
	v_mov_b32_dpp v109, v108 row_shl:4 row_mask:0xf bank_mask:0x5
	s_nop 1
	v_mov_b32_dpp v109, v108 row_shr:4 row_mask:0xf bank_mask:0xa
	s_nop 1
	v_mov_b32_dpp v111, v110 row_shl:4 row_mask:0xf bank_mask:0x5
	s_nop 1
	v_mov_b32_dpp v111, v110 row_shr:4 row_mask:0xf bank_mask:0xa
	s_nop 1
	v_mov_b32_dpp v113, v112 row_shl:4 row_mask:0xf bank_mask:0x5
	s_nop 1
	v_mov_b32_dpp v113, v112 row_shr:4 row_mask:0xf bank_mask:0xa
	s_nop 1
	v_mov_b32_dpp v115, v114 row_shl:4 row_mask:0xf bank_mask:0x5
	s_nop 1
	v_mov_b32_dpp v115, v114 row_shr:4 row_mask:0xf bank_mask:0xa
	s_nop 1
	v_mov_b32_dpp v117, v116 row_shl:4 row_mask:0xf bank_mask:0x5
	s_nop 1
	v_mov_b32_dpp v117, v116 row_shr:4 row_mask:0xf bank_mask:0xa
	v_mul_f32_e32 v125, v131, v145
	v_mul_f32_e32 v100, v22, v125
	s_waitcnt lgkmcnt(7)
	v_mul_f32_e32 v125, v48, v84
	v_mov_b32_e32 v48, v45
	s_waitcnt lgkmcnt(5)
	v_pk_mul_f32 v[84:85], v[106:107], v[86:87]
	s_waitcnt lgkmcnt(4)
	v_pk_mul_f32 v[50:51], v[108:109], v[50:51]
	s_waitcnt lgkmcnt(3)
	v_pk_mul_f32 v[46:47], v[110:111], v[46:47]
	s_waitcnt lgkmcnt(2)
	v_pk_mul_f32 v[52:53], v[112:113], v[52:53]
	v_cndmask_b32_e64 v45, v125, -v125, s[4:5]
	v_pk_mul_f32 v[48:49], v[104:105], v[48:49]
	s_waitcnt lgkmcnt(1)
	v_pk_mul_f32 v[86:87], v[114:115], v[88:89]
	s_waitcnt lgkmcnt(0)
	v_pk_mul_f32 v[54:55], v[116:117], v[54:55]
	v_sub_f32_e32 v88, v84, v85
	v_add_f32_e32 v84, v84, v85
	v_sub_f32_e32 v85, v50, v51
	v_add_f32_e32 v50, v50, v51
	v_sub_f32_e32 v51, v46, v47
	v_add_f32_e32 v46, v46, v47
	v_sub_f32_e32 v47, v52, v53
	v_add_f32_e32 v52, v52, v53
	v_fmac_f32_e32 v45, v118, v44
	v_sub_f32_e32 v44, v48, v49
	v_add_f32_e32 v48, v48, v49
	v_sub_f32_e32 v53, v86, v87
	v_add_f32_e32 v86, v86, v87
	v_sub_f32_e32 v87, v54, v55
	v_add_f32_e32 v54, v54, v55
	v_cndmask_b32_e64 v46, v46, v51, s[4:5]
	v_cndmask_b32_e64 v47, v52, v47, s[4:5]
	v_cndmask_b32_e64 v44, v48, v44, s[4:5]
	v_add_co_u32_e32 v80, vcc, s64, v80
	v_cndmask_b32_e64 v49, v84, v88, s[4:5]
	v_cndmask_b32_e64 v50, v50, v85, s[4:5]
	v_cndmask_b32_e64 v51, v86, v53, s[4:5]
	v_cndmask_b32_e64 v52, v54, v87, s[4:5]
	v_mul_f32_e32 v45, 0x3dd53b94, v45
	v_mul_f32_e32 v46, 0x3dd53b94, v46
	v_mul_f32_e32 v47, 0x3dd53b94, v47
	v_mul_f32_e32 v44, 0x3dd53b94, v44
	v_addc_co_u32_e32 v81, vcc, 0, v81, vcc
	v_mul_f32_e32 v121, v131, v142
	v_mul_f32_e32 v123, v131, v143
	v_mul_f32_e32 v124, v131, v144
	v_mul_f32_e32 v48, 0x3dd53b94, v49
	v_mul_f32_e32 v49, 0x3dd53b94, v50
	v_mul_f32_e32 v50, 0x3dd53b94, v51
	v_mul_f32_e32 v51, 0x3dd53b94, v52
	v_cvt_pk_bf16_f32 v44, v45, v44
	v_cvt_pk_bf16_f32 v45, v48, v49
	v_cvt_pk_bf16_f32 v46, v46, v47
	v_cvt_pk_bf16_f32 v47, v50, v51
	v_add_co_u32_e32 v78, vcc, 0x9400000, v78
	v_mul_f32_e32 v127, v131, v135
	v_mul_f32_e32 v128, v131, v136
	v_mul_f32_e32 v129, v131, v137
	v_mul_f32_e32 v130, v131, v138
	v_mul_f32_e32 v132, v131, v139
	v_mul_f32_e32 v133, v131, v140
	v_mul_f32_e32 v102, v131, v102
	v_mul_f32_e32 v103, v131, v103
	v_mul_f32_e32 v94, v16, v119
	v_mul_f32_e32 v95, v17, v120
	v_mul_f32_e32 v96, v18, v121
	v_mul_f32_e32 v97, v19, v122
	v_mul_f32_e32 v98, v20, v123
	v_mul_f32_e32 v99, v21, v124
	v_mul_f32_e32 v101, v23, v126
	global_store_dwordx4 v[82:83], v[44:47], off offset:256
	v_addc_co_u32_e32 v79, vcc, 0, v79, vcc
	s_nop 0
	v_cvt_pk_bf16_f32 v44, v94, v95
	v_cvt_pk_bf16_f32 v45, v96, v97
	v_cvt_pk_bf16_f32 v46, v98, v99
	v_cvt_pk_bf16_f32 v47, v100, v101
	v_mul_f32_e32 v119, v24, v127
	v_mul_f32_e32 v120, v25, v128
	v_mul_f32_e32 v121, v26, v129
	v_mul_f32_e32 v122, v27, v130
	v_mul_f32_e32 v123, v28, v132
	v_mul_f32_e32 v124, v29, v133
	v_mul_f32_e32 v102, v30, v102
	v_mul_f32_e32 v103, v31, v103
	v_cvt_pk_bf16_f32 v48, v119, v120
	v_cvt_pk_bf16_f32 v49, v121, v122
	v_cvt_pk_bf16_f32 v50, v123, v124
	v_cvt_pk_bf16_f32 v51, v102, v103
	global_store_dwordx4 v[80:81], v[44:47], off
	global_store_dwordx4 v[80:81], v[48:51], off offset:16
	global_store_dwordx4 v[78:79], v[40:43], off offset:256
	s_cbranch_scc0 .LBB0_314
	s_branch .LBB0_306

; #define PG8_STAGE(bufoff, gbase, voff) do { _Pragma("unroll") for (int _i = 0; _i < 2; ++_i) \
;         __builtin_amdgcn_global_load_lds((const unsigned*)((const char*)(gbase) + (voff)[_i]), (LAS unsigned*)(lds + (bufoff) + ldsw + _i * 8192), 16, 0, 0); } while (0)
; #define PG8_LDA(dst, b, h) do { _Pragma("unroll") for (int m = 0; m < 4; ++m) _Pragma("unroll") for (int k = 0; k < 2; ++k) dst[m][k] = *(const LAS bf16x8*)(lds + PG8_SA(b, h) + aoff + m * 2048 + k * 1024); } while (0)
; #define PG8_LDB(dst, b, h) do { _Pragma("unroll") for (int n = 0; n < 2; ++n) _Pragma("unroll") for (int k = 0; k < 2; ++k) dst[n][k] = *(const LAS bf16x8*)(lds + PG8_SB(b, h) + boff + n * 2048 + k * 1024); } while (0)
; #define PG8_MMA(ai, bj, At, Bt) do { __builtin_amdgcn_s_setprio(1); _Pragma("unroll") for (int m = 0; m < 4; ++m) _Pragma("unroll") for (int n = 0; n < 2; ++n) _Pragma("unroll") for (int k = 0; k < 2; ++k) \
;         acc[ai][bj][m][n] = __builtin_amdgcn_mfma_f32_16x16x32_bf16(Bt[n][k], At[m][k], acc[ai][bj][m][n], 0, 0, 0); __builtin_amdgcn_s_setprio(0); } while (0)
; #define PG8_WAIT_V(n) asm volatile("s_waitcnt vmcnt(" #n ")" ::: "memory")
; #define PG8_WAIT_L(n) asm volatile("s_waitcnt lgkmcnt(" #n ")" ::: "memory")
; #define PG8_BAR __builtin_amdgcn_s_barrier()
; #define PG8_SCHED __builtin_amdgcn_sched_barrier(0)
; template <class Epi>
; __device__ __forceinline__ void gemm_phase(LAS unsigned char* lds, const Gemm g, const StaticOrder& S, const Epi& E) {
;     ...
;             PG8_LDB(B0, 0, 0); PG8_SCHED; PG8_LDA(At, 0, 0); PG8_STAGE(PG8_SA(1, 1), a1 + hstep, voffA);
;             PG8_WAIT_L(8); PG8_BAR; PG8_WAIT_L(0); PG8_MMA(0, 0, At, B0); PG8_BAR; PG8_SCHED;
;             PG8_LDB(B1, 0, 1); PG8_STAGE(PG8_SB(0, 0), b2, voffB0);
;             PG8_BAR; PG8_WAIT_L(0); PG8_MMA(0, 1, At, B1); PG8_BAR;
;             PG8_LDA(At, 0, 1); PG8_STAGE(PG8_SA(0, 0), a2, voffA);
;             PG8_BAR; PG8_WAIT_L(0); PG8_MMA(1, 0, At, B0); PG8_BAR; PG8_SCHED;
;             PG8_STAGE(PG8_SB(0, 1), b2, voffB1);
;             PG8_WAIT_V(6); PG8_BAR; PG8_MMA(1, 1, At, B1); PG8_BAR;
;             PG8_LDB(B0, 1, 0); PG8_SCHED; PG8_LDA(At, 1, 0); PG8_STAGE(PG8_SA(0, 1), a2 + hstep, voffA);
;             PG8_WAIT_L(8); PG8_BAR; PG8_WAIT_L(0); PG8_MMA(0, 0, At, B0); PG8_BAR; PG8_SCHED;
.LBB0_613:
	ds_read_b128 v[146:149], v155
	ds_read_b128 v[158:161], v155 offset:1024
	ds_read_b128 v[162:165], v155 offset:2048
	ds_read_b128 v[166:169], v155 offset:3072
	s_add_u32 s33, s54, 0xfff80080
	s_addc_u32 s56, s55, -1
	s_cmp_eq_u32 s88, 28
	s_cselect_b32 s57, s43, s56
	s_cselect_b32 s56, s51, s33
	s_cselect_b32 s59, s41, s87
	s_cselect_b32 s58, s85, s86
	v_lshl_add_u64 v[204:205], s[54:55], 0, v[140:141]
	s_add_i32 m0, s53, 0xc000
	ds_read_b128 v[170:173], v156
	ds_read_b128 v[174:177], v156 offset:1024
	ds_read_b128 v[178:181], v156 offset:2048
	ds_read_b128 v[182:185], v156 offset:3072
	ds_read_b128 v[186:189], v156 offset:4096
	ds_read_b128 v[190:193], v156 offset:5120
	ds_read_b128 v[194:197], v156 offset:6144
	ds_read_b128 v[198:201], v156 offset:7168
	global_load_lds_dwordx4 v[204:205], off
	v_lshl_add_u64 v[204:205], s[54:55], 0, v[142:143]
	s_add_i32 m0, s53, 0xe000
	s_nop 0
	global_load_lds_dwordx4 v[204:205], off
	s_waitcnt lgkmcnt(8)
	s_barrier
	s_waitcnt lgkmcnt(0)
	v_mfma_f32_16x16x32_bf16 v[124:127], v[146:149], v[170:173], v[124:127]
	v_mfma_f32_16x16x32_bf16 v[120:123], v[162:165], v[170:173], v[120:123]
	v_mfma_f32_16x16x32_bf16 v[108:111], v[146:149], v[178:181], v[108:111]
	v_mfma_f32_16x16x32_bf16 v[104:107], v[162:165], v[178:181], v[104:107]
	v_mfma_f32_16x16x32_bf16 v[92:95], v[146:149], v[186:189], v[92:95]
	v_mfma_f32_16x16x32_bf16 v[88:91], v[162:165], v[186:189], v[88:91]
	v_mfma_f32_16x16x32_bf16 v[76:79], v[146:149], v[194:197], v[76:79]
	v_mfma_f32_16x16x32_bf16 v[72:75], v[162:165], v[194:197], v[72:75]
	v_mfma_f32_16x16x32_bf16 v[124:127], v[158:161], v[174:177], v[124:127]
	v_mfma_f32_16x16x32_bf16 v[120:123], v[166:169], v[174:177], v[120:123]
	v_mfma_f32_16x16x32_bf16 v[108:111], v[158:161], v[182:185], v[108:111]
	v_mfma_f32_16x16x32_bf16 v[104:107], v[166:169], v[182:185], v[104:107]
	v_mfma_f32_16x16x32_bf16 v[92:95], v[158:161], v[190:193], v[92:95]
	v_mfma_f32_16x16x32_bf16 v[88:91], v[166:169], v[190:193], v[88:91]
	v_mfma_f32_16x16x32_bf16 v[76:79], v[158:161], v[198:201], v[76:79]
	v_mfma_f32_16x16x32_bf16 v[72:75], v[166:169], v[198:201], v[72:75]
	s_barrier
	s_add_i32 s33, s79, s65
	v_lshl_add_u64 v[220:221], s[58:59], 0, v[130:131]
	s_mov_b32 m0, s33
	ds_read_b128 v[204:207], v157
	ds_read_b128 v[208:211], v157 offset:1024
	ds_read_b128 v[212:215], v157 offset:2048
	ds_read_b128 v[216:219], v157 offset:3072
	global_load_lds_dwordx4 v[220:221], off
	v_lshl_add_u64 v[222:223], s[58:59], 0, v[136:137]
	s_add_i32 m0, s33, 0x2000
	s_nop 0
	global_load_lds_dwordx4 v[222:223], off
	s_barrier
	s_waitcnt lgkmcnt(0)
	v_mfma_f32_16x16x32_bf16 v[116:119], v[204:207], v[170:173], v[116:119]
	v_mfma_f32_16x16x32_bf16 v[112:115], v[212:215], v[170:173], v[112:115]
	v_mfma_f32_16x16x32_bf16 v[100:103], v[204:207], v[178:181], v[100:103]
	v_mfma_f32_16x16x32_bf16 v[96:99], v[212:215], v[178:181], v[96:99]
	v_mfma_f32_16x16x32_bf16 v[84:87], v[204:207], v[186:189], v[84:87]
	v_mfma_f32_16x16x32_bf16 v[80:83], v[212:215], v[186:189], v[80:83]
	v_mfma_f32_16x16x32_bf16 v[68:71], v[204:207], v[194:197], v[68:71]
	v_mfma_f32_16x16x32_bf16 v[64:67], v[212:215], v[194:197], v[64:67]
	v_mfma_f32_16x16x32_bf16 v[116:119], v[208:211], v[174:177], v[116:119]
	v_mfma_f32_16x16x32_bf16 v[112:115], v[216:219], v[174:177], v[112:115]
	v_mfma_f32_16x16x32_bf16 v[100:103], v[208:211], v[182:185], v[100:103]
	v_mfma_f32_16x16x32_bf16 v[96:99], v[216:219], v[182:185], v[96:99]
	v_mfma_f32_16x16x32_bf16 v[84:87], v[208:211], v[190:193], v[84:87]
	v_mfma_f32_16x16x32_bf16 v[80:83], v[216:219], v[190:193], v[80:83]
	v_mfma_f32_16x16x32_bf16 v[68:71], v[208:211], v[198:201], v[68:71]
	v_mfma_f32_16x16x32_bf16 v[64:67], v[216:219], v[198:201], v[64:67]
	s_mov_b32 m0, s53
	v_lshl_add_u64 v[224:225], s[56:57], 0, v[128:129]
	s_barrier
	ds_read_b128 v[170:173], v156 offset:16384
	ds_read_b128 v[174:177], v156 offset:17408
	ds_read_b128 v[178:181], v156 offset:18432
	ds_read_b128 v[182:185], v156 offset:19456
	ds_read_b128 v[186:189], v156 offset:20480
	ds_read_b128 v[190:193], v156 offset:21504
	ds_read_b128 v[194:197], v156 offset:22528
	ds_read_b128 v[198:201], v156 offset:23552
	global_load_lds_dwordx4 v[224:225], off
	v_lshl_add_u64 v[226:227], s[56:57], 0, v[134:135]
	s_mov_b32 m0, s66
	s_nop 0
	global_load_lds_dwordx4 v[226:227], off
	s_barrier
	s_waitcnt lgkmcnt(0)
	v_mfma_f32_16x16x32_bf16 v[60:63], v[146:149], v[170:173], v[60:63]
	v_mfma_f32_16x16x32_bf16 v[56:59], v[162:165], v[170:173], v[56:59]
	v_mfma_f32_16x16x32_bf16 v[44:47], v[146:149], v[178:181], v[44:47]
	v_mfma_f32_16x16x32_bf16 v[40:43], v[162:165], v[178:181], v[40:43]
	v_mfma_f32_16x16x32_bf16 v[28:31], v[146:149], v[186:189], v[28:31]
	v_mfma_f32_16x16x32_bf16 v[24:27], v[162:165], v[186:189], v[24:27]
	v_mfma_f32_16x16x32_bf16 v[12:15], v[146:149], v[194:197], v[12:15]
	v_mfma_f32_16x16x32_bf16 v[8:11], v[162:165], v[194:197], v[8:11]
	v_mfma_f32_16x16x32_bf16 v[60:63], v[158:161], v[174:177], v[60:63]
	v_mfma_f32_16x16x32_bf16 v[56:59], v[166:169], v[174:177], v[56:59]
	v_mfma_f32_16x16x32_bf16 v[44:47], v[158:161], v[182:185], v[44:47]
	v_mfma_f32_16x16x32_bf16 v[40:43], v[166:169], v[182:185], v[40:43]
	v_mfma_f32_16x16x32_bf16 v[28:31], v[158:161], v[190:193], v[28:31]
	v_mfma_f32_16x16x32_bf16 v[24:27], v[166:169], v[190:193], v[24:27]
	v_mfma_f32_16x16x32_bf16 v[12:15], v[158:161], v[198:201], v[12:15]
	v_mfma_f32_16x16x32_bf16 v[8:11], v[166:169], v[198:201], v[8:11]
	s_barrier
	s_add_i32 s33, s80, s65
	v_lshl_add_u64 v[228:229], s[58:59], 0, v[132:133]
	s_mov_b32 m0, s33
	v_lshl_add_u64 v[230:231], s[58:59], 0, v[138:139]
	global_load_lds_dwordx4 v[228:229], off
	s_add_i32 m0, s33, 0x2000
	s_nop 0
	global_load_lds_dwordx4 v[230:231], off
	s_waitcnt vmcnt(6)
	s_barrier
; #define PG8_STAGE(bufoff, gbase, voff) do { _Pragma("unroll") for (int _i = 0; _i < 2; ++_i) \
;         __builtin_amdgcn_global_load_lds((const unsigned*)((const char*)(gbase) + (voff)[_i]), (LAS unsigned*)(lds + (bufoff) + ldsw + _i * 8192), 16, 0, 0); } while (0)
; #define PG8_LDA(dst, b, h) do { _Pragma("unroll") for (int m = 0; m < 4; ++m) _Pragma("unroll") for (int k = 0; k < 2; ++k) dst[m][k] = *(const LAS bf16x8*)(lds + PG8_SA(b, h) + aoff + m * 2048 + k * 1024); } while (0)
; #define PG8_LDB(dst, b, h) do { _Pragma("unroll") for (int n = 0; n < 2; ++n) _Pragma("unroll") for (int k = 0; k < 2; ++k) dst[n][k] = *(const LAS bf16x8*)(lds + PG8_SB(b, h) + boff + n * 2048 + k * 1024); } while (0)
; #define PG8_MMA(ai, bj, At, Bt) do { __builtin_amdgcn_s_setprio(1); _Pragma("unroll") for (int m = 0; m < 4; ++m) _Pragma("unroll") for (int n = 0; n < 2; ++n) _Pragma("unroll") for (int k = 0; k < 2; ++k) \
;         acc[ai][bj][m][n] = __builtin_amdgcn_mfma_f32_16x16x32_bf16(Bt[n][k], At[m][k], acc[ai][bj][m][n], 0, 0, 0); __builtin_amdgcn_s_setprio(0); } while (0)
; #define PG8_WAIT_L(n) asm volatile("s_waitcnt lgkmcnt(" #n ")" ::: "memory")
; #define PG8_BAR __builtin_amdgcn_s_barrier()
; #define PG8_SCHED __builtin_amdgcn_sched_barrier(0)
; template <class Epi>
; __device__ __forceinline__ void gemm_phase(LAS unsigned char* lds, const Gemm g, const StaticOrder& S, const Epi& E) {
;     ...
;             PG8_LDB(B0, 1, 0); PG8_SCHED; PG8_LDA(At, 1, 0); PG8_STAGE(PG8_SA(0, 1), a2 + hstep, voffA);
;             PG8_WAIT_L(8); PG8_BAR; PG8_WAIT_L(0); PG8_MMA(0, 0, At, B0); PG8_BAR; PG8_SCHED;
;             PG8_LDB(B1, 1, 1); PG8_STAGE(PG8_SB(1, 0), b3, voffB0);
;             PG8_BAR; PG8_WAIT_L(0); PG8_MMA(0, 1, At, B1); PG8_BAR;
;             PG8_LDA(At, 1, 1); PG8_STAGE(PG8_SA(1, 0), a3, voffA);
;             PG8_BAR; PG8_WAIT_L(0); PG8_MMA(1, 0, At, B0); PG8_BAR; PG8_SCHED;
	v_mfma_f32_16x16x32_bf16 v[52:55], v[204:207], v[170:173], v[52:55]
	v_mfma_f32_16x16x32_bf16 v[48:51], v[212:215], v[170:173], v[48:51]
	v_mfma_f32_16x16x32_bf16 v[36:39], v[204:207], v[178:181], v[36:39]
	v_mfma_f32_16x16x32_bf16 v[32:35], v[212:215], v[178:181], v[32:35]
	v_mfma_f32_16x16x32_bf16 v[20:23], v[204:207], v[186:189], v[20:23]
	v_mfma_f32_16x16x32_bf16 v[16:19], v[212:215], v[186:189], v[16:19]
	v_mfma_f32_16x16x32_bf16 v[4:7], v[204:207], v[194:197], v[4:7]
	v_mfma_f32_16x16x32_bf16 v[0:3], v[212:215], v[194:197], v[0:3]
	v_mfma_f32_16x16x32_bf16 v[52:55], v[208:211], v[174:177], v[52:55]
	v_mfma_f32_16x16x32_bf16 v[48:51], v[216:219], v[174:177], v[48:51]
	v_mfma_f32_16x16x32_bf16 v[36:39], v[208:211], v[182:185], v[36:39]
	v_mfma_f32_16x16x32_bf16 v[32:35], v[216:219], v[182:185], v[32:35]
	v_mfma_f32_16x16x32_bf16 v[20:23], v[208:211], v[190:193], v[20:23]
	v_mfma_f32_16x16x32_bf16 v[16:19], v[216:219], v[190:193], v[16:19]
	v_mfma_f32_16x16x32_bf16 v[4:7], v[208:211], v[198:201], v[4:7]
	v_mfma_f32_16x16x32_bf16 v[0:3], v[216:219], v[198:201], v[0:3]
	s_add_i32 s33, 0, 0x18000
	v_add_u32_e32 v166, s33, v151
	s_barrier
	ds_read_b128 v[146:149], v166
	ds_read_b128 v[158:161], v166 offset:1024
	ds_read_b128 v[162:165], v166 offset:2048
	ds_read_b128 v[166:169], v166 offset:3072
	s_add_u32 s56, s56, 0x80000
	s_addc_u32 s57, s57, 0
	s_mov_b32 m0, s67
	v_lshl_add_u64 v[204:205], s[56:57], 0, v[128:129]
	ds_read_b128 v[170:173], v156 offset:32768
	ds_read_b128 v[174:177], v156 offset:33792
	ds_read_b128 v[178:181], v156 offset:34816
	ds_read_b128 v[182:185], v156 offset:35840
	ds_read_b128 v[186:189], v156 offset:36864
	ds_read_b128 v[190:193], v156 offset:37888
	ds_read_b128 v[194:197], v156 offset:38912
	ds_read_b128 v[198:201], v156 offset:39936
	global_load_lds_dwordx4 v[204:205], off
	v_lshl_add_u64 v[204:205], s[56:57], 0, v[134:135]
	s_mov_b32 m0, s68
	s_nop 0
	global_load_lds_dwordx4 v[204:205], off
	s_waitcnt lgkmcnt(8)
	s_barrier
	s_waitcnt lgkmcnt(0)
	v_mfma_f32_16x16x32_bf16 v[124:127], v[146:149], v[170:173], v[124:127]
	v_mfma_f32_16x16x32_bf16 v[120:123], v[162:165], v[170:173], v[120:123]
	v_mfma_f32_16x16x32_bf16 v[108:111], v[146:149], v[178:181], v[108:111]
	v_mfma_f32_16x16x32_bf16 v[104:107], v[162:165], v[178:181], v[104:107]
	v_mfma_f32_16x16x32_bf16 v[92:95], v[146:149], v[186:189], v[92:95]
	v_mfma_f32_16x16x32_bf16 v[88:91], v[162:165], v[186:189], v[88:91]
	v_mfma_f32_16x16x32_bf16 v[76:79], v[146:149], v[194:197], v[76:79]
	v_mfma_f32_16x16x32_bf16 v[72:75], v[162:165], v[194:197], v[72:75]
	v_mfma_f32_16x16x32_bf16 v[124:127], v[158:161], v[174:177], v[124:127]
	v_mfma_f32_16x16x32_bf16 v[120:123], v[166:169], v[174:177], v[120:123]
	v_mfma_f32_16x16x32_bf16 v[108:111], v[158:161], v[182:185], v[108:111]
	v_mfma_f32_16x16x32_bf16 v[104:107], v[166:169], v[182:185], v[104:107]
	v_mfma_f32_16x16x32_bf16 v[92:95], v[158:161], v[190:193], v[92:95]
	v_mfma_f32_16x16x32_bf16 v[88:91], v[166:169], v[190:193], v[88:91]
	v_mfma_f32_16x16x32_bf16 v[76:79], v[158:161], v[198:201], v[76:79]
	v_mfma_f32_16x16x32_bf16 v[72:75], v[166:169], v[198:201], v[72:75]
	s_barrier
	s_add_i32 s56, 0, 0x1c000
	s_add_i32 s33, s33, s65
	v_add_u32_e32 v216, s56, v151
	v_lshl_add_u64 v[220:221], v[220:221], 0, s[36:37]
	s_mov_b32 m0, s33
	ds_read_b128 v[204:207], v216
	ds_read_b128 v[208:211], v216 offset:1024
	ds_read_b128 v[212:215], v216 offset:2048
	ds_read_b128 v[216:219], v216 offset:3072
	global_load_lds_dwordx4 v[220:221], off
	v_lshl_add_u64 v[220:221], v[222:223], 0, s[36:37]
	s_add_i32 m0, s33, 0x2000
	s_nop 0
	global_load_lds_dwordx4 v[220:221], off
	s_barrier
	s_waitcnt lgkmcnt(0)
	v_mfma_f32_16x16x32_bf16 v[116:119], v[204:207], v[170:173], v[116:119]
	v_mfma_f32_16x16x32_bf16 v[112:115], v[212:215], v[170:173], v[112:115]
	v_mfma_f32_16x16x32_bf16 v[100:103], v[204:207], v[178:181], v[100:103]
	v_mfma_f32_16x16x32_bf16 v[96:99], v[212:215], v[178:181], v[96:99]
	v_mfma_f32_16x16x32_bf16 v[84:87], v[204:207], v[186:189], v[84:87]
	v_mfma_f32_16x16x32_bf16 v[80:83], v[212:215], v[186:189], v[80:83]
	v_mfma_f32_16x16x32_bf16 v[68:71], v[204:207], v[194:197], v[68:71]
	v_mfma_f32_16x16x32_bf16 v[64:67], v[212:215], v[194:197], v[64:67]
	v_mfma_f32_16x16x32_bf16 v[116:119], v[208:211], v[174:177], v[116:119]
	v_mfma_f32_16x16x32_bf16 v[112:115], v[216:219], v[174:177], v[112:115]
	v_mfma_f32_16x16x32_bf16 v[100:103], v[208:211], v[182:185], v[100:103]
	v_mfma_f32_16x16x32_bf16 v[96:99], v[216:219], v[182:185], v[96:99]
	v_mfma_f32_16x16x32_bf16 v[84:87], v[208:211], v[190:193], v[84:87]
	v_mfma_f32_16x16x32_bf16 v[80:83], v[216:219], v[190:193], v[80:83]
	v_mfma_f32_16x16x32_bf16 v[68:71], v[208:211], v[198:201], v[68:71]
	v_mfma_f32_16x16x32_bf16 v[64:67], v[216:219], v[198:201], v[64:67]
	s_mov_b32 m0, s72
	v_lshl_add_u64 v[220:221], v[224:225], 0, s[36:37]
	s_barrier
	ds_read_b128 v[170:173], v156 offset:49152
	ds_read_b128 v[174:177], v156 offset:50176
	ds_read_b128 v[178:181], v156 offset:51200
	ds_read_b128 v[182:185], v156 offset:52224
	ds_read_b128 v[186:189], v156 offset:53248
	ds_read_b128 v[190:193], v156 offset:54272
	ds_read_b128 v[194:197], v156 offset:55296
	ds_read_b128 v[198:201], v156 offset:56320
	global_load_lds_dwordx4 v[220:221], off
	v_lshl_add_u64 v[220:221], v[226:227], 0, s[36:37]
	s_mov_b32 m0, s73
	s_nop 0
	global_load_lds_dwordx4 v[220:221], off
	s_barrier
; __device__ __forceinline__ float bflo(unsigned w) { return __uint_as_float(w << 16); }
; __device__ __forceinline__ float bfhi(unsigned w) { return __uint_as_float(w & 0xffff0000u); }
; #define PG8_STAGE(bufoff, gbase, voff) do { _Pragma("unroll") for (int _i = 0; _i < 2; ++_i) \
;         __builtin_amdgcn_global_load_lds((const unsigned*)((const char*)(gbase) + (voff)[_i]), (LAS unsigned*)(lds + (bufoff) + ldsw + _i * 8192), 16, 0, 0); } while (0)
; #define PG8_MMA(ai, bj, At, Bt) do { __builtin_amdgcn_s_setprio(1); _Pragma("unroll") for (int m = 0; m < 4; ++m) _Pragma("unroll") for (int n = 0; n < 2; ++n) _Pragma("unroll") for (int k = 0; k < 2; ++k) \
;         acc[ai][bj][m][n] = __builtin_amdgcn_mfma_f32_16x16x32_bf16(Bt[n][k], At[m][k], acc[ai][bj][m][n], 0, 0, 0); __builtin_amdgcn_s_setprio(0); } while (0)
; #define PG8_WAIT_V(n) asm volatile("s_waitcnt vmcnt(" #n ")" ::: "memory")
; #define PG8_WAIT_L(n) asm volatile("s_waitcnt lgkmcnt(" #n ")" ::: "memory")
; #define PG8_BAR __builtin_amdgcn_s_barrier()
; #define PG8_SCHED __builtin_amdgcn_sched_barrier(0)
;     __device__ __forceinline__ void operator()(const f32x4 (&acc)[2][2][4][2], const Unit& u, int wr, int wc, int fr, int fq) const {
;     ...
;             for (int m = 0; m < 4; ++m) { const int row = row0 + ai * HALF + m * 16; const size_t off = (size_t)row * D + col0; float sq = 0.f; u32x4 w[2];
;                 const float sc = rsin ? __builtin_amdgcn_rcpf(rsin[row] * (1.f / D) + EPS) : 1.0f;
;                 u32x4 rr[2]; if (R) load_pair_lines(R, D, row, fr, col0, rr[0], rr[1]);
; #pragma unroll
;                 for (int bj = 0; bj < 2; ++bj) { f32x4 r0, r1;
;                     if (R) { const u32x4 rw = rr[bj]; r0 = (f32x4){bflo(rw.x), bfhi(rw.x), bflo(rw.y), bfhi(rw.y)}; r1 = (f32x4){bflo(rw.z), bfhi(rw.z), bflo(rw.w), bfhi(rw.w)}; }
;                     else { const float* rp = (row < 8192 ? src_p + off : src_s + (off - (size_t)8192 * D)) + 8 * bj; r0 = *(const f32x4*)rp; r1 = *(const f32x4*)(rp + 4); }
; template <class Epi>
; __device__ __forceinline__ void gemm_phase(LAS unsigned char* lds, const Gemm g, const StaticOrder& S, const Epi& E) {
;     ...
;             PG8_BAR; PG8_WAIT_L(0); PG8_MMA(1, 0, At, B0); PG8_BAR; PG8_SCHED;
;             PG8_STAGE(PG8_SB(1, 1), b3, voffB1);
;             PG8_WAIT_V(6); PG8_BAR; PG8_MMA(1, 1, At, B1); PG8_BAR;
;         }
	s_waitcnt lgkmcnt(0)
	v_mfma_f32_16x16x32_bf16 v[60:63], v[146:149], v[170:173], v[60:63]
	v_mfma_f32_16x16x32_bf16 v[56:59], v[162:165], v[170:173], v[56:59]
	v_mfma_f32_16x16x32_bf16 v[44:47], v[146:149], v[178:181], v[44:47]
	v_mfma_f32_16x16x32_bf16 v[40:43], v[162:165], v[178:181], v[40:43]
	v_mfma_f32_16x16x32_bf16 v[28:31], v[146:149], v[186:189], v[28:31]
	v_mfma_f32_16x16x32_bf16 v[24:27], v[162:165], v[186:189], v[24:27]
	v_mfma_f32_16x16x32_bf16 v[12:15], v[146:149], v[194:197], v[12:15]
	v_mfma_f32_16x16x32_bf16 v[8:11], v[162:165], v[194:197], v[8:11]
	v_mfma_f32_16x16x32_bf16 v[60:63], v[158:161], v[174:177], v[60:63]
	v_mfma_f32_16x16x32_bf16 v[56:59], v[166:169], v[174:177], v[56:59]
	v_mfma_f32_16x16x32_bf16 v[44:47], v[158:161], v[182:185], v[44:47]
	v_mfma_f32_16x16x32_bf16 v[40:43], v[166:169], v[182:185], v[40:43]
	v_mfma_f32_16x16x32_bf16 v[28:31], v[158:161], v[190:193], v[28:31]
	v_mfma_f32_16x16x32_bf16 v[24:27], v[166:169], v[190:193], v[24:27]
	v_mfma_f32_16x16x32_bf16 v[12:15], v[158:161], v[198:201], v[12:15]
	v_mfma_f32_16x16x32_bf16 v[8:11], v[166:169], v[198:201], v[8:11]
	s_barrier
	s_add_i32 s33, s56, s65
	v_lshl_add_u64 v[146:147], v[228:229], 0, s[36:37]
	s_mov_b32 m0, s33
	s_nop 0
	global_load_lds_dwordx4 v[146:147], off
	v_lshl_add_u64 v[146:147], v[230:231], 0, s[36:37]
	s_add_i32 m0, s33, 0x2000
	s_nop 0
	global_load_lds_dwordx4 v[146:147], off
	s_waitcnt vmcnt(6)
	s_barrier
	v_mfma_f32_16x16x32_bf16 v[52:55], v[204:207], v[170:173], v[52:55]
	v_mfma_f32_16x16x32_bf16 v[48:51], v[212:215], v[170:173], v[48:51]
	v_mfma_f32_16x16x32_bf16 v[36:39], v[204:207], v[178:181], v[36:39]
	v_mfma_f32_16x16x32_bf16 v[32:35], v[212:215], v[178:181], v[32:35]
	v_mfma_f32_16x16x32_bf16 v[20:23], v[204:207], v[186:189], v[20:23]
	v_mfma_f32_16x16x32_bf16 v[16:19], v[212:215], v[186:189], v[16:19]
	v_mfma_f32_16x16x32_bf16 v[4:7], v[204:207], v[194:197], v[4:7]
	v_mfma_f32_16x16x32_bf16 v[0:3], v[212:215], v[194:197], v[0:3]
	v_mfma_f32_16x16x32_bf16 v[52:55], v[208:211], v[174:177], v[52:55]
	v_mfma_f32_16x16x32_bf16 v[48:51], v[216:219], v[174:177], v[48:51]
	v_mfma_f32_16x16x32_bf16 v[36:39], v[208:211], v[182:185], v[36:39]
	v_mfma_f32_16x16x32_bf16 v[32:35], v[216:219], v[182:185], v[32:35]
	v_mfma_f32_16x16x32_bf16 v[20:23], v[208:211], v[190:193], v[20:23]
	v_mfma_f32_16x16x32_bf16 v[16:19], v[216:219], v[190:193], v[16:19]
	v_mfma_f32_16x16x32_bf16 v[4:7], v[208:211], v[198:201], v[4:7]
	v_mfma_f32_16x16x32_bf16 v[0:3], v[216:219], v[198:201], v[0:3]
	s_add_i32 s88, s88, 2
	s_add_u32 s54, s54, 0x100
	s_addc_u32 s55, s55, 0
	s_add_u32 s86, s86, 0x100
	s_addc_u32 s87, s87, 0
	s_cmp_gt_u32 s88, 29
	s_barrier
	s_cbranch_scc0 .LBB0_613
	s_lshl_b32 s33, s52, 8
	s_add_i32 s33, s33, s74
	v_or_b32_e32 v146, s33, v150
	v_lshl_or_b32 v148, s50, 8, v154
	v_ashrrev_i32_e32 v147, 31, v146
	v_ashrrev_i32_e32 v149, 31, v148
	v_lshlrev_b64 v[158:159], 11, v[146:147]
	v_lshl_add_u64 v[158:159], v[158:159], 0, v[148:149]
	v_lshlrev_b64 v[158:159], 2, v[158:159]
	v_lshl_add_u64 v[160:161], s[16:17], 0, v[158:159]
	v_lshl_add_u64 v[158:159], s[18:19], 0, v[158:159]
	v_lshl_add_u64 v[158:159], v[158:159], 0, s[38:39]
	v_cmp_gt_i32_e32 vcc, s70, v146
	v_mov_b32_e32 v183, 0
	v_mov_b32_e32 v184, 0
	v_cndmask_b32_e32 v167, v159, v161, vcc
	v_cndmask_b32_e32 v166, v158, v160, vcc
	global_load_dwordx4 v[158:161], v[166:167], off
	global_load_dwordx4 v[162:165], v[166:167], off offset:16
	v_or_b32_e32 v188, 16, v146
	v_ashrrev_i32_e32 v189, 31, v188
	v_lshlrev_b64 v[190:191], 11, v[188:189]
	v_lshl_add_u64 v[190:191], v[190:191], 0, v[148:149]
	v_lshlrev_b64 v[190:191], 2, v[190:191]
	v_lshl_add_u64 v[192:193], s[16:17], 0, v[190:191]
	v_lshl_add_u64 v[190:191], s[18:19], 0, v[190:191]
	v_lshl_add_u64 v[190:191], v[190:191], 0, s[38:39]
	v_cmp_gt_i32_e32 vcc, s70, v188
	s_nop 1
	v_cndmask_b32_e32 v195, v191, v193, vcc
	v_cndmask_b32_e32 v194, v190, v192, vcc
	global_load_dwordx4 v[196:199], v[194:195], off
	global_load_dwordx4 v[204:207], v[194:195], off offset:16
	global_load_dwordx4 v[208:211], v[194:195], off offset:32
	global_load_dwordx4 v[212:215], v[194:195], off offset:48
	v_or_b32_e32 v188, 32, v146
	v_ashrrev_i32_e32 v189, 31, v188
	v_lshlrev_b64 v[190:191], 11, v[188:189]
	v_lshl_add_u64 v[190:191], v[190:191], 0, v[148:149]
	v_lshlrev_b64 v[190:191], 2, v[190:191]
	v_lshl_add_u64 v[192:193], s[16:17], 0, v[190:191]
	v_lshl_add_u64 v[190:191], s[18:19], 0, v[190:191]
	v_lshl_add_u64 v[190:191], v[190:191], 0, s[38:39]
	v_cmp_gt_i32_e32 vcc, s70, v188
	s_nop 1
	v_cndmask_b32_e32 v195, v191, v193, vcc
	v_cndmask_b32_e32 v194, v190, v192, vcc
	global_load_dwordx4 v[216:219], v[194:195], off
	global_load_dwordx4 v[220:223], v[194:195], off offset:16
	global_load_dwordx4 v[224:227], v[194:195], off offset:32
	global_load_dwordx4 v[228:231], v[194:195], off offset:48
	v_or_b32_e32 v188, 48, v146
	v_ashrrev_i32_e32 v189, 31, v188
	v_lshlrev_b64 v[190:191], 11, v[188:189]
	v_lshl_add_u64 v[190:191], v[190:191], 0, v[148:149]
	v_lshlrev_b64 v[190:191], 2, v[190:191]
	v_lshl_add_u64 v[192:193], s[16:17], 0, v[190:191]
	v_lshl_add_u64 v[190:191], s[18:19], 0, v[190:191]
	v_lshl_add_u64 v[190:191], v[190:191], 0, s[38:39]
	v_cmp_gt_i32_e32 vcc, s70, v188
	s_nop 1
	v_cndmask_b32_e32 v195, v191, v193, vcc
	v_cndmask_b32_e32 v194, v190, v192, vcc
	global_load_dwordx4 v[232:235], v[194:195], off
	global_load_dwordx4 v[236:239], v[194:195], off offset:16
	global_load_dwordx4 v[240:243], v[194:195], off offset:32
	global_load_dwordx4 v[244:247], v[194:195], off offset:48
	s_waitcnt vmcnt(12)
; __device__ __forceinline__ unsigned cvt_pk_bf16(float lo, float hi) { unsigned r; asm volatile("v_cvt_pk_bf16_f32 %0, %1, %2" : "=v"(r) : "v"(lo), "v"(hi)); return r; }
; __device__ __forceinline__ float bflo(unsigned w) { return __uint_as_float(w << 16); }
; __device__ __forceinline__ void store_pair_lines(bf16_t* O, int ldc, int row, int fr, int col0, u32x4 wA, u32x4 wB) {
;     const u32x4 sA = {dpp_ror8(wA.x), dpp_ror8(wA.y), dpp_ror8(wA.z), dpp_ror8(wA.w)}, sB = {dpp_ror8(wB.x), dpp_ror8(wB.y), dpp_ror8(wB.z), dpp_ror8(wB.w)};
;     const bool lo = fr < 8;
;     const u32x4 o1 = lo ? wA : sB, o2 = lo ? sA : wB;
;     const int r1 = row - fr + (fr & 7), cb = col0 + (lo ? 0 : 8);
;     *(u32x4*)(O + (size_t)r1 * ldc + cb) = o1;
;     *(u32x4*)(O + (size_t)(r1 + 8) * ldc + cb) = o2;
; }
;     __device__ __forceinline__ void operator()(const f32x4 (&acc)[2][2][4][2], const Unit& u, int wr, int wc, int fr, int fq) const {
;     ...
;             for (int m = 0; m < 4; ++m) { const int row = row0 + ai * HALF + m * 16; const size_t off = (size_t)row * D + col0; float sq = 0.f; u32x4 w[2];
;                 const float sc = rsin ? __builtin_amdgcn_rcpf(rsin[row] * (1.f / D) + EPS) : 1.0f;
;                 u32x4 rr[2]; if (R) load_pair_lines(R, D, row, fr, col0, rr[0], rr[1]);
; #pragma unroll
;                 for (int bj = 0; bj < 2; ++bj) { f32x4 r0, r1;
;                     if (R) { const u32x4 rw = rr[bj]; r0 = (f32x4){bflo(rw.x), bfhi(rw.x), bflo(rw.y), bfhi(rw.y)}; r1 = (f32x4){bflo(rw.z), bfhi(rw.z), bflo(rw.w), bfhi(rw.w)}; }
;                     else { const float* rp = (row < 8192 ? src_p + off : src_s + (off - (size_t)8192 * D)) + 8 * bj; r0 = *(const f32x4*)rp; r1 = *(const f32x4*)(rp + 4); }
;                     const f32x4 o0 = r0 + acc[ai][bj][m][0] * sc, o1 = r1 + acc[ai][bj][m][1] * sc;
;                     sq += (o0[0] * o0[0] + o0[1] * o0[1]) + (o0[2] * o0[2] + o0[3] * o0[3]) + (o1[0] * o1[0] + o1[1] * o1[1]) + (o1[2] * o1[2] + o1[3] * o1[3]);
;                     w[bj].x = cvt_pk_bf16(o0[0], o0[1]); w[bj].y = cvt_pk_bf16(o0[2], o0[3]); w[bj].z = cvt_pk_bf16(o1[0], o1[1]); w[bj].w = cvt_pk_bf16(o1[2], o1[3]); }
;                 store_pair_lines(O, D, row, fr, col0, w[0], w[1]);
;                 if (ssout) { sq += __shfl_xor(sq, 16); sq += __shfl_xor(sq, 32); if (fq == 0) unsafeAtomicAdd(ssout + row, sq); } }
	v_pk_add_f32 v[168:169], v[126:127], v[160:161]
	v_pk_add_f32 v[170:171], v[124:125], v[158:159]
	v_pk_add_f32 v[164:165], v[122:123], v[164:165]
	v_pk_add_f32 v[162:163], v[120:121], v[162:163]
	v_cvt_pk_bf16_f32 v123, v170, v171
	v_cvt_pk_bf16_f32 v176, v168, v169
	v_mul_f32_e32 v171, v171, v171
	v_cvt_pk_bf16_f32 v177, v162, v163
	v_cvt_pk_bf16_f32 v178, v164, v165
	global_load_dwordx4 v[124:127], v[166:167], off offset:32
	global_load_dwordx4 v[158:161], v[166:167], off offset:48
	v_mul_f32_e32 v169, v169, v169
	v_and_b32_e32 v121, 64, v203
	v_mul_f32_e32 v163, v163, v163
	v_fmac_f32_e32 v171, v170, v170
	v_fmac_f32_e32 v169, v168, v168
	v_xor_b32_e32 v122, 16, v203
	v_add_u32_e32 v172, 64, v121
	v_mul_f32_e32 v165, v165, v165
	v_fmac_f32_e32 v163, v162, v162
	v_add_f32_e32 v162, v171, v169
	v_cmp_lt_i32_e32 vcc, v122, v172
	v_fmac_f32_e32 v165, v164, v164
	v_add_f32_e32 v162, v163, v162
	v_cndmask_b32_e32 v122, v203, v122, vcc
	v_add_f32_e32 v162, v165, v162
	v_xor_b32_e32 v167, 32, v203
	v_lshlrev_b32_e32 v122, 2, v122
	v_or_b32_e32 v166, s33, v152
	v_cmp_lt_i32_e32 vcc, v167, v172
	v_or_b32_e32 v120, v148, v153
	v_ashrrev_i32_e32 v121, 31, v120
	v_cndmask_b32_e32 v187, v203, v167, vcc
	v_ashrrev_i32_e32 v167, 31, v166
	v_or_b32_e32 v174, 8, v166
	v_lshlrev_b64 v[166:167], 12, v[166:167]
	v_lshlrev_b64 v[172:173], 1, v[120:121]
	v_lshl_add_u64 v[166:167], s[10:11], 0, v[166:167]
	v_lshl_add_u64 v[166:167], v[166:167], 0, v[172:173]
	v_ashrrev_i32_e32 v175, 31, v174
	v_mov_b32_dpp v179, v123 row_ror:8 row_mask:0xf bank_mask:0xf
	v_mov_b32_dpp v180, v176 row_ror:8 row_mask:0xf bank_mask:0xf
	v_mov_b32_dpp v181, v177 row_ror:8 row_mask:0xf bank_mask:0xf
	v_mov_b32_dpp v182, v178 row_ror:8 row_mask:0xf bank_mask:0xf
	s_waitcnt vmcnt(0)
	v_pk_add_f32 v[126:127], v[118:119], v[126:127]
	v_pk_add_f32 v[124:125], v[116:117], v[124:125]
	v_pk_add_f32 v[112:113], v[112:113], v[158:159]
	v_cvt_pk_bf16_f32 v116, v124, v125
	v_cvt_pk_bf16_f32 v117, v126, v127
	v_mul_f32_e32 v125, v125, v125
	v_mul_f32_e32 v127, v127, v127
	v_pk_add_f32 v[114:115], v[114:115], v[160:161]
	v_mul_f32_e32 v158, v113, v113
	v_fmac_f32_e32 v125, v124, v124
	v_fmac_f32_e32 v127, v126, v126
	v_cvt_pk_bf16_f32 v118, v112, v113
	v_cvt_pk_bf16_f32 v119, v114, v115
	v_mul_f32_e32 v115, v115, v115
	v_fmac_f32_e32 v158, v112, v112
	v_add_f32_e32 v112, v125, v127
	v_fmac_f32_e32 v115, v114, v114
	v_add_f32_e32 v112, v158, v112
	v_add_f32_e32 v112, v115, v112
	v_add_f32_e32 v124, v162, v112
	v_mov_b32_e32 v125, v124
	s_nop 1
	v_permlane16_swap_b32_e32 v125, v124
	v_mov_b32_dpp v183, v116 row_ror:8 row_mask:0xf bank_mask:0xf
	v_mov_b32_dpp v184, v117 row_ror:8 row_mask:0xf bank_mask:0xf
	v_mov_b32_dpp v185, v118 row_ror:8 row_mask:0xf bank_mask:0xf
	v_mov_b32_dpp v186, v119 row_ror:8 row_mask:0xf bank_mask:0xf
	v_cndmask_b32_e64 v113, v184, v176, s[6:7]
	v_cndmask_b32_e64 v115, v186, v178, s[6:7]
	v_cndmask_b32_e64 v112, v183, v123, s[6:7]
	v_cndmask_b32_e64 v114, v185, v177, s[6:7]
	global_store_dwordx4 v[166:167], v[112:115], off
	v_cndmask_b32_e64 v117, v117, v180, s[6:7]
	v_cndmask_b32_e64 v119, v119, v182, s[6:7]
	s_waitcnt lgkmcnt(0)
	v_add_f32_e32 v112, v124, v125
	v_lshlrev_b32_e32 v114, 2, v187
	v_mov_b32_e32 v113, v112
	s_nop 1
	v_permlane32_swap_b32_e32 v113, v112
	v_lshlrev_b64 v[124:125], 12, v[174:175]
	v_lshl_add_u64 v[124:125], s[10:11], 0, v[124:125]
	v_cndmask_b32_e64 v116, v116, v179, s[6:7]
	v_cndmask_b32_e64 v118, v118, v181, s[6:7]
	v_lshl_add_u64 v[124:125], v[124:125], 0, v[172:173]
	global_store_dwordx4 v[124:125], v[116:119], off
	s_and_saveexec_b64 s[50:51], s[8:9]
	s_cbranch_execz .LBB0_616
	s_waitcnt lgkmcnt(0)
	v_add_f32_e32 v115, v112, v113
	v_lshl_add_u64 v[112:113], v[146:147], 2, s[12:13]
	global_atomic_add_f32 v[112:113], v115, off
.LBB0_616:
	s_or_b64 exec, exec, s[50:51]
	v_or_b32_e32 v112, 16, v146
	s_waitcnt lgkmcnt(0)
	v_ashrrev_i32_e32 v113, 31, v112
	v_lshlrev_b64 v[116:117], 11, v[112:113]
	v_lshl_add_u64 v[116:117], v[116:117], 0, v[148:149]
	v_lshlrev_b64 v[116:117], 2, v[116:117]
	v_lshl_add_u64 v[118:119], s[16:17], 0, v[116:117]
	v_lshl_add_u64 v[116:117], s[18:19], 0, v[116:117]
	v_lshl_add_u64 v[116:117], v[116:117], 0, s[38:39]
	v_cmp_gt_i32_e32 vcc, s70, v112
	v_mov_b32_e32 v165, 0
	v_mov_b32_e32 v166, 0
	v_cndmask_b32_e32 v159, v117, v119, vcc
	v_cndmask_b32_e32 v158, v116, v118, vcc
	s_waitcnt vmcnt(12)
; __device__ __forceinline__ unsigned cvt_pk_bf16(float lo, float hi) { unsigned r; asm volatile("v_cvt_pk_bf16_f32 %0, %1, %2" : "=v"(r) : "v"(lo), "v"(hi)); return r; }
; __device__ __forceinline__ float bflo(unsigned w) { return __uint_as_float(w << 16); }
; __device__ __forceinline__ float bfhi(unsigned w) { return __uint_as_float(w & 0xffff0000u); }
;     __device__ __forceinline__ void operator()(const f32x4 (&acc)[2][2][4][2], const Unit& u, int wr, int wc, int fr, int fq) const {
;     ...
;             for (int m = 0; m < 4; ++m) { const int row = row0 + ai * HALF + m * 16; const size_t off = (size_t)row * D + col0; float sq = 0.f; u32x4 w[2];
;                 const float sc = rsin ? __builtin_amdgcn_rcpf(rsin[row] * (1.f / D) + EPS) : 1.0f;
;                 u32x4 rr[2]; if (R) load_pair_lines(R, D, row, fr, col0, rr[0], rr[1]);
; #pragma unroll
;                 for (int bj = 0; bj < 2; ++bj) { f32x4 r0, r1;
;                     if (R) { const u32x4 rw = rr[bj]; r0 = (f32x4){bflo(rw.x), bfhi(rw.x), bflo(rw.y), bfhi(rw.y)}; r1 = (f32x4){bflo(rw.z), bfhi(rw.z), bflo(rw.w), bfhi(rw.w)}; }
;                     else { const float* rp = (row < 8192 ? src_p + off : src_s + (off - (size_t)8192 * D)) + 8 * bj; r0 = *(const f32x4*)rp; r1 = *(const f32x4*)(rp + 4); }
;                     const f32x4 o0 = r0 + acc[ai][bj][m][0] * sc, o1 = r1 + acc[ai][bj][m][1] * sc;
;                     sq += (o0[0] * o0[0] + o0[1] * o0[1]) + (o0[2] * o0[2] + o0[3] * o0[3]) + (o1[0] * o1[0] + o1[1] * o1[1]) + (o1[2] * o1[2] + o1[3] * o1[3]);
;                     w[bj].x = cvt_pk_bf16(o0[0], o0[1]); w[bj].y = cvt_pk_bf16(o0[2], o0[3]); w[bj].z = cvt_pk_bf16(o1[0], o1[1]); w[bj].w = cvt_pk_bf16(o1[2], o1[3]); }
;                 store_pair_lines(O, D, row, fr, col0, w[0], w[1]);
;                 if (ssout) { sq += __shfl_xor(sq, 16); sq += __shfl_xor(sq, 32); if (fq == 0) unsafeAtomicAdd(ssout + row, sq); } }
	s_nop 0
	v_mov_b64_e32 v[116:117], v[196:197]
	v_mov_b64_e32 v[118:119], v[198:199]
	v_mov_b64_e32 v[124:125], v[204:205]
	v_mov_b64_e32 v[126:127], v[206:207]
	v_pk_add_f32 v[118:119], v[110:111], v[118:119]
	v_pk_add_f32 v[116:117], v[108:109], v[116:117]
	v_pk_add_f32 v[126:127], v[106:107], v[126:127]
	v_pk_add_f32 v[124:125], v[104:105], v[124:125]
	v_cvt_pk_bf16_f32 v115, v116, v117
	v_cvt_pk_bf16_f32 v123, v118, v119
	v_mul_f32_e32 v117, v117, v117
	v_cvt_pk_bf16_f32 v147, v124, v125
	v_cvt_pk_bf16_f32 v160, v126, v127
	v_mov_b64_e32 v[104:105], v[208:209]
	v_mov_b64_e32 v[106:107], v[210:211]
	v_mov_b64_e32 v[108:109], v[212:213]
	v_mov_b64_e32 v[110:111], v[214:215]
	s_nop 1
	v_add_u32_e32 v188, 0x80, v146
	v_ashrrev_i32_e32 v189, 31, v188
	v_lshlrev_b64 v[190:191], 11, v[188:189]
	v_lshl_add_u64 v[190:191], v[190:191], 0, v[148:149]
	v_lshlrev_b64 v[190:191], 2, v[190:191]
	v_lshl_add_u64 v[192:193], s[16:17], 0, v[190:191]
	v_lshl_add_u64 v[190:191], s[18:19], 0, v[190:191]
	v_lshl_add_u64 v[190:191], v[190:191], 0, s[38:39]
	v_cmp_gt_i32_e32 vcc, s81, v146
	s_nop 1
	v_cndmask_b32_e32 v195, v191, v193, vcc
	v_cndmask_b32_e32 v194, v190, v192, vcc
	global_load_dwordx4 v[196:199], v[194:195], off
	global_load_dwordx4 v[204:207], v[194:195], off offset:16
	global_load_dwordx4 v[208:211], v[194:195], off offset:32
	global_load_dwordx4 v[212:215], v[194:195], off offset:48
	v_mul_f32_e32 v119, v119, v119
	v_mul_f32_e32 v125, v125, v125
	v_fmac_f32_e32 v117, v116, v116
	v_fmac_f32_e32 v119, v118, v118
	v_mul_f32_e32 v127, v127, v127
	v_fmac_f32_e32 v125, v124, v124
	v_add_f32_e32 v116, v117, v119
	v_fmac_f32_e32 v127, v126, v126
	v_add_f32_e32 v116, v125, v116
	v_add_f32_e32 v116, v127, v116
	v_sub_u32_e32 v158, v112, v150
	v_add_u32_e32 v158, v158, v152
	v_ashrrev_i32_e32 v159, 31, v158
	v_lshlrev_b64 v[158:159], 12, v[158:159]
	v_lshl_add_u64 v[158:159], s[10:11], 0, v[158:159]
	v_lshl_add_u64 v[158:159], v[120:121], 1, v[158:159]
	v_mov_b32_dpp v161, v115 row_ror:8 row_mask:0xf bank_mask:0xf
	v_mov_b32_dpp v162, v123 row_ror:8 row_mask:0xf bank_mask:0xf
	v_mov_b32_dpp v163, v147 row_ror:8 row_mask:0xf bank_mask:0xf
	v_mov_b32_dpp v164, v160 row_ror:8 row_mask:0xf bank_mask:0xf
	v_pk_add_f32 v[102:103], v[102:103], v[106:107]
	v_pk_add_f32 v[104:105], v[100:101], v[104:105]
	v_pk_add_f32 v[106:107], v[98:99], v[110:111]
	v_pk_add_f32 v[96:97], v[96:97], v[108:109]
	v_cvt_pk_bf16_f32 v98, v104, v105
	v_mul_f32_e32 v105, v105, v105
	v_mul_f32_e32 v108, v103, v103
	v_cvt_pk_bf16_f32 v99, v102, v103
	v_cvt_pk_bf16_f32 v100, v96, v97
	v_mul_f32_e32 v97, v97, v97
	v_fmac_f32_e32 v105, v104, v104
	v_fmac_f32_e32 v108, v102, v102
	v_cvt_pk_bf16_f32 v101, v106, v107
	v_mul_f32_e32 v107, v107, v107
	v_fmac_f32_e32 v97, v96, v96
	v_add_f32_e32 v96, v105, v108
	v_fmac_f32_e32 v107, v106, v106
	v_add_f32_e32 v96, v97, v96
	v_add_f32_e32 v96, v107, v96
	v_add_f32_e32 v96, v116, v96
	v_mov_b32_e32 v97, v96
	s_nop 1
	v_permlane16_swap_b32_e32 v97, v96
	v_mov_b32_dpp v165, v98 row_ror:8 row_mask:0xf bank_mask:0xf
	v_mov_b32_dpp v166, v99 row_ror:8 row_mask:0xf bank_mask:0xf
	v_mov_b32_dpp v167, v100 row_ror:8 row_mask:0xf bank_mask:0xf
	v_mov_b32_dpp v168, v101 row_ror:8 row_mask:0xf bank_mask:0xf
	s_waitcnt lgkmcnt(0)
	v_add_f32_e32 v96, v96, v97
	v_mov_b32_e32 v97, v96
	s_nop 1
	v_permlane32_swap_b32_e32 v97, v96
	v_cndmask_b32_e64 v103, v166, v123, s[6:7]
	v_cndmask_b32_e64 v105, v168, v160, s[6:7]
	v_cndmask_b32_e64 v102, v165, v115, s[6:7]
	v_cndmask_b32_e64 v104, v167, v147, s[6:7]
	global_store_dwordx4 v[158:159], v[102:105], off
	v_cndmask_b32_e64 v99, v99, v162, s[6:7]
	v_cndmask_b32_e64 v101, v101, v164, s[6:7]
	v_add_co_u32_e32 v102, vcc, s69, v158
	v_cndmask_b32_e64 v98, v98, v161, s[6:7]
	v_cndmask_b32_e64 v100, v100, v163, s[6:7]
	v_addc_co_u32_e32 v103, vcc, 0, v159, vcc
	global_store_dwordx4 v[102:103], v[98:101], off
	s_and_saveexec_b64 s[50:51], s[8:9]
	s_cbranch_execz .LBB0_618
	s_waitcnt lgkmcnt(0)
	v_add_f32_e32 v98, v96, v97
	v_lshl_add_u64 v[96:97], v[112:113], 2, s[12:13]
	global_atomic_add_f32 v[96:97], v98, off
.LBB0_618:
	s_or_b64 exec, exec, s[50:51]
	v_or_b32_e32 v96, 32, v146
	s_waitcnt lgkmcnt(0)
	v_ashrrev_i32_e32 v97, 31, v96
	v_lshlrev_b64 v[98:99], 11, v[96:97]
	v_lshl_add_u64 v[98:99], v[98:99], 0, v[148:149]
	v_lshlrev_b64 v[98:99], 2, v[98:99]
	v_lshl_add_u64 v[100:101], s[16:17], 0, v[98:99]
	v_lshl_add_u64 v[98:99], s[18:19], 0, v[98:99]
	v_lshl_add_u64 v[98:99], v[98:99], 0, s[38:39]
	v_cmp_gt_i32_e32 vcc, s70, v96
	v_mov_b32_e32 v117, 0
	v_mov_b32_e32 v118, 0
	v_cndmask_b32_e32 v107, v99, v101, vcc
	v_cndmask_b32_e32 v106, v98, v100, vcc
	s_waitcnt vmcnt(14)
; __device__ __forceinline__ unsigned cvt_pk_bf16(float lo, float hi) { unsigned r; asm volatile("v_cvt_pk_bf16_f32 %0, %1, %2" : "=v"(r) : "v"(lo), "v"(hi)); return r; }
; __device__ __forceinline__ float bflo(unsigned w) { return __uint_as_float(w << 16); }
; __device__ __forceinline__ float bfhi(unsigned w) { return __uint_as_float(w & 0xffff0000u); }
;     __device__ __forceinline__ void operator()(const f32x4 (&acc)[2][2][4][2], const Unit& u, int wr, int wc, int fr, int fq) const {
;     ...
;             for (int m = 0; m < 4; ++m) { const int row = row0 + ai * HALF + m * 16; const size_t off = (size_t)row * D + col0; float sq = 0.f; u32x4 w[2];
;                 const float sc = rsin ? __builtin_amdgcn_rcpf(rsin[row] * (1.f / D) + EPS) : 1.0f;
;                 u32x4 rr[2]; if (R) load_pair_lines(R, D, row, fr, col0, rr[0], rr[1]);
; #pragma unroll
;                 for (int bj = 0; bj < 2; ++bj) { f32x4 r0, r1;
;                     if (R) { const u32x4 rw = rr[bj]; r0 = (f32x4){bflo(rw.x), bfhi(rw.x), bflo(rw.y), bfhi(rw.y)}; r1 = (f32x4){bflo(rw.z), bfhi(rw.z), bflo(rw.w), bfhi(rw.w)}; }
;                     else { const float* rp = (row < 8192 ? src_p + off : src_s + (off - (size_t)8192 * D)) + 8 * bj; r0 = *(const f32x4*)rp; r1 = *(const f32x4*)(rp + 4); }
;                     const f32x4 o0 = r0 + acc[ai][bj][m][0] * sc, o1 = r1 + acc[ai][bj][m][1] * sc;
;                     sq += (o0[0] * o0[0] + o0[1] * o0[1]) + (o0[2] * o0[2] + o0[3] * o0[3]) + (o1[0] * o1[0] + o1[1] * o1[1]) + (o1[2] * o1[2] + o1[3] * o1[3]);
;                     w[bj].x = cvt_pk_bf16(o0[0], o0[1]); w[bj].y = cvt_pk_bf16(o0[2], o0[3]); w[bj].z = cvt_pk_bf16(o1[0], o1[1]); w[bj].w = cvt_pk_bf16(o1[2], o1[3]); }
;                 store_pair_lines(O, D, row, fr, col0, w[0], w[1]);
;                 if (ssout) { sq += __shfl_xor(sq, 16); sq += __shfl_xor(sq, 32); if (fq == 0) unsafeAtomicAdd(ssout + row, sq); } }
	s_nop 0
	v_mov_b64_e32 v[98:99], v[216:217]
	v_mov_b64_e32 v[100:101], v[218:219]
	v_mov_b64_e32 v[102:103], v[220:221]
	v_mov_b64_e32 v[104:105], v[222:223]
	v_pk_add_f32 v[100:101], v[94:95], v[100:101]
	v_pk_add_f32 v[98:99], v[92:93], v[98:99]
	v_pk_add_f32 v[104:105], v[90:91], v[104:105]
	v_pk_add_f32 v[102:103], v[88:89], v[102:103]
	v_cvt_pk_bf16_f32 v108, v98, v99
	v_cvt_pk_bf16_f32 v109, v100, v101
	v_mul_f32_e32 v99, v99, v99
	v_cvt_pk_bf16_f32 v110, v102, v103
	v_cvt_pk_bf16_f32 v111, v104, v105
	v_mov_b64_e32 v[88:89], v[224:225]
	v_mov_b64_e32 v[90:91], v[226:227]
	v_mov_b64_e32 v[92:93], v[228:229]
	v_mov_b64_e32 v[94:95], v[230:231]
	s_nop 1
	v_add_u32_e32 v188, 0x90, v146
	v_ashrrev_i32_e32 v189, 31, v188
	v_lshlrev_b64 v[190:191], 11, v[188:189]
	v_lshl_add_u64 v[190:191], v[190:191], 0, v[148:149]
	v_lshlrev_b64 v[190:191], 2, v[190:191]
	v_lshl_add_u64 v[192:193], s[16:17], 0, v[190:191]
	v_lshl_add_u64 v[190:191], s[18:19], 0, v[190:191]
	v_lshl_add_u64 v[190:191], v[190:191], 0, s[38:39]
	v_cmp_gt_i32_e32 vcc, s82, v146
	s_nop 1
	v_cndmask_b32_e32 v195, v191, v193, vcc
	v_cndmask_b32_e32 v194, v190, v192, vcc
	global_load_dwordx4 v[216:219], v[194:195], off
	global_load_dwordx4 v[220:223], v[194:195], off offset:16
	global_load_dwordx4 v[224:227], v[194:195], off offset:32
	global_load_dwordx4 v[228:231], v[194:195], off offset:48
	v_mul_f32_e32 v101, v101, v101
	v_mul_f32_e32 v103, v103, v103
	v_fmac_f32_e32 v99, v98, v98
	v_fmac_f32_e32 v101, v100, v100
	v_mul_f32_e32 v105, v105, v105
	v_fmac_f32_e32 v103, v102, v102
	v_add_f32_e32 v98, v99, v101
	v_fmac_f32_e32 v105, v104, v104
	v_add_f32_e32 v98, v103, v98
	v_add_f32_e32 v98, v105, v98
	v_sub_u32_e32 v106, v96, v150
	v_add_u32_e32 v106, v106, v152
	v_ashrrev_i32_e32 v107, 31, v106
	v_lshlrev_b64 v[106:107], 12, v[106:107]
	v_lshl_add_u64 v[106:107], s[10:11], 0, v[106:107]
	v_lshl_add_u64 v[106:107], v[120:121], 1, v[106:107]
	v_mov_b32_dpp v112, v108 row_ror:8 row_mask:0xf bank_mask:0xf
	v_mov_b32_dpp v113, v109 row_ror:8 row_mask:0xf bank_mask:0xf
	v_mov_b32_dpp v115, v110 row_ror:8 row_mask:0xf bank_mask:0xf
	v_mov_b32_dpp v116, v111 row_ror:8 row_mask:0xf bank_mask:0xf
	v_pk_add_f32 v[86:87], v[86:87], v[90:91]
	v_pk_add_f32 v[88:89], v[84:85], v[88:89]
	v_pk_add_f32 v[90:91], v[82:83], v[94:95]
	v_pk_add_f32 v[80:81], v[80:81], v[92:93]
	v_cvt_pk_bf16_f32 v82, v88, v89
	v_mul_f32_e32 v89, v89, v89
	v_mul_f32_e32 v92, v87, v87
	v_cvt_pk_bf16_f32 v83, v86, v87
	v_cvt_pk_bf16_f32 v84, v80, v81
	v_mul_f32_e32 v81, v81, v81
	v_fmac_f32_e32 v89, v88, v88
	v_fmac_f32_e32 v92, v86, v86
	v_cvt_pk_bf16_f32 v85, v90, v91
	v_mul_f32_e32 v91, v91, v91
	v_fmac_f32_e32 v81, v80, v80
	v_add_f32_e32 v80, v89, v92
	v_fmac_f32_e32 v91, v90, v90
	v_add_f32_e32 v80, v81, v80
	v_add_f32_e32 v80, v91, v80
	v_add_f32_e32 v80, v98, v80
	v_mov_b32_e32 v81, v80
	s_nop 1
	v_permlane16_swap_b32_e32 v81, v80
	v_mov_b32_dpp v117, v82 row_ror:8 row_mask:0xf bank_mask:0xf
	v_mov_b32_dpp v118, v83 row_ror:8 row_mask:0xf bank_mask:0xf
	v_mov_b32_dpp v119, v84 row_ror:8 row_mask:0xf bank_mask:0xf
	v_mov_b32_dpp v123, v85 row_ror:8 row_mask:0xf bank_mask:0xf
	s_waitcnt lgkmcnt(0)
	v_add_f32_e32 v80, v80, v81
	v_mov_b32_e32 v81, v80
	s_nop 1
	v_permlane32_swap_b32_e32 v81, v80
	v_cndmask_b32_e64 v87, v118, v109, s[6:7]
	v_cndmask_b32_e64 v89, v123, v111, s[6:7]
	v_cndmask_b32_e64 v86, v117, v108, s[6:7]
	v_cndmask_b32_e64 v88, v119, v110, s[6:7]
	global_store_dwordx4 v[106:107], v[86:89], off
	v_cndmask_b32_e64 v83, v83, v113, s[6:7]
	v_cndmask_b32_e64 v85, v85, v116, s[6:7]
	v_add_co_u32_e32 v86, vcc, s69, v106
	v_cndmask_b32_e64 v82, v82, v112, s[6:7]
	v_cndmask_b32_e64 v84, v84, v115, s[6:7]
	v_addc_co_u32_e32 v87, vcc, 0, v107, vcc
	global_store_dwordx4 v[86:87], v[82:85], off
	s_and_saveexec_b64 s[50:51], s[8:9]
	s_cbranch_execz .LBB0_620
	s_waitcnt lgkmcnt(0)
	v_add_f32_e32 v82, v80, v81
	v_lshl_add_u64 v[80:81], v[96:97], 2, s[12:13]
	global_atomic_add_f32 v[80:81], v82, off
.LBB0_620:
	s_or_b64 exec, exec, s[50:51]
	v_or_b32_e32 v80, 48, v146
	s_waitcnt lgkmcnt(0)
	v_ashrrev_i32_e32 v81, 31, v80
	v_lshlrev_b64 v[82:83], 11, v[80:81]
	v_lshl_add_u64 v[82:83], v[82:83], 0, v[148:149]
	v_lshlrev_b64 v[82:83], 2, v[82:83]
	v_lshl_add_u64 v[84:85], s[16:17], 0, v[82:83]
	v_lshl_add_u64 v[82:83], s[18:19], 0, v[82:83]
	v_lshl_add_u64 v[82:83], v[82:83], 0, s[38:39]
	v_cmp_gt_i32_e32 vcc, s70, v80
	v_mov_b32_e32 v100, 0
	v_mov_b32_e32 v101, 0
	v_cndmask_b32_e32 v91, v83, v85, vcc
	v_cndmask_b32_e32 v90, v82, v84, vcc
	s_waitcnt vmcnt(16)
; __device__ __forceinline__ unsigned cvt_pk_bf16(float lo, float hi) { unsigned r; asm volatile("v_cvt_pk_bf16_f32 %0, %1, %2" : "=v"(r) : "v"(lo), "v"(hi)); return r; }
; __device__ __forceinline__ float bflo(unsigned w) { return __uint_as_float(w << 16); }
; __device__ __forceinline__ float bfhi(unsigned w) { return __uint_as_float(w & 0xffff0000u); }
;     __device__ __forceinline__ void operator()(const f32x4 (&acc)[2][2][4][2], const Unit& u, int wr, int wc, int fr, int fq) const {
;     ...
;             for (int m = 0; m < 4; ++m) { const int row = row0 + ai * HALF + m * 16; const size_t off = (size_t)row * D + col0; float sq = 0.f; u32x4 w[2];
;                 const float sc = rsin ? __builtin_amdgcn_rcpf(rsin[row] * (1.f / D) + EPS) : 1.0f;
;                 u32x4 rr[2]; if (R) load_pair_lines(R, D, row, fr, col0, rr[0], rr[1]);
; #pragma unroll
;                 for (int bj = 0; bj < 2; ++bj) { f32x4 r0, r1;
;                     if (R) { const u32x4 rw = rr[bj]; r0 = (f32x4){bflo(rw.x), bfhi(rw.x), bflo(rw.y), bfhi(rw.y)}; r1 = (f32x4){bflo(rw.z), bfhi(rw.z), bflo(rw.w), bfhi(rw.w)}; }
;                     else { const float* rp = (row < 8192 ? src_p + off : src_s + (off - (size_t)8192 * D)) + 8 * bj; r0 = *(const f32x4*)rp; r1 = *(const f32x4*)(rp + 4); }
;                     const f32x4 o0 = r0 + acc[ai][bj][m][0] * sc, o1 = r1 + acc[ai][bj][m][1] * sc;
;                     sq += (o0[0] * o0[0] + o0[1] * o0[1]) + (o0[2] * o0[2] + o0[3] * o0[3]) + (o1[0] * o1[0] + o1[1] * o1[1]) + (o1[2] * o1[2] + o1[3] * o1[3]);
;                     w[bj].x = cvt_pk_bf16(o0[0], o0[1]); w[bj].y = cvt_pk_bf16(o0[2], o0[3]); w[bj].z = cvt_pk_bf16(o1[0], o1[1]); w[bj].w = cvt_pk_bf16(o1[2], o1[3]); }
;                 store_pair_lines(O, D, row, fr, col0, w[0], w[1]);
;                 if (ssout) { sq += __shfl_xor(sq, 16); sq += __shfl_xor(sq, 32); if (fq == 0) unsafeAtomicAdd(ssout + row, sq); } }
	s_nop 0
	v_mov_b64_e32 v[82:83], v[232:233]
	v_mov_b64_e32 v[84:85], v[234:235]
	v_mov_b64_e32 v[86:87], v[236:237]
	v_mov_b64_e32 v[88:89], v[238:239]
	v_pk_add_f32 v[84:85], v[78:79], v[84:85]
	v_pk_add_f32 v[82:83], v[76:77], v[82:83]
	v_pk_add_f32 v[88:89], v[74:75], v[88:89]
	v_pk_add_f32 v[86:87], v[72:73], v[86:87]
	v_cvt_pk_bf16_f32 v92, v82, v83
	v_cvt_pk_bf16_f32 v93, v84, v85
	v_mul_f32_e32 v83, v83, v83
	v_cvt_pk_bf16_f32 v94, v86, v87
	v_cvt_pk_bf16_f32 v95, v88, v89
	v_mov_b64_e32 v[72:73], v[240:241]
	v_mov_b64_e32 v[74:75], v[242:243]
	v_mov_b64_e32 v[76:77], v[244:245]
	v_mov_b64_e32 v[78:79], v[246:247]
	s_nop 1
	v_add_u32_e32 v188, 0xa0, v146
	v_ashrrev_i32_e32 v189, 31, v188
	v_lshlrev_b64 v[190:191], 11, v[188:189]
	v_lshl_add_u64 v[190:191], v[190:191], 0, v[148:149]
	v_lshlrev_b64 v[190:191], 2, v[190:191]
	v_lshl_add_u64 v[192:193], s[16:17], 0, v[190:191]
	v_lshl_add_u64 v[190:191], s[18:19], 0, v[190:191]
	v_lshl_add_u64 v[190:191], v[190:191], 0, s[38:39]
	v_cmp_gt_i32_e32 vcc, s83, v146
	s_nop 1
	v_cndmask_b32_e32 v195, v191, v193, vcc
	v_cndmask_b32_e32 v194, v190, v192, vcc
	global_load_dwordx4 v[232:235], v[194:195], off
	global_load_dwordx4 v[236:239], v[194:195], off offset:16
	global_load_dwordx4 v[240:243], v[194:195], off offset:32
	global_load_dwordx4 v[244:247], v[194:195], off offset:48
	v_mul_f32_e32 v85, v85, v85
	v_mul_f32_e32 v87, v87, v87
	v_fmac_f32_e32 v83, v82, v82
	v_fmac_f32_e32 v85, v84, v84
	v_mul_f32_e32 v89, v89, v89
	v_fmac_f32_e32 v87, v86, v86
	v_add_f32_e32 v82, v83, v85
	v_fmac_f32_e32 v89, v88, v88
	v_add_f32_e32 v82, v87, v82
	v_add_f32_e32 v82, v89, v82
	v_sub_u32_e32 v90, v80, v150
	v_add_u32_e32 v90, v90, v152
	v_ashrrev_i32_e32 v91, 31, v90
	v_lshlrev_b64 v[90:91], 12, v[90:91]
	v_lshl_add_u64 v[90:91], s[10:11], 0, v[90:91]
	v_lshl_add_u64 v[90:91], v[120:121], 1, v[90:91]
	v_mov_b32_dpp v96, v92 row_ror:8 row_mask:0xf bank_mask:0xf
	v_mov_b32_dpp v97, v93 row_ror:8 row_mask:0xf bank_mask:0xf
	v_mov_b32_dpp v98, v94 row_ror:8 row_mask:0xf bank_mask:0xf
	v_mov_b32_dpp v99, v95 row_ror:8 row_mask:0xf bank_mask:0xf
	v_pk_add_f32 v[70:71], v[70:71], v[74:75]
	v_pk_add_f32 v[72:73], v[68:69], v[72:73]
	v_pk_add_f32 v[74:75], v[66:67], v[78:79]
	v_pk_add_f32 v[64:65], v[64:65], v[76:77]
	v_cvt_pk_bf16_f32 v66, v72, v73
	v_mul_f32_e32 v73, v73, v73
	v_mul_f32_e32 v76, v71, v71
	v_cvt_pk_bf16_f32 v67, v70, v71
	v_cvt_pk_bf16_f32 v68, v64, v65
	v_mul_f32_e32 v65, v65, v65
	v_fmac_f32_e32 v73, v72, v72
	v_fmac_f32_e32 v76, v70, v70
	v_cvt_pk_bf16_f32 v69, v74, v75
	v_mul_f32_e32 v75, v75, v75
	v_fmac_f32_e32 v65, v64, v64
	v_add_f32_e32 v64, v73, v76
	v_fmac_f32_e32 v75, v74, v74
	v_add_f32_e32 v64, v65, v64
	v_add_f32_e32 v64, v75, v64
	v_add_f32_e32 v64, v82, v64
	v_mov_b32_e32 v65, v64
	s_nop 1
	v_permlane16_swap_b32_e32 v65, v64
	v_mov_b32_dpp v100, v66 row_ror:8 row_mask:0xf bank_mask:0xf
	v_mov_b32_dpp v101, v67 row_ror:8 row_mask:0xf bank_mask:0xf
	v_mov_b32_dpp v102, v68 row_ror:8 row_mask:0xf bank_mask:0xf
	v_mov_b32_dpp v103, v69 row_ror:8 row_mask:0xf bank_mask:0xf
	s_waitcnt lgkmcnt(0)
	v_add_f32_e32 v64, v64, v65
	v_mov_b32_e32 v65, v64
	s_nop 1
	v_permlane32_swap_b32_e32 v65, v64
	v_cndmask_b32_e64 v71, v101, v93, s[6:7]
	v_cndmask_b32_e64 v73, v103, v95, s[6:7]
	v_cndmask_b32_e64 v70, v100, v92, s[6:7]
	v_cndmask_b32_e64 v72, v102, v94, s[6:7]
	global_store_dwordx4 v[90:91], v[70:73], off
	v_cndmask_b32_e64 v67, v67, v97, s[6:7]
	v_cndmask_b32_e64 v69, v69, v99, s[6:7]
	v_add_co_u32_e32 v70, vcc, s69, v90
	v_cndmask_b32_e64 v66, v66, v96, s[6:7]
	v_cndmask_b32_e64 v68, v68, v98, s[6:7]
	v_addc_co_u32_e32 v71, vcc, 0, v91, vcc
	global_store_dwordx4 v[70:71], v[66:69], off
	s_and_saveexec_b64 s[50:51], s[8:9]
	s_cbranch_execz .LBB0_622
	s_waitcnt lgkmcnt(0)
	v_add_f32_e32 v66, v64, v65
	v_lshl_add_u64 v[64:65], v[80:81], 2, s[12:13]
	global_atomic_add_f32 v[64:65], v66, off
.LBB0_622:
	s_or_b64 exec, exec, s[50:51]
	v_add_u32_e32 v64, 0x80, v146
	s_waitcnt lgkmcnt(0)
	v_ashrrev_i32_e32 v65, 31, v64
	v_lshlrev_b64 v[66:67], 11, v[64:65]
	v_lshl_add_u64 v[66:67], v[66:67], 0, v[148:149]
	v_lshlrev_b64 v[66:67], 2, v[66:67]
	v_lshl_add_u64 v[68:69], s[16:17], 0, v[66:67]
	v_lshl_add_u64 v[66:67], s[18:19], 0, v[66:67]
	v_lshl_add_u64 v[66:67], v[66:67], 0, s[38:39]
	v_cmp_gt_i32_e32 vcc, s81, v146
	v_mov_b32_e32 v84, 0
	v_mov_b32_e32 v85, 0
	v_cndmask_b32_e32 v75, v67, v69, vcc
	v_cndmask_b32_e32 v74, v66, v68, vcc
	s_waitcnt vmcnt(14)
; __device__ __forceinline__ unsigned cvt_pk_bf16(float lo, float hi) { unsigned r; asm volatile("v_cvt_pk_bf16_f32 %0, %1, %2" : "=v"(r) : "v"(lo), "v"(hi)); return r; }
; __device__ __forceinline__ float bflo(unsigned w) { return __uint_as_float(w << 16); }
; __device__ __forceinline__ float bfhi(unsigned w) { return __uint_as_float(w & 0xffff0000u); }
;     __device__ __forceinline__ void operator()(const f32x4 (&acc)[2][2][4][2], const Unit& u, int wr, int wc, int fr, int fq) const {
;     ...
;             for (int m = 0; m < 4; ++m) { const int row = row0 + ai * HALF + m * 16; const size_t off = (size_t)row * D + col0; float sq = 0.f; u32x4 w[2];
;                 const float sc = rsin ? __builtin_amdgcn_rcpf(rsin[row] * (1.f / D) + EPS) : 1.0f;
;                 u32x4 rr[2]; if (R) load_pair_lines(R, D, row, fr, col0, rr[0], rr[1]);
; #pragma unroll
;                 for (int bj = 0; bj < 2; ++bj) { f32x4 r0, r1;
;                     if (R) { const u32x4 rw = rr[bj]; r0 = (f32x4){bflo(rw.x), bfhi(rw.x), bflo(rw.y), bfhi(rw.y)}; r1 = (f32x4){bflo(rw.z), bfhi(rw.z), bflo(rw.w), bfhi(rw.w)}; }
;                     else { const float* rp = (row < 8192 ? src_p + off : src_s + (off - (size_t)8192 * D)) + 8 * bj; r0 = *(const f32x4*)rp; r1 = *(const f32x4*)(rp + 4); }
;                     const f32x4 o0 = r0 + acc[ai][bj][m][0] * sc, o1 = r1 + acc[ai][bj][m][1] * sc;
;                     sq += (o0[0] * o0[0] + o0[1] * o0[1]) + (o0[2] * o0[2] + o0[3] * o0[3]) + (o1[0] * o1[0] + o1[1] * o1[1]) + (o1[2] * o1[2] + o1[3] * o1[3]);
;                     w[bj].x = cvt_pk_bf16(o0[0], o0[1]); w[bj].y = cvt_pk_bf16(o0[2], o0[3]); w[bj].z = cvt_pk_bf16(o1[0], o1[1]); w[bj].w = cvt_pk_bf16(o1[2], o1[3]); }
;                 store_pair_lines(O, D, row, fr, col0, w[0], w[1]);
;                 if (ssout) { sq += __shfl_xor(sq, 16); sq += __shfl_xor(sq, 32); if (fq == 0) unsafeAtomicAdd(ssout + row, sq); } }
	s_nop 0
	v_mov_b64_e32 v[66:67], v[196:197]
	v_mov_b64_e32 v[68:69], v[198:199]
	v_mov_b64_e32 v[70:71], v[204:205]
	v_mov_b64_e32 v[72:73], v[206:207]
	v_pk_add_f32 v[68:69], v[62:63], v[68:69]
	v_pk_add_f32 v[66:67], v[60:61], v[66:67]
	v_pk_add_f32 v[72:73], v[58:59], v[72:73]
	v_pk_add_f32 v[70:71], v[56:57], v[70:71]
	v_cvt_pk_bf16_f32 v76, v66, v67
	v_cvt_pk_bf16_f32 v77, v68, v69
	v_mul_f32_e32 v67, v67, v67
	v_cvt_pk_bf16_f32 v78, v70, v71
	v_cvt_pk_bf16_f32 v79, v72, v73
	v_mov_b64_e32 v[56:57], v[208:209]
	v_mov_b64_e32 v[58:59], v[210:211]
	v_mov_b64_e32 v[60:61], v[212:213]
	v_mov_b64_e32 v[62:63], v[214:215]
	s_nop 1
	v_add_u32_e32 v188, 0xb0, v146
	v_ashrrev_i32_e32 v189, 31, v188
	v_lshlrev_b64 v[190:191], 11, v[188:189]
	v_lshl_add_u64 v[190:191], v[190:191], 0, v[148:149]
	v_lshlrev_b64 v[190:191], 2, v[190:191]
	v_lshl_add_u64 v[192:193], s[16:17], 0, v[190:191]
	v_lshl_add_u64 v[190:191], s[18:19], 0, v[190:191]
	v_lshl_add_u64 v[190:191], v[190:191], 0, s[38:39]
	v_cmp_gt_i32_e32 vcc, s84, v146
	s_nop 1
	v_cndmask_b32_e32 v195, v191, v193, vcc
	v_cndmask_b32_e32 v194, v190, v192, vcc
	global_load_dwordx4 v[196:199], v[194:195], off
	global_load_dwordx4 v[204:207], v[194:195], off offset:16
	global_load_dwordx4 v[208:211], v[194:195], off offset:32
	global_load_dwordx4 v[212:215], v[194:195], off offset:48
	v_mul_f32_e32 v69, v69, v69
	v_mul_f32_e32 v71, v71, v71
	v_fmac_f32_e32 v67, v66, v66
	v_fmac_f32_e32 v69, v68, v68
	v_mul_f32_e32 v73, v73, v73
	v_fmac_f32_e32 v71, v70, v70
	v_add_f32_e32 v66, v67, v69
	v_fmac_f32_e32 v73, v72, v72
	v_add_f32_e32 v66, v71, v66
	v_add_f32_e32 v66, v73, v66
	v_sub_u32_e32 v74, v64, v150
	v_add_u32_e32 v74, v74, v152
	v_ashrrev_i32_e32 v75, 31, v74
	v_lshlrev_b64 v[74:75], 12, v[74:75]
	v_lshl_add_u64 v[74:75], s[10:11], 0, v[74:75]
	v_lshl_add_u64 v[74:75], v[120:121], 1, v[74:75]
	v_mov_b32_dpp v80, v76 row_ror:8 row_mask:0xf bank_mask:0xf
	v_mov_b32_dpp v81, v77 row_ror:8 row_mask:0xf bank_mask:0xf
	v_mov_b32_dpp v82, v78 row_ror:8 row_mask:0xf bank_mask:0xf
	v_mov_b32_dpp v83, v79 row_ror:8 row_mask:0xf bank_mask:0xf
	v_pk_add_f32 v[54:55], v[54:55], v[58:59]
	v_pk_add_f32 v[56:57], v[52:53], v[56:57]
	v_pk_add_f32 v[58:59], v[50:51], v[62:63]
	v_pk_add_f32 v[48:49], v[48:49], v[60:61]
	v_cvt_pk_bf16_f32 v50, v56, v57
	v_mul_f32_e32 v57, v57, v57
	v_mul_f32_e32 v60, v55, v55
	v_cvt_pk_bf16_f32 v51, v54, v55
	v_cvt_pk_bf16_f32 v52, v48, v49
	v_mul_f32_e32 v49, v49, v49
	v_fmac_f32_e32 v57, v56, v56
	v_fmac_f32_e32 v60, v54, v54
	v_cvt_pk_bf16_f32 v53, v58, v59
	v_mul_f32_e32 v59, v59, v59
	v_fmac_f32_e32 v49, v48, v48
	v_add_f32_e32 v48, v57, v60
	v_fmac_f32_e32 v59, v58, v58
	v_add_f32_e32 v48, v49, v48
	v_add_f32_e32 v48, v59, v48
	v_add_f32_e32 v48, v66, v48
	v_mov_b32_e32 v49, v48
	s_nop 1
	v_permlane16_swap_b32_e32 v49, v48
	v_mov_b32_dpp v84, v50 row_ror:8 row_mask:0xf bank_mask:0xf
	v_mov_b32_dpp v85, v51 row_ror:8 row_mask:0xf bank_mask:0xf
	v_mov_b32_dpp v86, v52 row_ror:8 row_mask:0xf bank_mask:0xf
	v_mov_b32_dpp v87, v53 row_ror:8 row_mask:0xf bank_mask:0xf
	s_waitcnt lgkmcnt(0)
	v_add_f32_e32 v48, v48, v49
	v_mov_b32_e32 v49, v48
	s_nop 1
	v_permlane32_swap_b32_e32 v49, v48
	v_cndmask_b32_e64 v55, v85, v77, s[6:7]
	v_cndmask_b32_e64 v57, v87, v79, s[6:7]
	v_cndmask_b32_e64 v54, v84, v76, s[6:7]
	v_cndmask_b32_e64 v56, v86, v78, s[6:7]
	global_store_dwordx4 v[74:75], v[54:57], off
	v_cndmask_b32_e64 v51, v51, v81, s[6:7]
	v_cndmask_b32_e64 v53, v53, v83, s[6:7]
	v_add_co_u32_e32 v54, vcc, s69, v74
	v_cndmask_b32_e64 v50, v50, v80, s[6:7]
	v_cndmask_b32_e64 v52, v52, v82, s[6:7]
	v_addc_co_u32_e32 v55, vcc, 0, v75, vcc
	global_store_dwordx4 v[54:55], v[50:53], off
	s_and_saveexec_b64 s[50:51], s[8:9]
	s_cbranch_execz .LBB0_624
	s_waitcnt lgkmcnt(0)
	v_add_f32_e32 v50, v48, v49
	v_lshl_add_u64 v[48:49], v[64:65], 2, s[12:13]
	global_atomic_add_f32 v[48:49], v50, off
.LBB0_624:
	s_or_b64 exec, exec, s[50:51]
	v_add_u32_e32 v48, 0x90, v146
	s_waitcnt lgkmcnt(0)
	v_ashrrev_i32_e32 v49, 31, v48
	v_lshlrev_b64 v[50:51], 11, v[48:49]
	v_lshl_add_u64 v[50:51], v[50:51], 0, v[148:149]
	v_lshlrev_b64 v[50:51], 2, v[50:51]
	v_lshl_add_u64 v[52:53], s[16:17], 0, v[50:51]
	v_lshl_add_u64 v[50:51], s[18:19], 0, v[50:51]
	v_lshl_add_u64 v[50:51], v[50:51], 0, s[38:39]
	v_cmp_gt_i32_e32 vcc, s82, v146
	v_mov_b32_e32 v68, 0
	v_mov_b32_e32 v69, 0
	v_cndmask_b32_e32 v59, v51, v53, vcc
	v_cndmask_b32_e32 v58, v50, v52, vcc
	s_waitcnt vmcnt(14)
; __device__ __forceinline__ unsigned cvt_pk_bf16(float lo, float hi) { unsigned r; asm volatile("v_cvt_pk_bf16_f32 %0, %1, %2" : "=v"(r) : "v"(lo), "v"(hi)); return r; }
; __device__ __forceinline__ float bflo(unsigned w) { return __uint_as_float(w << 16); }
; __device__ __forceinline__ float bfhi(unsigned w) { return __uint_as_float(w & 0xffff0000u); }
;     __device__ __forceinline__ void operator()(const f32x4 (&acc)[2][2][4][2], const Unit& u, int wr, int wc, int fr, int fq) const {
;     ...
;             for (int m = 0; m < 4; ++m) { const int row = row0 + ai * HALF + m * 16; const size_t off = (size_t)row * D + col0; float sq = 0.f; u32x4 w[2];
;                 const float sc = rsin ? __builtin_amdgcn_rcpf(rsin[row] * (1.f / D) + EPS) : 1.0f;
;                 u32x4 rr[2]; if (R) load_pair_lines(R, D, row, fr, col0, rr[0], rr[1]);
; #pragma unroll
;                 for (int bj = 0; bj < 2; ++bj) { f32x4 r0, r1;
;                     if (R) { const u32x4 rw = rr[bj]; r0 = (f32x4){bflo(rw.x), bfhi(rw.x), bflo(rw.y), bfhi(rw.y)}; r1 = (f32x4){bflo(rw.z), bfhi(rw.z), bflo(rw.w), bfhi(rw.w)}; }
;                     else { const float* rp = (row < 8192 ? src_p + off : src_s + (off - (size_t)8192 * D)) + 8 * bj; r0 = *(const f32x4*)rp; r1 = *(const f32x4*)(rp + 4); }
;                     const f32x4 o0 = r0 + acc[ai][bj][m][0] * sc, o1 = r1 + acc[ai][bj][m][1] * sc;
;                     sq += (o0[0] * o0[0] + o0[1] * o0[1]) + (o0[2] * o0[2] + o0[3] * o0[3]) + (o1[0] * o1[0] + o1[1] * o1[1]) + (o1[2] * o1[2] + o1[3] * o1[3]);
;                     w[bj].x = cvt_pk_bf16(o0[0], o0[1]); w[bj].y = cvt_pk_bf16(o0[2], o0[3]); w[bj].z = cvt_pk_bf16(o1[0], o1[1]); w[bj].w = cvt_pk_bf16(o1[2], o1[3]); }
;                 store_pair_lines(O, D, row, fr, col0, w[0], w[1]);
;                 if (ssout) { sq += __shfl_xor(sq, 16); sq += __shfl_xor(sq, 32); if (fq == 0) unsafeAtomicAdd(ssout + row, sq); } }
	s_nop 0
	v_mov_b64_e32 v[50:51], v[216:217]
	v_mov_b64_e32 v[52:53], v[218:219]
	v_mov_b64_e32 v[54:55], v[220:221]
	v_mov_b64_e32 v[56:57], v[222:223]
	v_pk_add_f32 v[52:53], v[46:47], v[52:53]
	v_pk_add_f32 v[50:51], v[44:45], v[50:51]
	v_pk_add_f32 v[56:57], v[42:43], v[56:57]
	v_pk_add_f32 v[54:55], v[40:41], v[54:55]
	v_cvt_pk_bf16_f32 v60, v50, v51
	v_cvt_pk_bf16_f32 v61, v52, v53
	v_mul_f32_e32 v51, v51, v51
	v_cvt_pk_bf16_f32 v62, v54, v55
	v_cvt_pk_bf16_f32 v63, v56, v57
	v_mov_b64_e32 v[40:41], v[224:225]
	v_mov_b64_e32 v[42:43], v[226:227]
	v_mov_b64_e32 v[44:45], v[228:229]
	v_mov_b64_e32 v[46:47], v[230:231]
	s_nop 1
	v_mul_f32_e32 v53, v53, v53
	v_mul_f32_e32 v55, v55, v55
	v_fmac_f32_e32 v51, v50, v50
	v_fmac_f32_e32 v53, v52, v52
	v_mul_f32_e32 v57, v57, v57
	v_fmac_f32_e32 v55, v54, v54
	v_add_f32_e32 v50, v51, v53
	v_fmac_f32_e32 v57, v56, v56
	v_add_f32_e32 v50, v55, v50
	v_add_f32_e32 v50, v57, v50
	v_sub_u32_e32 v58, v48, v150
	v_add_u32_e32 v58, v58, v152
	v_ashrrev_i32_e32 v59, 31, v58
	v_lshlrev_b64 v[58:59], 12, v[58:59]
	v_lshl_add_u64 v[58:59], s[10:11], 0, v[58:59]
	v_lshl_add_u64 v[58:59], v[120:121], 1, v[58:59]
	v_mov_b32_dpp v64, v60 row_ror:8 row_mask:0xf bank_mask:0xf
	v_mov_b32_dpp v65, v61 row_ror:8 row_mask:0xf bank_mask:0xf
	v_mov_b32_dpp v66, v62 row_ror:8 row_mask:0xf bank_mask:0xf
	v_mov_b32_dpp v67, v63 row_ror:8 row_mask:0xf bank_mask:0xf
	v_pk_add_f32 v[38:39], v[38:39], v[42:43]
	v_pk_add_f32 v[40:41], v[36:37], v[40:41]
	v_pk_add_f32 v[42:43], v[34:35], v[46:47]
	v_pk_add_f32 v[32:33], v[32:33], v[44:45]
	v_cvt_pk_bf16_f32 v34, v40, v41
	v_mul_f32_e32 v41, v41, v41
	v_mul_f32_e32 v44, v39, v39
	v_cvt_pk_bf16_f32 v35, v38, v39
	v_cvt_pk_bf16_f32 v36, v32, v33
	v_mul_f32_e32 v33, v33, v33
	v_fmac_f32_e32 v41, v40, v40
	v_fmac_f32_e32 v44, v38, v38
	v_cvt_pk_bf16_f32 v37, v42, v43
	v_mul_f32_e32 v43, v43, v43
	v_fmac_f32_e32 v33, v32, v32
	v_add_f32_e32 v32, v41, v44
	v_fmac_f32_e32 v43, v42, v42
	v_add_f32_e32 v32, v33, v32
	v_add_f32_e32 v32, v43, v32
	v_add_f32_e32 v32, v50, v32
	v_mov_b32_e32 v33, v32
	s_nop 1
	v_permlane16_swap_b32_e32 v33, v32
	v_mov_b32_dpp v68, v34 row_ror:8 row_mask:0xf bank_mask:0xf
	v_mov_b32_dpp v69, v35 row_ror:8 row_mask:0xf bank_mask:0xf
	v_mov_b32_dpp v70, v36 row_ror:8 row_mask:0xf bank_mask:0xf
	v_mov_b32_dpp v71, v37 row_ror:8 row_mask:0xf bank_mask:0xf
	s_waitcnt lgkmcnt(0)
	v_add_f32_e32 v32, v32, v33
	v_mov_b32_e32 v33, v32
	s_nop 1
	v_permlane32_swap_b32_e32 v33, v32
	v_cndmask_b32_e64 v39, v69, v61, s[6:7]
	v_cndmask_b32_e64 v41, v71, v63, s[6:7]
	v_cndmask_b32_e64 v38, v68, v60, s[6:7]
	v_cndmask_b32_e64 v40, v70, v62, s[6:7]
	global_store_dwordx4 v[58:59], v[38:41], off
	v_cndmask_b32_e64 v35, v35, v65, s[6:7]
	v_cndmask_b32_e64 v37, v37, v67, s[6:7]
	v_add_co_u32_e32 v38, vcc, s69, v58
	v_cndmask_b32_e64 v34, v34, v64, s[6:7]
	v_cndmask_b32_e64 v36, v36, v66, s[6:7]
	v_addc_co_u32_e32 v39, vcc, 0, v59, vcc
	global_store_dwordx4 v[38:39], v[34:37], off
	s_and_saveexec_b64 s[50:51], s[8:9]
	s_cbranch_execz .LBB0_626
	s_waitcnt lgkmcnt(0)
	v_add_f32_e32 v34, v32, v33
	v_lshl_add_u64 v[32:33], v[48:49], 2, s[12:13]
	global_atomic_add_f32 v[32:33], v34, off
.LBB0_626:
	s_or_b64 exec, exec, s[50:51]
	v_add_u32_e32 v32, 0xa0, v146
	s_waitcnt lgkmcnt(0)
	v_ashrrev_i32_e32 v33, 31, v32
	v_lshlrev_b64 v[34:35], 11, v[32:33]
	v_lshl_add_u64 v[34:35], v[34:35], 0, v[148:149]
	v_lshlrev_b64 v[34:35], 2, v[34:35]
	v_lshl_add_u64 v[36:37], s[16:17], 0, v[34:35]
	v_lshl_add_u64 v[34:35], s[18:19], 0, v[34:35]
	v_lshl_add_u64 v[34:35], v[34:35], 0, s[38:39]
	v_cmp_gt_i32_e32 vcc, s83, v146
	v_mov_b32_e32 v52, 0
	v_mov_b32_e32 v53, 0
	v_cndmask_b32_e32 v43, v35, v37, vcc
	v_cndmask_b32_e32 v42, v34, v36, vcc
	s_waitcnt vmcnt(10)
	s_nop 0
	v_mov_b64_e32 v[34:35], v[232:233]
	v_mov_b64_e32 v[36:37], v[234:235]
	v_mov_b64_e32 v[38:39], v[236:237]
	v_mov_b64_e32 v[40:41], v[238:239]
	v_pk_add_f32 v[36:37], v[30:31], v[36:37]
	v_pk_add_f32 v[34:35], v[28:29], v[34:35]
	v_pk_add_f32 v[40:41], v[26:27], v[40:41]
	v_pk_add_f32 v[38:39], v[24:25], v[38:39]
	v_cvt_pk_bf16_f32 v44, v34, v35
	v_cvt_pk_bf16_f32 v45, v36, v37
	v_mul_f32_e32 v35, v35, v35
	v_cvt_pk_bf16_f32 v46, v38, v39
	v_cvt_pk_bf16_f32 v47, v40, v41
	v_mov_b64_e32 v[24:25], v[240:241]
	v_mov_b64_e32 v[26:27], v[242:243]
	v_mov_b64_e32 v[28:29], v[244:245]
	v_mov_b64_e32 v[30:31], v[246:247]
	s_nop 1
	v_mul_f32_e32 v37, v37, v37
	v_mul_f32_e32 v39, v39, v39
	v_fmac_f32_e32 v35, v34, v34
	v_fmac_f32_e32 v37, v36, v36
	v_mul_f32_e32 v41, v41, v41
	v_fmac_f32_e32 v39, v38, v38
	v_add_f32_e32 v34, v35, v37
	v_fmac_f32_e32 v41, v40, v40
	v_add_f32_e32 v34, v39, v34
	v_add_f32_e32 v34, v41, v34
	v_sub_u32_e32 v42, v32, v150
	v_add_u32_e32 v42, v42, v152
	v_ashrrev_i32_e32 v43, 31, v42
	v_lshlrev_b64 v[42:43], 12, v[42:43]
	v_lshl_add_u64 v[42:43], s[10:11], 0, v[42:43]
	v_lshl_add_u64 v[42:43], v[120:121], 1, v[42:43]
	v_mov_b32_dpp v48, v44 row_ror:8 row_mask:0xf bank_mask:0xf
	v_mov_b32_dpp v49, v45 row_ror:8 row_mask:0xf bank_mask:0xf
	v_mov_b32_dpp v50, v46 row_ror:8 row_mask:0xf bank_mask:0xf
	v_mov_b32_dpp v51, v47 row_ror:8 row_mask:0xf bank_mask:0xf
	v_pk_add_f32 v[22:23], v[22:23], v[26:27]
	v_pk_add_f32 v[24:25], v[20:21], v[24:25]
	v_pk_add_f32 v[26:27], v[18:19], v[30:31]
	v_pk_add_f32 v[16:17], v[16:17], v[28:29]
	v_cvt_pk_bf16_f32 v18, v24, v25
	v_mul_f32_e32 v25, v25, v25
	v_mul_f32_e32 v28, v23, v23
	v_cvt_pk_bf16_f32 v19, v22, v23
	v_cvt_pk_bf16_f32 v20, v16, v17
	v_mul_f32_e32 v17, v17, v17
	v_fmac_f32_e32 v25, v24, v24
	v_fmac_f32_e32 v28, v22, v22
	v_cvt_pk_bf16_f32 v21, v26, v27
	v_mul_f32_e32 v27, v27, v27
	v_fmac_f32_e32 v17, v16, v16
	v_add_f32_e32 v16, v25, v28
	v_fmac_f32_e32 v27, v26, v26
	v_add_f32_e32 v16, v17, v16
	v_add_f32_e32 v16, v27, v16
	v_add_f32_e32 v16, v34, v16
	v_mov_b32_e32 v17, v16
	s_nop 1
	v_permlane16_swap_b32_e32 v17, v16
	v_mov_b32_dpp v52, v18 row_ror:8 row_mask:0xf bank_mask:0xf
	v_mov_b32_dpp v53, v19 row_ror:8 row_mask:0xf bank_mask:0xf
	v_mov_b32_dpp v54, v20 row_ror:8 row_mask:0xf bank_mask:0xf
	v_mov_b32_dpp v55, v21 row_ror:8 row_mask:0xf bank_mask:0xf
	s_waitcnt lgkmcnt(0)
	v_add_f32_e32 v16, v16, v17
	v_mov_b32_e32 v17, v16
	s_nop 1
	v_permlane32_swap_b32_e32 v17, v16
	v_cndmask_b32_e64 v23, v53, v45, s[6:7]
	v_cndmask_b32_e64 v25, v55, v47, s[6:7]
	v_cndmask_b32_e64 v22, v52, v44, s[6:7]
	v_cndmask_b32_e64 v24, v54, v46, s[6:7]
	global_store_dwordx4 v[42:43], v[22:25], off
	v_cndmask_b32_e64 v19, v19, v49, s[6:7]
	v_cndmask_b32_e64 v21, v21, v51, s[6:7]
	v_add_co_u32_e32 v22, vcc, s69, v42
	v_cndmask_b32_e64 v18, v18, v48, s[6:7]
	v_cndmask_b32_e64 v20, v20, v50, s[6:7]
	v_addc_co_u32_e32 v23, vcc, 0, v43, vcc
	global_store_dwordx4 v[22:23], v[18:21], off
	s_and_saveexec_b64 s[50:51], s[8:9]
	s_cbranch_execz .LBB0_628
	s_waitcnt lgkmcnt(0)
	v_add_f32_e32 v18, v16, v17
	v_lshl_add_u64 v[16:17], v[32:33], 2, s[12:13]
	global_atomic_add_f32 v[16:17], v18, off
; __device__ __forceinline__ unsigned cvt_pk_bf16(float lo, float hi) { unsigned r; asm volatile("v_cvt_pk_bf16_f32 %0, %1, %2" : "=v"(r) : "v"(lo), "v"(hi)); return r; }
; __device__ __forceinline__ float bflo(unsigned w) { return __uint_as_float(w << 16); }
; __device__ __forceinline__ float bfhi(unsigned w) { return __uint_as_float(w & 0xffff0000u); }
;     __device__ __forceinline__ void operator()(const f32x4 (&acc)[2][2][4][2], const Unit& u, int wr, int wc, int fr, int fq) const {
;     ...
;             for (int m = 0; m < 4; ++m) { const int row = row0 + ai * HALF + m * 16; const size_t off = (size_t)row * D + col0; float sq = 0.f; u32x4 w[2];
;                 const float sc = rsin ? __builtin_amdgcn_rcpf(rsin[row] * (1.f / D) + EPS) : 1.0f;
;                 u32x4 rr[2]; if (R) load_pair_lines(R, D, row, fr, col0, rr[0], rr[1]);
; #pragma unroll
;                 for (int bj = 0; bj < 2; ++bj) { f32x4 r0, r1;
;                     if (R) { const u32x4 rw = rr[bj]; r0 = (f32x4){bflo(rw.x), bfhi(rw.x), bflo(rw.y), bfhi(rw.y)}; r1 = (f32x4){bflo(rw.z), bfhi(rw.z), bflo(rw.w), bfhi(rw.w)}; }
;                     else { const float* rp = (row < 8192 ? src_p + off : src_s + (off - (size_t)8192 * D)) + 8 * bj; r0 = *(const f32x4*)rp; r1 = *(const f32x4*)(rp + 4); }
;                     const f32x4 o0 = r0 + acc[ai][bj][m][0] * sc, o1 = r1 + acc[ai][bj][m][1] * sc;
;                     sq += (o0[0] * o0[0] + o0[1] * o0[1]) + (o0[2] * o0[2] + o0[3] * o0[3]) + (o1[0] * o1[0] + o1[1] * o1[1]) + (o1[2] * o1[2] + o1[3] * o1[3]);
;                     w[bj].x = cvt_pk_bf16(o0[0], o0[1]); w[bj].y = cvt_pk_bf16(o0[2], o0[3]); w[bj].z = cvt_pk_bf16(o1[0], o1[1]); w[bj].w = cvt_pk_bf16(o1[2], o1[3]); }
;                 store_pair_lines(O, D, row, fr, col0, w[0], w[1]);
;                 if (ssout) { sq += __shfl_xor(sq, 16); sq += __shfl_xor(sq, 32); if (fq == 0) unsafeAtomicAdd(ssout + row, sq); } }
.LBB0_628:
	s_or_b64 exec, exec, s[50:51]
	v_add_u32_e32 v16, 0xb0, v146
	s_waitcnt lgkmcnt(0)
	v_ashrrev_i32_e32 v17, 31, v16
	v_lshlrev_b64 v[18:19], 11, v[16:17]
	v_lshl_add_u64 v[18:19], v[18:19], 0, v[148:149]
	v_lshlrev_b64 v[18:19], 2, v[18:19]
	v_lshl_add_u64 v[20:21], s[16:17], 0, v[18:19]
	v_lshl_add_u64 v[18:19], s[18:19], 0, v[18:19]
	v_lshl_add_u64 v[18:19], v[18:19], 0, s[38:39]
	v_cmp_gt_i32_e32 vcc, s84, v146
	v_mov_b32_e32 v36, 0
	v_mov_b32_e32 v37, 0
	v_cndmask_b32_e32 v27, v19, v21, vcc
	v_cndmask_b32_e32 v26, v18, v20, vcc
	s_waitcnt vmcnt(6)
	s_nop 0
	v_mov_b64_e32 v[18:19], v[196:197]
	v_mov_b64_e32 v[20:21], v[198:199]
	v_mov_b64_e32 v[22:23], v[204:205]
	v_mov_b64_e32 v[24:25], v[206:207]
	v_pk_add_f32 v[20:21], v[14:15], v[20:21]
	v_pk_add_f32 v[18:19], v[12:13], v[18:19]
	v_pk_add_f32 v[24:25], v[10:11], v[24:25]
	v_pk_add_f32 v[22:23], v[8:9], v[22:23]
	v_cvt_pk_bf16_f32 v28, v18, v19
	v_cvt_pk_bf16_f32 v29, v20, v21
	v_mul_f32_e32 v19, v19, v19
	v_cvt_pk_bf16_f32 v30, v22, v23
	v_cvt_pk_bf16_f32 v31, v24, v25
	v_mov_b64_e32 v[8:9], v[208:209]
	v_mov_b64_e32 v[10:11], v[210:211]
	v_mov_b64_e32 v[12:13], v[212:213]
	v_mov_b64_e32 v[14:15], v[214:215]
	s_nop 1
	v_mul_f32_e32 v21, v21, v21
	v_mul_f32_e32 v23, v23, v23
	v_fmac_f32_e32 v19, v18, v18
	v_fmac_f32_e32 v21, v20, v20
	v_mul_f32_e32 v25, v25, v25
	v_fmac_f32_e32 v23, v22, v22
	v_add_f32_e32 v18, v19, v21
	v_fmac_f32_e32 v25, v24, v24
	v_add_f32_e32 v18, v23, v18
	v_add_f32_e32 v18, v25, v18
	v_sub_u32_e32 v26, v16, v150
	v_add_u32_e32 v26, v26, v152
	v_ashrrev_i32_e32 v27, 31, v26
	v_lshlrev_b64 v[26:27], 12, v[26:27]
	v_lshl_add_u64 v[26:27], s[10:11], 0, v[26:27]
	v_lshl_add_u64 v[26:27], v[120:121], 1, v[26:27]
	v_mov_b32_dpp v32, v28 row_ror:8 row_mask:0xf bank_mask:0xf
	v_mov_b32_dpp v33, v29 row_ror:8 row_mask:0xf bank_mask:0xf
	v_mov_b32_dpp v34, v30 row_ror:8 row_mask:0xf bank_mask:0xf
	v_mov_b32_dpp v35, v31 row_ror:8 row_mask:0xf bank_mask:0xf
	v_pk_add_f32 v[6:7], v[6:7], v[10:11]
	v_pk_add_f32 v[8:9], v[4:5], v[8:9]
	v_pk_add_f32 v[10:11], v[2:3], v[14:15]
	v_pk_add_f32 v[0:1], v[0:1], v[12:13]
	v_cvt_pk_bf16_f32 v2, v8, v9
	v_mul_f32_e32 v9, v9, v9
	v_mul_f32_e32 v12, v7, v7
	v_cvt_pk_bf16_f32 v3, v6, v7
	v_cvt_pk_bf16_f32 v4, v0, v1
	v_mul_f32_e32 v1, v1, v1
	v_fmac_f32_e32 v9, v8, v8
	v_fmac_f32_e32 v12, v6, v6
	v_cvt_pk_bf16_f32 v5, v10, v11
	v_mul_f32_e32 v11, v11, v11
	v_fmac_f32_e32 v1, v0, v0
	v_add_f32_e32 v0, v9, v12
	v_fmac_f32_e32 v11, v10, v10
	v_add_f32_e32 v0, v1, v0
	v_add_f32_e32 v0, v11, v0
	v_add_f32_e32 v0, v18, v0
	v_mov_b32_e32 v1, v0
	s_nop 1
	v_permlane16_swap_b32_e32 v1, v0
	v_mov_b32_dpp v36, v2 row_ror:8 row_mask:0xf bank_mask:0xf
	v_mov_b32_dpp v37, v3 row_ror:8 row_mask:0xf bank_mask:0xf
	v_mov_b32_dpp v38, v4 row_ror:8 row_mask:0xf bank_mask:0xf
	v_mov_b32_dpp v39, v5 row_ror:8 row_mask:0xf bank_mask:0xf
	s_waitcnt lgkmcnt(0)
	v_add_f32_e32 v0, v0, v1
	v_mov_b32_e32 v1, v0
	s_nop 1
	v_permlane32_swap_b32_e32 v1, v0
	v_cndmask_b32_e64 v7, v37, v29, s[6:7]
	v_cndmask_b32_e64 v9, v39, v31, s[6:7]
	v_cndmask_b32_e64 v6, v36, v28, s[6:7]
	v_cndmask_b32_e64 v8, v38, v30, s[6:7]
	global_store_dwordx4 v[26:27], v[6:9], off
	v_cndmask_b32_e64 v3, v3, v33, s[6:7]
	v_cndmask_b32_e64 v5, v5, v35, s[6:7]
	v_add_co_u32_e32 v6, vcc, s69, v26
	v_cndmask_b32_e64 v2, v2, v32, s[6:7]
	v_cndmask_b32_e64 v4, v4, v34, s[6:7]
	v_addc_co_u32_e32 v7, vcc, 0, v27, vcc
	global_store_dwordx4 v[6:7], v[2:5], off
	s_and_saveexec_b64 s[50:51], s[8:9]
	s_cbranch_execz .LBB0_604
	s_waitcnt lgkmcnt(0)
	v_add_f32_e32 v2, v0, v1
	v_lshl_add_u64 v[0:1], v[16:17], 2, s[12:13]
	global_atomic_add_f32 v[0:1], v2, off
	s_branch .LBB0_604

; #define PG8_STAGE(bufoff, gbase, voff) do { _Pragma("unroll") for (int _i = 0; _i < 2; ++_i) \
;         __builtin_amdgcn_global_load_lds((const unsigned*)((const char*)(gbase) + (voff)[_i]), (LAS unsigned*)(lds + (bufoff) + ldsw + _i * 8192), 16, 0, 0); } while (0)
; #define PG8_LDA(dst, b, h) do { _Pragma("unroll") for (int m = 0; m < 4; ++m) _Pragma("unroll") for (int k = 0; k < 2; ++k) dst[m][k] = *(const LAS bf16x8*)(lds + PG8_SA(b, h) + aoff + m * 2048 + k * 1024); } while (0)
; #define PG8_LDB(dst, b, h) do { _Pragma("unroll") for (int n = 0; n < 2; ++n) _Pragma("unroll") for (int k = 0; k < 2; ++k) dst[n][k] = *(const LAS bf16x8*)(lds + PG8_SB(b, h) + boff + n * 2048 + k * 1024); } while (0)
; #define PG8_MMA(ai, bj, At, Bt) do { __builtin_amdgcn_s_setprio(1); _Pragma("unroll") for (int m = 0; m < 4; ++m) _Pragma("unroll") for (int n = 0; n < 2; ++n) _Pragma("unroll") for (int k = 0; k < 2; ++k) \
;         acc[ai][bj][m][n] = __builtin_amdgcn_mfma_f32_16x16x32_bf16(Bt[n][k], At[m][k], acc[ai][bj][m][n], 0, 0, 0); __builtin_amdgcn_s_setprio(0); } while (0)
; #define PG8_WAIT_L(n) asm volatile("s_waitcnt lgkmcnt(" #n ")" ::: "memory")
; template <class Epi>
; __device__ __forceinline__ void gemm_phase(LAS unsigned char* lds, const Gemm g, const StaticOrder& S, const Epi& E) {
;     ...
;         const bool has_next = S.next(ui + 1, nxt);
;         const char* nA = has_next ? (const char*)g.A + (size_t)nxt.pm * tstep : cA; const char* nB = has_next ? (const char*)g.Bt + (size_t)nxt.pn * tstep : cB;
;         for (int t = 0; t < nt; t += 2) {
;             const bool last = (t == nt - 2);
;             const char* a1 = cA + (size_t)(t + 1) * kstep;
;             const char* a2 = last ? nA : cA + (size_t)(t + 2) * kstep; const char* b2 = last ? nB : cB + (size_t)(t + 2) * kstep;
;             const char* a3 = a2 + kstep; const char* b3 = b2 + kstep;
;             PG8_LDB(B0, 0, 0); PG8_SCHED; PG8_LDA(At, 0, 0); PG8_STAGE(PG8_SA(1, 1), a1 + hstep, voffA);
;             PG8_WAIT_L(8); PG8_BAR; PG8_WAIT_L(0); PG8_MMA(0, 0, At, B0); PG8_BAR; PG8_SCHED;
;             PG8_LDB(B1, 0, 1); PG8_STAGE(PG8_SB(0, 0), b2, voffB0);
;             PG8_BAR; PG8_WAIT_L(0); PG8_MMA(0, 1, At, B1); PG8_BAR;
;             PG8_LDA(At, 0, 1); PG8_STAGE(PG8_SA(0, 0), a2, voffA);
;             PG8_BAR; PG8_WAIT_L(0); PG8_MMA(1, 0, At, B0); PG8_BAR; PG8_SCHED;
.LBB0_645:
	s_add_u32 s33, s50, s58
	s_addc_u32 s59, s51, 0
	s_add_u32 s56, s33, 0x100
	s_addc_u32 s57, s59, 0
	v_cndmask_b32_e64 v153, 0, 1, s[54:55]
	s_and_b64 s[54:55], s[52:53], exec
	s_cselect_b32 s57, s37, s57
	s_cselect_b32 s56, s45, s56
	s_add_u32 s54, s48, s58
	s_addc_u32 s55, s49, 0
	s_add_u32 s54, s54, 0x100
	s_addc_u32 s55, s55, 0
	s_and_b64 s[52:53], s[52:53], exec
	ds_read_b128 v[142:145], v150
	ds_read_b128 v[154:157], v150 offset:1024
	ds_read_b128 v[158:161], v150 offset:2048
	ds_read_b128 v[162:165], v150 offset:3072
	s_cselect_b32 s54, s80, s54
	s_cselect_b32 s55, s19, s55
	s_add_u32 s58, s33, 0x10080
	s_addc_u32 s59, s59, 0
	s_add_i32 s89, s78, s65
	s_add_i32 s85, s79, s65
	s_add_i32 m0, s47, 0xc000
	s_add_i32 s33, s47, 0xe000
	s_add_i32 s88, s89, 0x2000
	s_add_i32 s84, s85, 0x2000
	s_add_i32 s83, 0, 0x18000
	s_add_u32 s52, s56, 0x10000
	s_addc_u32 s53, s57, 0
	s_add_i32 s81, 0, 0x1c000
	s_add_i32 s82, s83, s65
	s_add_i32 s87, s81, s65
	s_add_i32 s90, s82, 0x2000
	s_add_i32 s86, s87, 0x2000
	v_cmp_ne_u32_e32 vcc, 1, v153
	v_lshl_add_u64 v[198:199], s[58:59], 0, v[128:129]
	ds_read_b128 v[166:169], v151
	ds_read_b128 v[170:173], v151 offset:1024
	ds_read_b128 v[174:177], v151 offset:2048
	ds_read_b128 v[178:181], v151 offset:3072
	ds_read_b128 v[182:185], v151 offset:4096
	ds_read_b128 v[186:189], v151 offset:5120
	ds_read_b128 v[190:193], v151 offset:6144
	ds_read_b128 v[194:197], v151 offset:7168
	global_load_lds_dwordx4 v[198:199], off
	v_lshl_add_u64 v[198:199], s[58:59], 0, v[134:135]
	s_mov_b32 m0, s33
	s_nop 0
	global_load_lds_dwordx4 v[198:199], off
	s_waitcnt lgkmcnt(8)
	s_barrier
	s_waitcnt lgkmcnt(0)
	v_mfma_f32_16x16x32_bf16 v[124:127], v[142:145], v[166:169], v[124:127]
	v_mfma_f32_16x16x32_bf16 v[120:123], v[158:161], v[166:169], v[120:123]
	v_mfma_f32_16x16x32_bf16 v[108:111], v[142:145], v[174:177], v[108:111]
	v_mfma_f32_16x16x32_bf16 v[104:107], v[158:161], v[174:177], v[104:107]
	v_mfma_f32_16x16x32_bf16 v[92:95], v[142:145], v[182:185], v[92:95]
	v_mfma_f32_16x16x32_bf16 v[88:91], v[158:161], v[182:185], v[88:91]
	v_mfma_f32_16x16x32_bf16 v[76:79], v[142:145], v[190:193], v[76:79]
	v_mfma_f32_16x16x32_bf16 v[72:75], v[158:161], v[190:193], v[72:75]
	v_mfma_f32_16x16x32_bf16 v[124:127], v[154:157], v[170:173], v[124:127]
	v_mfma_f32_16x16x32_bf16 v[120:123], v[162:165], v[170:173], v[120:123]
	v_mfma_f32_16x16x32_bf16 v[108:111], v[154:157], v[178:181], v[108:111]
	v_mfma_f32_16x16x32_bf16 v[104:107], v[162:165], v[178:181], v[104:107]
	v_mfma_f32_16x16x32_bf16 v[92:95], v[154:157], v[186:189], v[92:95]
	v_mfma_f32_16x16x32_bf16 v[88:91], v[162:165], v[186:189], v[88:91]
	v_mfma_f32_16x16x32_bf16 v[76:79], v[154:157], v[194:197], v[76:79]
	v_mfma_f32_16x16x32_bf16 v[72:75], v[162:165], v[194:197], v[72:75]
	s_barrier
	s_mov_b32 m0, s89
	v_lshl_add_u64 v[216:217], s[54:55], 0, v[130:131]
	ds_read_b128 v[198:201], v152
	ds_read_b128 v[204:207], v152 offset:1024
	ds_read_b128 v[208:211], v152 offset:2048
	ds_read_b128 v[212:215], v152 offset:3072
	global_load_lds_dwordx4 v[216:217], off
	v_lshl_add_u64 v[218:219], s[54:55], 0, v[136:137]
	s_mov_b32 m0, s88
	s_nop 0
	global_load_lds_dwordx4 v[218:219], off
	s_barrier
	s_waitcnt lgkmcnt(0)
	v_mfma_f32_16x16x32_bf16 v[116:119], v[198:201], v[166:169], v[116:119]
	v_mfma_f32_16x16x32_bf16 v[112:115], v[208:211], v[166:169], v[112:115]
	v_mfma_f32_16x16x32_bf16 v[100:103], v[198:201], v[174:177], v[100:103]
	v_mfma_f32_16x16x32_bf16 v[96:99], v[208:211], v[174:177], v[96:99]
	v_mfma_f32_16x16x32_bf16 v[84:87], v[198:201], v[182:185], v[84:87]
	v_mfma_f32_16x16x32_bf16 v[80:83], v[208:211], v[182:185], v[80:83]
	v_mfma_f32_16x16x32_bf16 v[68:71], v[198:201], v[190:193], v[68:71]
	v_mfma_f32_16x16x32_bf16 v[64:67], v[208:211], v[190:193], v[64:67]
	v_mfma_f32_16x16x32_bf16 v[116:119], v[204:207], v[170:173], v[116:119]
	v_mfma_f32_16x16x32_bf16 v[112:115], v[212:215], v[170:173], v[112:115]
	v_mfma_f32_16x16x32_bf16 v[100:103], v[204:207], v[178:181], v[100:103]
	v_mfma_f32_16x16x32_bf16 v[96:99], v[212:215], v[178:181], v[96:99]
	v_mfma_f32_16x16x32_bf16 v[84:87], v[204:207], v[186:189], v[84:87]
	v_mfma_f32_16x16x32_bf16 v[80:83], v[212:215], v[186:189], v[80:83]
	v_mfma_f32_16x16x32_bf16 v[68:71], v[204:207], v[194:197], v[68:71]
	v_mfma_f32_16x16x32_bf16 v[64:67], v[212:215], v[194:197], v[64:67]
	s_mov_b32 m0, s47
	v_lshl_add_u64 v[220:221], s[56:57], 0, v[128:129]
	s_barrier
	ds_read_b128 v[166:169], v151 offset:16384
	ds_read_b128 v[170:173], v151 offset:17408
	ds_read_b128 v[174:177], v151 offset:18432
	ds_read_b128 v[178:181], v151 offset:19456
	ds_read_b128 v[182:185], v151 offset:20480
	ds_read_b128 v[186:189], v151 offset:21504
	ds_read_b128 v[190:193], v151 offset:22528
	ds_read_b128 v[194:197], v151 offset:23552
	global_load_lds_dwordx4 v[220:221], off
	v_lshl_add_u64 v[222:223], s[56:57], 0, v[134:135]
	s_mov_b32 m0, s66
	s_nop 0
	global_load_lds_dwordx4 v[222:223], off
	s_barrier
	s_waitcnt lgkmcnt(0)
	v_mfma_f32_16x16x32_bf16 v[60:63], v[142:145], v[166:169], v[60:63]
	v_mfma_f32_16x16x32_bf16 v[56:59], v[158:161], v[166:169], v[56:59]
	v_mfma_f32_16x16x32_bf16 v[44:47], v[142:145], v[174:177], v[44:47]
	v_mfma_f32_16x16x32_bf16 v[40:43], v[158:161], v[174:177], v[40:43]
	v_mfma_f32_16x16x32_bf16 v[28:31], v[142:145], v[182:185], v[28:31]
	v_mfma_f32_16x16x32_bf16 v[24:27], v[158:161], v[182:185], v[24:27]
	v_mfma_f32_16x16x32_bf16 v[12:15], v[142:145], v[190:193], v[12:15]
	v_mfma_f32_16x16x32_bf16 v[8:11], v[158:161], v[190:193], v[8:11]
	v_mfma_f32_16x16x32_bf16 v[60:63], v[154:157], v[170:173], v[60:63]
	v_mfma_f32_16x16x32_bf16 v[56:59], v[162:165], v[170:173], v[56:59]
	v_mfma_f32_16x16x32_bf16 v[44:47], v[154:157], v[178:181], v[44:47]
	v_mfma_f32_16x16x32_bf16 v[40:43], v[162:165], v[178:181], v[40:43]
	v_mfma_f32_16x16x32_bf16 v[28:31], v[154:157], v[186:189], v[28:31]
	v_mfma_f32_16x16x32_bf16 v[24:27], v[162:165], v[186:189], v[24:27]
	v_mfma_f32_16x16x32_bf16 v[12:15], v[154:157], v[194:197], v[12:15]
	v_mfma_f32_16x16x32_bf16 v[8:11], v[162:165], v[194:197], v[8:11]
	s_barrier
; #define PG8_STAGE(bufoff, gbase, voff) do { _Pragma("unroll") for (int _i = 0; _i < 2; ++_i) \
;         __builtin_amdgcn_global_load_lds((const unsigned*)((const char*)(gbase) + (voff)[_i]), (LAS unsigned*)(lds + (bufoff) + ldsw + _i * 8192), 16, 0, 0); } while (0)
; #define PG8_LDA(dst, b, h) do { _Pragma("unroll") for (int m = 0; m < 4; ++m) _Pragma("unroll") for (int k = 0; k < 2; ++k) dst[m][k] = *(const LAS bf16x8*)(lds + PG8_SA(b, h) + aoff + m * 2048 + k * 1024); } while (0)
; #define PG8_LDB(dst, b, h) do { _Pragma("unroll") for (int n = 0; n < 2; ++n) _Pragma("unroll") for (int k = 0; k < 2; ++k) dst[n][k] = *(const LAS bf16x8*)(lds + PG8_SB(b, h) + boff + n * 2048 + k * 1024); } while (0)
; #define PG8_MMA(ai, bj, At, Bt) do { __builtin_amdgcn_s_setprio(1); _Pragma("unroll") for (int m = 0; m < 4; ++m) _Pragma("unroll") for (int n = 0; n < 2; ++n) _Pragma("unroll") for (int k = 0; k < 2; ++k) \
;         acc[ai][bj][m][n] = __builtin_amdgcn_mfma_f32_16x16x32_bf16(Bt[n][k], At[m][k], acc[ai][bj][m][n], 0, 0, 0); __builtin_amdgcn_s_setprio(0); } while (0)
; #define PG8_WAIT_V(n) asm volatile("s_waitcnt vmcnt(" #n ")" ::: "memory")
; #define PG8_WAIT_L(n) asm volatile("s_waitcnt lgkmcnt(" #n ")" ::: "memory")
; #define PG8_BAR __builtin_amdgcn_s_barrier()
; #define PG8_SCHED __builtin_amdgcn_sched_barrier(0)
; template <class Epi>
; __device__ __forceinline__ void gemm_phase(LAS unsigned char* lds, const Gemm g, const StaticOrder& S, const Epi& E) {
;     ...
;             PG8_STAGE(PG8_SB(0, 1), b2, voffB1);
;             PG8_WAIT_V(6); PG8_BAR; PG8_MMA(1, 1, At, B1); PG8_BAR;
;             PG8_LDB(B0, 1, 0); PG8_SCHED; PG8_LDA(At, 1, 0); PG8_STAGE(PG8_SA(0, 1), a2 + hstep, voffA);
;             PG8_WAIT_L(8); PG8_BAR; PG8_WAIT_L(0); PG8_MMA(0, 0, At, B0); PG8_BAR; PG8_SCHED;
;             PG8_LDB(B1, 1, 1); PG8_STAGE(PG8_SB(1, 0), b3, voffB0);
;             PG8_BAR; PG8_WAIT_L(0); PG8_MMA(0, 1, At, B1); PG8_BAR;
;             PG8_LDA(At, 1, 1); PG8_STAGE(PG8_SA(1, 0), a3, voffA);
;             PG8_BAR; PG8_WAIT_L(0); PG8_MMA(1, 0, At, B0); PG8_BAR; PG8_SCHED;
;             PG8_STAGE(PG8_SB(1, 1), b3, voffB1);
	s_mov_b32 m0, s85
	v_lshl_add_u64 v[224:225], s[54:55], 0, v[132:133]
	global_load_lds_dwordx4 v[224:225], off
	v_lshl_add_u64 v[226:227], s[54:55], 0, v[138:139]
	s_mov_b32 m0, s84
	s_nop 0
	global_load_lds_dwordx4 v[226:227], off
	s_waitcnt vmcnt(6)
	s_barrier
	v_mfma_f32_16x16x32_bf16 v[52:55], v[198:201], v[166:169], v[52:55]
	v_mfma_f32_16x16x32_bf16 v[48:51], v[208:211], v[166:169], v[48:51]
	v_mfma_f32_16x16x32_bf16 v[36:39], v[198:201], v[174:177], v[36:39]
	v_mfma_f32_16x16x32_bf16 v[32:35], v[208:211], v[174:177], v[32:35]
	v_mfma_f32_16x16x32_bf16 v[20:23], v[198:201], v[182:185], v[20:23]
	v_mfma_f32_16x16x32_bf16 v[16:19], v[208:211], v[182:185], v[16:19]
	v_mfma_f32_16x16x32_bf16 v[4:7], v[198:201], v[190:193], v[4:7]
	v_mfma_f32_16x16x32_bf16 v[0:3], v[208:211], v[190:193], v[0:3]
	v_mfma_f32_16x16x32_bf16 v[52:55], v[204:207], v[170:173], v[52:55]
	v_mfma_f32_16x16x32_bf16 v[48:51], v[212:215], v[170:173], v[48:51]
	v_mfma_f32_16x16x32_bf16 v[36:39], v[204:207], v[178:181], v[36:39]
	v_mfma_f32_16x16x32_bf16 v[32:35], v[212:215], v[178:181], v[32:35]
	v_mfma_f32_16x16x32_bf16 v[20:23], v[204:207], v[186:189], v[20:23]
	v_mfma_f32_16x16x32_bf16 v[16:19], v[212:215], v[186:189], v[16:19]
	v_mfma_f32_16x16x32_bf16 v[4:7], v[204:207], v[194:197], v[4:7]
	v_mfma_f32_16x16x32_bf16 v[0:3], v[212:215], v[194:197], v[0:3]
	v_add_u32_e32 v153, s83, v147
	s_barrier
	ds_read_b128 v[142:145], v153
	ds_read_b128 v[154:157], v153 offset:1024
	ds_read_b128 v[158:161], v153 offset:2048
	ds_read_b128 v[162:165], v153 offset:3072
	s_mov_b32 m0, s67
	v_lshl_add_u64 v[198:199], s[52:53], 0, v[128:129]
	ds_read_b128 v[166:169], v151 offset:32768
	ds_read_b128 v[170:173], v151 offset:33792
	ds_read_b128 v[174:177], v151 offset:34816
	ds_read_b128 v[178:181], v151 offset:35840
	ds_read_b128 v[182:185], v151 offset:36864
	ds_read_b128 v[186:189], v151 offset:37888
	ds_read_b128 v[190:193], v151 offset:38912
	ds_read_b128 v[194:197], v151 offset:39936
	global_load_lds_dwordx4 v[198:199], off
	v_lshl_add_u64 v[198:199], s[52:53], 0, v[134:135]
	s_mov_b32 m0, s68
	s_nop 0
	global_load_lds_dwordx4 v[198:199], off
	s_waitcnt lgkmcnt(8)
	s_barrier
	s_waitcnt lgkmcnt(0)
	v_mfma_f32_16x16x32_bf16 v[124:127], v[142:145], v[166:169], v[124:127]
	v_mfma_f32_16x16x32_bf16 v[120:123], v[158:161], v[166:169], v[120:123]
	v_mfma_f32_16x16x32_bf16 v[108:111], v[142:145], v[174:177], v[108:111]
	v_mfma_f32_16x16x32_bf16 v[104:107], v[158:161], v[174:177], v[104:107]
	v_mfma_f32_16x16x32_bf16 v[92:95], v[142:145], v[182:185], v[92:95]
	v_mfma_f32_16x16x32_bf16 v[88:91], v[158:161], v[182:185], v[88:91]
	v_mfma_f32_16x16x32_bf16 v[76:79], v[142:145], v[190:193], v[76:79]
	v_mfma_f32_16x16x32_bf16 v[72:75], v[158:161], v[190:193], v[72:75]
	v_mfma_f32_16x16x32_bf16 v[124:127], v[154:157], v[170:173], v[124:127]
	v_mfma_f32_16x16x32_bf16 v[120:123], v[162:165], v[170:173], v[120:123]
	v_mfma_f32_16x16x32_bf16 v[108:111], v[154:157], v[178:181], v[108:111]
	v_mfma_f32_16x16x32_bf16 v[104:107], v[162:165], v[178:181], v[104:107]
	v_mfma_f32_16x16x32_bf16 v[92:95], v[154:157], v[186:189], v[92:95]
	v_mfma_f32_16x16x32_bf16 v[88:91], v[162:165], v[186:189], v[88:91]
	v_mfma_f32_16x16x32_bf16 v[76:79], v[154:157], v[194:197], v[76:79]
	v_mfma_f32_16x16x32_bf16 v[72:75], v[162:165], v[194:197], v[72:75]
	s_barrier
	s_mov_b32 m0, s82
	v_add_u32_e32 v153, s81, v147
	v_lshl_add_u64 v[216:217], v[216:217], 0, s[16:17]
	ds_read_b128 v[198:201], v153
	ds_read_b128 v[204:207], v153 offset:1024
	ds_read_b128 v[208:211], v153 offset:2048
	ds_read_b128 v[212:215], v153 offset:3072
	global_load_lds_dwordx4 v[216:217], off
	v_lshl_add_u64 v[216:217], v[218:219], 0, s[16:17]
	s_mov_b32 m0, s90
	s_nop 0
	global_load_lds_dwordx4 v[216:217], off
	s_barrier
	s_waitcnt lgkmcnt(0)
	v_mfma_f32_16x16x32_bf16 v[116:119], v[198:201], v[166:169], v[116:119]
	v_mfma_f32_16x16x32_bf16 v[112:115], v[208:211], v[166:169], v[112:115]
	v_mfma_f32_16x16x32_bf16 v[100:103], v[198:201], v[174:177], v[100:103]
	v_mfma_f32_16x16x32_bf16 v[96:99], v[208:211], v[174:177], v[96:99]
	v_mfma_f32_16x16x32_bf16 v[84:87], v[198:201], v[182:185], v[84:87]
	v_mfma_f32_16x16x32_bf16 v[80:83], v[208:211], v[182:185], v[80:83]
	v_mfma_f32_16x16x32_bf16 v[68:71], v[198:201], v[190:193], v[68:71]
	v_mfma_f32_16x16x32_bf16 v[64:67], v[208:211], v[190:193], v[64:67]
	v_mfma_f32_16x16x32_bf16 v[116:119], v[204:207], v[170:173], v[116:119]
	v_mfma_f32_16x16x32_bf16 v[112:115], v[212:215], v[170:173], v[112:115]
	v_mfma_f32_16x16x32_bf16 v[100:103], v[204:207], v[178:181], v[100:103]
	v_mfma_f32_16x16x32_bf16 v[96:99], v[212:215], v[178:181], v[96:99]
	v_mfma_f32_16x16x32_bf16 v[84:87], v[204:207], v[186:189], v[84:87]
	v_mfma_f32_16x16x32_bf16 v[80:83], v[212:215], v[186:189], v[80:83]
	v_mfma_f32_16x16x32_bf16 v[68:71], v[204:207], v[194:197], v[68:71]
	v_mfma_f32_16x16x32_bf16 v[64:67], v[212:215], v[194:197], v[64:67]
	s_mov_b32 m0, s70
	v_lshl_add_u64 v[216:217], v[220:221], 0, s[16:17]
	s_barrier
	ds_read_b128 v[166:169], v151 offset:49152
	ds_read_b128 v[170:173], v151 offset:50176
	ds_read_b128 v[174:177], v151 offset:51200
	ds_read_b128 v[178:181], v151 offset:52224
	ds_read_b128 v[182:185], v151 offset:53248
	ds_read_b128 v[186:189], v151 offset:54272
	ds_read_b128 v[190:193], v151 offset:55296
	ds_read_b128 v[194:197], v151 offset:56320
	global_load_lds_dwordx4 v[216:217], off
	v_lshl_add_u64 v[216:217], v[222:223], 0, s[16:17]
	s_mov_b32 m0, s71
	s_nop 0
	global_load_lds_dwordx4 v[216:217], off
	s_barrier
; __device__ __forceinline__ unsigned cvt_pk_bf16(float lo, float hi) { unsigned r; asm volatile("v_cvt_pk_bf16_f32 %0, %1, %2" : "=v"(r) : "v"(lo), "v"(hi)); return r; }
; #define PG8_WAIT_V(n) asm volatile("s_waitcnt vmcnt(" #n ")" ::: "memory")
; #define PG8_WAIT_L(n) asm volatile("s_waitcnt lgkmcnt(" #n ")" ::: "memory")
;     __device__ __forceinline__ void operator()(const f32x4 (&acc)[2][2][4][2], const Unit& u, int wr, int wc, int fr, int fq) const {
;     ...
;             for (int m = 0; m < 4; ++m) { const int row = row0 + ai * HALF + m * 16;
;                 const float rs = ssin ? __builtin_amdgcn_rsqf(ssin[row] * (1.f / D) + EPS) : 1.0f; float sq = 0.f; u32x4 w[2];
; #pragma unroll
;                 for (int bj = 0; bj < 2; ++bj) { f32x4 v0 = acc[ai][bj][m][0] * rs, v1 = acc[ai][bj][m][1] * rs;
;                     if (ACT == 1) {
; #pragma unroll
;                         for (int j = 0; j < 4; ++j) { const float a = fmaxf(v0[j], 0.f), b = fmaxf(v1[j], 0.f); v0[j] = a * a; v1[j] = b * b; } }
;                     sq += (v0[0] * v0[0] + v0[1] * v0[1]) + (v0[2] * v0[2] + v0[3] * v0[3]) + (v1[0] * v1[0] + v1[1] * v1[1]) + (v1[2] * v1[2] + v1[3] * v1[3]);
;                     w[bj].x = cvt_pk_bf16(v0[0], v0[1]); w[bj].y = cvt_pk_bf16(v0[2], v0[3]); w[bj].z = cvt_pk_bf16(v1[0], v1[1]); w[bj].w = cvt_pk_bf16(v1[2], v1[3]); }
;                 store_pair_lines(O, ldc, row, fr, col0, w[0], w[1]);
;                 if (ssout) { sq += __shfl_xor(sq, 16); sq += __shfl_xor(sq, 32); if (fq == 0) unsafeAtomicAdd(ssout + row, sq); } }
; template <class Epi>
; __device__ __forceinline__ void gemm_phase(LAS unsigned char* lds, const Gemm g, const StaticOrder& S, const Epi& E) {
;     ...
;             PG8_WAIT_V(6); PG8_BAR; PG8_MMA(1, 1, At, B1); PG8_BAR;
;             PG8_LDB(B0, 1, 0); PG8_SCHED; PG8_LDA(At, 1, 0); PG8_STAGE(PG8_SA(0, 1), a2 + hstep, voffA);
;             PG8_WAIT_L(8); PG8_BAR; PG8_WAIT_L(0); PG8_MMA(0, 0, At, B0); PG8_BAR; PG8_SCHED;
;             PG8_LDB(B1, 1, 1); PG8_STAGE(PG8_SB(1, 0), b3, voffB0);
;             PG8_BAR; PG8_WAIT_L(0); PG8_MMA(0, 1, At, B1); PG8_BAR;
;             PG8_LDA(At, 1, 1); PG8_STAGE(PG8_SA(1, 0), a3, voffA);
;             PG8_BAR; PG8_WAIT_L(0); PG8_MMA(1, 0, At, B0); PG8_BAR; PG8_SCHED;
;             PG8_STAGE(PG8_SB(1, 1), b3, voffB1);
;             PG8_WAIT_V(6); PG8_BAR; PG8_MMA(1, 1, At, B1); PG8_BAR;
	s_waitcnt lgkmcnt(0)
	v_mfma_f32_16x16x32_bf16 v[60:63], v[142:145], v[166:169], v[60:63]
	v_mfma_f32_16x16x32_bf16 v[56:59], v[158:161], v[166:169], v[56:59]
	v_mfma_f32_16x16x32_bf16 v[44:47], v[142:145], v[174:177], v[44:47]
	v_mfma_f32_16x16x32_bf16 v[40:43], v[158:161], v[174:177], v[40:43]
	v_mfma_f32_16x16x32_bf16 v[28:31], v[142:145], v[182:185], v[28:31]
	v_mfma_f32_16x16x32_bf16 v[24:27], v[158:161], v[182:185], v[24:27]
	v_mfma_f32_16x16x32_bf16 v[12:15], v[142:145], v[190:193], v[12:15]
	v_mfma_f32_16x16x32_bf16 v[8:11], v[158:161], v[190:193], v[8:11]
	v_mfma_f32_16x16x32_bf16 v[60:63], v[154:157], v[170:173], v[60:63]
	v_mfma_f32_16x16x32_bf16 v[56:59], v[162:165], v[170:173], v[56:59]
	v_mfma_f32_16x16x32_bf16 v[44:47], v[154:157], v[178:181], v[44:47]
	v_mfma_f32_16x16x32_bf16 v[40:43], v[162:165], v[178:181], v[40:43]
	v_mfma_f32_16x16x32_bf16 v[28:31], v[154:157], v[186:189], v[28:31]
	v_mfma_f32_16x16x32_bf16 v[24:27], v[162:165], v[186:189], v[24:27]
	v_mfma_f32_16x16x32_bf16 v[12:15], v[154:157], v[194:197], v[12:15]
	v_mfma_f32_16x16x32_bf16 v[8:11], v[162:165], v[194:197], v[8:11]
	s_barrier
	s_mov_b32 m0, s87
	v_lshl_add_u64 v[142:143], v[224:225], 0, s[16:17]
	global_load_lds_dwordx4 v[142:143], off
	v_lshl_add_u64 v[142:143], v[226:227], 0, s[16:17]
	s_mov_b32 m0, s86
	s_nop 0
	global_load_lds_dwordx4 v[142:143], off
	s_waitcnt vmcnt(6)
	s_barrier
	v_mfma_f32_16x16x32_bf16 v[52:55], v[198:201], v[166:169], v[52:55]
	v_mfma_f32_16x16x32_bf16 v[48:51], v[208:211], v[166:169], v[48:51]
	v_mfma_f32_16x16x32_bf16 v[36:39], v[198:201], v[174:177], v[36:39]
	v_mfma_f32_16x16x32_bf16 v[32:35], v[208:211], v[174:177], v[32:35]
	v_mfma_f32_16x16x32_bf16 v[20:23], v[198:201], v[182:185], v[20:23]
	v_mfma_f32_16x16x32_bf16 v[16:19], v[208:211], v[182:185], v[16:19]
	v_mfma_f32_16x16x32_bf16 v[4:7], v[198:201], v[190:193], v[4:7]
	v_mfma_f32_16x16x32_bf16 v[0:3], v[208:211], v[190:193], v[0:3]
	v_mfma_f32_16x16x32_bf16 v[52:55], v[204:207], v[170:173], v[52:55]
	v_mfma_f32_16x16x32_bf16 v[48:51], v[212:215], v[170:173], v[48:51]
	v_mfma_f32_16x16x32_bf16 v[36:39], v[204:207], v[178:181], v[36:39]
	v_mfma_f32_16x16x32_bf16 v[32:35], v[212:215], v[178:181], v[32:35]
	v_mfma_f32_16x16x32_bf16 v[20:23], v[204:207], v[186:189], v[20:23]
	v_mfma_f32_16x16x32_bf16 v[16:19], v[212:215], v[186:189], v[16:19]
	v_mfma_f32_16x16x32_bf16 v[4:7], v[204:207], v[194:197], v[4:7]
	v_mfma_f32_16x16x32_bf16 v[0:3], v[212:215], v[194:197], v[0:3]
	s_movk_i32 s58, 0x100
	s_mov_b64 s[54:55], 0
	s_mov_b64 s[52:53], -1
	s_barrier
	s_cbranch_vccz .LBB0_645
	v_cvt_pk_bf16_f32 v145, v124, v125
	v_cvt_pk_bf16_f32 v153, v126, v127
	v_cvt_pk_bf16_f32 v156, v120, v121
	v_cvt_pk_bf16_f32 v157, v122, v123
	v_cvt_pk_bf16_f32 v158, v116, v117
	v_cvt_pk_bf16_f32 v159, v118, v119
	v_cvt_pk_bf16_f32 v160, v112, v113
	v_cvt_pk_bf16_f32 v161, v114, v115
	v_mul_f32_e32 v123, v123, v123
	v_mul_f32_e32 v115, v115, v115
	v_fmac_f32_e32 v123, v122, v122
	v_mul_f32_e32 v122, v125, v125
	v_fmac_f32_e32 v115, v114, v114
	v_mul_f32_e32 v114, v117, v117
	v_fmac_f32_e32 v122, v124, v124
	v_mul_f32_e32 v124, v127, v127
	v_fmac_f32_e32 v114, v116, v116
	v_mul_f32_e32 v116, v119, v119
	v_fmac_f32_e32 v124, v126, v126
	v_mul_f32_e32 v121, v121, v121
	v_fmac_f32_e32 v116, v118, v118
	v_mul_f32_e32 v113, v113, v113
	v_add_f32_e32 v122, v122, v124
	v_fmac_f32_e32 v121, v120, v120
	v_add_f32_e32 v114, v114, v116
	v_fmac_f32_e32 v113, v112, v112
	v_add_f32_e32 v120, v122, v121
	v_add_f32_e32 v112, v114, v113
	s_lshl_b32 s19, s46, 8
	v_add_f32_e32 v120, v123, v120
	v_add_f32_e32 v112, v115, v112
	v_and_b32_e32 v113, 64, v203
	s_add_i32 s19, s19, s72
	v_mov_b32_dpp v162, v145 row_ror:8 row_mask:0xf bank_mask:0xf
	v_add_f32_e32 v115, v120, v112
	v_xor_b32_e32 v112, 16, v203
	v_add_u32_e32 v118, 64, v113
	v_mov_b32_dpp v163, v153 row_ror:8 row_mask:0xf bank_mask:0xf
	v_mov_b32_dpp v154, v158 row_ror:8 row_mask:0xf bank_mask:0xf
	v_cndmask_b32_e64 v158, v158, v162, s[6:7]
	v_or_b32_e32 v162, s19, v148
	v_cmp_lt_i32_e32 vcc, v112, v118
	v_lshl_or_b32 v142, s44, 8, v149
	v_mov_b32_dpp v164, v156 row_ror:8 row_mask:0xf bank_mask:0xf
	v_mov_b32_dpp v165, v157 row_ror:8 row_mask:0xf bank_mask:0xf
	v_mov_b32_dpp v155, v159 row_ror:8 row_mask:0xf bank_mask:0xf
	v_cndmask_b32_e64 v159, v159, v163, s[6:7]
	v_ashrrev_i32_e32 v163, 31, v162
	v_cndmask_b32_e32 v112, v203, v112, vcc
	v_ashrrev_i32_e32 v143, 31, v142
	v_mov_b32_dpp v166, v160 row_ror:8 row_mask:0xf bank_mask:0xf
	v_mov_b32_dpp v167, v161 row_ror:8 row_mask:0xf bank_mask:0xf
	v_cndmask_b32_e64 v160, v160, v164, s[6:7]
	v_cndmask_b32_e64 v161, v161, v165, s[6:7]
	v_lshlrev_b64 v[164:165], 12, v[162:163]
	v_lshlrev_b32_e32 v114, 2, v112
	v_cndmask_b32_e64 v156, v166, v156, s[6:7]
	v_cndmask_b32_e64 v157, v167, v157, s[6:7]
	v_lshl_add_u64 v[164:165], s[10:11], 0, v[164:165]
	v_lshlrev_b64 v[166:167], 1, v[142:143]
	v_mov_b32_e32 v119, v115
	s_nop 1
	v_permlane16_swap_b32_e32 v119, v115
	v_cndmask_b32_e64 v154, v154, v145, s[6:7]
	v_cndmask_b32_e64 v155, v155, v153, s[6:7]
	v_lshl_add_u64 v[112:113], v[164:165], 0, v[166:167]
	global_store_dwordx4 v[112:113], v[154:157], off
	v_xor_b32_e32 v113, 32, v203
	v_cmp_lt_i32_e32 vcc, v113, v118
	s_waitcnt lgkmcnt(0)
	v_add_f32_e32 v112, v115, v119
	v_or_b32_e32 v116, 8, v162
	v_cndmask_b32_e32 v113, v203, v113, vcc
	v_lshlrev_b32_e32 v115, 2, v113
	v_mov_b32_e32 v113, v112
	s_nop 1
	v_permlane32_swap_b32_e32 v113, v112
	v_ashrrev_i32_e32 v117, 31, v116
	v_lshlrev_b64 v[116:117], 12, v[116:117]
	v_lshl_add_u64 v[116:117], s[10:11], 0, v[116:117]
	v_or_b32_e32 v144, s19, v146
	v_lshl_add_u64 v[116:117], v[116:117], 0, v[166:167]
	global_store_dwordx4 v[116:117], v[158:161], off
	s_and_saveexec_b64 s[44:45], s[8:9]
	s_cbranch_execz .LBB0_648
	v_ashrrev_i32_e32 v145, 31, v144
	s_waitcnt lgkmcnt(0)
	v_add_f32_e32 v116, v112, v113
	v_lshl_add_u64 v[112:113], v[144:145], 2, s[12:13]
	global_atomic_add_f32 v[112:113], v116, off
; __device__ __forceinline__ unsigned cvt_pk_bf16(float lo, float hi) { unsigned r; asm volatile("v_cvt_pk_bf16_f32 %0, %1, %2" : "=v"(r) : "v"(lo), "v"(hi)); return r; }
; __device__ __forceinline__ unsigned dpp_ror8(unsigned x) { return (unsigned)__builtin_amdgcn_update_dpp(0, (int)x, 0x128, 0xf, 0xf, false); }
; __device__ __forceinline__ void store_pair_lines(bf16_t* O, int ldc, int row, int fr, int col0, u32x4 wA, u32x4 wB) {
;     const u32x4 sA = {dpp_ror8(wA.x), dpp_ror8(wA.y), dpp_ror8(wA.z), dpp_ror8(wA.w)}, sB = {dpp_ror8(wB.x), dpp_ror8(wB.y), dpp_ror8(wB.z), dpp_ror8(wB.w)};
;     const bool lo = fr < 8;
;     const u32x4 o1 = lo ? wA : sB, o2 = lo ? sA : wB;
;     const int r1 = row - fr + (fr & 7), cb = col0 + (lo ? 0 : 8);
;     *(u32x4*)(O + (size_t)r1 * ldc + cb) = o1;
;     *(u32x4*)(O + (size_t)(r1 + 8) * ldc + cb) = o2;
; }
;     __device__ __forceinline__ void operator()(const f32x4 (&acc)[2][2][4][2], const Unit& u, int wr, int wc, int fr, int fq) const {
;     ...
;             for (int m = 0; m < 4; ++m) { const int row = row0 + ai * HALF + m * 16;
;                 const float rs = ssin ? __builtin_amdgcn_rsqf(ssin[row] * (1.f / D) + EPS) : 1.0f; float sq = 0.f; u32x4 w[2];
; #pragma unroll
;                 for (int bj = 0; bj < 2; ++bj) { f32x4 v0 = acc[ai][bj][m][0] * rs, v1 = acc[ai][bj][m][1] * rs;
;                     if (ACT == 1) {
; #pragma unroll
;                         for (int j = 0; j < 4; ++j) { const float a = fmaxf(v0[j], 0.f), b = fmaxf(v1[j], 0.f); v0[j] = a * a; v1[j] = b * b; } }
;                     sq += (v0[0] * v0[0] + v0[1] * v0[1]) + (v0[2] * v0[2] + v0[3] * v0[3]) + (v1[0] * v1[0] + v1[1] * v1[1]) + (v1[2] * v1[2] + v1[3] * v1[3]);
;                     w[bj].x = cvt_pk_bf16(v0[0], v0[1]); w[bj].y = cvt_pk_bf16(v0[2], v0[3]); w[bj].z = cvt_pk_bf16(v1[0], v1[1]); w[bj].w = cvt_pk_bf16(v1[2], v1[3]); }
;                 store_pair_lines(O, ldc, row, fr, col0, w[0], w[1]);
;                 if (ssout) { sq += __shfl_xor(sq, 16); sq += __shfl_xor(sq, 32); if (fq == 0) unsafeAtomicAdd(ssout + row, sq); } }
.LBB0_648:
	s_or_b64 exec, exec, s[44:45]
	s_waitcnt lgkmcnt(0)
	v_cvt_pk_bf16_f32 v113, v108, v109
	v_cvt_pk_bf16_f32 v117, v110, v111
	v_cvt_pk_bf16_f32 v118, v104, v105
	v_cvt_pk_bf16_f32 v119, v106, v107
	v_cvt_pk_bf16_f32 v120, v100, v101
	v_cvt_pk_bf16_f32 v121, v102, v103
	v_cvt_pk_bf16_f32 v122, v96, v97
	v_cvt_pk_bf16_f32 v123, v98, v99
	v_mul_f32_e32 v107, v107, v107
	v_mul_f32_e32 v99, v99, v99
	v_fmac_f32_e32 v107, v106, v106
	v_mul_f32_e32 v106, v109, v109
	v_fmac_f32_e32 v99, v98, v98
	v_mul_f32_e32 v98, v101, v101
	v_fmac_f32_e32 v106, v108, v108
	v_mul_f32_e32 v108, v111, v111
	v_fmac_f32_e32 v98, v100, v100
	v_mul_f32_e32 v100, v103, v103
	v_fmac_f32_e32 v108, v110, v110
	v_mul_f32_e32 v105, v105, v105
	v_fmac_f32_e32 v100, v102, v102
	v_mul_f32_e32 v97, v97, v97
	v_add_f32_e32 v106, v106, v108
	v_fmac_f32_e32 v105, v104, v104
	v_add_f32_e32 v98, v98, v100
	v_fmac_f32_e32 v97, v96, v96
	v_add_f32_e32 v104, v106, v105
	v_add_f32_e32 v96, v98, v97
	v_add_f32_e32 v104, v107, v104
	v_add_f32_e32 v96, v99, v96
	v_or_b32_e32 v112, 16, v144
	v_mov_b32_dpp v116, v120 row_ror:8 row_mask:0xf bank_mask:0xf
	v_add_f32_e32 v100, v104, v96
	v_mov_b32_dpp v124, v113 row_ror:8 row_mask:0xf bank_mask:0xf
	v_cndmask_b32_e64 v116, v116, v113, s[6:7]
	v_sub_u32_e32 v113, v112, v146
	v_mov_b32_e32 v101, v100
	s_nop 1
	v_permlane16_swap_b32_e32 v101, v100
	v_mov_b32_dpp v125, v117 row_ror:8 row_mask:0xf bank_mask:0xf
	v_cndmask_b32_e64 v120, v120, v124, s[6:7]
	v_add_u32_e32 v124, v113, v148
	v_mov_b32_dpp v145, v121 row_ror:8 row_mask:0xf bank_mask:0xf
	v_cndmask_b32_e64 v121, v121, v125, s[6:7]
	v_ashrrev_i32_e32 v125, 31, v124
	v_lshlrev_b64 v[96:97], 12, v[124:125]
	v_lshl_add_u64 v[96:97], s[10:11], 0, v[96:97]
	v_lshl_add_u64 v[98:99], v[142:143], 1, v[96:97]
	s_waitcnt lgkmcnt(0)
	v_add_f32_e32 v96, v100, v101
	v_mov_b32_e32 v97, v96
	s_nop 1
	v_permlane32_swap_b32_e32 v97, v96
	v_mov_b32_dpp v153, v122 row_ror:8 row_mask:0xf bank_mask:0xf
	v_mov_b32_dpp v154, v123 row_ror:8 row_mask:0xf bank_mask:0xf
	v_mov_b32_dpp v126, v118 row_ror:8 row_mask:0xf bank_mask:0xf
	v_mov_b32_dpp v127, v119 row_ror:8 row_mask:0xf bank_mask:0xf
	v_cndmask_b32_e64 v117, v145, v117, s[6:7]
	v_cndmask_b32_e64 v118, v153, v118, s[6:7]
	v_cndmask_b32_e64 v119, v154, v119, s[6:7]
	global_store_dwordx4 v[98:99], v[116:119], off
	v_add_co_u32_e32 v98, vcc, s73, v98
	v_cndmask_b32_e64 v122, v122, v126, s[6:7]
	v_cndmask_b32_e64 v123, v123, v127, s[6:7]
	v_addc_co_u32_e32 v99, vcc, 0, v99, vcc
	global_store_dwordx4 v[98:99], v[120:123], off
	s_and_saveexec_b64 s[44:45], s[8:9]
	s_cbranch_execz .LBB0_650
	v_ashrrev_i32_e32 v113, 31, v112
	s_waitcnt lgkmcnt(0)
	v_add_f32_e32 v98, v96, v97
	v_lshl_add_u64 v[96:97], v[112:113], 2, s[12:13]
	global_atomic_add_f32 v[96:97], v98, off
.LBB0_650:
	s_or_b64 exec, exec, s[44:45]
	s_waitcnt lgkmcnt(0)
	v_cvt_pk_bf16_f32 v97, v92, v93
	v_cvt_pk_bf16_f32 v99, v94, v95
	v_cvt_pk_bf16_f32 v100, v88, v89
	v_cvt_pk_bf16_f32 v101, v90, v91
	v_cvt_pk_bf16_f32 v102, v84, v85
	v_cvt_pk_bf16_f32 v103, v86, v87
	v_cvt_pk_bf16_f32 v104, v80, v81
	v_cvt_pk_bf16_f32 v105, v82, v83
	v_mul_f32_e32 v91, v91, v91
	v_mul_f32_e32 v83, v83, v83
	v_fmac_f32_e32 v91, v90, v90
	v_mul_f32_e32 v90, v93, v93
	v_fmac_f32_e32 v83, v82, v82
	v_mul_f32_e32 v82, v85, v85
	v_fmac_f32_e32 v90, v92, v92
	v_mul_f32_e32 v92, v95, v95
	v_fmac_f32_e32 v82, v84, v84
	v_mul_f32_e32 v84, v87, v87
	v_fmac_f32_e32 v92, v94, v94
	v_mul_f32_e32 v89, v89, v89
	v_fmac_f32_e32 v84, v86, v86
	v_mul_f32_e32 v81, v81, v81
	v_add_f32_e32 v90, v90, v92
	v_fmac_f32_e32 v89, v88, v88
	v_add_f32_e32 v82, v82, v84
	v_fmac_f32_e32 v81, v80, v80
	v_add_f32_e32 v88, v90, v89
	v_add_f32_e32 v80, v82, v81
	v_add_f32_e32 v88, v91, v88
	v_add_f32_e32 v80, v83, v80
	v_or_b32_e32 v96, 32, v144
	v_mov_b32_dpp v98, v102 row_ror:8 row_mask:0xf bank_mask:0xf
	v_add_f32_e32 v84, v88, v80
	v_mov_b32_dpp v106, v97 row_ror:8 row_mask:0xf bank_mask:0xf
	v_cndmask_b32_e64 v98, v98, v97, s[6:7]
	v_sub_u32_e32 v97, v96, v146
	v_mov_b32_e32 v85, v84
	s_nop 1
	v_permlane16_swap_b32_e32 v85, v84
	v_mov_b32_dpp v107, v99 row_ror:8 row_mask:0xf bank_mask:0xf
	v_cndmask_b32_e64 v102, v102, v106, s[6:7]
	v_add_u32_e32 v106, v97, v148
	v_mov_b32_dpp v110, v103 row_ror:8 row_mask:0xf bank_mask:0xf
	v_cndmask_b32_e64 v103, v103, v107, s[6:7]
	v_ashrrev_i32_e32 v107, 31, v106
	v_lshlrev_b64 v[80:81], 12, v[106:107]
	v_lshl_add_u64 v[80:81], s[10:11], 0, v[80:81]
	v_lshl_add_u64 v[82:83], v[142:143], 1, v[80:81]
	s_waitcnt lgkmcnt(0)
	v_add_f32_e32 v80, v84, v85
	v_mov_b32_e32 v81, v80
	s_nop 1
	v_permlane32_swap_b32_e32 v81, v80
	v_mov_b32_dpp v111, v104 row_ror:8 row_mask:0xf bank_mask:0xf
	v_mov_b32_dpp v112, v105 row_ror:8 row_mask:0xf bank_mask:0xf
	v_mov_b32_dpp v108, v100 row_ror:8 row_mask:0xf bank_mask:0xf
	v_mov_b32_dpp v109, v101 row_ror:8 row_mask:0xf bank_mask:0xf
	v_cndmask_b32_e64 v99, v110, v99, s[6:7]
	v_cndmask_b32_e64 v100, v111, v100, s[6:7]
	v_cndmask_b32_e64 v101, v112, v101, s[6:7]
	global_store_dwordx4 v[82:83], v[98:101], off
	v_add_co_u32_e32 v82, vcc, s73, v82
	v_cndmask_b32_e64 v104, v104, v108, s[6:7]
	v_cndmask_b32_e64 v105, v105, v109, s[6:7]
	v_addc_co_u32_e32 v83, vcc, 0, v83, vcc
	global_store_dwordx4 v[82:83], v[102:105], off
	s_and_saveexec_b64 s[44:45], s[8:9]
	s_cbranch_execz .LBB0_652
	v_ashrrev_i32_e32 v97, 31, v96
	s_waitcnt lgkmcnt(0)
	v_add_f32_e32 v82, v80, v81
	v_lshl_add_u64 v[80:81], v[96:97], 2, s[12:13]
	global_atomic_add_f32 v[80:81], v82, off
; __device__ __forceinline__ unsigned cvt_pk_bf16(float lo, float hi) { unsigned r; asm volatile("v_cvt_pk_bf16_f32 %0, %1, %2" : "=v"(r) : "v"(lo), "v"(hi)); return r; }
; __device__ __forceinline__ unsigned dpp_ror8(unsigned x) { return (unsigned)__builtin_amdgcn_update_dpp(0, (int)x, 0x128, 0xf, 0xf, false); }
; __device__ __forceinline__ void store_pair_lines(bf16_t* O, int ldc, int row, int fr, int col0, u32x4 wA, u32x4 wB) {
;     const u32x4 sA = {dpp_ror8(wA.x), dpp_ror8(wA.y), dpp_ror8(wA.z), dpp_ror8(wA.w)}, sB = {dpp_ror8(wB.x), dpp_ror8(wB.y), dpp_ror8(wB.z), dpp_ror8(wB.w)};
;     const bool lo = fr < 8;
;     const u32x4 o1 = lo ? wA : sB, o2 = lo ? sA : wB;
;     const int r1 = row - fr + (fr & 7), cb = col0 + (lo ? 0 : 8);
;     *(u32x4*)(O + (size_t)r1 * ldc + cb) = o1;
;     *(u32x4*)(O + (size_t)(r1 + 8) * ldc + cb) = o2;
; }
;     __device__ __forceinline__ void operator()(const f32x4 (&acc)[2][2][4][2], const Unit& u, int wr, int wc, int fr, int fq) const {
;     ...
;             for (int m = 0; m < 4; ++m) { const int row = row0 + ai * HALF + m * 16;
;                 const float rs = ssin ? __builtin_amdgcn_rsqf(ssin[row] * (1.f / D) + EPS) : 1.0f; float sq = 0.f; u32x4 w[2];
; #pragma unroll
;                 for (int bj = 0; bj < 2; ++bj) { f32x4 v0 = acc[ai][bj][m][0] * rs, v1 = acc[ai][bj][m][1] * rs;
;                     if (ACT == 1) {
; #pragma unroll
;                         for (int j = 0; j < 4; ++j) { const float a = fmaxf(v0[j], 0.f), b = fmaxf(v1[j], 0.f); v0[j] = a * a; v1[j] = b * b; } }
;                     sq += (v0[0] * v0[0] + v0[1] * v0[1]) + (v0[2] * v0[2] + v0[3] * v0[3]) + (v1[0] * v1[0] + v1[1] * v1[1]) + (v1[2] * v1[2] + v1[3] * v1[3]);
;                     w[bj].x = cvt_pk_bf16(v0[0], v0[1]); w[bj].y = cvt_pk_bf16(v0[2], v0[3]); w[bj].z = cvt_pk_bf16(v1[0], v1[1]); w[bj].w = cvt_pk_bf16(v1[2], v1[3]); }
;                 store_pair_lines(O, ldc, row, fr, col0, w[0], w[1]);
;                 if (ssout) { sq += __shfl_xor(sq, 16); sq += __shfl_xor(sq, 32); if (fq == 0) unsafeAtomicAdd(ssout + row, sq); } }
.LBB0_652:
	s_or_b64 exec, exec, s[44:45]
	s_waitcnt lgkmcnt(0)
	v_cvt_pk_bf16_f32 v81, v76, v77
	v_cvt_pk_bf16_f32 v83, v78, v79
	v_cvt_pk_bf16_f32 v84, v72, v73
	v_cvt_pk_bf16_f32 v85, v74, v75
	v_cvt_pk_bf16_f32 v86, v68, v69
	v_cvt_pk_bf16_f32 v87, v70, v71
	v_cvt_pk_bf16_f32 v88, v64, v65
	v_cvt_pk_bf16_f32 v89, v66, v67
	v_mul_f32_e32 v75, v75, v75
	v_mul_f32_e32 v67, v67, v67
	v_fmac_f32_e32 v75, v74, v74
	v_mul_f32_e32 v74, v77, v77
	v_fmac_f32_e32 v67, v66, v66
	v_mul_f32_e32 v66, v69, v69
	v_fmac_f32_e32 v74, v76, v76
	v_mul_f32_e32 v76, v79, v79
	v_fmac_f32_e32 v66, v68, v68
	v_mul_f32_e32 v68, v71, v71
	v_fmac_f32_e32 v76, v78, v78
	v_mul_f32_e32 v73, v73, v73
	v_fmac_f32_e32 v68, v70, v70
	v_mul_f32_e32 v65, v65, v65
	v_add_f32_e32 v74, v74, v76
	v_fmac_f32_e32 v73, v72, v72
	v_add_f32_e32 v66, v66, v68
	v_fmac_f32_e32 v65, v64, v64
	v_add_f32_e32 v72, v74, v73
	v_add_f32_e32 v64, v66, v65
	v_add_f32_e32 v72, v75, v72
	v_add_f32_e32 v64, v67, v64
	v_or_b32_e32 v80, 48, v144
	v_mov_b32_dpp v82, v86 row_ror:8 row_mask:0xf bank_mask:0xf
	v_add_f32_e32 v68, v72, v64
	v_mov_b32_dpp v90, v81 row_ror:8 row_mask:0xf bank_mask:0xf
	v_cndmask_b32_e64 v82, v82, v81, s[6:7]
	v_sub_u32_e32 v81, v80, v146
	v_mov_b32_e32 v69, v68
	s_nop 1
	v_permlane16_swap_b32_e32 v69, v68
	v_mov_b32_dpp v91, v83 row_ror:8 row_mask:0xf bank_mask:0xf
	v_cndmask_b32_e64 v86, v86, v90, s[6:7]
	v_add_u32_e32 v90, v81, v148
	v_mov_b32_dpp v94, v87 row_ror:8 row_mask:0xf bank_mask:0xf
	v_cndmask_b32_e64 v87, v87, v91, s[6:7]
	v_ashrrev_i32_e32 v91, 31, v90
	v_lshlrev_b64 v[64:65], 12, v[90:91]
	v_lshl_add_u64 v[64:65], s[10:11], 0, v[64:65]
	v_lshl_add_u64 v[66:67], v[142:143], 1, v[64:65]
	s_waitcnt lgkmcnt(0)
	v_add_f32_e32 v64, v68, v69
	v_mov_b32_e32 v65, v64
	s_nop 1
	v_permlane32_swap_b32_e32 v65, v64
	v_mov_b32_dpp v95, v88 row_ror:8 row_mask:0xf bank_mask:0xf
	v_mov_b32_dpp v96, v89 row_ror:8 row_mask:0xf bank_mask:0xf
	v_mov_b32_dpp v92, v84 row_ror:8 row_mask:0xf bank_mask:0xf
	v_mov_b32_dpp v93, v85 row_ror:8 row_mask:0xf bank_mask:0xf
	v_cndmask_b32_e64 v83, v94, v83, s[6:7]
	v_cndmask_b32_e64 v84, v95, v84, s[6:7]
	v_cndmask_b32_e64 v85, v96, v85, s[6:7]
	global_store_dwordx4 v[66:67], v[82:85], off
	v_add_co_u32_e32 v66, vcc, s73, v66
	v_cndmask_b32_e64 v88, v88, v92, s[6:7]
	v_cndmask_b32_e64 v89, v89, v93, s[6:7]
	v_addc_co_u32_e32 v67, vcc, 0, v67, vcc
	global_store_dwordx4 v[66:67], v[86:89], off
	s_and_saveexec_b64 s[44:45], s[8:9]
	s_cbranch_execz .LBB0_654
	v_ashrrev_i32_e32 v81, 31, v80
	s_waitcnt lgkmcnt(0)
	v_add_f32_e32 v66, v64, v65
	v_lshl_add_u64 v[64:65], v[80:81], 2, s[12:13]
	global_atomic_add_f32 v[64:65], v66, off
.LBB0_654:
	s_or_b64 exec, exec, s[44:45]
	s_waitcnt lgkmcnt(0)
	v_cvt_pk_bf16_f32 v65, v60, v61
	v_cvt_pk_bf16_f32 v67, v62, v63
	v_cvt_pk_bf16_f32 v68, v56, v57
	v_cvt_pk_bf16_f32 v69, v58, v59
	v_cvt_pk_bf16_f32 v70, v52, v53
	v_cvt_pk_bf16_f32 v71, v54, v55
	v_cvt_pk_bf16_f32 v72, v48, v49
	v_cvt_pk_bf16_f32 v73, v50, v51
	v_mul_f32_e32 v59, v59, v59
	v_mul_f32_e32 v51, v51, v51
	v_fmac_f32_e32 v59, v58, v58
	v_mul_f32_e32 v58, v61, v61
	v_fmac_f32_e32 v51, v50, v50
	v_mul_f32_e32 v50, v53, v53
	v_fmac_f32_e32 v58, v60, v60
	v_mul_f32_e32 v60, v63, v63
	v_fmac_f32_e32 v50, v52, v52
	v_mul_f32_e32 v52, v55, v55
	v_fmac_f32_e32 v60, v62, v62
	v_mul_f32_e32 v57, v57, v57
	v_fmac_f32_e32 v52, v54, v54
	v_mul_f32_e32 v49, v49, v49
	v_add_f32_e32 v58, v58, v60
	v_fmac_f32_e32 v57, v56, v56
	v_add_f32_e32 v50, v50, v52
	v_fmac_f32_e32 v49, v48, v48
	v_add_f32_e32 v56, v58, v57
	v_add_f32_e32 v48, v50, v49
	v_add_f32_e32 v56, v59, v56
	v_add_f32_e32 v48, v51, v48
	v_add_u32_e32 v64, 0x80, v144
	v_mov_b32_dpp v66, v70 row_ror:8 row_mask:0xf bank_mask:0xf
	v_add_f32_e32 v52, v56, v48
	v_mov_b32_dpp v74, v65 row_ror:8 row_mask:0xf bank_mask:0xf
	v_cndmask_b32_e64 v66, v66, v65, s[6:7]
	v_sub_u32_e32 v65, v64, v146
	v_mov_b32_e32 v53, v52
	s_nop 1
	v_permlane16_swap_b32_e32 v53, v52
	v_mov_b32_dpp v75, v67 row_ror:8 row_mask:0xf bank_mask:0xf
	v_cndmask_b32_e64 v70, v70, v74, s[6:7]
	v_add_u32_e32 v74, v65, v148
	v_mov_b32_dpp v78, v71 row_ror:8 row_mask:0xf bank_mask:0xf
	v_cndmask_b32_e64 v71, v71, v75, s[6:7]
	v_ashrrev_i32_e32 v75, 31, v74
	v_lshlrev_b64 v[48:49], 12, v[74:75]
	v_lshl_add_u64 v[48:49], s[10:11], 0, v[48:49]
	v_lshl_add_u64 v[50:51], v[142:143], 1, v[48:49]
	s_waitcnt lgkmcnt(0)
	v_add_f32_e32 v48, v52, v53
	v_mov_b32_e32 v49, v48
	s_nop 1
	v_permlane32_swap_b32_e32 v49, v48
	v_mov_b32_dpp v79, v72 row_ror:8 row_mask:0xf bank_mask:0xf
	v_mov_b32_dpp v80, v73 row_ror:8 row_mask:0xf bank_mask:0xf
	v_mov_b32_dpp v76, v68 row_ror:8 row_mask:0xf bank_mask:0xf
	v_mov_b32_dpp v77, v69 row_ror:8 row_mask:0xf bank_mask:0xf
	v_cndmask_b32_e64 v67, v78, v67, s[6:7]
	v_cndmask_b32_e64 v68, v79, v68, s[6:7]
	v_cndmask_b32_e64 v69, v80, v69, s[6:7]
	global_store_dwordx4 v[50:51], v[66:69], off
	v_add_co_u32_e32 v50, vcc, s73, v50
	v_cndmask_b32_e64 v72, v72, v76, s[6:7]
	v_cndmask_b32_e64 v73, v73, v77, s[6:7]
	v_addc_co_u32_e32 v51, vcc, 0, v51, vcc
	global_store_dwordx4 v[50:51], v[70:73], off
	s_and_saveexec_b64 s[44:45], s[8:9]
	s_cbranch_execz .LBB0_656
	v_ashrrev_i32_e32 v65, 31, v64
	s_waitcnt lgkmcnt(0)
	v_add_f32_e32 v50, v48, v49
	v_lshl_add_u64 v[48:49], v[64:65], 2, s[12:13]
	global_atomic_add_f32 v[48:49], v50, off
; __device__ __forceinline__ unsigned cvt_pk_bf16(float lo, float hi) { unsigned r; asm volatile("v_cvt_pk_bf16_f32 %0, %1, %2" : "=v"(r) : "v"(lo), "v"(hi)); return r; }
; __device__ __forceinline__ unsigned dpp_ror8(unsigned x) { return (unsigned)__builtin_amdgcn_update_dpp(0, (int)x, 0x128, 0xf, 0xf, false); }
; __device__ __forceinline__ void store_pair_lines(bf16_t* O, int ldc, int row, int fr, int col0, u32x4 wA, u32x4 wB) {
;     const u32x4 sA = {dpp_ror8(wA.x), dpp_ror8(wA.y), dpp_ror8(wA.z), dpp_ror8(wA.w)}, sB = {dpp_ror8(wB.x), dpp_ror8(wB.y), dpp_ror8(wB.z), dpp_ror8(wB.w)};
;     const bool lo = fr < 8;
;     const u32x4 o1 = lo ? wA : sB, o2 = lo ? sA : wB;
;     const int r1 = row - fr + (fr & 7), cb = col0 + (lo ? 0 : 8);
;     *(u32x4*)(O + (size_t)r1 * ldc + cb) = o1;
;     *(u32x4*)(O + (size_t)(r1 + 8) * ldc + cb) = o2;
; }
;     __device__ __forceinline__ void operator()(const f32x4 (&acc)[2][2][4][2], const Unit& u, int wr, int wc, int fr, int fq) const {
;     ...
;             for (int m = 0; m < 4; ++m) { const int row = row0 + ai * HALF + m * 16;
;                 const float rs = ssin ? __builtin_amdgcn_rsqf(ssin[row] * (1.f / D) + EPS) : 1.0f; float sq = 0.f; u32x4 w[2];
; #pragma unroll
;                 for (int bj = 0; bj < 2; ++bj) { f32x4 v0 = acc[ai][bj][m][0] * rs, v1 = acc[ai][bj][m][1] * rs;
;                     if (ACT == 1) {
; #pragma unroll
;                         for (int j = 0; j < 4; ++j) { const float a = fmaxf(v0[j], 0.f), b = fmaxf(v1[j], 0.f); v0[j] = a * a; v1[j] = b * b; } }
;                     sq += (v0[0] * v0[0] + v0[1] * v0[1]) + (v0[2] * v0[2] + v0[3] * v0[3]) + (v1[0] * v1[0] + v1[1] * v1[1]) + (v1[2] * v1[2] + v1[3] * v1[3]);
;                     w[bj].x = cvt_pk_bf16(v0[0], v0[1]); w[bj].y = cvt_pk_bf16(v0[2], v0[3]); w[bj].z = cvt_pk_bf16(v1[0], v1[1]); w[bj].w = cvt_pk_bf16(v1[2], v1[3]); }
;                 store_pair_lines(O, ldc, row, fr, col0, w[0], w[1]);
;                 if (ssout) { sq += __shfl_xor(sq, 16); sq += __shfl_xor(sq, 32); if (fq == 0) unsafeAtomicAdd(ssout + row, sq); } }
.LBB0_656:
	s_or_b64 exec, exec, s[44:45]
	s_waitcnt lgkmcnt(0)
	v_cvt_pk_bf16_f32 v49, v44, v45
	v_cvt_pk_bf16_f32 v51, v46, v47
	v_cvt_pk_bf16_f32 v52, v40, v41
	v_cvt_pk_bf16_f32 v53, v42, v43
	v_cvt_pk_bf16_f32 v54, v36, v37
	v_cvt_pk_bf16_f32 v55, v38, v39
	v_cvt_pk_bf16_f32 v56, v32, v33
	v_cvt_pk_bf16_f32 v57, v34, v35
	v_mul_f32_e32 v43, v43, v43
	v_mul_f32_e32 v35, v35, v35
	v_fmac_f32_e32 v43, v42, v42
	v_mul_f32_e32 v42, v45, v45
	v_fmac_f32_e32 v35, v34, v34
	v_mul_f32_e32 v34, v37, v37
	v_fmac_f32_e32 v42, v44, v44
	v_mul_f32_e32 v44, v47, v47
	v_fmac_f32_e32 v34, v36, v36
	v_mul_f32_e32 v36, v39, v39
	v_fmac_f32_e32 v44, v46, v46
	v_mul_f32_e32 v41, v41, v41
	v_fmac_f32_e32 v36, v38, v38
	v_mul_f32_e32 v33, v33, v33
	v_add_f32_e32 v42, v42, v44
	v_fmac_f32_e32 v41, v40, v40
	v_add_f32_e32 v34, v34, v36
	v_fmac_f32_e32 v33, v32, v32
	v_add_f32_e32 v40, v42, v41
	v_add_f32_e32 v32, v34, v33
	v_add_f32_e32 v40, v43, v40
	v_add_f32_e32 v32, v35, v32
	v_add_u32_e32 v48, 0x90, v144
	v_mov_b32_dpp v50, v54 row_ror:8 row_mask:0xf bank_mask:0xf
	v_add_f32_e32 v36, v40, v32
	v_mov_b32_dpp v58, v49 row_ror:8 row_mask:0xf bank_mask:0xf
	v_cndmask_b32_e64 v50, v50, v49, s[6:7]
	v_sub_u32_e32 v49, v48, v146
	v_mov_b32_e32 v37, v36
	s_nop 1
	v_permlane16_swap_b32_e32 v37, v36
	v_mov_b32_dpp v59, v51 row_ror:8 row_mask:0xf bank_mask:0xf
	v_cndmask_b32_e64 v54, v54, v58, s[6:7]
	v_add_u32_e32 v58, v49, v148
	v_mov_b32_dpp v62, v55 row_ror:8 row_mask:0xf bank_mask:0xf
	v_cndmask_b32_e64 v55, v55, v59, s[6:7]
	v_ashrrev_i32_e32 v59, 31, v58
	v_lshlrev_b64 v[32:33], 12, v[58:59]
	v_lshl_add_u64 v[32:33], s[10:11], 0, v[32:33]
	v_lshl_add_u64 v[34:35], v[142:143], 1, v[32:33]
	s_waitcnt lgkmcnt(0)
	v_add_f32_e32 v32, v36, v37
	v_mov_b32_e32 v33, v32
	s_nop 1
	v_permlane32_swap_b32_e32 v33, v32
	v_mov_b32_dpp v63, v56 row_ror:8 row_mask:0xf bank_mask:0xf
	v_mov_b32_dpp v64, v57 row_ror:8 row_mask:0xf bank_mask:0xf
	v_mov_b32_dpp v60, v52 row_ror:8 row_mask:0xf bank_mask:0xf
	v_mov_b32_dpp v61, v53 row_ror:8 row_mask:0xf bank_mask:0xf
	v_cndmask_b32_e64 v51, v62, v51, s[6:7]
	v_cndmask_b32_e64 v52, v63, v52, s[6:7]
	v_cndmask_b32_e64 v53, v64, v53, s[6:7]
	global_store_dwordx4 v[34:35], v[50:53], off
	v_add_co_u32_e32 v34, vcc, s73, v34
	v_cndmask_b32_e64 v56, v56, v60, s[6:7]
	v_cndmask_b32_e64 v57, v57, v61, s[6:7]
	v_addc_co_u32_e32 v35, vcc, 0, v35, vcc
	global_store_dwordx4 v[34:35], v[54:57], off
	s_and_saveexec_b64 s[44:45], s[8:9]
	s_cbranch_execz .LBB0_658
	v_ashrrev_i32_e32 v49, 31, v48
	s_waitcnt lgkmcnt(0)
	v_add_f32_e32 v34, v32, v33
	v_lshl_add_u64 v[32:33], v[48:49], 2, s[12:13]
	global_atomic_add_f32 v[32:33], v34, off
; __device__ __forceinline__ unsigned cvt_pk_bf16(float lo, float hi) { unsigned r; asm volatile("v_cvt_pk_bf16_f32 %0, %1, %2" : "=v"(r) : "v"(lo), "v"(hi)); return r; }
; __device__ __forceinline__ unsigned dpp_ror8(unsigned x) { return (unsigned)__builtin_amdgcn_update_dpp(0, (int)x, 0x128, 0xf, 0xf, false); }
; __device__ __forceinline__ void store_pair_lines(bf16_t* O, int ldc, int row, int fr, int col0, u32x4 wA, u32x4 wB) {
;     const u32x4 sA = {dpp_ror8(wA.x), dpp_ror8(wA.y), dpp_ror8(wA.z), dpp_ror8(wA.w)}, sB = {dpp_ror8(wB.x), dpp_ror8(wB.y), dpp_ror8(wB.z), dpp_ror8(wB.w)};
;     const bool lo = fr < 8;
;     const u32x4 o1 = lo ? wA : sB, o2 = lo ? sA : wB;
;     const int r1 = row - fr + (fr & 7), cb = col0 + (lo ? 0 : 8);
;     *(u32x4*)(O + (size_t)r1 * ldc + cb) = o1;
;     *(u32x4*)(O + (size_t)(r1 + 8) * ldc + cb) = o2;
; }
;     __device__ __forceinline__ void operator()(const f32x4 (&acc)[2][2][4][2], const Unit& u, int wr, int wc, int fr, int fq) const {
;     ...
;             for (int m = 0; m < 4; ++m) { const int row = row0 + ai * HALF + m * 16;
;                 const float rs = ssin ? __builtin_amdgcn_rsqf(ssin[row] * (1.f / D) + EPS) : 1.0f; float sq = 0.f; u32x4 w[2];
; #pragma unroll
;                 for (int bj = 0; bj < 2; ++bj) { f32x4 v0 = acc[ai][bj][m][0] * rs, v1 = acc[ai][bj][m][1] * rs;
;                     if (ACT == 1) {
; #pragma unroll
;                         for (int j = 0; j < 4; ++j) { const float a = fmaxf(v0[j], 0.f), b = fmaxf(v1[j], 0.f); v0[j] = a * a; v1[j] = b * b; } }
;                     sq += (v0[0] * v0[0] + v0[1] * v0[1]) + (v0[2] * v0[2] + v0[3] * v0[3]) + (v1[0] * v1[0] + v1[1] * v1[1]) + (v1[2] * v1[2] + v1[3] * v1[3]);
;                     w[bj].x = cvt_pk_bf16(v0[0], v0[1]); w[bj].y = cvt_pk_bf16(v0[2], v0[3]); w[bj].z = cvt_pk_bf16(v1[0], v1[1]); w[bj].w = cvt_pk_bf16(v1[2], v1[3]); }
;                 store_pair_lines(O, ldc, row, fr, col0, w[0], w[1]);
;                 if (ssout) { sq += __shfl_xor(sq, 16); sq += __shfl_xor(sq, 32); if (fq == 0) unsafeAtomicAdd(ssout + row, sq); } }
.LBB0_658:
	s_or_b64 exec, exec, s[44:45]
	s_waitcnt lgkmcnt(0)
	v_cvt_pk_bf16_f32 v33, v28, v29
	v_cvt_pk_bf16_f32 v35, v30, v31
	v_cvt_pk_bf16_f32 v36, v24, v25
	v_cvt_pk_bf16_f32 v37, v26, v27
	v_cvt_pk_bf16_f32 v38, v20, v21
	v_cvt_pk_bf16_f32 v39, v22, v23
	v_cvt_pk_bf16_f32 v40, v16, v17
	v_cvt_pk_bf16_f32 v41, v18, v19
	v_mul_f32_e32 v27, v27, v27
	v_mul_f32_e32 v19, v19, v19
	v_fmac_f32_e32 v27, v26, v26
	v_mul_f32_e32 v26, v29, v29
	v_fmac_f32_e32 v19, v18, v18
	v_mul_f32_e32 v18, v21, v21
	v_fmac_f32_e32 v26, v28, v28
	v_mul_f32_e32 v28, v31, v31
	v_fmac_f32_e32 v18, v20, v20
	v_mul_f32_e32 v20, v23, v23
	v_fmac_f32_e32 v28, v30, v30
	v_mul_f32_e32 v25, v25, v25
	v_fmac_f32_e32 v20, v22, v22
	v_mul_f32_e32 v17, v17, v17
	v_add_f32_e32 v26, v26, v28
	v_fmac_f32_e32 v25, v24, v24
	v_add_f32_e32 v18, v18, v20
	v_fmac_f32_e32 v17, v16, v16
	v_add_f32_e32 v24, v26, v25
	v_add_f32_e32 v16, v18, v17
	v_add_f32_e32 v24, v27, v24
	v_add_f32_e32 v16, v19, v16
	v_add_u32_e32 v32, 0xa0, v144
	v_mov_b32_dpp v34, v38 row_ror:8 row_mask:0xf bank_mask:0xf
	v_add_f32_e32 v20, v24, v16
	v_mov_b32_dpp v42, v33 row_ror:8 row_mask:0xf bank_mask:0xf
	v_cndmask_b32_e64 v34, v34, v33, s[6:7]
	v_sub_u32_e32 v33, v32, v146
	v_mov_b32_e32 v21, v20
	s_nop 1
	v_permlane16_swap_b32_e32 v21, v20
	v_mov_b32_dpp v43, v35 row_ror:8 row_mask:0xf bank_mask:0xf
	v_cndmask_b32_e64 v38, v38, v42, s[6:7]
	v_add_u32_e32 v42, v33, v148
	v_mov_b32_dpp v46, v39 row_ror:8 row_mask:0xf bank_mask:0xf
	v_cndmask_b32_e64 v39, v39, v43, s[6:7]
	v_ashrrev_i32_e32 v43, 31, v42
	v_lshlrev_b64 v[16:17], 12, v[42:43]
	v_lshl_add_u64 v[16:17], s[10:11], 0, v[16:17]
	v_lshl_add_u64 v[18:19], v[142:143], 1, v[16:17]
	s_waitcnt lgkmcnt(0)
	v_add_f32_e32 v16, v20, v21
	v_mov_b32_e32 v17, v16
	s_nop 1
	v_permlane32_swap_b32_e32 v17, v16
	v_mov_b32_dpp v47, v40 row_ror:8 row_mask:0xf bank_mask:0xf
	v_mov_b32_dpp v48, v41 row_ror:8 row_mask:0xf bank_mask:0xf
	v_mov_b32_dpp v44, v36 row_ror:8 row_mask:0xf bank_mask:0xf
	v_mov_b32_dpp v45, v37 row_ror:8 row_mask:0xf bank_mask:0xf
	v_cndmask_b32_e64 v35, v46, v35, s[6:7]
	v_cndmask_b32_e64 v36, v47, v36, s[6:7]
	v_cndmask_b32_e64 v37, v48, v37, s[6:7]
	global_store_dwordx4 v[18:19], v[34:37], off
	v_add_co_u32_e32 v18, vcc, s73, v18
	v_cndmask_b32_e64 v40, v40, v44, s[6:7]
	v_cndmask_b32_e64 v41, v41, v45, s[6:7]
	v_addc_co_u32_e32 v19, vcc, 0, v19, vcc
	global_store_dwordx4 v[18:19], v[38:41], off
	s_and_saveexec_b64 s[44:45], s[8:9]
	s_cbranch_execz .LBB0_660
	v_ashrrev_i32_e32 v33, 31, v32
	s_waitcnt lgkmcnt(0)
	v_add_f32_e32 v18, v16, v17
	v_lshl_add_u64 v[16:17], v[32:33], 2, s[12:13]
	global_atomic_add_f32 v[16:17], v18, off
.LBB0_660:
	s_or_b64 exec, exec, s[44:45]
	s_waitcnt lgkmcnt(0)
	v_cvt_pk_bf16_f32 v17, v12, v13
	v_cvt_pk_bf16_f32 v19, v14, v15
	v_cvt_pk_bf16_f32 v20, v8, v9
	v_cvt_pk_bf16_f32 v21, v10, v11
	v_cvt_pk_bf16_f32 v22, v4, v5
	v_cvt_pk_bf16_f32 v23, v6, v7
	v_cvt_pk_bf16_f32 v24, v0, v1
	v_cvt_pk_bf16_f32 v25, v2, v3
	v_mul_f32_e32 v11, v11, v11
	v_mul_f32_e32 v3, v3, v3
	v_fmac_f32_e32 v11, v10, v10
	v_mul_f32_e32 v10, v13, v13
	v_fmac_f32_e32 v3, v2, v2
	v_mul_f32_e32 v2, v5, v5
	v_fmac_f32_e32 v10, v12, v12
	v_mul_f32_e32 v12, v15, v15
	v_fmac_f32_e32 v2, v4, v4
	v_mul_f32_e32 v4, v7, v7
	v_fmac_f32_e32 v12, v14, v14
	v_mul_f32_e32 v9, v9, v9
	v_fmac_f32_e32 v4, v6, v6
	v_mul_f32_e32 v1, v1, v1
	v_add_f32_e32 v10, v10, v12
	v_fmac_f32_e32 v9, v8, v8
	v_add_f32_e32 v2, v2, v4
	v_fmac_f32_e32 v1, v0, v0
	v_add_f32_e32 v8, v10, v9
	v_add_f32_e32 v0, v2, v1
	v_add_f32_e32 v8, v11, v8
	v_add_f32_e32 v0, v3, v0
	v_add_u32_e32 v16, 0xb0, v144
	v_mov_b32_dpp v18, v22 row_ror:8 row_mask:0xf bank_mask:0xf
	v_add_f32_e32 v4, v8, v0
	v_mov_b32_dpp v26, v17 row_ror:8 row_mask:0xf bank_mask:0xf
	v_cndmask_b32_e64 v18, v18, v17, s[6:7]
	v_sub_u32_e32 v17, v16, v146
	v_mov_b32_e32 v5, v4
	s_nop 1
	v_permlane16_swap_b32_e32 v5, v4
	v_mov_b32_dpp v27, v19 row_ror:8 row_mask:0xf bank_mask:0xf
	v_cndmask_b32_e64 v22, v22, v26, s[6:7]
	v_add_u32_e32 v26, v17, v148
	v_mov_b32_dpp v30, v23 row_ror:8 row_mask:0xf bank_mask:0xf
	v_cndmask_b32_e64 v23, v23, v27, s[6:7]
	v_ashrrev_i32_e32 v27, 31, v26
	v_lshlrev_b64 v[0:1], 12, v[26:27]
	v_lshl_add_u64 v[0:1], s[10:11], 0, v[0:1]
	v_lshl_add_u64 v[2:3], v[142:143], 1, v[0:1]
	s_waitcnt lgkmcnt(0)
	v_add_f32_e32 v0, v4, v5
	v_mov_b32_e32 v1, v0
	s_nop 1
	v_permlane32_swap_b32_e32 v1, v0
	v_mov_b32_dpp v31, v24 row_ror:8 row_mask:0xf bank_mask:0xf
	v_mov_b32_dpp v32, v25 row_ror:8 row_mask:0xf bank_mask:0xf
	v_mov_b32_dpp v28, v20 row_ror:8 row_mask:0xf bank_mask:0xf
	v_mov_b32_dpp v29, v21 row_ror:8 row_mask:0xf bank_mask:0xf
	v_cndmask_b32_e64 v19, v30, v19, s[6:7]
	v_cndmask_b32_e64 v20, v31, v20, s[6:7]
	v_cndmask_b32_e64 v21, v32, v21, s[6:7]
	global_store_dwordx4 v[2:3], v[18:21], off
	v_add_co_u32_e32 v2, vcc, s73, v2
	v_cndmask_b32_e64 v24, v24, v28, s[6:7]
	v_cndmask_b32_e64 v25, v25, v29, s[6:7]
	v_addc_co_u32_e32 v3, vcc, 0, v3, vcc
	global_store_dwordx4 v[2:3], v[22:25], off
	s_and_saveexec_b64 s[44:45], s[8:9]
	s_cbranch_execz .LBB0_639
	v_ashrrev_i32_e32 v17, 31, v16
	s_waitcnt lgkmcnt(0)
	v_add_f32_e32 v2, v0, v1
	v_lshl_add_u64 v[0:1], v[16:17], 2, s[12:13]
	global_atomic_add_f32 v[0:1], v2, off
	s_branch .LBB0_639

; #define PG8_STAGE(bufoff, gbase, voff) do { _Pragma("unroll") for (int _i = 0; _i < 2; ++_i) \
;         __builtin_amdgcn_global_load_lds((const unsigned*)((const char*)(gbase) + (voff)[_i]), (LAS unsigned*)(lds + (bufoff) + ldsw + _i * 8192), 16, 0, 0); } while (0)
; #define PG8_LDA(dst, b, h) do { _Pragma("unroll") for (int m = 0; m < 4; ++m) _Pragma("unroll") for (int k = 0; k < 2; ++k) dst[m][k] = *(const LAS bf16x8*)(lds + PG8_SA(b, h) + aoff + m * 2048 + k * 1024); } while (0)
; #define PG8_LDB(dst, b, h) do { _Pragma("unroll") for (int n = 0; n < 2; ++n) _Pragma("unroll") for (int k = 0; k < 2; ++k) dst[n][k] = *(const LAS bf16x8*)(lds + PG8_SB(b, h) + boff + n * 2048 + k * 1024); } while (0)
; #define PG8_MMA(ai, bj, At, Bt) do { __builtin_amdgcn_s_setprio(1); _Pragma("unroll") for (int m = 0; m < 4; ++m) _Pragma("unroll") for (int n = 0; n < 2; ++n) _Pragma("unroll") for (int k = 0; k < 2; ++k) \
;         acc[ai][bj][m][n] = __builtin_amdgcn_mfma_f32_16x16x32_bf16(Bt[n][k], At[m][k], acc[ai][bj][m][n], 0, 0, 0); __builtin_amdgcn_s_setprio(0); } while (0)
; #define PG8_WAIT_V(n) asm volatile("s_waitcnt vmcnt(" #n ")" ::: "memory")
; #define PG8_WAIT_L(n) asm volatile("s_waitcnt lgkmcnt(" #n ")" ::: "memory")
; #define PG8_BAR __builtin_amdgcn_s_barrier()
; #define PG8_SCHED __builtin_amdgcn_sched_barrier(0)
; template <class Epi>
; __device__ __forceinline__ void gemm_phase(LAS unsigned char* lds, const Gemm g, const StaticOrder& S, const Epi& E) {
;     ...
;             PG8_LDB(B0, 0, 0); PG8_SCHED; PG8_LDA(At, 0, 0); PG8_STAGE(PG8_SA(1, 1), a1 + hstep, voffA);
;             PG8_WAIT_L(8); PG8_BAR; PG8_WAIT_L(0); PG8_MMA(0, 0, At, B0); PG8_BAR; PG8_SCHED;
;             PG8_LDB(B1, 0, 1); PG8_STAGE(PG8_SB(0, 0), b2, voffB0);
;             PG8_BAR; PG8_WAIT_L(0); PG8_MMA(0, 1, At, B1); PG8_BAR;
;             PG8_LDA(At, 0, 1); PG8_STAGE(PG8_SA(0, 0), a2, voffA);
;             PG8_BAR; PG8_WAIT_L(0); PG8_MMA(1, 0, At, B0); PG8_BAR; PG8_SCHED;
;             PG8_STAGE(PG8_SB(0, 1), b2, voffB1);
;             PG8_WAIT_V(6); PG8_BAR; PG8_MMA(1, 1, At, B1); PG8_BAR;
.LBB0_882:
	ds_read_b128 v[32:35], v177
	ds_read_b128 v[40:43], v177 offset:1024
	ds_read_b128 v[48:51], v177 offset:2048
	ds_read_b128 v[52:55], v177 offset:3072
	s_add_u32 s33, s60, 0xfff80080
	s_addc_u32 s62, s61, -1
	s_cmp_eq_u32 s86, 28
	s_cselect_b32 s63, s49, s62
	s_cselect_b32 s62, s57, s33
	s_cselect_b32 s65, s47, s85
	s_cselect_b32 s64, s83, s84
	v_lshl_add_u64 v[170:171], s[60:61], 0, v[156:157]
	s_add_i32 m0, s59, 0xc000
	ds_read_b128 v[162:165], v178
	ds_read_b128 v[166:169], v178 offset:1024
	ds_read_b128 v[182:185], v178 offset:2048
	ds_read_b128 v[186:189], v178 offset:3072
	ds_read_b128 v[190:193], v178 offset:4096
	ds_read_b128 v[194:197], v178 offset:5120
	ds_read_b128 v[198:201], v178 offset:6144
	ds_read_b128 v[204:207], v178 offset:7168
	global_load_lds_dwordx4 v[170:171], off
	v_lshl_add_u64 v[170:171], s[60:61], 0, v[158:159]
	s_add_i32 m0, s59, 0xe000
	s_nop 0
	global_load_lds_dwordx4 v[170:171], off
	s_waitcnt lgkmcnt(8)
	s_barrier
	s_waitcnt lgkmcnt(0)
	v_mfma_f32_16x16x32_bf16 v[140:143], v[32:35], v[162:165], v[140:143]
	v_mfma_f32_16x16x32_bf16 v[136:139], v[48:51], v[162:165], v[136:139]
	v_mfma_f32_16x16x32_bf16 v[124:127], v[32:35], v[182:185], v[124:127]
	v_mfma_f32_16x16x32_bf16 v[120:123], v[48:51], v[182:185], v[120:123]
	v_mfma_f32_16x16x32_bf16 v[108:111], v[32:35], v[190:193], v[108:111]
	v_mfma_f32_16x16x32_bf16 v[104:107], v[48:51], v[190:193], v[104:107]
	v_mfma_f32_16x16x32_bf16 v[92:95], v[32:35], v[198:201], v[92:95]
	v_mfma_f32_16x16x32_bf16 v[88:91], v[48:51], v[198:201], v[88:91]
	v_mfma_f32_16x16x32_bf16 v[140:143], v[40:43], v[166:169], v[140:143]
	v_mfma_f32_16x16x32_bf16 v[136:139], v[52:55], v[166:169], v[136:139]
	v_mfma_f32_16x16x32_bf16 v[124:127], v[40:43], v[186:189], v[124:127]
	v_mfma_f32_16x16x32_bf16 v[120:123], v[52:55], v[186:189], v[120:123]
	v_mfma_f32_16x16x32_bf16 v[108:111], v[40:43], v[194:197], v[108:111]
	v_mfma_f32_16x16x32_bf16 v[104:107], v[52:55], v[194:197], v[104:107]
	v_mfma_f32_16x16x32_bf16 v[92:95], v[40:43], v[204:207], v[92:95]
	v_mfma_f32_16x16x32_bf16 v[88:91], v[52:55], v[204:207], v[88:91]
	s_barrier
	s_add_i32 s33, s81, s69
	v_lshl_add_u64 v[170:171], s[64:65], 0, v[146:147]
	s_mov_b32 m0, s33
	ds_read_b128 v[208:211], v179
	ds_read_b128 v[212:215], v179 offset:1024
	ds_read_b128 v[216:219], v179 offset:2048
	ds_read_b128 v[220:223], v179 offset:3072
	global_load_lds_dwordx4 v[170:171], off
	v_lshl_add_u64 v[224:225], s[64:65], 0, v[152:153]
	s_add_i32 m0, s33, 0x2000
	s_nop 0
	global_load_lds_dwordx4 v[224:225], off
	s_barrier
	s_waitcnt lgkmcnt(0)
	v_mfma_f32_16x16x32_bf16 v[132:135], v[208:211], v[162:165], v[132:135]
	v_mfma_f32_16x16x32_bf16 v[128:131], v[216:219], v[162:165], v[128:131]
	v_mfma_f32_16x16x32_bf16 v[116:119], v[208:211], v[182:185], v[116:119]
	v_mfma_f32_16x16x32_bf16 v[112:115], v[216:219], v[182:185], v[112:115]
	v_mfma_f32_16x16x32_bf16 v[100:103], v[208:211], v[190:193], v[100:103]
	v_mfma_f32_16x16x32_bf16 v[96:99], v[216:219], v[190:193], v[96:99]
	v_mfma_f32_16x16x32_bf16 v[84:87], v[208:211], v[198:201], v[84:87]
	v_mfma_f32_16x16x32_bf16 v[80:83], v[216:219], v[198:201], v[80:83]
	v_mfma_f32_16x16x32_bf16 v[132:135], v[212:215], v[166:169], v[132:135]
	v_mfma_f32_16x16x32_bf16 v[128:131], v[220:223], v[166:169], v[128:131]
	v_mfma_f32_16x16x32_bf16 v[116:119], v[212:215], v[186:189], v[116:119]
	v_mfma_f32_16x16x32_bf16 v[112:115], v[220:223], v[186:189], v[112:115]
	v_mfma_f32_16x16x32_bf16 v[100:103], v[212:215], v[194:197], v[100:103]
	v_mfma_f32_16x16x32_bf16 v[96:99], v[220:223], v[194:197], v[96:99]
	v_mfma_f32_16x16x32_bf16 v[84:87], v[212:215], v[204:207], v[84:87]
	v_mfma_f32_16x16x32_bf16 v[80:83], v[220:223], v[204:207], v[80:83]
	s_mov_b32 m0, s59
	v_lshl_add_u64 v[226:227], s[62:63], 0, v[144:145]
	s_barrier
	ds_read_b128 v[162:165], v178 offset:16384
	ds_read_b128 v[166:169], v178 offset:17408
	ds_read_b128 v[182:185], v178 offset:18432
	ds_read_b128 v[186:189], v178 offset:19456
	ds_read_b128 v[190:193], v178 offset:20480
	ds_read_b128 v[194:197], v178 offset:21504
	ds_read_b128 v[198:201], v178 offset:22528
	ds_read_b128 v[204:207], v178 offset:23552
	global_load_lds_dwordx4 v[226:227], off
	v_lshl_add_u64 v[228:229], s[62:63], 0, v[150:151]
	s_mov_b32 m0, s70
	s_nop 0
	global_load_lds_dwordx4 v[228:229], off
	s_barrier
	s_waitcnt lgkmcnt(0)
	v_mfma_f32_16x16x32_bf16 v[76:79], v[32:35], v[162:165], v[76:79]
	v_mfma_f32_16x16x32_bf16 v[72:75], v[48:51], v[162:165], v[72:75]
	v_mfma_f32_16x16x32_bf16 v[60:63], v[32:35], v[182:185], v[60:63]
	v_mfma_f32_16x16x32_bf16 v[56:59], v[48:51], v[182:185], v[56:59]
	v_mfma_f32_16x16x32_bf16 v[28:31], v[32:35], v[190:193], v[28:31]
	v_mfma_f32_16x16x32_bf16 v[24:27], v[48:51], v[190:193], v[24:27]
	v_mfma_f32_16x16x32_bf16 v[12:15], v[32:35], v[198:201], v[12:15]
	v_mfma_f32_16x16x32_bf16 v[8:11], v[48:51], v[198:201], v[8:11]
	v_mfma_f32_16x16x32_bf16 v[76:79], v[40:43], v[166:169], v[76:79]
	v_mfma_f32_16x16x32_bf16 v[72:75], v[52:55], v[166:169], v[72:75]
	v_mfma_f32_16x16x32_bf16 v[60:63], v[40:43], v[186:189], v[60:63]
	v_mfma_f32_16x16x32_bf16 v[56:59], v[52:55], v[186:189], v[56:59]
	v_mfma_f32_16x16x32_bf16 v[28:31], v[40:43], v[194:197], v[28:31]
	v_mfma_f32_16x16x32_bf16 v[24:27], v[52:55], v[194:197], v[24:27]
	v_mfma_f32_16x16x32_bf16 v[12:15], v[40:43], v[204:207], v[12:15]
	v_mfma_f32_16x16x32_bf16 v[8:11], v[52:55], v[204:207], v[8:11]
	s_barrier
	s_add_i32 s33, s82, s69
	v_lshl_add_u64 v[230:231], s[64:65], 0, v[148:149]
	s_mov_b32 m0, s33
	v_lshl_add_u64 v[232:233], s[64:65], 0, v[154:155]
	global_load_lds_dwordx4 v[230:231], off
	s_add_i32 m0, s33, 0x2000
	s_nop 0
	global_load_lds_dwordx4 v[232:233], off
	s_waitcnt vmcnt(6)
	s_barrier
; #define PG8_STAGE(bufoff, gbase, voff) do { _Pragma("unroll") for (int _i = 0; _i < 2; ++_i) \
;         __builtin_amdgcn_global_load_lds((const unsigned*)((const char*)(gbase) + (voff)[_i]), (LAS unsigned*)(lds + (bufoff) + ldsw + _i * 8192), 16, 0, 0); } while (0)
; #define PG8_LDA(dst, b, h) do { _Pragma("unroll") for (int m = 0; m < 4; ++m) _Pragma("unroll") for (int k = 0; k < 2; ++k) dst[m][k] = *(const LAS bf16x8*)(lds + PG8_SA(b, h) + aoff + m * 2048 + k * 1024); } while (0)
; #define PG8_LDB(dst, b, h) do { _Pragma("unroll") for (int n = 0; n < 2; ++n) _Pragma("unroll") for (int k = 0; k < 2; ++k) dst[n][k] = *(const LAS bf16x8*)(lds + PG8_SB(b, h) + boff + n * 2048 + k * 1024); } while (0)
; #define PG8_MMA(ai, bj, At, Bt) do { __builtin_amdgcn_s_setprio(1); _Pragma("unroll") for (int m = 0; m < 4; ++m) _Pragma("unroll") for (int n = 0; n < 2; ++n) _Pragma("unroll") for (int k = 0; k < 2; ++k) \
;         acc[ai][bj][m][n] = __builtin_amdgcn_mfma_f32_16x16x32_bf16(Bt[n][k], At[m][k], acc[ai][bj][m][n], 0, 0, 0); __builtin_amdgcn_s_setprio(0); } while (0)
; #define PG8_WAIT_V(n) asm volatile("s_waitcnt vmcnt(" #n ")" ::: "memory")
; #define PG8_WAIT_L(n) asm volatile("s_waitcnt lgkmcnt(" #n ")" ::: "memory")
; #define PG8_BAR __builtin_amdgcn_s_barrier()
; #define PG8_SCHED __builtin_amdgcn_sched_barrier(0)
; template <class Epi>
; __device__ __forceinline__ void gemm_phase(LAS unsigned char* lds, const Gemm g, const StaticOrder& S, const Epi& E) {
;     ...
;             PG8_WAIT_V(6); PG8_BAR; PG8_MMA(1, 1, At, B1); PG8_BAR;
;             PG8_LDB(B0, 1, 0); PG8_SCHED; PG8_LDA(At, 1, 0); PG8_STAGE(PG8_SA(0, 1), a2 + hstep, voffA);
;             PG8_WAIT_L(8); PG8_BAR; PG8_WAIT_L(0); PG8_MMA(0, 0, At, B0); PG8_BAR; PG8_SCHED;
;             PG8_LDB(B1, 1, 1); PG8_STAGE(PG8_SB(1, 0), b3, voffB0);
;             PG8_BAR; PG8_WAIT_L(0); PG8_MMA(0, 1, At, B1); PG8_BAR;
;             PG8_LDA(At, 1, 1); PG8_STAGE(PG8_SA(1, 0), a3, voffA);
;             PG8_BAR; PG8_WAIT_L(0); PG8_MMA(1, 0, At, B0); PG8_BAR; PG8_SCHED;
	v_mfma_f32_16x16x32_bf16 v[44:47], v[208:211], v[182:185], v[44:47]
	v_mfma_f32_16x16x32_bf16 v[36:39], v[216:219], v[182:185], v[36:39]
	v_mfma_f32_16x16x32_bf16 v[20:23], v[208:211], v[190:193], v[20:23]
	v_mfma_f32_16x16x32_bf16 v[16:19], v[216:219], v[190:193], v[16:19]
	v_mfma_f32_16x16x32_bf16 v[4:7], v[208:211], v[198:201], v[4:7]
	v_mfma_f32_16x16x32_bf16 v[0:3], v[216:219], v[198:201], v[0:3]
	v_mfma_f32_16x16x32_bf16 v[32:35], v[208:211], v[162:165], v[68:71]
	v_mfma_f32_16x16x32_bf16 v[40:43], v[216:219], v[162:165], v[64:67]
	v_mfma_f32_16x16x32_bf16 v[44:47], v[212:215], v[186:189], v[44:47]
	v_mfma_f32_16x16x32_bf16 v[36:39], v[220:223], v[186:189], v[36:39]
	v_mfma_f32_16x16x32_bf16 v[20:23], v[212:215], v[194:197], v[20:23]
	v_mfma_f32_16x16x32_bf16 v[16:19], v[220:223], v[194:197], v[16:19]
	v_mfma_f32_16x16x32_bf16 v[4:7], v[212:215], v[204:207], v[4:7]
	v_mfma_f32_16x16x32_bf16 v[0:3], v[220:223], v[204:207], v[0:3]
	v_mfma_f32_16x16x32_bf16 v[32:35], v[212:215], v[166:169], v[32:35]
	v_mfma_f32_16x16x32_bf16 v[40:43], v[220:223], v[166:169], v[40:43]
	s_add_i32 s33, 0, 0x18000
	v_add_u32_e32 v68, s33, v173
	s_barrier
	ds_read_b128 v[48:51], v68
	ds_read_b128 v[52:55], v68 offset:1024
	ds_read_b128 v[64:67], v68 offset:2048
	ds_read_b128 v[68:71], v68 offset:3072
	s_add_u32 s62, s62, 0x80000
	s_addc_u32 s63, s63, 0
	s_mov_b32 m0, s71
	v_lshl_add_u64 v[208:209], s[62:63], 0, v[144:145]
	ds_read_b128 v[162:165], v178 offset:32768
	ds_read_b128 v[166:169], v178 offset:33792
	ds_read_b128 v[182:185], v178 offset:34816
	ds_read_b128 v[186:189], v178 offset:35840
	ds_read_b128 v[190:193], v178 offset:36864
	ds_read_b128 v[194:197], v178 offset:37888
	ds_read_b128 v[198:201], v178 offset:38912
	ds_read_b128 v[204:207], v178 offset:39936
	global_load_lds_dwordx4 v[208:209], off
	v_lshl_add_u64 v[208:209], s[62:63], 0, v[150:151]
	s_mov_b32 m0, s72
	s_nop 0
	global_load_lds_dwordx4 v[208:209], off
	s_waitcnt lgkmcnt(8)
	s_barrier
	s_waitcnt lgkmcnt(0)
	v_mfma_f32_16x16x32_bf16 v[140:143], v[48:51], v[162:165], v[140:143]
	v_mfma_f32_16x16x32_bf16 v[136:139], v[64:67], v[162:165], v[136:139]
	v_mfma_f32_16x16x32_bf16 v[124:127], v[48:51], v[182:185], v[124:127]
	v_mfma_f32_16x16x32_bf16 v[120:123], v[64:67], v[182:185], v[120:123]
	v_mfma_f32_16x16x32_bf16 v[108:111], v[48:51], v[190:193], v[108:111]
	v_mfma_f32_16x16x32_bf16 v[104:107], v[64:67], v[190:193], v[104:107]
	v_mfma_f32_16x16x32_bf16 v[92:95], v[48:51], v[198:201], v[92:95]
	v_mfma_f32_16x16x32_bf16 v[88:91], v[64:67], v[198:201], v[88:91]
	v_mfma_f32_16x16x32_bf16 v[140:143], v[52:55], v[166:169], v[140:143]
	v_mfma_f32_16x16x32_bf16 v[136:139], v[68:71], v[166:169], v[136:139]
	v_mfma_f32_16x16x32_bf16 v[124:127], v[52:55], v[186:189], v[124:127]
	v_mfma_f32_16x16x32_bf16 v[120:123], v[68:71], v[186:189], v[120:123]
	v_mfma_f32_16x16x32_bf16 v[108:111], v[52:55], v[194:197], v[108:111]
	v_mfma_f32_16x16x32_bf16 v[104:107], v[68:71], v[194:197], v[104:107]
	v_mfma_f32_16x16x32_bf16 v[92:95], v[52:55], v[204:207], v[92:95]
	v_mfma_f32_16x16x32_bf16 v[88:91], v[68:71], v[204:207], v[88:91]
	s_barrier
	s_add_i32 s62, 0, 0x1c000
	s_add_i32 s33, s33, s69
	v_add_u32_e32 v181, s62, v173
	v_lshl_add_u64 v[170:171], v[170:171], 0, s[42:43]
	s_mov_b32 m0, s33
	ds_read_b128 v[208:211], v181
	ds_read_b128 v[212:215], v181 offset:1024
	ds_read_b128 v[216:219], v181 offset:2048
	ds_read_b128 v[220:223], v181 offset:3072
	global_load_lds_dwordx4 v[170:171], off
	v_lshl_add_u64 v[170:171], v[224:225], 0, s[42:43]
	s_add_i32 m0, s33, 0x2000
	s_nop 0
	global_load_lds_dwordx4 v[170:171], off
	s_barrier
	s_waitcnt lgkmcnt(0)
	v_mfma_f32_16x16x32_bf16 v[132:135], v[208:211], v[162:165], v[132:135]
	v_mfma_f32_16x16x32_bf16 v[128:131], v[216:219], v[162:165], v[128:131]
	v_mfma_f32_16x16x32_bf16 v[116:119], v[208:211], v[182:185], v[116:119]
	v_mfma_f32_16x16x32_bf16 v[112:115], v[216:219], v[182:185], v[112:115]
	v_mfma_f32_16x16x32_bf16 v[100:103], v[208:211], v[190:193], v[100:103]
	v_mfma_f32_16x16x32_bf16 v[96:99], v[216:219], v[190:193], v[96:99]
	v_mfma_f32_16x16x32_bf16 v[84:87], v[208:211], v[198:201], v[84:87]
	v_mfma_f32_16x16x32_bf16 v[80:83], v[216:219], v[198:201], v[80:83]
	v_mfma_f32_16x16x32_bf16 v[132:135], v[212:215], v[166:169], v[132:135]
	v_mfma_f32_16x16x32_bf16 v[128:131], v[220:223], v[166:169], v[128:131]
	v_mfma_f32_16x16x32_bf16 v[116:119], v[212:215], v[186:189], v[116:119]
	v_mfma_f32_16x16x32_bf16 v[112:115], v[220:223], v[186:189], v[112:115]
	v_mfma_f32_16x16x32_bf16 v[100:103], v[212:215], v[194:197], v[100:103]
	v_mfma_f32_16x16x32_bf16 v[96:99], v[220:223], v[194:197], v[96:99]
	v_mfma_f32_16x16x32_bf16 v[84:87], v[212:215], v[204:207], v[84:87]
	v_mfma_f32_16x16x32_bf16 v[80:83], v[220:223], v[204:207], v[80:83]
	s_mov_b32 m0, s74
	v_lshl_add_u64 v[170:171], v[226:227], 0, s[42:43]
	s_barrier
	ds_read_b128 v[162:165], v178 offset:49152
	ds_read_b128 v[166:169], v178 offset:50176
	ds_read_b128 v[182:185], v178 offset:51200
	ds_read_b128 v[186:189], v178 offset:52224
	ds_read_b128 v[190:193], v178 offset:53248
	ds_read_b128 v[194:197], v178 offset:54272
	ds_read_b128 v[198:201], v178 offset:55296
	ds_read_b128 v[204:207], v178 offset:56320
	global_load_lds_dwordx4 v[170:171], off
	v_lshl_add_u64 v[170:171], v[228:229], 0, s[42:43]
	s_mov_b32 m0, s75
	s_nop 0
	global_load_lds_dwordx4 v[170:171], off
	s_barrier
; #define PG8_STAGE(bufoff, gbase, voff) do { _Pragma("unroll") for (int _i = 0; _i < 2; ++_i) \
;         __builtin_amdgcn_global_load_lds((const unsigned*)((const char*)(gbase) + (voff)[_i]), (LAS unsigned*)(lds + (bufoff) + ldsw + _i * 8192), 16, 0, 0); } while (0)
; #define PG8_MMA(ai, bj, At, Bt) do { __builtin_amdgcn_s_setprio(1); _Pragma("unroll") for (int m = 0; m < 4; ++m) _Pragma("unroll") for (int n = 0; n < 2; ++n) _Pragma("unroll") for (int k = 0; k < 2; ++k) \
;         acc[ai][bj][m][n] = __builtin_amdgcn_mfma_f32_16x16x32_bf16(Bt[n][k], At[m][k], acc[ai][bj][m][n], 0, 0, 0); __builtin_amdgcn_s_setprio(0); } while (0)
; #define PG8_WAIT_V(n) asm volatile("s_waitcnt vmcnt(" #n ")" ::: "memory")
; #define PG8_WAIT_L(n) asm volatile("s_waitcnt lgkmcnt(" #n ")" ::: "memory")
; #define PG8_BAR __builtin_amdgcn_s_barrier()
; #define PG8_SCHED __builtin_amdgcn_sched_barrier(0)
;     __device__ __forceinline__ void operator()(const f32x4 (&acc)[2][2][4][2], const Unit& u, int wr, int wc, int fr, int fq) const {
;         const int row0 = u.pm * BM + wr * 64 + fr, col0 = u.pn * BM + wc * 64 + 16 * fq;
;         f32x4 gv[2][2];
; #pragma unroll
;         for (int bj = 0; bj < 2; ++bj) { gv[bj][0] = *(const f32x4*)(g + col0 + 8 * bj); gv[bj][1] = *(const f32x4*)(g + col0 + 8 * bj + 4); }
; #pragma unroll
;         for (int ai = 0; ai < 2; ++ai)
; #pragma unroll
;             for (int m = 0; m < 4; ++m) { const int row = row0 + ai * HALF + m * 16; const size_t off = (size_t)row * D + col0; const float ri = __builtin_amdgcn_rsqf(sse[row] * (1.f / D) + EPS); float sq = 0.f; u32x4 w[2];
;                 u32x4 rr[2], ee[2]; load_pair_lines(R, D, row, fr, col0, rr[0], rr[1]); load_pair_lines(E, D, row, fr, col0, ee[0], ee[1]);
; template <class Epi>
; __device__ __forceinline__ void gemm_phase(LAS unsigned char* lds, const Gemm g, const StaticOrder& S, const Epi& E) {
;     ...
;             PG8_BAR; PG8_WAIT_L(0); PG8_MMA(1, 0, At, B0); PG8_BAR; PG8_SCHED;
;             PG8_STAGE(PG8_SB(1, 1), b3, voffB1);
;             PG8_WAIT_V(6); PG8_BAR; PG8_MMA(1, 1, At, B1); PG8_BAR;
	s_waitcnt lgkmcnt(0)
	v_mfma_f32_16x16x32_bf16 v[76:79], v[48:51], v[162:165], v[76:79]
	v_mfma_f32_16x16x32_bf16 v[72:75], v[64:67], v[162:165], v[72:75]
	v_mfma_f32_16x16x32_bf16 v[60:63], v[48:51], v[182:185], v[60:63]
	v_mfma_f32_16x16x32_bf16 v[56:59], v[64:67], v[182:185], v[56:59]
	v_mfma_f32_16x16x32_bf16 v[28:31], v[48:51], v[190:193], v[28:31]
	v_mfma_f32_16x16x32_bf16 v[24:27], v[64:67], v[190:193], v[24:27]
	v_mfma_f32_16x16x32_bf16 v[12:15], v[48:51], v[198:201], v[12:15]
	v_mfma_f32_16x16x32_bf16 v[8:11], v[64:67], v[198:201], v[8:11]
	v_mfma_f32_16x16x32_bf16 v[76:79], v[52:55], v[166:169], v[76:79]
	v_mfma_f32_16x16x32_bf16 v[72:75], v[68:71], v[166:169], v[72:75]
	v_mfma_f32_16x16x32_bf16 v[60:63], v[52:55], v[186:189], v[60:63]
	v_mfma_f32_16x16x32_bf16 v[56:59], v[68:71], v[186:189], v[56:59]
	v_mfma_f32_16x16x32_bf16 v[28:31], v[52:55], v[194:197], v[28:31]
	v_mfma_f32_16x16x32_bf16 v[24:27], v[68:71], v[194:197], v[24:27]
	v_mfma_f32_16x16x32_bf16 v[12:15], v[52:55], v[204:207], v[12:15]
	v_mfma_f32_16x16x32_bf16 v[8:11], v[68:71], v[204:207], v[8:11]
	s_barrier
	s_add_i32 s33, s62, s69
	v_lshl_add_u64 v[48:49], v[230:231], 0, s[42:43]
	s_mov_b32 m0, s33
	s_nop 0
	global_load_lds_dwordx4 v[48:49], off
	v_lshl_add_u64 v[48:49], v[232:233], 0, s[42:43]
	s_add_i32 m0, s33, 0x2000
	s_nop 0
	global_load_lds_dwordx4 v[48:49], off
	s_waitcnt vmcnt(6)
	s_barrier
	v_mfma_f32_16x16x32_bf16 v[32:35], v[208:211], v[162:165], v[32:35]
	v_mfma_f32_16x16x32_bf16 v[68:71], v[212:215], v[166:169], v[32:35]
	v_mfma_f32_16x16x32_bf16 v[32:35], v[216:219], v[162:165], v[40:43]
	v_mfma_f32_16x16x32_bf16 v[64:67], v[220:223], v[166:169], v[32:35]
	v_mfma_f32_16x16x32_bf16 v[32:35], v[208:211], v[182:185], v[44:47]
	v_mfma_f32_16x16x32_bf16 v[44:47], v[212:215], v[186:189], v[32:35]
	v_mfma_f32_16x16x32_bf16 v[32:35], v[216:219], v[182:185], v[36:39]
	v_mfma_f32_16x16x32_bf16 v[20:23], v[208:211], v[190:193], v[20:23]
	v_mfma_f32_16x16x32_bf16 v[16:19], v[216:219], v[190:193], v[16:19]
	v_mfma_f32_16x16x32_bf16 v[4:7], v[208:211], v[198:201], v[4:7]
	v_mfma_f32_16x16x32_bf16 v[0:3], v[216:219], v[198:201], v[0:3]
	v_mfma_f32_16x16x32_bf16 v[36:39], v[220:223], v[186:189], v[32:35]
	v_mfma_f32_16x16x32_bf16 v[20:23], v[212:215], v[194:197], v[20:23]
	v_mfma_f32_16x16x32_bf16 v[16:19], v[220:223], v[194:197], v[16:19]
	v_mfma_f32_16x16x32_bf16 v[4:7], v[212:215], v[204:207], v[4:7]
	v_mfma_f32_16x16x32_bf16 v[0:3], v[220:223], v[204:207], v[0:3]
	s_add_i32 s86, s86, 2
	s_add_u32 s60, s60, 0x100
	s_addc_u32 s61, s61, 0
	s_add_u32 s84, s84, 0x100
	s_addc_u32 s85, s85, 0
	s_cmp_gt_u32 s86, 29
	s_barrier
	s_cbranch_scc0 .LBB0_882
	s_lshl_b32 s33, s58, 8
	s_add_i32 s33, s33, s77
	v_lshl_or_b32 v32, s56, 8, v176
	v_or_b32_e32 v40, s33, v174
	v_or_b32_e32 v34, v32, v175
	v_ashrrev_i32_e32 v41, 31, v40
	v_ashrrev_i32_e32 v35, 31, v34
	v_lshlrev_b64 v[168:169], 12, v[40:41]
	v_lshl_add_u64 v[42:43], s[16:17], 0, v[168:169]
	v_lshlrev_b64 v[162:163], 1, v[34:35]
	v_lshl_add_u64 v[34:35], v[42:43], 0, v[162:163]
	global_load_dwordx4 v[182:185], v[34:35], off
	v_or_b32_e32 v34, 8, v40
	v_ashrrev_i32_e32 v35, 31, v34
	v_or_b32_e32 v164, s33, v172
	v_lshlrev_b64 v[170:171], 12, v[34:35]
	v_ashrrev_i32_e32 v165, 31, v164
	v_lshl_add_u64 v[34:35], s[16:17], 0, v[170:171]
	v_lshl_add_u64 v[166:167], v[164:165], 2, s[40:41]
	v_lshl_add_u64 v[34:35], v[34:35], 0, v[162:163]
	global_load_dword v181, v[166:167], off
	v_lshl_add_u64 v[40:41], s[38:39], 0, v[168:169]
	global_load_dwordx4 v[190:193], v[34:35], off
	v_lshl_add_u64 v[34:35], s[38:39], 0, v[170:171]
	v_lshl_add_u64 v[40:41], v[40:41], 0, v[162:163]
	v_lshl_add_u64 v[34:35], v[34:35], 0, v[162:163]
	global_load_dwordx4 v[186:189], v[40:41], off
	global_load_dwordx4 v[194:197], v[34:35], off
	v_ashrrev_i32_e32 v33, 31, v32
	v_lshl_add_u64 v[40:41], v[32:33], 2, s[10:11]
	global_load_dwordx4 v[52:55], v[40:41], off
	global_load_dwordx4 v[48:51], v[40:41], off offset:16
	global_load_dwordx4 v[32:35], v[40:41], off offset:48
	s_nop 0
	global_load_dwordx4 v[40:43], v[40:41], off offset:32
	v_or_b32_e32 v216, 16, v164
	v_ashrrev_i32_e32 v217, 31, v216
	v_lshl_add_u64 v[218:219], v[216:217], 2, s[40:41]
	global_load_dword v226, v[218:219], off
	v_sub_u32_e32 v218, v216, v172
	v_add_u32_e32 v218, v218, v174
	v_ashrrev_i32_e32 v219, 31, v218
	v_lshlrev_b64 v[218:219], 12, v[218:219]
	v_lshl_add_u64 v[220:221], s[16:17], 0, v[218:219]
	v_lshl_add_u64 v[220:221], v[220:221], 0, v[162:163]
	global_load_dwordx4 v[228:231], v[220:221], off
	v_lshl_add_u64 v[220:221], s[38:39], 0, v[218:219]
	v_lshl_add_u64 v[220:221], v[220:221], 0, v[162:163]
	global_load_dwordx4 v[232:235], v[220:221], off
	v_lshl_add_u64 v[220:221], v[218:219], 0, s[44:45]
	v_lshl_add_u64 v[224:225], s[38:39], 0, v[220:221]
	v_lshl_add_u64 v[222:223], s[16:17], 0, v[220:221]
	v_lshl_add_u64 v[224:225], v[224:225], 0, v[162:163]
	v_lshl_add_u64 v[222:223], v[222:223], 0, v[162:163]
	global_load_dwordx4 v[236:239], v[224:225], off
	global_load_dwordx4 v[240:243], v[222:223], off
	v_mul_f32_e32 v140, 0xbfb8aa3b, v140
	v_exp_f32_e32 v140, v140
	v_mul_f32_e32 v141, 0xbfb8aa3b, v141
	v_exp_f32_e32 v141, v141
	v_add_f32_e32 v140, 1.0, v140
	v_rcp_f32_e32 v140, v140
	v_add_f32_e32 v141, 1.0, v141
	v_rcp_f32_e32 v141, v141
	v_mul_f32_e32 v136, 0xbfb8aa3b, v136
	v_exp_f32_e32 v136, v136
	v_mul_f32_e32 v137, 0xbfb8aa3b, v137
	v_exp_f32_e32 v137, v137
	v_add_f32_e32 v136, 1.0, v136
	v_rcp_f32_e32 v136, v136
	v_add_f32_e32 v137, 1.0, v137
	v_mul_f32_e32 v132, 0xbfb8aa3b, v132
	v_rcp_f32_e32 v137, v137
	v_exp_f32_e32 v132, v132
	v_mul_f32_e32 v133, 0xbfb8aa3b, v133
	v_exp_f32_e32 v133, v133
	v_add_f32_e32 v132, 1.0, v132
	v_rcp_f32_e32 v132, v132
	v_add_f32_e32 v133, 1.0, v133
	v_rcp_f32_e32 v133, v133
	v_mul_f32_e32 v128, 0xbfb8aa3b, v128
	v_exp_f32_e32 v128, v128
	v_mul_f32_e32 v129, 0xbfb8aa3b, v129
	v_exp_f32_e32 v129, v129
	v_add_f32_e32 v128, 1.0, v128
	v_rcp_f32_e32 v128, v128
	v_add_f32_e32 v129, 1.0, v129
	v_rcp_f32_e32 v129, v129
	s_waitcnt vmcnt(5)
; __device__ __forceinline__ unsigned cvt_pk_bf16(float lo, float hi) { unsigned r; asm volatile("v_cvt_pk_bf16_f32 %0, %1, %2" : "=v"(r) : "v"(lo), "v"(hi)); return r; }
; __device__ __forceinline__ float bflo(unsigned w) { return __uint_as_float(w << 16); }
; __device__ __forceinline__ float bfhi(unsigned w) { return __uint_as_float(w & 0xffff0000u); }
;     __device__ __forceinline__ void operator()(const f32x4 (&acc)[2][2][4][2], const Unit& u, int wr, int wc, int fr, int fq) const {
;     ...
;             for (int m = 0; m < 4; ++m) { const int row = row0 + ai * HALF + m * 16; const size_t off = (size_t)row * D + col0; const float ri = __builtin_amdgcn_rsqf(sse[row] * (1.f / D) + EPS); float sq = 0.f; u32x4 w[2];
;                 u32x4 rr[2], ee[2]; load_pair_lines(R, D, row, fr, col0, rr[0], rr[1]); load_pair_lines(E, D, row, fr, col0, ee[0], ee[1]);
; #pragma unroll
;                 for (int bj = 0; bj < 2; ++bj) { const u32x4 rw = rr[bj], ew = ee[bj];
;                     const float r[8] = {bflo(rw.x), bfhi(rw.x), bflo(rw.y), bfhi(rw.y), bflo(rw.z), bfhi(rw.z), bflo(rw.w), bfhi(rw.w)};
;                     const float e[8] = {bflo(ew.x), bfhi(ew.x), bflo(ew.y), bfhi(ew.y), bflo(ew.z), bfhi(ew.z), bflo(ew.w), bfhi(ew.w)};
;                     float o[8];
; #pragma unroll
;                     for (int j = 0; j < 8; ++j) { const float a = acc[ai][bj][m][j >> 2][j & 3]; const float gg = gv[bj][j >> 2][j & 3];
;                         o[j] = r[j] + e[j] * ri * gg * __builtin_amdgcn_rcpf(1.f + __builtin_amdgcn_exp2f(-a * LOG2E)); }
;                     if (OUT) { *(f32x4*)(OUT + off + 8 * bj) = (f32x4){o[0], o[1], o[2], o[3]}; *(f32x4*)(OUT + off + 8 * bj + 4) = (f32x4){o[4], o[5], o[6], o[7]}; }
;                     else { sq += (o[0] * o[0] + o[1] * o[1]) + (o[2] * o[2] + o[3] * o[3]) + (o[4] * o[4] + o[5] * o[5]) + (o[6] * o[6] + o[7] * o[7]);
;                         w[bj].x = cvt_pk_bf16(o[0], o[1]); w[bj].y = cvt_pk_bf16(o[2], o[3]); w[bj].z = cvt_pk_bf16(o[4], o[5]); w[bj].w = cvt_pk_bf16(o[6], o[7]); } }
	v_mov_b32_dpp v198, v182 row_ror:8 row_mask:0xf bank_mask:0xf
	v_mov_b32_dpp v199, v183 row_ror:8 row_mask:0xf bank_mask:0xf
	v_mov_b32_dpp v200, v184 row_ror:8 row_mask:0xf bank_mask:0xf
	v_mov_b32_dpp v201, v185 row_ror:8 row_mask:0xf bank_mask:0xf
	v_fmamk_f32 v181, v181, 0x3a000000, v180
	v_rsq_f32_e32 v181, v181
	v_mov_b32_dpp v204, v190 row_ror:8 row_mask:0xf bank_mask:0xf
	v_cndmask_b32_e64 v182, v204, v182, s[6:7]
	v_cndmask_b32_e64 v190, v190, v198, s[6:7]
	v_lshlrev_b32_e32 v198, 16, v182
	v_mov_b32_dpp v208, v186 row_ror:8 row_mask:0xf bank_mask:0xf
	v_mov_b32_dpp v212, v194 row_ror:8 row_mask:0xf bank_mask:0xf
	v_cndmask_b32_e64 v186, v212, v186, s[6:7]
	v_lshlrev_b32_e32 v204, 16, v186
	v_mul_f32_e32 v204, v181, v204
	v_and_b32_e32 v186, 0xffff0000, v186
	v_mul_f32_e32 v204, v52, v204
	v_fmac_f32_e32 v198, v140, v204
	v_mul_f32_e32 v140, v181, v186
	v_and_b32_e32 v182, 0xffff0000, v182
	v_mul_f32_e32 v140, v53, v140
	v_fmac_f32_e32 v182, v141, v140
	v_mul_f32_e32 v140, 0xbfb8aa3b, v142
	v_exp_f32_e32 v140, v140
	v_mul_f32_e32 v142, 0xbfb8aa3b, v143
	v_exp_f32_e32 v142, v142
	v_mov_b32_dpp v213, v195 row_ror:8 row_mask:0xf bank_mask:0xf
	v_add_f32_e32 v140, 1.0, v140
	v_mov_b32_dpp v209, v187 row_ror:8 row_mask:0xf bank_mask:0xf
	v_mov_b32_dpp v205, v191 row_ror:8 row_mask:0xf bank_mask:0xf
	v_cndmask_b32_e64 v187, v213, v187, s[6:7]
	v_rcp_f32_e32 v140, v140
	v_cndmask_b32_e64 v183, v205, v183, s[6:7]
	v_lshlrev_b32_e32 v205, 16, v187
	v_add_f32_e32 v142, 1.0, v142
	v_mul_f32_e32 v141, v181, v205
	v_rcp_f32_e32 v142, v142
	v_cndmask_b32_e64 v191, v191, v199, s[6:7]
	v_mov_b32_dpp v214, v196 row_ror:8 row_mask:0xf bank_mask:0xf
	v_lshlrev_b32_e32 v199, 16, v183
	v_and_b32_e32 v187, 0xffff0000, v187
	v_mul_f32_e32 v141, v54, v141
	v_mov_b32_dpp v210, v188 row_ror:8 row_mask:0xf bank_mask:0xf
	v_mov_b32_dpp v206, v192 row_ror:8 row_mask:0xf bank_mask:0xf
	v_cndmask_b32_e64 v188, v214, v188, s[6:7]
	v_fmac_f32_e32 v199, v140, v141
	v_mul_f32_e32 v140, v181, v187
	v_cndmask_b32_e64 v184, v206, v184, s[6:7]
	v_and_b32_e32 v183, 0xffff0000, v183
	v_lshlrev_b32_e32 v206, 16, v188
	v_mul_f32_e32 v140, v55, v140
	v_fmac_f32_e32 v183, v142, v140
	v_mul_f32_e32 v140, v181, v206
	v_cndmask_b32_e64 v192, v192, v200, s[6:7]
	v_lshlrev_b32_e32 v200, 16, v184
	v_and_b32_e32 v188, 0xffff0000, v188
	v_mul_f32_e32 v140, v48, v140
	v_fmac_f32_e32 v200, v136, v140
	v_mul_f32_e32 v136, v181, v188
	v_and_b32_e32 v184, 0xffff0000, v184
	v_mul_f32_e32 v136, v49, v136
	v_fmac_f32_e32 v184, v137, v136
	v_mul_f32_e32 v136, 0xbfb8aa3b, v138
	v_cndmask_b32_e64 v194, v194, v208, s[6:7]
	v_exp_f32_e32 v136, v136
	v_mul_f32_e32 v138, 0xbfb8aa3b, v139
	v_lshlrev_b32_e32 v187, 16, v194
	v_exp_f32_e32 v138, v138
	v_mul_f32_e32 v187, v181, v187
	v_lshlrev_b32_e32 v141, 16, v190
	v_and_b32_e32 v188, 0xffff0000, v194
	v_mul_f32_e32 v187, v40, v187
	v_mov_b32_dpp v215, v197 row_ror:8 row_mask:0xf bank_mask:0xf
	v_add_f32_e32 v136, 1.0, v136
	v_fmac_f32_e32 v141, v132, v187
	v_mul_f32_e32 v132, v181, v188
	v_mov_b32_dpp v211, v189 row_ror:8 row_mask:0xf bank_mask:0xf
	v_mov_b32_dpp v207, v193 row_ror:8 row_mask:0xf bank_mask:0xf
	v_cndmask_b32_e64 v189, v215, v189, s[6:7]
	v_rcp_f32_e32 v136, v136
	v_and_b32_e32 v142, 0xffff0000, v190
	v_mul_f32_e32 v132, v41, v132
	v_cndmask_b32_e64 v185, v207, v185, s[6:7]
	v_lshlrev_b32_e32 v207, 16, v189
	v_add_f32_e32 v138, 1.0, v138
	v_fmac_f32_e32 v142, v133, v132
	v_mul_f32_e32 v132, 0xbfb8aa3b, v134
	v_mul_f32_e32 v137, v181, v207
	v_rcp_f32_e32 v138, v138
	v_exp_f32_e32 v132, v132
	v_cndmask_b32_e64 v193, v193, v201, s[6:7]
	v_lshlrev_b32_e32 v201, 16, v185
	v_and_b32_e32 v189, 0xffff0000, v189
	v_mul_f32_e32 v137, v50, v137
	v_mul_f32_e32 v134, 0xbfb8aa3b, v135
	v_fmac_f32_e32 v201, v136, v137
	v_mul_f32_e32 v136, v181, v189
	v_exp_f32_e32 v134, v134
	v_and_b32_e32 v185, 0xffff0000, v185
	v_mul_f32_e32 v136, v51, v136
	v_fmac_f32_e32 v185, v138, v136
	v_mul_f32_e32 v136, v182, v182
	v_mul_f32_e32 v137, v183, v183
	v_add_f32_e32 v132, 1.0, v132
	v_cndmask_b32_e64 v195, v195, v209, s[6:7]
	v_fmac_f32_e32 v136, v198, v198
	v_fmac_f32_e32 v137, v199, v199
	v_rcp_f32_e32 v132, v132
	v_add_f32_e32 v136, v136, v137
	v_mul_f32_e32 v137, v184, v184
	v_lshlrev_b32_e32 v189, 16, v195
	v_add_f32_e32 v134, 1.0, v134
	v_fmac_f32_e32 v137, v200, v200
	v_mul_f32_e32 v133, v181, v189
	v_rcp_f32_e32 v134, v134
	v_add_f32_e32 v136, v137, v136
	v_mul_f32_e32 v137, v185, v185
	v_lshlrev_b32_e32 v143, 16, v191
	v_and_b32_e32 v190, 0xffff0000, v195
	v_mul_f32_e32 v133, v42, v133
	v_cndmask_b32_e64 v196, v196, v210, s[6:7]
	v_fmac_f32_e32 v137, v201, v201
	v_fmac_f32_e32 v143, v132, v133
	v_mul_f32_e32 v132, v181, v190
	v_add_f32_e32 v136, v137, v136
	v_cvt_pk_bf16_f32 v137, v198, v182
	v_and_b32_e32 v182, 0xffff0000, v191
	v_lshlrev_b32_e32 v191, 16, v196
	v_mul_f32_e32 v132, v43, v132
	v_fmac_f32_e32 v182, v134, v132
	v_mul_f32_e32 v132, v181, v191
	v_cvt_pk_bf16_f32 v138, v199, v183
	v_cvt_pk_bf16_f32 v139, v200, v184
	v_lshlrev_b32_e32 v183, 16, v192
	v_and_b32_e32 v184, 0xffff0000, v192
	v_and_b32_e32 v192, 0xffff0000, v196
	v_mul_f32_e32 v132, v32, v132
	v_fmac_f32_e32 v183, v128, v132
	v_mul_f32_e32 v128, v181, v192
	v_mul_f32_e32 v128, v33, v128
	v_fmac_f32_e32 v184, v129, v128
	v_mul_f32_e32 v128, 0xbfb8aa3b, v130
	v_exp_f32_e32 v128, v128
	v_mul_f32_e32 v130, 0xbfb8aa3b, v131
	v_exp_f32_e32 v130, v130
	v_cndmask_b32_e64 v197, v197, v211, s[6:7]
	v_add_f32_e32 v128, 1.0, v128
	v_rcp_f32_e32 v128, v128
	v_cvt_pk_bf16_f32 v140, v201, v185
	v_lshlrev_b32_e32 v185, 16, v193
	v_and_b32_e32 v186, 0xffff0000, v193
	v_lshlrev_b32_e32 v193, 16, v197
; __device__ __forceinline__ unsigned cvt_pk_bf16(float lo, float hi) { unsigned r; asm volatile("v_cvt_pk_bf16_f32 %0, %1, %2" : "=v"(r) : "v"(lo), "v"(hi)); return r; }
;     __device__ __forceinline__ void operator()(const f32x4 (&acc)[2][2][4][2], const Unit& u, int wr, int wc, int fr, int fq) const {
;     ...
;                     for (int j = 0; j < 8; ++j) { const float a = acc[ai][bj][m][j >> 2][j & 3]; const float gg = gv[bj][j >> 2][j & 3];
;                         o[j] = r[j] + e[j] * ri * gg * __builtin_amdgcn_rcpf(1.f + __builtin_amdgcn_exp2f(-a * LOG2E)); }
;                     if (OUT) { *(f32x4*)(OUT + off + 8 * bj) = (f32x4){o[0], o[1], o[2], o[3]}; *(f32x4*)(OUT + off + 8 * bj + 4) = (f32x4){o[4], o[5], o[6], o[7]}; }
;                     else { sq += (o[0] * o[0] + o[1] * o[1]) + (o[2] * o[2] + o[3] * o[3]) + (o[4] * o[4] + o[5] * o[5]) + (o[6] * o[6] + o[7] * o[7]);
;                         w[bj].x = cvt_pk_bf16(o[0], o[1]); w[bj].y = cvt_pk_bf16(o[2], o[3]); w[bj].z = cvt_pk_bf16(o[4], o[5]); w[bj].w = cvt_pk_bf16(o[6], o[7]); } }
;                 if (!OUT) { store_pair_lines(O, D, row, fr, col0, w[0], w[1]);
;                     sq += __shfl_xor(sq, 16); sq += __shfl_xor(sq, 32); if (fq == 0) unsafeAtomicAdd(ssout + row, sq); } }
	v_add_f32_e32 v130, 1.0, v130
	v_mul_f32_e32 v129, v181, v193
	v_rcp_f32_e32 v130, v130
	v_and_b32_e32 v194, 0xffff0000, v197
	v_mul_f32_e32 v129, v34, v129
	v_fmac_f32_e32 v185, v128, v129
	v_mul_f32_e32 v128, v181, v194
	v_mul_f32_e32 v128, v35, v128
	v_fmac_f32_e32 v186, v130, v128
	v_mul_f32_e32 v128, v142, v142
	v_mul_f32_e32 v129, v182, v182
	v_fmac_f32_e32 v128, v141, v141
	v_fmac_f32_e32 v129, v143, v143
	v_add_f32_e32 v128, v128, v129
	v_mul_f32_e32 v129, v184, v184
	v_fmac_f32_e32 v129, v183, v183
	v_add_f32_e32 v128, v129, v128
	v_mul_f32_e32 v129, v186, v186
	v_fmac_f32_e32 v129, v185, v185
	v_add_f32_e32 v128, v129, v128
	v_add_f32_e32 v135, v128, v136
	v_cvt_pk_bf16_f32 v128, v141, v142
	v_cvt_pk_bf16_f32 v129, v143, v182
	v_mov_b32_dpp v143, v138 row_ror:8 row_mask:0xf bank_mask:0xf
	v_mov_b32_dpp v130, v128 row_ror:8 row_mask:0xf bank_mask:0xf
	v_mov_b32_dpp v134, v137 row_ror:8 row_mask:0xf bank_mask:0xf
	v_cndmask_b32_e64 v130, v130, v137, s[6:7]
	v_mov_b32_dpp v131, v129 row_ror:8 row_mask:0xf bank_mask:0xf
	v_cndmask_b32_e64 v137, v129, v143, s[6:7]
	v_and_b32_e32 v129, 64, v203
	v_cndmask_b32_e64 v136, v128, v134, s[6:7]
	v_xor_b32_e32 v128, 16, v203
	v_add_u32_e32 v143, 64, v129
	v_cmp_lt_i32_e32 vcc, v128, v143
	v_cvt_pk_bf16_f32 v141, v183, v184
	v_mov_b32_e32 v181, 0
	v_mov_b32_e32 v133, 0
	v_cndmask_b32_e32 v128, v203, v128, vcc
	v_lshlrev_b32_e32 v134, 2, v128
	v_mov_b32_e32 v183, v135
	s_nop 1
	v_permlane16_swap_b32_e32 v183, v135
	v_cvt_pk_bf16_f32 v142, v185, v186
	v_mov_b32_dpp v181, v139 row_ror:8 row_mask:0xf bank_mask:0xf
	v_mov_b32_e32 v182, 0
	v_mov_b32_dpp v133, v142 row_ror:8 row_mask:0xf bank_mask:0xf
	v_lshl_add_u64 v[128:129], s[36:37], 0, v[168:169]
	v_mov_b32_dpp v182, v140 row_ror:8 row_mask:0xf bank_mask:0xf
	v_mov_b32_dpp v132, v141 row_ror:8 row_mask:0xf bank_mask:0xf
	v_cndmask_b32_e64 v131, v131, v138, s[6:7]
	v_cndmask_b32_e64 v133, v133, v140, s[6:7]
	v_cndmask_b32_e64 v138, v141, v181, s[6:7]
	v_lshl_add_u64 v[140:141], v[128:129], 0, v[162:163]
	v_xor_b32_e32 v129, 32, v203
	v_cmp_lt_i32_e32 vcc, v129, v143
	s_waitcnt lgkmcnt(0)
	v_add_f32_e32 v128, v135, v183
	v_cndmask_b32_e64 v132, v132, v139, s[6:7]
	v_cndmask_b32_e32 v129, v203, v129, vcc
	v_lshlrev_b32_e32 v135, 2, v129
	v_mov_b32_e32 v129, v128
	s_nop 1
	v_permlane32_swap_b32_e32 v129, v128
	global_store_dwordx4 v[140:141], v[130:133], off
	v_cndmask_b32_e64 v139, v142, v182, s[6:7]
	s_nop 0
	v_lshl_add_u64 v[130:131], s[36:37], 0, v[170:171]
	v_lshl_add_u64 v[130:131], v[130:131], 0, v[162:163]
	global_store_dwordx4 v[130:131], v[136:139], off
	s_and_saveexec_b64 s[56:57], s[8:9]
	s_cbranch_execz .LBB0_885
	v_lshl_add_u64 v[130:131], v[164:165], 2, s[18:19]
	s_waitcnt lgkmcnt(0)
	v_add_f32_e32 v128, v128, v129
	global_atomic_add_f32 v[130:131], v128, off
.LBB0_885:
	s_or_b64 exec, exec, s[56:57]
	v_or_b32_e32 v128, 16, v164
	s_waitcnt lgkmcnt(0)
	v_ashrrev_i32_e32 v129, 31, v128
	v_lshl_add_u64 v[130:131], v[128:129], 2, s[40:41]
	s_waitcnt vmcnt(2)
	s_nop 0
	v_mov_b32_e32 v165, v226
	v_sub_u32_e32 v130, v128, v172
	v_add_u32_e32 v130, v130, v174
	v_ashrrev_i32_e32 v131, 31, v130
	v_lshlrev_b64 v[130:131], 12, v[130:131]
	v_lshl_add_u64 v[132:133], s[16:17], 0, v[130:131]
	v_lshl_add_u64 v[132:133], v[132:133], 0, v[162:163]
	v_mov_b64_e32 v[136:137], v[228:229]
	v_mov_b64_e32 v[138:139], v[230:231]
	v_lshl_add_u64 v[132:133], s[38:39], 0, v[130:131]
	v_lshl_add_u64 v[132:133], v[132:133], 0, v[162:163]
	v_mov_b64_e32 v[140:141], v[232:233]
	v_mov_b64_e32 v[142:143], v[234:235]
	v_lshl_add_u64 v[132:133], v[130:131], 0, s[44:45]
	v_lshl_add_u64 v[182:183], s[38:39], 0, v[132:133]
	v_lshl_add_u64 v[168:169], s[16:17], 0, v[132:133]
	v_lshl_add_u64 v[182:183], v[182:183], 0, v[162:163]
	v_lshl_add_u64 v[168:169], v[168:169], 0, v[162:163]
	v_mov_b64_e32 v[182:183], v[236:237]
	v_mov_b64_e32 v[184:185], v[238:239]
	v_mul_f32_e32 v124, 0xbfb8aa3b, v124
	v_mov_b64_e32 v[168:169], v[240:241]
	v_mov_b64_e32 v[170:171], v[242:243]
	s_nop 1
	v_or_b32_e32 v216, 32, v164
	v_ashrrev_i32_e32 v217, 31, v216
	v_lshl_add_u64 v[218:219], v[216:217], 2, s[40:41]
	global_load_dword v226, v[218:219], off
	v_sub_u32_e32 v218, v216, v172
	v_add_u32_e32 v218, v218, v174
	v_ashrrev_i32_e32 v219, 31, v218
	v_lshlrev_b64 v[218:219], 12, v[218:219]
	v_lshl_add_u64 v[220:221], s[16:17], 0, v[218:219]
	v_lshl_add_u64 v[220:221], v[220:221], 0, v[162:163]
	global_load_dwordx4 v[228:231], v[220:221], off
	v_lshl_add_u64 v[220:221], s[38:39], 0, v[218:219]
	v_lshl_add_u64 v[220:221], v[220:221], 0, v[162:163]
	global_load_dwordx4 v[232:235], v[220:221], off
	v_lshl_add_u64 v[220:221], v[218:219], 0, s[44:45]
	v_lshl_add_u64 v[224:225], s[38:39], 0, v[220:221]
	v_lshl_add_u64 v[222:223], s[16:17], 0, v[220:221]
	v_lshl_add_u64 v[224:225], v[224:225], 0, v[162:163]
	v_lshl_add_u64 v[222:223], v[222:223], 0, v[162:163]
	global_load_dwordx4 v[236:239], v[224:225], off
	global_load_dwordx4 v[240:243], v[222:223], off
	v_exp_f32_e32 v124, v124
	v_mul_f32_e32 v125, 0xbfb8aa3b, v125
	v_exp_f32_e32 v125, v125
	v_add_f32_e32 v124, 1.0, v124
	v_rcp_f32_e32 v124, v124
	v_add_f32_e32 v125, 1.0, v125
	v_rcp_f32_e32 v125, v125
	v_mul_f32_e32 v120, 0xbfb8aa3b, v120
	v_exp_f32_e32 v120, v120
	v_mul_f32_e32 v121, 0xbfb8aa3b, v121
	v_exp_f32_e32 v121, v121
	v_add_f32_e32 v120, 1.0, v120
	v_rcp_f32_e32 v120, v120
	v_add_f32_e32 v121, 1.0, v121
	v_mul_f32_e32 v116, 0xbfb8aa3b, v116
	v_rcp_f32_e32 v121, v121
	v_exp_f32_e32 v116, v116
	v_mul_f32_e32 v117, 0xbfb8aa3b, v117
	v_exp_f32_e32 v117, v117
	v_add_f32_e32 v116, 1.0, v116
	v_rcp_f32_e32 v116, v116
	v_add_f32_e32 v117, 1.0, v117
; __device__ __forceinline__ unsigned cvt_pk_bf16(float lo, float hi) { unsigned r; asm volatile("v_cvt_pk_bf16_f32 %0, %1, %2" : "=v"(r) : "v"(lo), "v"(hi)); return r; }
; __device__ __forceinline__ float bflo(unsigned w) { return __uint_as_float(w << 16); }
; __device__ __forceinline__ float bfhi(unsigned w) { return __uint_as_float(w & 0xffff0000u); }
;     __device__ __forceinline__ void operator()(const f32x4 (&acc)[2][2][4][2], const Unit& u, int wr, int wc, int fr, int fq) const {
;     ...
;             for (int m = 0; m < 4; ++m) { const int row = row0 + ai * HALF + m * 16; const size_t off = (size_t)row * D + col0; const float ri = __builtin_amdgcn_rsqf(sse[row] * (1.f / D) + EPS); float sq = 0.f; u32x4 w[2];
;                 u32x4 rr[2], ee[2]; load_pair_lines(R, D, row, fr, col0, rr[0], rr[1]); load_pair_lines(E, D, row, fr, col0, ee[0], ee[1]);
; #pragma unroll
;                 for (int bj = 0; bj < 2; ++bj) { const u32x4 rw = rr[bj], ew = ee[bj];
;                     const float r[8] = {bflo(rw.x), bfhi(rw.x), bflo(rw.y), bfhi(rw.y), bflo(rw.z), bfhi(rw.z), bflo(rw.w), bfhi(rw.w)};
;                     const float e[8] = {bflo(ew.x), bfhi(ew.x), bflo(ew.y), bfhi(ew.y), bflo(ew.z), bfhi(ew.z), bflo(ew.w), bfhi(ew.w)};
;                     float o[8];
; #pragma unroll
;                     for (int j = 0; j < 8; ++j) { const float a = acc[ai][bj][m][j >> 2][j & 3]; const float gg = gv[bj][j >> 2][j & 3];
;                         o[j] = r[j] + e[j] * ri * gg * __builtin_amdgcn_rcpf(1.f + __builtin_amdgcn_exp2f(-a * LOG2E)); }
;                     if (OUT) { *(f32x4*)(OUT + off + 8 * bj) = (f32x4){o[0], o[1], o[2], o[3]}; *(f32x4*)(OUT + off + 8 * bj + 4) = (f32x4){o[4], o[5], o[6], o[7]}; }
;                     else { sq += (o[0] * o[0] + o[1] * o[1]) + (o[2] * o[2] + o[3] * o[3]) + (o[4] * o[4] + o[5] * o[5]) + (o[6] * o[6] + o[7] * o[7]);
;                         w[bj].x = cvt_pk_bf16(o[0], o[1]); w[bj].y = cvt_pk_bf16(o[2], o[3]); w[bj].z = cvt_pk_bf16(o[4], o[5]); w[bj].w = cvt_pk_bf16(o[6], o[7]); } }
	v_rcp_f32_e32 v117, v117
	v_mul_f32_e32 v112, 0xbfb8aa3b, v112
	v_exp_f32_e32 v112, v112
	v_mul_f32_e32 v113, 0xbfb8aa3b, v113
	v_exp_f32_e32 v113, v113
	v_add_f32_e32 v112, 1.0, v112
	v_rcp_f32_e32 v112, v112
	v_add_f32_e32 v113, 1.0, v113
	v_rcp_f32_e32 v113, v113
	v_fmamk_f32 v165, v165, 0x3a000000, v180
	v_rsq_f32_e32 v165, v165
	v_mov_b32_dpp v181, v136 row_ror:8 row_mask:0xf bank_mask:0xf
	v_mov_b32_dpp v186, v137 row_ror:8 row_mask:0xf bank_mask:0xf
	v_mov_b32_dpp v187, v138 row_ror:8 row_mask:0xf bank_mask:0xf
	v_mov_b32_dpp v193, v140 row_ror:8 row_mask:0xf bank_mask:0xf
	v_mov_b32_dpp v196, v143 row_ror:8 row_mask:0xf bank_mask:0xf
	v_mov_b32_dpp v194, v141 row_ror:8 row_mask:0xf bank_mask:0xf
	v_mov_b32_dpp v195, v142 row_ror:8 row_mask:0xf bank_mask:0xf
	v_mov_b32_dpp v188, v139 row_ror:8 row_mask:0xf bank_mask:0xf
	v_mov_b32_dpp v197, v182 row_ror:8 row_mask:0xf bank_mask:0xf
	v_cndmask_b32_e64 v140, v197, v140, s[6:7]
	v_mov_b32_dpp v189, v168 row_ror:8 row_mask:0xf bank_mask:0xf
	v_cndmask_b32_e64 v136, v189, v136, s[6:7]
	v_lshlrev_b32_e32 v189, 16, v140
	v_mul_f32_e32 v189, v165, v189
	v_cndmask_b32_e64 v168, v168, v181, s[6:7]
	v_mov_b32_dpp v200, v185 row_ror:8 row_mask:0xf bank_mask:0xf
	v_cndmask_b32_e64 v181, v185, v196, s[6:7]
	v_lshlrev_b32_e32 v185, 16, v136
	v_and_b32_e32 v140, 0xffff0000, v140
	v_mul_f32_e32 v189, v52, v189
	v_fmac_f32_e32 v185, v124, v189
	v_mul_f32_e32 v124, v165, v140
	v_and_b32_e32 v136, 0xffff0000, v136
	v_mul_f32_e32 v124, v53, v124
	v_fmac_f32_e32 v136, v125, v124
	v_mul_f32_e32 v124, 0xbfb8aa3b, v126
	v_exp_f32_e32 v124, v124
	v_mul_f32_e32 v126, 0xbfb8aa3b, v127
	v_exp_f32_e32 v126, v126
	v_mov_b32_dpp v198, v183 row_ror:8 row_mask:0xf bank_mask:0xf
	v_add_f32_e32 v124, 1.0, v124
	v_mov_b32_dpp v190, v169 row_ror:8 row_mask:0xf bank_mask:0xf
	v_cndmask_b32_e64 v141, v198, v141, s[6:7]
	v_rcp_f32_e32 v124, v124
	v_cndmask_b32_e64 v137, v190, v137, s[6:7]
	v_lshlrev_b32_e32 v190, 16, v141
	v_add_f32_e32 v126, 1.0, v126
	v_mul_f32_e32 v125, v165, v190
	v_rcp_f32_e32 v126, v126
	v_cndmask_b32_e64 v169, v169, v186, s[6:7]
	v_mov_b32_dpp v199, v184 row_ror:8 row_mask:0xf bank_mask:0xf
	v_lshlrev_b32_e32 v186, 16, v137
	v_and_b32_e32 v141, 0xffff0000, v141
	v_mul_f32_e32 v125, v54, v125
	v_mov_b32_dpp v191, v170 row_ror:8 row_mask:0xf bank_mask:0xf
	v_cndmask_b32_e64 v142, v199, v142, s[6:7]
	v_fmac_f32_e32 v186, v124, v125
	v_mul_f32_e32 v124, v165, v141
	v_cndmask_b32_e64 v138, v191, v138, s[6:7]
	v_and_b32_e32 v137, 0xffff0000, v137
	v_lshlrev_b32_e32 v191, 16, v142
	v_mul_f32_e32 v124, v55, v124
	v_fmac_f32_e32 v137, v126, v124
	v_mul_f32_e32 v124, v165, v191
	v_cndmask_b32_e64 v170, v170, v187, s[6:7]
	v_lshlrev_b32_e32 v187, 16, v138
	v_and_b32_e32 v142, 0xffff0000, v142
	v_mul_f32_e32 v124, v48, v124
	v_fmac_f32_e32 v187, v120, v124
	v_mul_f32_e32 v120, v165, v142
	v_and_b32_e32 v138, 0xffff0000, v138
	v_mul_f32_e32 v120, v49, v120
	v_fmac_f32_e32 v138, v121, v120
	v_mul_f32_e32 v120, 0xbfb8aa3b, v122
	v_cndmask_b32_e64 v182, v182, v193, s[6:7]
	v_exp_f32_e32 v120, v120
	v_mul_f32_e32 v122, 0xbfb8aa3b, v123
	v_lshlrev_b32_e32 v141, 16, v182
	v_exp_f32_e32 v122, v122
	v_mul_f32_e32 v141, v165, v141
	v_lshlrev_b32_e32 v125, 16, v168
	v_and_b32_e32 v142, 0xffff0000, v182
	v_mul_f32_e32 v141, v40, v141
	v_add_f32_e32 v120, 1.0, v120
	v_fmac_f32_e32 v125, v116, v141
	v_mul_f32_e32 v116, v165, v142
	v_mov_b32_dpp v192, v171 row_ror:8 row_mask:0xf bank_mask:0xf
	v_cndmask_b32_e64 v143, v200, v143, s[6:7]
	v_rcp_f32_e32 v120, v120
	v_and_b32_e32 v126, 0xffff0000, v168
	v_mul_f32_e32 v116, v41, v116
	v_cndmask_b32_e64 v139, v192, v139, s[6:7]
	v_lshlrev_b32_e32 v192, 16, v143
	v_add_f32_e32 v122, 1.0, v122
	v_fmac_f32_e32 v126, v117, v116
	v_mul_f32_e32 v116, 0xbfb8aa3b, v118
	v_mul_f32_e32 v121, v165, v192
	v_rcp_f32_e32 v122, v122
	v_exp_f32_e32 v116, v116
	v_cndmask_b32_e64 v171, v171, v188, s[6:7]
	v_lshlrev_b32_e32 v188, 16, v139
	v_and_b32_e32 v143, 0xffff0000, v143
	v_mul_f32_e32 v121, v50, v121
	v_mul_f32_e32 v118, 0xbfb8aa3b, v119
	v_fmac_f32_e32 v188, v120, v121
	v_mul_f32_e32 v120, v165, v143
	v_exp_f32_e32 v118, v118
	v_and_b32_e32 v139, 0xffff0000, v139
	v_mul_f32_e32 v120, v51, v120
	v_fmac_f32_e32 v139, v122, v120
	v_mul_f32_e32 v120, v136, v136
	v_mul_f32_e32 v121, v137, v137
	v_add_f32_e32 v116, 1.0, v116
	v_cndmask_b32_e64 v183, v183, v194, s[6:7]
	v_fmac_f32_e32 v120, v185, v185
	v_fmac_f32_e32 v121, v186, v186
	v_rcp_f32_e32 v116, v116
	v_add_f32_e32 v120, v120, v121
	v_mul_f32_e32 v121, v138, v138
	v_lshlrev_b32_e32 v143, 16, v183
	v_add_f32_e32 v118, 1.0, v118
	v_fmac_f32_e32 v121, v187, v187
	v_mul_f32_e32 v117, v165, v143
	v_rcp_f32_e32 v118, v118
	v_add_f32_e32 v120, v121, v120
	v_mul_f32_e32 v121, v139, v139
	v_lshlrev_b32_e32 v127, 16, v169
	v_and_b32_e32 v168, 0xffff0000, v183
	v_mul_f32_e32 v117, v42, v117
	v_cndmask_b32_e64 v184, v184, v195, s[6:7]
	v_fmac_f32_e32 v121, v188, v188
	v_fmac_f32_e32 v127, v116, v117
	v_mul_f32_e32 v116, v165, v168
	v_add_f32_e32 v120, v121, v120
	v_cvt_pk_bf16_f32 v121, v185, v136
	v_and_b32_e32 v136, 0xffff0000, v169
	v_lshlrev_b32_e32 v169, 16, v184
	v_mul_f32_e32 v116, v43, v116
	v_fmac_f32_e32 v136, v118, v116
	v_mul_f32_e32 v116, v165, v169
	v_cvt_pk_bf16_f32 v122, v186, v137
	v_cvt_pk_bf16_f32 v123, v187, v138
	v_lshlrev_b32_e32 v137, 16, v170
	v_and_b32_e32 v138, 0xffff0000, v170
	v_and_b32_e32 v170, 0xffff0000, v184
	v_mul_f32_e32 v116, v32, v116
	v_fmac_f32_e32 v137, v112, v116
	v_mul_f32_e32 v112, v165, v170
	v_mul_f32_e32 v112, v33, v112
	v_fmac_f32_e32 v138, v113, v112
	v_mul_f32_e32 v112, 0xbfb8aa3b, v114
; __device__ __forceinline__ unsigned cvt_pk_bf16(float lo, float hi) { unsigned r; asm volatile("v_cvt_pk_bf16_f32 %0, %1, %2" : "=v"(r) : "v"(lo), "v"(hi)); return r; }
;     __device__ __forceinline__ void operator()(const f32x4 (&acc)[2][2][4][2], const Unit& u, int wr, int wc, int fr, int fq) const {
;     ...
;             for (int m = 0; m < 4; ++m) { const int row = row0 + ai * HALF + m * 16; const size_t off = (size_t)row * D + col0; const float ri = __builtin_amdgcn_rsqf(sse[row] * (1.f / D) + EPS); float sq = 0.f; u32x4 w[2];
;                 u32x4 rr[2], ee[2]; load_pair_lines(R, D, row, fr, col0, rr[0], rr[1]); load_pair_lines(E, D, row, fr, col0, ee[0], ee[1]);
;     ...
;                     for (int j = 0; j < 8; ++j) { const float a = acc[ai][bj][m][j >> 2][j & 3]; const float gg = gv[bj][j >> 2][j & 3];
;                         o[j] = r[j] + e[j] * ri * gg * __builtin_amdgcn_rcpf(1.f + __builtin_amdgcn_exp2f(-a * LOG2E)); }
;                     if (OUT) { *(f32x4*)(OUT + off + 8 * bj) = (f32x4){o[0], o[1], o[2], o[3]}; *(f32x4*)(OUT + off + 8 * bj + 4) = (f32x4){o[4], o[5], o[6], o[7]}; }
;                     else { sq += (o[0] * o[0] + o[1] * o[1]) + (o[2] * o[2] + o[3] * o[3]) + (o[4] * o[4] + o[5] * o[5]) + (o[6] * o[6] + o[7] * o[7]);
;                         w[bj].x = cvt_pk_bf16(o[0], o[1]); w[bj].y = cvt_pk_bf16(o[2], o[3]); w[bj].z = cvt_pk_bf16(o[4], o[5]); w[bj].w = cvt_pk_bf16(o[6], o[7]); } }
;                 if (!OUT) { store_pair_lines(O, D, row, fr, col0, w[0], w[1]);
;                     sq += __shfl_xor(sq, 16); sq += __shfl_xor(sq, 32); if (fq == 0) unsafeAtomicAdd(ssout + row, sq); } }
	v_exp_f32_e32 v112, v112
	v_mul_f32_e32 v114, 0xbfb8aa3b, v115
	v_exp_f32_e32 v114, v114
	v_cvt_pk_bf16_f32 v124, v188, v139
	v_add_f32_e32 v112, 1.0, v112
	v_rcp_f32_e32 v112, v112
	v_lshlrev_b32_e32 v139, 16, v171
	v_and_b32_e32 v140, 0xffff0000, v171
	v_lshlrev_b32_e32 v171, 16, v181
	v_add_f32_e32 v114, 1.0, v114
	v_mul_f32_e32 v113, v165, v171
	v_rcp_f32_e32 v114, v114
	v_and_b32_e32 v181, 0xffff0000, v181
	v_mul_f32_e32 v113, v34, v113
	v_fmac_f32_e32 v139, v112, v113
	v_mul_f32_e32 v112, v165, v181
	v_mul_f32_e32 v112, v35, v112
	v_fmac_f32_e32 v140, v114, v112
	v_mul_f32_e32 v112, v126, v126
	v_mul_f32_e32 v113, v136, v136
	v_fmac_f32_e32 v112, v125, v125
	v_fmac_f32_e32 v113, v127, v127
	v_add_f32_e32 v112, v112, v113
	v_mul_f32_e32 v113, v138, v138
	v_fmac_f32_e32 v113, v137, v137
	v_add_f32_e32 v112, v113, v112
	v_mul_f32_e32 v113, v140, v140
	v_fmac_f32_e32 v113, v139, v139
	v_add_f32_e32 v112, v113, v112
	v_add_f32_e32 v141, v112, v120
	v_cvt_pk_bf16_f32 v112, v125, v126
	v_cvt_pk_bf16_f32 v113, v127, v136
	v_cvt_pk_bf16_f32 v120, v137, v138
	v_cvt_pk_bf16_f32 v125, v139, v140
	v_mov_b32_e32 v127, 0
	v_mov_b32_e32 v118, 0
	v_mov_b32_dpp v117, v125 row_ror:8 row_mask:0xf bank_mask:0xf
	v_mov_b32_dpp v127, v124 row_ror:8 row_mask:0xf bank_mask:0xf
	v_cndmask_b32_e64 v117, v117, v124, s[6:7]
	ds_bpermute_b32 v124, v134, v141
	v_mov_b32_dpp v118, v121 row_ror:8 row_mask:0xf bank_mask:0xf
	v_mov_b32_dpp v119, v122 row_ror:8 row_mask:0xf bank_mask:0xf
	v_mov_b32_dpp v114, v112 row_ror:8 row_mask:0xf bank_mask:0xf
	v_mov_b32_dpp v115, v113 row_ror:8 row_mask:0xf bank_mask:0xf
	v_mov_b32_dpp v116, v120 row_ror:8 row_mask:0xf bank_mask:0xf
	v_cndmask_b32_e64 v118, v112, v118, s[6:7]
	v_cndmask_b32_e64 v119, v113, v119, s[6:7]
	v_lshl_add_u64 v[112:113], s[36:37], 0, v[130:131]
	v_mov_b32_dpp v126, v123 row_ror:8 row_mask:0xf bank_mask:0xf
	v_cndmask_b32_e64 v115, v115, v122, s[6:7]
	v_cndmask_b32_e64 v116, v116, v123, s[6:7]
	v_lshl_add_u64 v[122:123], v[112:113], 0, v[162:163]
	s_waitcnt lgkmcnt(0)
	v_add_f32_e32 v112, v141, v124
	v_mov_b32_e32 v113, v112
	s_nop 1
	v_permlane32_swap_b32_e32 v113, v112
	v_cndmask_b32_e64 v114, v114, v121, s[6:7]
	global_store_dwordx4 v[122:123], v[114:117], off
	v_cndmask_b32_e64 v120, v120, v126, s[6:7]
	v_cndmask_b32_e64 v121, v125, v127, s[6:7]
	v_lshl_add_u64 v[114:115], s[36:37], 0, v[132:133]
	v_lshl_add_u64 v[114:115], v[114:115], 0, v[162:163]
	global_store_dwordx4 v[114:115], v[118:121], off
	s_and_saveexec_b64 s[56:57], s[8:9]
	s_cbranch_execz .LBB0_887
	v_lshl_add_u64 v[114:115], v[128:129], 2, s[18:19]
	s_waitcnt lgkmcnt(0)
	v_add_f32_e32 v112, v112, v113
	global_atomic_add_f32 v[114:115], v112, off
.LBB0_887:
	s_or_b64 exec, exec, s[56:57]
	v_or_b32_e32 v112, 32, v164
	s_waitcnt lgkmcnt(0)
	v_ashrrev_i32_e32 v113, 31, v112
	v_lshl_add_u64 v[114:115], v[112:113], 2, s[40:41]
	s_waitcnt vmcnt(2)
	s_nop 0
	v_mov_b32_e32 v136, v226
	v_sub_u32_e32 v114, v112, v172
	v_add_u32_e32 v114, v114, v174
	v_ashrrev_i32_e32 v115, 31, v114
	v_lshlrev_b64 v[114:115], 12, v[114:115]
	v_lshl_add_u64 v[116:117], s[16:17], 0, v[114:115]
	v_lshl_add_u64 v[116:117], v[116:117], 0, v[162:163]
	v_mov_b64_e32 v[118:119], v[228:229]
	v_mov_b64_e32 v[120:121], v[230:231]
	v_lshl_add_u64 v[116:117], s[38:39], 0, v[114:115]
	v_lshl_add_u64 v[116:117], v[116:117], 0, v[162:163]
	v_mov_b64_e32 v[122:123], v[232:233]
	v_mov_b64_e32 v[124:125], v[234:235]
	v_lshl_add_u64 v[116:117], v[114:115], 0, s[44:45]
	v_lshl_add_u64 v[130:131], s[38:39], 0, v[116:117]
	v_lshl_add_u64 v[126:127], s[16:17], 0, v[116:117]
	v_lshl_add_u64 v[130:131], v[130:131], 0, v[162:163]
	v_lshl_add_u64 v[126:127], v[126:127], 0, v[162:163]
	v_mov_b64_e32 v[130:131], v[236:237]
	v_mov_b64_e32 v[132:133], v[238:239]
	v_mul_f32_e32 v108, 0xbfb8aa3b, v108
	v_mov_b64_e32 v[126:127], v[240:241]
	v_mov_b64_e32 v[128:129], v[242:243]
	s_nop 1
	v_or_b32_e32 v216, 48, v164
	v_ashrrev_i32_e32 v217, 31, v216
	v_lshl_add_u64 v[218:219], v[216:217], 2, s[40:41]
	global_load_dword v226, v[218:219], off
	v_sub_u32_e32 v218, v216, v172
	v_add_u32_e32 v218, v218, v174
	v_ashrrev_i32_e32 v219, 31, v218
	v_lshlrev_b64 v[218:219], 12, v[218:219]
	v_lshl_add_u64 v[220:221], s[16:17], 0, v[218:219]
	v_lshl_add_u64 v[220:221], v[220:221], 0, v[162:163]
	global_load_dwordx4 v[228:231], v[220:221], off
	v_lshl_add_u64 v[220:221], s[38:39], 0, v[218:219]
	v_lshl_add_u64 v[220:221], v[220:221], 0, v[162:163]
	global_load_dwordx4 v[232:235], v[220:221], off
	v_lshl_add_u64 v[220:221], v[218:219], 0, s[44:45]
	v_lshl_add_u64 v[224:225], s[38:39], 0, v[220:221]
	v_lshl_add_u64 v[222:223], s[16:17], 0, v[220:221]
	v_lshl_add_u64 v[224:225], v[224:225], 0, v[162:163]
	v_lshl_add_u64 v[222:223], v[222:223], 0, v[162:163]
	global_load_dwordx4 v[236:239], v[224:225], off
	global_load_dwordx4 v[240:243], v[222:223], off
	v_exp_f32_e32 v108, v108
	v_mul_f32_e32 v109, 0xbfb8aa3b, v109
	v_exp_f32_e32 v109, v109
	v_add_f32_e32 v108, 1.0, v108
	v_rcp_f32_e32 v108, v108
	v_add_f32_e32 v109, 1.0, v109
	v_rcp_f32_e32 v109, v109
	v_mul_f32_e32 v104, 0xbfb8aa3b, v104
	v_exp_f32_e32 v104, v104
	v_mul_f32_e32 v105, 0xbfb8aa3b, v105
	v_exp_f32_e32 v105, v105
	v_add_f32_e32 v104, 1.0, v104
	v_rcp_f32_e32 v104, v104
	v_add_f32_e32 v105, 1.0, v105
	v_mul_f32_e32 v100, 0xbfb8aa3b, v100
	v_rcp_f32_e32 v105, v105
	v_exp_f32_e32 v100, v100
	v_mul_f32_e32 v101, 0xbfb8aa3b, v101
	v_exp_f32_e32 v101, v101
	v_add_f32_e32 v100, 1.0, v100
	v_rcp_f32_e32 v100, v100
	v_add_f32_e32 v101, 1.0, v101
	v_rcp_f32_e32 v101, v101
	v_mul_f32_e32 v96, 0xbfb8aa3b, v96
	v_exp_f32_e32 v96, v96
	v_mul_f32_e32 v97, 0xbfb8aa3b, v97
; __device__ __forceinline__ unsigned cvt_pk_bf16(float lo, float hi) { unsigned r; asm volatile("v_cvt_pk_bf16_f32 %0, %1, %2" : "=v"(r) : "v"(lo), "v"(hi)); return r; }
; __device__ __forceinline__ float bflo(unsigned w) { return __uint_as_float(w << 16); }
; __device__ __forceinline__ float bfhi(unsigned w) { return __uint_as_float(w & 0xffff0000u); }
;     __device__ __forceinline__ void operator()(const f32x4 (&acc)[2][2][4][2], const Unit& u, int wr, int wc, int fr, int fq) const {
;     ...
;             for (int m = 0; m < 4; ++m) { const int row = row0 + ai * HALF + m * 16; const size_t off = (size_t)row * D + col0; const float ri = __builtin_amdgcn_rsqf(sse[row] * (1.f / D) + EPS); float sq = 0.f; u32x4 w[2];
;                 u32x4 rr[2], ee[2]; load_pair_lines(R, D, row, fr, col0, rr[0], rr[1]); load_pair_lines(E, D, row, fr, col0, ee[0], ee[1]);
; #pragma unroll
;                 for (int bj = 0; bj < 2; ++bj) { const u32x4 rw = rr[bj], ew = ee[bj];
;                     const float r[8] = {bflo(rw.x), bfhi(rw.x), bflo(rw.y), bfhi(rw.y), bflo(rw.z), bfhi(rw.z), bflo(rw.w), bfhi(rw.w)};
;                     const float e[8] = {bflo(ew.x), bfhi(ew.x), bflo(ew.y), bfhi(ew.y), bflo(ew.z), bfhi(ew.z), bflo(ew.w), bfhi(ew.w)};
;                     float o[8];
; #pragma unroll
;                     for (int j = 0; j < 8; ++j) { const float a = acc[ai][bj][m][j >> 2][j & 3]; const float gg = gv[bj][j >> 2][j & 3];
;                         o[j] = r[j] + e[j] * ri * gg * __builtin_amdgcn_rcpf(1.f + __builtin_amdgcn_exp2f(-a * LOG2E)); }
;                     if (OUT) { *(f32x4*)(OUT + off + 8 * bj) = (f32x4){o[0], o[1], o[2], o[3]}; *(f32x4*)(OUT + off + 8 * bj + 4) = (f32x4){o[4], o[5], o[6], o[7]}; }
;                     else { sq += (o[0] * o[0] + o[1] * o[1]) + (o[2] * o[2] + o[3] * o[3]) + (o[4] * o[4] + o[5] * o[5]) + (o[6] * o[6] + o[7] * o[7]);
;                         w[bj].x = cvt_pk_bf16(o[0], o[1]); w[bj].y = cvt_pk_bf16(o[2], o[3]); w[bj].z = cvt_pk_bf16(o[4], o[5]); w[bj].w = cvt_pk_bf16(o[6], o[7]); } }
	v_exp_f32_e32 v97, v97
	v_add_f32_e32 v96, 1.0, v96
	v_rcp_f32_e32 v96, v96
	v_add_f32_e32 v97, 1.0, v97
	v_rcp_f32_e32 v97, v97
	v_fmamk_f32 v136, v136, 0x3a000000, v180
	v_rsq_f32_e32 v136, v136
	v_mov_b32_dpp v137, v118 row_ror:8 row_mask:0xf bank_mask:0xf
	v_mov_b32_dpp v138, v119 row_ror:8 row_mask:0xf bank_mask:0xf
	v_mov_b32_dpp v139, v120 row_ror:8 row_mask:0xf bank_mask:0xf
	v_mov_b32_dpp v168, v122 row_ror:8 row_mask:0xf bank_mask:0xf
	v_mov_b32_dpp v169, v123 row_ror:8 row_mask:0xf bank_mask:0xf
	v_mov_b32_dpp v170, v124 row_ror:8 row_mask:0xf bank_mask:0xf
	v_mov_b32_dpp v171, v125 row_ror:8 row_mask:0xf bank_mask:0xf
	v_mov_b32_dpp v140, v121 row_ror:8 row_mask:0xf bank_mask:0xf
	v_mov_b32_dpp v181, v130 row_ror:8 row_mask:0xf bank_mask:0xf
	v_cndmask_b32_e64 v122, v181, v122, s[6:7]
	v_mov_b32_dpp v141, v126 row_ror:8 row_mask:0xf bank_mask:0xf
	v_cndmask_b32_e64 v118, v141, v118, s[6:7]
	v_lshlrev_b32_e32 v141, 16, v122
	v_mul_f32_e32 v141, v136, v141
	v_cndmask_b32_e64 v126, v126, v137, s[6:7]
	v_lshlrev_b32_e32 v137, 16, v118
	v_and_b32_e32 v122, 0xffff0000, v122
	v_mul_f32_e32 v141, v52, v141
	v_fmac_f32_e32 v137, v108, v141
	v_mul_f32_e32 v108, v136, v122
	v_and_b32_e32 v118, 0xffff0000, v118
	v_mul_f32_e32 v108, v53, v108
	v_fmac_f32_e32 v118, v109, v108
	v_mul_f32_e32 v108, 0xbfb8aa3b, v110
	v_exp_f32_e32 v108, v108
	v_mul_f32_e32 v110, 0xbfb8aa3b, v111
	v_exp_f32_e32 v110, v110
	v_mov_b32_dpp v182, v131 row_ror:8 row_mask:0xf bank_mask:0xf
	v_add_f32_e32 v108, 1.0, v108
	v_mov_b32_dpp v142, v127 row_ror:8 row_mask:0xf bank_mask:0xf
	v_cndmask_b32_e64 v123, v182, v123, s[6:7]
	v_rcp_f32_e32 v108, v108
	v_cndmask_b32_e64 v119, v142, v119, s[6:7]
	v_lshlrev_b32_e32 v142, 16, v123
	v_add_f32_e32 v110, 1.0, v110
	v_mul_f32_e32 v109, v136, v142
	v_rcp_f32_e32 v110, v110
	v_cndmask_b32_e64 v127, v127, v138, s[6:7]
	v_mov_b32_dpp v183, v132 row_ror:8 row_mask:0xf bank_mask:0xf
	v_lshlrev_b32_e32 v138, 16, v119
	v_and_b32_e32 v123, 0xffff0000, v123
	v_mul_f32_e32 v109, v54, v109
	v_mov_b32_dpp v143, v128 row_ror:8 row_mask:0xf bank_mask:0xf
	v_cndmask_b32_e64 v124, v183, v124, s[6:7]
	v_fmac_f32_e32 v138, v108, v109
	v_mul_f32_e32 v108, v136, v123
	v_cndmask_b32_e64 v120, v143, v120, s[6:7]
	v_and_b32_e32 v119, 0xffff0000, v119
	v_lshlrev_b32_e32 v143, 16, v124
	v_mul_f32_e32 v108, v55, v108
	v_fmac_f32_e32 v119, v110, v108
	v_mul_f32_e32 v108, v136, v143
	v_cndmask_b32_e64 v128, v128, v139, s[6:7]
	v_lshlrev_b32_e32 v139, 16, v120
	v_and_b32_e32 v124, 0xffff0000, v124
	v_mul_f32_e32 v108, v48, v108
	v_fmac_f32_e32 v139, v104, v108
	v_mul_f32_e32 v104, v136, v124
	v_and_b32_e32 v120, 0xffff0000, v120
	v_mul_f32_e32 v104, v49, v104
	v_fmac_f32_e32 v120, v105, v104
	v_mul_f32_e32 v104, 0xbfb8aa3b, v106
	v_cndmask_b32_e64 v130, v130, v168, s[6:7]
	v_exp_f32_e32 v104, v104
	v_mul_f32_e32 v106, 0xbfb8aa3b, v107
	v_lshlrev_b32_e32 v123, 16, v130
	v_exp_f32_e32 v106, v106
	v_mul_f32_e32 v123, v136, v123
	v_lshlrev_b32_e32 v109, 16, v126
	v_and_b32_e32 v124, 0xffff0000, v130
	v_mul_f32_e32 v123, v40, v123
	v_mov_b32_dpp v184, v133 row_ror:8 row_mask:0xf bank_mask:0xf
	v_add_f32_e32 v104, 1.0, v104
	v_fmac_f32_e32 v109, v100, v123
	v_mul_f32_e32 v100, v136, v124
	v_mov_b32_dpp v165, v129 row_ror:8 row_mask:0xf bank_mask:0xf
	v_cndmask_b32_e64 v125, v184, v125, s[6:7]
	v_rcp_f32_e32 v104, v104
	v_and_b32_e32 v110, 0xffff0000, v126
	v_mul_f32_e32 v100, v41, v100
	v_cndmask_b32_e64 v121, v165, v121, s[6:7]
	v_lshlrev_b32_e32 v165, 16, v125
	v_add_f32_e32 v106, 1.0, v106
	v_fmac_f32_e32 v110, v101, v100
	v_mul_f32_e32 v100, 0xbfb8aa3b, v102
	v_mul_f32_e32 v105, v136, v165
	v_rcp_f32_e32 v106, v106
	v_exp_f32_e32 v100, v100
	v_cndmask_b32_e64 v129, v129, v140, s[6:7]
	v_lshlrev_b32_e32 v140, 16, v121
	v_and_b32_e32 v125, 0xffff0000, v125
	v_mul_f32_e32 v105, v50, v105
	v_mul_f32_e32 v102, 0xbfb8aa3b, v103
	v_fmac_f32_e32 v140, v104, v105
	v_mul_f32_e32 v104, v136, v125
	v_exp_f32_e32 v102, v102
	v_and_b32_e32 v121, 0xffff0000, v121
	v_mul_f32_e32 v104, v51, v104
	v_fmac_f32_e32 v121, v106, v104
	v_mul_f32_e32 v104, v118, v118
	v_mul_f32_e32 v105, v119, v119
	v_add_f32_e32 v100, 1.0, v100
	v_cndmask_b32_e64 v131, v131, v169, s[6:7]
	v_fmac_f32_e32 v104, v137, v137
	v_fmac_f32_e32 v105, v138, v138
	v_rcp_f32_e32 v100, v100
	v_add_f32_e32 v104, v104, v105
	v_mul_f32_e32 v105, v120, v120
	v_lshlrev_b32_e32 v125, 16, v131
	v_add_f32_e32 v102, 1.0, v102
	v_fmac_f32_e32 v105, v139, v139
	v_mul_f32_e32 v101, v136, v125
	v_rcp_f32_e32 v102, v102
	v_add_f32_e32 v104, v105, v104
	v_mul_f32_e32 v105, v121, v121
	v_lshlrev_b32_e32 v111, 16, v127
	v_and_b32_e32 v126, 0xffff0000, v131
	v_mul_f32_e32 v101, v42, v101
	v_cndmask_b32_e64 v132, v132, v170, s[6:7]
	v_fmac_f32_e32 v105, v140, v140
	v_fmac_f32_e32 v111, v100, v101
	v_mul_f32_e32 v100, v136, v126
	v_add_f32_e32 v104, v105, v104
	v_cvt_pk_bf16_f32 v105, v137, v118
	v_and_b32_e32 v118, 0xffff0000, v127
	v_lshlrev_b32_e32 v127, 16, v132
	v_mul_f32_e32 v100, v43, v100
	v_fmac_f32_e32 v118, v102, v100
	v_mul_f32_e32 v100, v136, v127
	v_cvt_pk_bf16_f32 v106, v138, v119
	v_cvt_pk_bf16_f32 v107, v139, v120
	v_lshlrev_b32_e32 v119, 16, v128
	v_and_b32_e32 v120, 0xffff0000, v128
	v_and_b32_e32 v128, 0xffff0000, v132
	v_mul_f32_e32 v100, v32, v100
	v_fmac_f32_e32 v119, v96, v100
	v_mul_f32_e32 v96, v136, v128
	v_mul_f32_e32 v96, v33, v96
	v_fmac_f32_e32 v120, v97, v96
	v_mul_f32_e32 v96, 0xbfb8aa3b, v98
	v_exp_f32_e32 v96, v96
	v_mul_f32_e32 v98, 0xbfb8aa3b, v99
	v_exp_f32_e32 v98, v98
	v_cndmask_b32_e64 v133, v133, v171, s[6:7]
	v_add_f32_e32 v96, 1.0, v96
	v_rcp_f32_e32 v96, v96
	v_cvt_pk_bf16_f32 v108, v140, v121
; __device__ __forceinline__ unsigned cvt_pk_bf16(float lo, float hi) { unsigned r; asm volatile("v_cvt_pk_bf16_f32 %0, %1, %2" : "=v"(r) : "v"(lo), "v"(hi)); return r; }
;     __device__ __forceinline__ void operator()(const f32x4 (&acc)[2][2][4][2], const Unit& u, int wr, int wc, int fr, int fq) const {
;     ...
;             for (int m = 0; m < 4; ++m) { const int row = row0 + ai * HALF + m * 16; const size_t off = (size_t)row * D + col0; const float ri = __builtin_amdgcn_rsqf(sse[row] * (1.f / D) + EPS); float sq = 0.f; u32x4 w[2];
;                 u32x4 rr[2], ee[2]; load_pair_lines(R, D, row, fr, col0, rr[0], rr[1]); load_pair_lines(E, D, row, fr, col0, ee[0], ee[1]);
;     ...
;                     for (int j = 0; j < 8; ++j) { const float a = acc[ai][bj][m][j >> 2][j & 3]; const float gg = gv[bj][j >> 2][j & 3];
;                         o[j] = r[j] + e[j] * ri * gg * __builtin_amdgcn_rcpf(1.f + __builtin_amdgcn_exp2f(-a * LOG2E)); }
;                     if (OUT) { *(f32x4*)(OUT + off + 8 * bj) = (f32x4){o[0], o[1], o[2], o[3]}; *(f32x4*)(OUT + off + 8 * bj + 4) = (f32x4){o[4], o[5], o[6], o[7]}; }
;                     else { sq += (o[0] * o[0] + o[1] * o[1]) + (o[2] * o[2] + o[3] * o[3]) + (o[4] * o[4] + o[5] * o[5]) + (o[6] * o[6] + o[7] * o[7]);
;                         w[bj].x = cvt_pk_bf16(o[0], o[1]); w[bj].y = cvt_pk_bf16(o[2], o[3]); w[bj].z = cvt_pk_bf16(o[4], o[5]); w[bj].w = cvt_pk_bf16(o[6], o[7]); } }
;                 if (!OUT) { store_pair_lines(O, D, row, fr, col0, w[0], w[1]);
;                     sq += __shfl_xor(sq, 16); sq += __shfl_xor(sq, 32); if (fq == 0) unsafeAtomicAdd(ssout + row, sq); } }
	v_lshlrev_b32_e32 v121, 16, v129
	v_and_b32_e32 v122, 0xffff0000, v129
	v_lshlrev_b32_e32 v129, 16, v133
	v_add_f32_e32 v98, 1.0, v98
	v_mul_f32_e32 v97, v136, v129
	v_rcp_f32_e32 v98, v98
	v_and_b32_e32 v130, 0xffff0000, v133
	v_mul_f32_e32 v97, v34, v97
	v_fmac_f32_e32 v121, v96, v97
	v_mul_f32_e32 v96, v136, v130
	v_mul_f32_e32 v96, v35, v96
	v_fmac_f32_e32 v122, v98, v96
	v_mul_f32_e32 v96, v110, v110
	v_mul_f32_e32 v97, v118, v118
	v_fmac_f32_e32 v96, v109, v109
	v_fmac_f32_e32 v97, v111, v111
	v_add_f32_e32 v96, v96, v97
	v_mul_f32_e32 v97, v120, v120
	v_fmac_f32_e32 v97, v119, v119
	v_add_f32_e32 v96, v97, v96
	v_mul_f32_e32 v97, v122, v122
	v_fmac_f32_e32 v97, v121, v121
	v_add_f32_e32 v96, v97, v96
	v_add_f32_e32 v123, v96, v104
	v_cvt_pk_bf16_f32 v96, v109, v110
	v_cvt_pk_bf16_f32 v97, v111, v118
	v_cvt_pk_bf16_f32 v104, v119, v120
	v_cvt_pk_bf16_f32 v109, v121, v122
	v_mov_b32_e32 v111, 0
	v_mov_b32_e32 v102, 0
	v_mov_b32_dpp v101, v109 row_ror:8 row_mask:0xf bank_mask:0xf
	v_mov_b32_dpp v111, v108 row_ror:8 row_mask:0xf bank_mask:0xf
	v_cndmask_b32_e64 v101, v101, v108, s[6:7]
	ds_bpermute_b32 v108, v134, v123
	v_mov_b32_dpp v102, v105 row_ror:8 row_mask:0xf bank_mask:0xf
	v_mov_b32_dpp v103, v106 row_ror:8 row_mask:0xf bank_mask:0xf
	v_mov_b32_dpp v98, v96 row_ror:8 row_mask:0xf bank_mask:0xf
	v_mov_b32_dpp v99, v97 row_ror:8 row_mask:0xf bank_mask:0xf
	v_mov_b32_dpp v100, v104 row_ror:8 row_mask:0xf bank_mask:0xf
	v_cndmask_b32_e64 v102, v96, v102, s[6:7]
	v_cndmask_b32_e64 v103, v97, v103, s[6:7]
	v_lshl_add_u64 v[96:97], s[36:37], 0, v[114:115]
	v_mov_b32_dpp v110, v107 row_ror:8 row_mask:0xf bank_mask:0xf
	v_cndmask_b32_e64 v99, v99, v106, s[6:7]
	v_cndmask_b32_e64 v100, v100, v107, s[6:7]
	v_lshl_add_u64 v[106:107], v[96:97], 0, v[162:163]
	s_waitcnt lgkmcnt(0)
	v_add_f32_e32 v96, v123, v108
	v_mov_b32_e32 v97, v96
	s_nop 1
	v_permlane32_swap_b32_e32 v97, v96
	v_cndmask_b32_e64 v98, v98, v105, s[6:7]
	global_store_dwordx4 v[106:107], v[98:101], off
	v_cndmask_b32_e64 v104, v104, v110, s[6:7]
	v_cndmask_b32_e64 v105, v109, v111, s[6:7]
	v_lshl_add_u64 v[98:99], s[36:37], 0, v[116:117]
	v_lshl_add_u64 v[98:99], v[98:99], 0, v[162:163]
	global_store_dwordx4 v[98:99], v[102:105], off
	s_and_saveexec_b64 s[56:57], s[8:9]
	s_cbranch_execz .LBB0_889
	v_lshl_add_u64 v[98:99], v[112:113], 2, s[18:19]
	s_waitcnt lgkmcnt(0)
	v_add_f32_e32 v96, v96, v97
	global_atomic_add_f32 v[98:99], v96, off
.LBB0_889:
	s_or_b64 exec, exec, s[56:57]
	v_or_b32_e32 v96, 48, v164
	s_waitcnt lgkmcnt(0)
	v_ashrrev_i32_e32 v97, 31, v96
	v_lshl_add_u64 v[98:99], v[96:97], 2, s[40:41]
	s_waitcnt vmcnt(2)
	s_nop 0
	v_mov_b32_e32 v118, v226
	v_sub_u32_e32 v98, v96, v172
	v_add_u32_e32 v98, v98, v174
	v_ashrrev_i32_e32 v99, 31, v98
	v_lshlrev_b64 v[98:99], 12, v[98:99]
	v_lshl_add_u64 v[100:101], s[16:17], 0, v[98:99]
	v_lshl_add_u64 v[100:101], v[100:101], 0, v[162:163]
	v_mov_b64_e32 v[102:103], v[228:229]
	v_mov_b64_e32 v[104:105], v[230:231]
	v_lshl_add_u64 v[100:101], s[38:39], 0, v[98:99]
	v_lshl_add_u64 v[100:101], v[100:101], 0, v[162:163]
	v_mov_b64_e32 v[106:107], v[232:233]
	v_mov_b64_e32 v[108:109], v[234:235]
	v_lshl_add_u64 v[100:101], v[98:99], 0, s[44:45]
	v_lshl_add_u64 v[114:115], s[38:39], 0, v[100:101]
	v_lshl_add_u64 v[110:111], s[16:17], 0, v[100:101]
	v_lshl_add_u64 v[114:115], v[114:115], 0, v[162:163]
	v_lshl_add_u64 v[110:111], v[110:111], 0, v[162:163]
	v_mov_b64_e32 v[114:115], v[236:237]
	v_mov_b64_e32 v[116:117], v[238:239]
	v_mul_f32_e32 v92, 0xbfb8aa3b, v92
	v_mov_b64_e32 v[110:111], v[240:241]
	v_mov_b64_e32 v[112:113], v[242:243]
	s_nop 1
	v_add_u32_e32 v216, 0x80, v164
	v_sub_u32_e32 v218, v216, v172
	v_add_u32_e32 v218, v218, v174
	v_ashrrev_i32_e32 v219, 31, v218
	v_lshlrev_b64 v[218:219], 12, v[218:219]
	v_lshl_add_u64 v[220:221], s[16:17], 0, v[218:219]
	v_lshl_add_u64 v[220:221], v[220:221], 0, v[162:163]
	global_load_dwordx4 v[228:231], v[220:221], off
	v_lshl_add_u64 v[220:221], s[38:39], 0, v[218:219]
	v_lshl_add_u64 v[220:221], v[220:221], 0, v[162:163]
	global_load_dword v226, v[166:167], off offset:512
	global_load_dwordx4 v[232:235], v[220:221], off
	v_lshl_add_u64 v[220:221], v[218:219], 0, s[44:45]
	v_lshl_add_u64 v[224:225], s[38:39], 0, v[220:221]
	v_lshl_add_u64 v[222:223], s[16:17], 0, v[220:221]
	v_lshl_add_u64 v[224:225], v[224:225], 0, v[162:163]
	v_lshl_add_u64 v[222:223], v[222:223], 0, v[162:163]
	global_load_dwordx4 v[236:239], v[224:225], off
	global_load_dwordx4 v[240:243], v[222:223], off
	v_exp_f32_e32 v92, v92
	v_mul_f32_e32 v93, 0xbfb8aa3b, v93
	v_exp_f32_e32 v93, v93
	v_add_f32_e32 v92, 1.0, v92
	v_rcp_f32_e32 v92, v92
	v_add_f32_e32 v93, 1.0, v93
	v_rcp_f32_e32 v93, v93
	v_mul_f32_e32 v88, 0xbfb8aa3b, v88
	v_exp_f32_e32 v88, v88
	v_mul_f32_e32 v89, 0xbfb8aa3b, v89
	v_exp_f32_e32 v89, v89
	v_add_f32_e32 v88, 1.0, v88
	v_rcp_f32_e32 v88, v88
	v_add_f32_e32 v89, 1.0, v89
	v_mul_f32_e32 v84, 0xbfb8aa3b, v84
	v_rcp_f32_e32 v89, v89
	v_exp_f32_e32 v84, v84
	v_mul_f32_e32 v85, 0xbfb8aa3b, v85
	v_exp_f32_e32 v85, v85
	v_add_f32_e32 v84, 1.0, v84
	v_rcp_f32_e32 v84, v84
	v_add_f32_e32 v85, 1.0, v85
	v_rcp_f32_e32 v85, v85
	v_mul_f32_e32 v80, 0xbfb8aa3b, v80
	v_exp_f32_e32 v80, v80
	v_mul_f32_e32 v81, 0xbfb8aa3b, v81
	v_exp_f32_e32 v81, v81
	v_add_f32_e32 v80, 1.0, v80
	v_rcp_f32_e32 v80, v80
	v_add_f32_e32 v81, 1.0, v81
	v_rcp_f32_e32 v81, v81
	v_fmamk_f32 v118, v118, 0x3a000000, v180
	v_rsq_f32_e32 v118, v118
	v_mov_b32_dpp v119, v102 row_ror:8 row_mask:0xf bank_mask:0xf
	v_mov_b32_dpp v120, v103 row_ror:8 row_mask:0xf bank_mask:0xf
	v_mov_b32_dpp v121, v104 row_ror:8 row_mask:0xf bank_mask:0xf
; __device__ __forceinline__ unsigned cvt_pk_bf16(float lo, float hi) { unsigned r; asm volatile("v_cvt_pk_bf16_f32 %0, %1, %2" : "=v"(r) : "v"(lo), "v"(hi)); return r; }
; __device__ __forceinline__ float bflo(unsigned w) { return __uint_as_float(w << 16); }
; __device__ __forceinline__ float bfhi(unsigned w) { return __uint_as_float(w & 0xffff0000u); }
;     __device__ __forceinline__ void operator()(const f32x4 (&acc)[2][2][4][2], const Unit& u, int wr, int wc, int fr, int fq) const {
;     ...
;             for (int m = 0; m < 4; ++m) { const int row = row0 + ai * HALF + m * 16; const size_t off = (size_t)row * D + col0; const float ri = __builtin_amdgcn_rsqf(sse[row] * (1.f / D) + EPS); float sq = 0.f; u32x4 w[2];
;                 u32x4 rr[2], ee[2]; load_pair_lines(R, D, row, fr, col0, rr[0], rr[1]); load_pair_lines(E, D, row, fr, col0, ee[0], ee[1]);
; #pragma unroll
;                 for (int bj = 0; bj < 2; ++bj) { const u32x4 rw = rr[bj], ew = ee[bj];
;                     const float r[8] = {bflo(rw.x), bfhi(rw.x), bflo(rw.y), bfhi(rw.y), bflo(rw.z), bfhi(rw.z), bflo(rw.w), bfhi(rw.w)};
;                     const float e[8] = {bflo(ew.x), bfhi(ew.x), bflo(ew.y), bfhi(ew.y), bflo(ew.z), bfhi(ew.z), bflo(ew.w), bfhi(ew.w)};
;                     float o[8];
; #pragma unroll
;                     for (int j = 0; j < 8; ++j) { const float a = acc[ai][bj][m][j >> 2][j & 3]; const float gg = gv[bj][j >> 2][j & 3];
;                         o[j] = r[j] + e[j] * ri * gg * __builtin_amdgcn_rcpf(1.f + __builtin_amdgcn_exp2f(-a * LOG2E)); }
;                     if (OUT) { *(f32x4*)(OUT + off + 8 * bj) = (f32x4){o[0], o[1], o[2], o[3]}; *(f32x4*)(OUT + off + 8 * bj + 4) = (f32x4){o[4], o[5], o[6], o[7]}; }
;                     else { sq += (o[0] * o[0] + o[1] * o[1]) + (o[2] * o[2] + o[3] * o[3]) + (o[4] * o[4] + o[5] * o[5]) + (o[6] * o[6] + o[7] * o[7]);
;                         w[bj].x = cvt_pk_bf16(o[0], o[1]); w[bj].y = cvt_pk_bf16(o[2], o[3]); w[bj].z = cvt_pk_bf16(o[4], o[5]); w[bj].w = cvt_pk_bf16(o[6], o[7]); } }
;                 if (!OUT) { store_pair_lines(O, D, row, fr, col0, w[0], w[1]);
;                     sq += __shfl_xor(sq, 16); sq += __shfl_xor(sq, 32); if (fq == 0) unsafeAtomicAdd(ssout + row, sq); } }
	v_mov_b32_dpp v127, v106 row_ror:8 row_mask:0xf bank_mask:0xf
	v_mov_b32_dpp v128, v107 row_ror:8 row_mask:0xf bank_mask:0xf
	v_mov_b32_dpp v129, v108 row_ror:8 row_mask:0xf bank_mask:0xf
	v_mov_b32_dpp v130, v109 row_ror:8 row_mask:0xf bank_mask:0xf
	v_mov_b32_dpp v122, v105 row_ror:8 row_mask:0xf bank_mask:0xf
	v_mov_b32_dpp v131, v114 row_ror:8 row_mask:0xf bank_mask:0xf
	v_cndmask_b32_e64 v106, v131, v106, s[6:7]
	v_mov_b32_dpp v123, v110 row_ror:8 row_mask:0xf bank_mask:0xf
	v_cndmask_b32_e64 v102, v123, v102, s[6:7]
	v_lshlrev_b32_e32 v123, 16, v106
	v_mul_f32_e32 v123, v118, v123
	v_cndmask_b32_e64 v110, v110, v119, s[6:7]
	v_lshlrev_b32_e32 v119, 16, v102
	v_and_b32_e32 v106, 0xffff0000, v106
	v_mul_f32_e32 v123, v52, v123
	v_fmac_f32_e32 v119, v92, v123
	v_mul_f32_e32 v92, v118, v106
	v_and_b32_e32 v102, 0xffff0000, v102
	v_mul_f32_e32 v92, v53, v92
	v_fmac_f32_e32 v102, v93, v92
	v_mul_f32_e32 v92, 0xbfb8aa3b, v94
	v_exp_f32_e32 v92, v92
	v_mul_f32_e32 v94, 0xbfb8aa3b, v95
	v_exp_f32_e32 v94, v94
	v_mov_b32_dpp v132, v115 row_ror:8 row_mask:0xf bank_mask:0xf
	v_add_f32_e32 v92, 1.0, v92
	v_mov_b32_dpp v124, v111 row_ror:8 row_mask:0xf bank_mask:0xf
	v_cndmask_b32_e64 v107, v132, v107, s[6:7]
	v_rcp_f32_e32 v92, v92
	v_cndmask_b32_e64 v103, v124, v103, s[6:7]
	v_lshlrev_b32_e32 v124, 16, v107
	v_add_f32_e32 v94, 1.0, v94
	v_mul_f32_e32 v93, v118, v124
	v_rcp_f32_e32 v94, v94
	v_cndmask_b32_e64 v111, v111, v120, s[6:7]
	v_mov_b32_dpp v133, v116 row_ror:8 row_mask:0xf bank_mask:0xf
	v_lshlrev_b32_e32 v120, 16, v103
	v_and_b32_e32 v107, 0xffff0000, v107
	v_mul_f32_e32 v93, v54, v93
	v_mov_b32_dpp v125, v112 row_ror:8 row_mask:0xf bank_mask:0xf
	v_cndmask_b32_e64 v108, v133, v108, s[6:7]
	v_fmac_f32_e32 v120, v92, v93
	v_mul_f32_e32 v92, v118, v107
	v_cndmask_b32_e64 v104, v125, v104, s[6:7]
	v_and_b32_e32 v103, 0xffff0000, v103
	v_lshlrev_b32_e32 v125, 16, v108
	v_mul_f32_e32 v92, v55, v92
	v_fmac_f32_e32 v103, v94, v92
	v_mul_f32_e32 v92, v118, v125
	v_cndmask_b32_e64 v112, v112, v121, s[6:7]
	v_lshlrev_b32_e32 v121, 16, v104
	v_and_b32_e32 v108, 0xffff0000, v108
	v_mul_f32_e32 v92, v48, v92
	v_fmac_f32_e32 v121, v88, v92
	v_mul_f32_e32 v88, v118, v108
	v_and_b32_e32 v104, 0xffff0000, v104
	v_mul_f32_e32 v88, v49, v88
	v_fmac_f32_e32 v104, v89, v88
	v_mul_f32_e32 v88, 0xbfb8aa3b, v90
	v_cndmask_b32_e64 v114, v114, v127, s[6:7]
	v_exp_f32_e32 v88, v88
	v_mul_f32_e32 v90, 0xbfb8aa3b, v91
	v_lshlrev_b32_e32 v107, 16, v114
	v_exp_f32_e32 v90, v90
	v_mul_f32_e32 v107, v118, v107
	v_lshlrev_b32_e32 v93, 16, v110
	v_and_b32_e32 v108, 0xffff0000, v114
	v_mul_f32_e32 v107, v40, v107
	v_mov_b32_dpp v136, v117 row_ror:8 row_mask:0xf bank_mask:0xf
	v_add_f32_e32 v88, 1.0, v88
	v_fmac_f32_e32 v93, v84, v107
	v_mul_f32_e32 v84, v118, v108
	v_mov_b32_dpp v126, v113 row_ror:8 row_mask:0xf bank_mask:0xf
	v_cndmask_b32_e64 v109, v136, v109, s[6:7]
	v_rcp_f32_e32 v88, v88
	v_and_b32_e32 v94, 0xffff0000, v110
	v_mul_f32_e32 v84, v41, v84
	v_cndmask_b32_e64 v105, v126, v105, s[6:7]
	v_lshlrev_b32_e32 v126, 16, v109
	v_add_f32_e32 v90, 1.0, v90
	v_fmac_f32_e32 v94, v85, v84
	v_mul_f32_e32 v84, 0xbfb8aa3b, v86
	v_mul_f32_e32 v89, v118, v126
	v_rcp_f32_e32 v90, v90
	v_exp_f32_e32 v84, v84
	v_cndmask_b32_e64 v113, v113, v122, s[6:7]
	v_lshlrev_b32_e32 v122, 16, v105
	v_and_b32_e32 v109, 0xffff0000, v109
	v_mul_f32_e32 v89, v50, v89
	v_mul_f32_e32 v86, 0xbfb8aa3b, v87
	v_fmac_f32_e32 v122, v88, v89
	v_mul_f32_e32 v88, v118, v109
	v_exp_f32_e32 v86, v86
	v_and_b32_e32 v105, 0xffff0000, v105
	v_mul_f32_e32 v88, v51, v88
	v_fmac_f32_e32 v105, v90, v88
	v_mul_f32_e32 v88, v102, v102
	v_mul_f32_e32 v89, v103, v103
	v_add_f32_e32 v84, 1.0, v84
	v_cndmask_b32_e64 v115, v115, v128, s[6:7]
	v_fmac_f32_e32 v88, v119, v119
	v_fmac_f32_e32 v89, v120, v120
	v_rcp_f32_e32 v84, v84
	v_add_f32_e32 v88, v88, v89
	v_mul_f32_e32 v89, v104, v104
	v_lshlrev_b32_e32 v109, 16, v115
	v_add_f32_e32 v86, 1.0, v86
	v_fmac_f32_e32 v89, v121, v121
	v_mul_f32_e32 v85, v118, v109
	v_rcp_f32_e32 v86, v86
	v_add_f32_e32 v88, v89, v88
	v_mul_f32_e32 v89, v105, v105
	v_lshlrev_b32_e32 v95, 16, v111
	v_and_b32_e32 v110, 0xffff0000, v115
	v_mul_f32_e32 v85, v42, v85
	v_cndmask_b32_e64 v116, v116, v129, s[6:7]
	v_fmac_f32_e32 v89, v122, v122
	v_fmac_f32_e32 v95, v84, v85
	v_mul_f32_e32 v84, v118, v110
	v_add_f32_e32 v88, v89, v88
	v_cvt_pk_bf16_f32 v89, v119, v102
	v_and_b32_e32 v102, 0xffff0000, v111
	v_lshlrev_b32_e32 v111, 16, v116
	v_mul_f32_e32 v84, v43, v84
	v_fmac_f32_e32 v102, v86, v84
	v_mul_f32_e32 v84, v118, v111
	v_cvt_pk_bf16_f32 v90, v120, v103
	v_cvt_pk_bf16_f32 v91, v121, v104
	v_lshlrev_b32_e32 v103, 16, v112
	v_and_b32_e32 v104, 0xffff0000, v112
	v_and_b32_e32 v112, 0xffff0000, v116
	v_mul_f32_e32 v84, v32, v84
	v_fmac_f32_e32 v103, v80, v84
	v_mul_f32_e32 v80, v118, v112
	v_mul_f32_e32 v80, v33, v80
	v_fmac_f32_e32 v104, v81, v80
	v_mul_f32_e32 v80, 0xbfb8aa3b, v82
	v_exp_f32_e32 v80, v80
	v_mul_f32_e32 v82, 0xbfb8aa3b, v83
	v_exp_f32_e32 v82, v82
	v_cndmask_b32_e64 v117, v117, v130, s[6:7]
	v_add_f32_e32 v80, 1.0, v80
	v_rcp_f32_e32 v80, v80
	v_cvt_pk_bf16_f32 v92, v122, v105
	v_lshlrev_b32_e32 v105, 16, v113
	v_and_b32_e32 v106, 0xffff0000, v113
	v_lshlrev_b32_e32 v113, 16, v117
	v_add_f32_e32 v82, 1.0, v82
	v_mul_f32_e32 v81, v118, v113
	v_rcp_f32_e32 v82, v82
	v_and_b32_e32 v114, 0xffff0000, v117
	v_mul_f32_e32 v81, v34, v81
	v_fmac_f32_e32 v105, v80, v81
	v_mul_f32_e32 v80, v118, v114
	v_mul_f32_e32 v80, v35, v80
	v_fmac_f32_e32 v106, v82, v80
	v_mul_f32_e32 v80, v94, v94
	v_mul_f32_e32 v81, v102, v102
	v_fmac_f32_e32 v80, v93, v93
	v_fmac_f32_e32 v81, v95, v95
	v_add_f32_e32 v80, v80, v81
	v_mul_f32_e32 v81, v104, v104
	v_fmac_f32_e32 v81, v103, v103
	v_add_f32_e32 v80, v81, v80
	v_mul_f32_e32 v81, v106, v106
	v_fmac_f32_e32 v81, v105, v105
	v_add_f32_e32 v80, v81, v80
	v_add_f32_e32 v107, v80, v88
	v_cvt_pk_bf16_f32 v80, v93, v94
	v_cvt_pk_bf16_f32 v81, v95, v102
	v_cvt_pk_bf16_f32 v88, v103, v104
	v_cvt_pk_bf16_f32 v93, v105, v106
	v_mov_b32_e32 v95, 0
	v_mov_b32_e32 v86, 0
	v_mov_b32_dpp v85, v93 row_ror:8 row_mask:0xf bank_mask:0xf
	v_mov_b32_dpp v95, v92 row_ror:8 row_mask:0xf bank_mask:0xf
	v_cndmask_b32_e64 v85, v85, v92, s[6:7]
	ds_bpermute_b32 v92, v134, v107
	v_mov_b32_dpp v86, v89 row_ror:8 row_mask:0xf bank_mask:0xf
	v_mov_b32_dpp v87, v90 row_ror:8 row_mask:0xf bank_mask:0xf
	v_mov_b32_dpp v82, v80 row_ror:8 row_mask:0xf bank_mask:0xf
	v_mov_b32_dpp v83, v81 row_ror:8 row_mask:0xf bank_mask:0xf
	v_mov_b32_dpp v84, v88 row_ror:8 row_mask:0xf bank_mask:0xf
	v_cndmask_b32_e64 v86, v80, v86, s[6:7]
	v_cndmask_b32_e64 v87, v81, v87, s[6:7]
	v_lshl_add_u64 v[80:81], s[36:37], 0, v[98:99]
	v_mov_b32_dpp v94, v91 row_ror:8 row_mask:0xf bank_mask:0xf
	v_cndmask_b32_e64 v83, v83, v90, s[6:7]
	v_cndmask_b32_e64 v84, v84, v91, s[6:7]
	v_lshl_add_u64 v[90:91], v[80:81], 0, v[162:163]
	s_waitcnt lgkmcnt(0)
; __device__ __forceinline__ unsigned cvt_pk_bf16(float lo, float hi) { unsigned r; asm volatile("v_cvt_pk_bf16_f32 %0, %1, %2" : "=v"(r) : "v"(lo), "v"(hi)); return r; }
;     __device__ __forceinline__ void operator()(const f32x4 (&acc)[2][2][4][2], const Unit& u, int wr, int wc, int fr, int fq) const {
;     ...
;             for (int m = 0; m < 4; ++m) { const int row = row0 + ai * HALF + m * 16; const size_t off = (size_t)row * D + col0; const float ri = __builtin_amdgcn_rsqf(sse[row] * (1.f / D) + EPS); float sq = 0.f; u32x4 w[2];
;                 u32x4 rr[2], ee[2]; load_pair_lines(R, D, row, fr, col0, rr[0], rr[1]); load_pair_lines(E, D, row, fr, col0, ee[0], ee[1]);
;     ...
;                     for (int j = 0; j < 8; ++j) { const float a = acc[ai][bj][m][j >> 2][j & 3]; const float gg = gv[bj][j >> 2][j & 3];
;                         o[j] = r[j] + e[j] * ri * gg * __builtin_amdgcn_rcpf(1.f + __builtin_amdgcn_exp2f(-a * LOG2E)); }
;                     if (OUT) { *(f32x4*)(OUT + off + 8 * bj) = (f32x4){o[0], o[1], o[2], o[3]}; *(f32x4*)(OUT + off + 8 * bj + 4) = (f32x4){o[4], o[5], o[6], o[7]}; }
;                     else { sq += (o[0] * o[0] + o[1] * o[1]) + (o[2] * o[2] + o[3] * o[3]) + (o[4] * o[4] + o[5] * o[5]) + (o[6] * o[6] + o[7] * o[7]);
;                         w[bj].x = cvt_pk_bf16(o[0], o[1]); w[bj].y = cvt_pk_bf16(o[2], o[3]); w[bj].z = cvt_pk_bf16(o[4], o[5]); w[bj].w = cvt_pk_bf16(o[6], o[7]); } }
;                 if (!OUT) { store_pair_lines(O, D, row, fr, col0, w[0], w[1]);
;                     sq += __shfl_xor(sq, 16); sq += __shfl_xor(sq, 32); if (fq == 0) unsafeAtomicAdd(ssout + row, sq); } }
	v_add_f32_e32 v80, v107, v92
	v_mov_b32_e32 v81, v80
	s_nop 1
	v_permlane32_swap_b32_e32 v81, v80
	v_cndmask_b32_e64 v82, v82, v89, s[6:7]
	global_store_dwordx4 v[90:91], v[82:85], off
	v_cndmask_b32_e64 v88, v88, v94, s[6:7]
	v_cndmask_b32_e64 v89, v93, v95, s[6:7]
	v_lshl_add_u64 v[82:83], s[36:37], 0, v[100:101]
	v_lshl_add_u64 v[82:83], v[82:83], 0, v[162:163]
	global_store_dwordx4 v[82:83], v[86:89], off
	s_and_saveexec_b64 s[56:57], s[8:9]
	s_cbranch_execz .LBB0_891
	v_lshl_add_u64 v[82:83], v[96:97], 2, s[18:19]
	s_waitcnt lgkmcnt(0)
	v_add_f32_e32 v80, v80, v81
	global_atomic_add_f32 v[82:83], v80, off
.LBB0_891:
	s_or_b64 exec, exec, s[56:57]
	v_add_u32_e32 v80, 0x80, v164
	v_sub_u32_e32 v82, v80, v172
	v_add_u32_e32 v82, v82, v174
	v_ashrrev_i32_e32 v83, 31, v82
	v_lshlrev_b64 v[82:83], 12, v[82:83]
	v_lshl_add_u64 v[84:85], s[16:17], 0, v[82:83]
	v_lshl_add_u64 v[84:85], v[84:85], 0, v[162:163]
	s_waitcnt vmcnt(2)
	s_nop 0
	v_mov_b64_e32 v[86:87], v[228:229]
	v_mov_b64_e32 v[88:89], v[230:231]
	v_lshl_add_u64 v[84:85], s[38:39], 0, v[82:83]
	v_lshl_add_u64 v[84:85], v[84:85], 0, v[162:163]
	s_waitcnt lgkmcnt(0)
	v_mov_b32_e32 v81, v226
	v_mov_b64_e32 v[90:91], v[232:233]
	v_mov_b64_e32 v[92:93], v[234:235]
	v_lshl_add_u64 v[84:85], v[82:83], 0, s[44:45]
	v_lshl_add_u64 v[98:99], s[38:39], 0, v[84:85]
	v_lshl_add_u64 v[94:95], s[16:17], 0, v[84:85]
	v_lshl_add_u64 v[98:99], v[98:99], 0, v[162:163]
	v_lshl_add_u64 v[94:95], v[94:95], 0, v[162:163]
	v_mov_b64_e32 v[98:99], v[236:237]
	v_mov_b64_e32 v[100:101], v[238:239]
	v_mul_f32_e32 v76, 0xbfb8aa3b, v76
	v_mov_b64_e32 v[94:95], v[240:241]
	v_mov_b64_e32 v[96:97], v[242:243]
	s_nop 1
	v_add_u32_e32 v216, 0x90, v164
	v_sub_u32_e32 v218, v216, v172
	v_add_u32_e32 v218, v218, v174
	v_ashrrev_i32_e32 v219, 31, v218
	v_lshlrev_b64 v[218:219], 12, v[218:219]
	v_lshl_add_u64 v[220:221], s[16:17], 0, v[218:219]
	v_lshl_add_u64 v[220:221], v[220:221], 0, v[162:163]
	global_load_dwordx4 v[228:231], v[220:221], off
	v_lshl_add_u64 v[220:221], s[38:39], 0, v[218:219]
	v_lshl_add_u64 v[220:221], v[220:221], 0, v[162:163]
	global_load_dword v226, v[166:167], off offset:576
	global_load_dwordx4 v[232:235], v[220:221], off
	v_lshl_add_u64 v[220:221], v[218:219], 0, s[44:45]
	v_lshl_add_u64 v[224:225], s[38:39], 0, v[220:221]
	v_lshl_add_u64 v[222:223], s[16:17], 0, v[220:221]
	v_lshl_add_u64 v[224:225], v[224:225], 0, v[162:163]
	v_lshl_add_u64 v[222:223], v[222:223], 0, v[162:163]
	global_load_dwordx4 v[236:239], v[224:225], off
	global_load_dwordx4 v[240:243], v[222:223], off
	v_exp_f32_e32 v76, v76
	v_mul_f32_e32 v77, 0xbfb8aa3b, v77
	v_exp_f32_e32 v77, v77
	v_add_f32_e32 v76, 1.0, v76
	v_rcp_f32_e32 v76, v76
	v_add_f32_e32 v77, 1.0, v77
	v_rcp_f32_e32 v77, v77
	v_mul_f32_e32 v72, 0xbfb8aa3b, v72
	v_exp_f32_e32 v72, v72
	v_mul_f32_e32 v73, 0xbfb8aa3b, v73
	v_exp_f32_e32 v73, v73
	v_add_f32_e32 v72, 1.0, v72
	v_rcp_f32_e32 v72, v72
	v_add_f32_e32 v73, 1.0, v73
	v_mul_f32_e32 v68, 0xbfb8aa3b, v68
	v_rcp_f32_e32 v73, v73
	v_exp_f32_e32 v68, v68
	v_mul_f32_e32 v69, 0xbfb8aa3b, v69
	v_exp_f32_e32 v69, v69
	v_add_f32_e32 v68, 1.0, v68
	v_rcp_f32_e32 v68, v68
	v_add_f32_e32 v69, 1.0, v69
	v_rcp_f32_e32 v69, v69
	v_mul_f32_e32 v64, 0xbfb8aa3b, v64
	v_exp_f32_e32 v64, v64
	v_mul_f32_e32 v65, 0xbfb8aa3b, v65
	v_exp_f32_e32 v65, v65
	v_add_f32_e32 v64, 1.0, v64
	v_rcp_f32_e32 v64, v64
	v_add_f32_e32 v65, 1.0, v65
	v_rcp_f32_e32 v65, v65
	v_mov_b32_dpp v102, v86 row_ror:8 row_mask:0xf bank_mask:0xf
	v_mov_b32_dpp v103, v87 row_ror:8 row_mask:0xf bank_mask:0xf
	v_mov_b32_dpp v104, v88 row_ror:8 row_mask:0xf bank_mask:0xf
	v_fmamk_f32 v81, v81, 0x3a000000, v180
	v_rsq_f32_e32 v81, v81
	v_mov_b32_dpp v110, v90 row_ror:8 row_mask:0xf bank_mask:0xf
	v_mov_b32_dpp v111, v91 row_ror:8 row_mask:0xf bank_mask:0xf
	v_mov_b32_dpp v112, v92 row_ror:8 row_mask:0xf bank_mask:0xf
	v_mov_b32_dpp v113, v93 row_ror:8 row_mask:0xf bank_mask:0xf
	v_mov_b32_dpp v105, v89 row_ror:8 row_mask:0xf bank_mask:0xf
	v_mov_b32_dpp v114, v98 row_ror:8 row_mask:0xf bank_mask:0xf
	v_cndmask_b32_e64 v90, v114, v90, s[6:7]
	v_mov_b32_dpp v106, v94 row_ror:8 row_mask:0xf bank_mask:0xf
	v_cndmask_b32_e64 v86, v106, v86, s[6:7]
	v_lshlrev_b32_e32 v106, 16, v90
	v_mul_f32_e32 v106, v81, v106
	v_cndmask_b32_e64 v94, v94, v102, s[6:7]
	v_lshlrev_b32_e32 v102, 16, v86
	v_and_b32_e32 v90, 0xffff0000, v90
	v_mul_f32_e32 v106, v52, v106
	v_fmac_f32_e32 v102, v76, v106
	v_mul_f32_e32 v76, v81, v90
	v_and_b32_e32 v86, 0xffff0000, v86
	v_mul_f32_e32 v76, v53, v76
	v_fmac_f32_e32 v86, v77, v76
	v_mul_f32_e32 v76, 0xbfb8aa3b, v78
	v_exp_f32_e32 v76, v76
	v_mul_f32_e32 v78, 0xbfb8aa3b, v79
	v_exp_f32_e32 v78, v78
	v_mov_b32_dpp v115, v99 row_ror:8 row_mask:0xf bank_mask:0xf
	v_add_f32_e32 v76, 1.0, v76
	v_mov_b32_dpp v107, v95 row_ror:8 row_mask:0xf bank_mask:0xf
	v_cndmask_b32_e64 v91, v115, v91, s[6:7]
	v_rcp_f32_e32 v76, v76
	v_cndmask_b32_e64 v87, v107, v87, s[6:7]
	v_lshlrev_b32_e32 v107, 16, v91
	v_add_f32_e32 v78, 1.0, v78
	v_mul_f32_e32 v77, v81, v107
	v_rcp_f32_e32 v78, v78
	v_cndmask_b32_e64 v95, v95, v103, s[6:7]
	v_mov_b32_dpp v116, v100 row_ror:8 row_mask:0xf bank_mask:0xf
	v_lshlrev_b32_e32 v103, 16, v87
	v_and_b32_e32 v91, 0xffff0000, v91
	v_mul_f32_e32 v77, v54, v77
	v_mov_b32_dpp v108, v96 row_ror:8 row_mask:0xf bank_mask:0xf
	v_cndmask_b32_e64 v92, v116, v92, s[6:7]
	v_fmac_f32_e32 v103, v76, v77
	v_mul_f32_e32 v76, v81, v91
	v_cndmask_b32_e64 v88, v108, v88, s[6:7]
	v_and_b32_e32 v87, 0xffff0000, v87
	v_lshlrev_b32_e32 v108, 16, v92
	v_mul_f32_e32 v76, v55, v76
	v_fmac_f32_e32 v87, v78, v76
	v_mul_f32_e32 v76, v81, v108
; __device__ __forceinline__ unsigned cvt_pk_bf16(float lo, float hi) { unsigned r; asm volatile("v_cvt_pk_bf16_f32 %0, %1, %2" : "=v"(r) : "v"(lo), "v"(hi)); return r; }
; __device__ __forceinline__ float bflo(unsigned w) { return __uint_as_float(w << 16); }
; __device__ __forceinline__ float bfhi(unsigned w) { return __uint_as_float(w & 0xffff0000u); }
;     __device__ __forceinline__ void operator()(const f32x4 (&acc)[2][2][4][2], const Unit& u, int wr, int wc, int fr, int fq) const {
;     ...
;             for (int m = 0; m < 4; ++m) { const int row = row0 + ai * HALF + m * 16; const size_t off = (size_t)row * D + col0; const float ri = __builtin_amdgcn_rsqf(sse[row] * (1.f / D) + EPS); float sq = 0.f; u32x4 w[2];
;                 u32x4 rr[2], ee[2]; load_pair_lines(R, D, row, fr, col0, rr[0], rr[1]); load_pair_lines(E, D, row, fr, col0, ee[0], ee[1]);
; #pragma unroll
;                 for (int bj = 0; bj < 2; ++bj) { const u32x4 rw = rr[bj], ew = ee[bj];
;                     const float r[8] = {bflo(rw.x), bfhi(rw.x), bflo(rw.y), bfhi(rw.y), bflo(rw.z), bfhi(rw.z), bflo(rw.w), bfhi(rw.w)};
;                     const float e[8] = {bflo(ew.x), bfhi(ew.x), bflo(ew.y), bfhi(ew.y), bflo(ew.z), bfhi(ew.z), bflo(ew.w), bfhi(ew.w)};
;                     float o[8];
; #pragma unroll
;                     for (int j = 0; j < 8; ++j) { const float a = acc[ai][bj][m][j >> 2][j & 3]; const float gg = gv[bj][j >> 2][j & 3];
;                         o[j] = r[j] + e[j] * ri * gg * __builtin_amdgcn_rcpf(1.f + __builtin_amdgcn_exp2f(-a * LOG2E)); }
;                     if (OUT) { *(f32x4*)(OUT + off + 8 * bj) = (f32x4){o[0], o[1], o[2], o[3]}; *(f32x4*)(OUT + off + 8 * bj + 4) = (f32x4){o[4], o[5], o[6], o[7]}; }
;                     else { sq += (o[0] * o[0] + o[1] * o[1]) + (o[2] * o[2] + o[3] * o[3]) + (o[4] * o[4] + o[5] * o[5]) + (o[6] * o[6] + o[7] * o[7]);
;                         w[bj].x = cvt_pk_bf16(o[0], o[1]); w[bj].y = cvt_pk_bf16(o[2], o[3]); w[bj].z = cvt_pk_bf16(o[4], o[5]); w[bj].w = cvt_pk_bf16(o[6], o[7]); } }
;                 if (!OUT) { store_pair_lines(O, D, row, fr, col0, w[0], w[1]);
;                     sq += __shfl_xor(sq, 16); sq += __shfl_xor(sq, 32); if (fq == 0) unsafeAtomicAdd(ssout + row, sq); } }
	v_cndmask_b32_e64 v96, v96, v104, s[6:7]
	v_lshlrev_b32_e32 v104, 16, v88
	v_and_b32_e32 v92, 0xffff0000, v92
	v_mul_f32_e32 v76, v48, v76
	v_fmac_f32_e32 v104, v72, v76
	v_mul_f32_e32 v72, v81, v92
	v_and_b32_e32 v88, 0xffff0000, v88
	v_mul_f32_e32 v72, v49, v72
	v_fmac_f32_e32 v88, v73, v72
	v_mul_f32_e32 v72, 0xbfb8aa3b, v74
	v_cndmask_b32_e64 v98, v98, v110, s[6:7]
	v_exp_f32_e32 v72, v72
	v_mul_f32_e32 v74, 0xbfb8aa3b, v75
	v_lshlrev_b32_e32 v91, 16, v98
	v_exp_f32_e32 v74, v74
	v_mul_f32_e32 v91, v81, v91
	v_lshlrev_b32_e32 v77, 16, v94
	v_and_b32_e32 v92, 0xffff0000, v98
	v_mul_f32_e32 v91, v40, v91
	v_mov_b32_dpp v117, v101 row_ror:8 row_mask:0xf bank_mask:0xf
	v_add_f32_e32 v72, 1.0, v72
	v_fmac_f32_e32 v77, v68, v91
	v_mul_f32_e32 v68, v81, v92
	v_mov_b32_dpp v109, v97 row_ror:8 row_mask:0xf bank_mask:0xf
	v_cndmask_b32_e64 v93, v117, v93, s[6:7]
	v_rcp_f32_e32 v72, v72
	v_and_b32_e32 v78, 0xffff0000, v94
	v_mul_f32_e32 v68, v41, v68
	v_cndmask_b32_e64 v89, v109, v89, s[6:7]
	v_lshlrev_b32_e32 v109, 16, v93
	v_add_f32_e32 v74, 1.0, v74
	v_fmac_f32_e32 v78, v69, v68
	v_mul_f32_e32 v68, 0xbfb8aa3b, v70
	v_mul_f32_e32 v73, v81, v109
	v_rcp_f32_e32 v74, v74
	v_exp_f32_e32 v68, v68
	v_cndmask_b32_e64 v97, v97, v105, s[6:7]
	v_lshlrev_b32_e32 v105, 16, v89
	v_and_b32_e32 v93, 0xffff0000, v93
	v_mul_f32_e32 v73, v50, v73
	v_mul_f32_e32 v70, 0xbfb8aa3b, v71
	v_fmac_f32_e32 v105, v72, v73
	v_mul_f32_e32 v72, v81, v93
	v_exp_f32_e32 v70, v70
	v_and_b32_e32 v89, 0xffff0000, v89
	v_mul_f32_e32 v72, v51, v72
	v_fmac_f32_e32 v89, v74, v72
	v_mul_f32_e32 v72, v86, v86
	v_mul_f32_e32 v73, v87, v87
	v_add_f32_e32 v68, 1.0, v68
	v_cndmask_b32_e64 v99, v99, v111, s[6:7]
	v_fmac_f32_e32 v72, v102, v102
	v_fmac_f32_e32 v73, v103, v103
	v_rcp_f32_e32 v68, v68
	v_add_f32_e32 v72, v72, v73
	v_mul_f32_e32 v73, v88, v88
	v_lshlrev_b32_e32 v93, 16, v99
	v_add_f32_e32 v70, 1.0, v70
	v_fmac_f32_e32 v73, v104, v104
	v_mul_f32_e32 v69, v81, v93
	v_rcp_f32_e32 v70, v70
	v_add_f32_e32 v72, v73, v72
	v_mul_f32_e32 v73, v89, v89
	v_lshlrev_b32_e32 v79, 16, v95
	v_and_b32_e32 v94, 0xffff0000, v99
	v_mul_f32_e32 v69, v42, v69
	v_cndmask_b32_e64 v100, v100, v112, s[6:7]
	v_fmac_f32_e32 v73, v105, v105
	v_fmac_f32_e32 v79, v68, v69
	v_mul_f32_e32 v68, v81, v94
	v_add_f32_e32 v72, v73, v72
	v_cvt_pk_bf16_f32 v73, v102, v86
	v_and_b32_e32 v86, 0xffff0000, v95
	v_lshlrev_b32_e32 v95, 16, v100
	v_mul_f32_e32 v68, v43, v68
	v_fmac_f32_e32 v86, v70, v68
	v_mul_f32_e32 v68, v81, v95
	v_cvt_pk_bf16_f32 v74, v103, v87
	v_cvt_pk_bf16_f32 v75, v104, v88
	v_lshlrev_b32_e32 v87, 16, v96
	v_and_b32_e32 v88, 0xffff0000, v96
	v_and_b32_e32 v96, 0xffff0000, v100
	v_mul_f32_e32 v68, v32, v68
	v_fmac_f32_e32 v87, v64, v68
	v_mul_f32_e32 v64, v81, v96
	v_mul_f32_e32 v64, v33, v64
	v_fmac_f32_e32 v88, v65, v64
	v_mul_f32_e32 v64, 0xbfb8aa3b, v66
	v_exp_f32_e32 v64, v64
	v_mul_f32_e32 v66, 0xbfb8aa3b, v67
	v_exp_f32_e32 v66, v66
	v_cndmask_b32_e64 v101, v101, v113, s[6:7]
	v_add_f32_e32 v64, 1.0, v64
	v_rcp_f32_e32 v64, v64
	v_cvt_pk_bf16_f32 v76, v105, v89
	v_lshlrev_b32_e32 v89, 16, v97
	v_and_b32_e32 v90, 0xffff0000, v97
	v_lshlrev_b32_e32 v97, 16, v101
	v_add_f32_e32 v66, 1.0, v66
	v_mul_f32_e32 v65, v81, v97
	v_rcp_f32_e32 v66, v66
	v_and_b32_e32 v98, 0xffff0000, v101
	v_mul_f32_e32 v65, v34, v65
	v_fmac_f32_e32 v89, v64, v65
	v_mul_f32_e32 v64, v81, v98
	v_mul_f32_e32 v64, v35, v64
	v_fmac_f32_e32 v90, v66, v64
	v_mul_f32_e32 v64, v78, v78
	v_mul_f32_e32 v65, v86, v86
	v_fmac_f32_e32 v64, v77, v77
	v_fmac_f32_e32 v65, v79, v79
	v_add_f32_e32 v64, v64, v65
	v_mul_f32_e32 v65, v88, v88
	v_fmac_f32_e32 v65, v87, v87
	v_add_f32_e32 v64, v65, v64
	v_mul_f32_e32 v65, v90, v90
	v_fmac_f32_e32 v65, v89, v89
	v_add_f32_e32 v64, v65, v64
	v_add_f32_e32 v81, v64, v72
	v_cvt_pk_bf16_f32 v64, v77, v78
	v_cvt_pk_bf16_f32 v65, v79, v86
	v_cvt_pk_bf16_f32 v72, v87, v88
	v_cvt_pk_bf16_f32 v77, v89, v90
	v_mov_b32_e32 v79, 0
	v_mov_b32_e32 v70, 0
	v_mov_b32_dpp v69, v77 row_ror:8 row_mask:0xf bank_mask:0xf
	v_mov_b32_dpp v79, v76 row_ror:8 row_mask:0xf bank_mask:0xf
	v_cndmask_b32_e64 v69, v69, v76, s[6:7]
	v_mov_b32_e32 v76, v81
	s_nop 1
	v_permlane16_swap_b32_e32 v76, v81
	v_mov_b32_dpp v70, v73 row_ror:8 row_mask:0xf bank_mask:0xf
	v_mov_b32_dpp v71, v74 row_ror:8 row_mask:0xf bank_mask:0xf
	v_mov_b32_dpp v66, v64 row_ror:8 row_mask:0xf bank_mask:0xf
	v_mov_b32_dpp v67, v65 row_ror:8 row_mask:0xf bank_mask:0xf
	v_mov_b32_dpp v68, v72 row_ror:8 row_mask:0xf bank_mask:0xf
	v_cndmask_b32_e64 v70, v64, v70, s[6:7]
	v_cndmask_b32_e64 v71, v65, v71, s[6:7]
	v_lshl_add_u64 v[64:65], s[36:37], 0, v[82:83]
	v_mov_b32_dpp v78, v75 row_ror:8 row_mask:0xf bank_mask:0xf
	v_cndmask_b32_e64 v67, v67, v74, s[6:7]
	v_cndmask_b32_e64 v68, v68, v75, s[6:7]
	v_lshl_add_u64 v[74:75], v[64:65], 0, v[162:163]
	s_waitcnt lgkmcnt(0)
	v_add_f32_e32 v64, v81, v76
	v_mov_b32_e32 v65, v64
	s_nop 1
	v_permlane32_swap_b32_e32 v65, v64
	v_cndmask_b32_e64 v66, v66, v73, s[6:7]
	global_store_dwordx4 v[74:75], v[66:69], off
	v_cndmask_b32_e64 v72, v72, v78, s[6:7]
	v_cndmask_b32_e64 v73, v77, v79, s[6:7]
	v_lshl_add_u64 v[66:67], s[36:37], 0, v[84:85]
	v_lshl_add_u64 v[66:67], v[66:67], 0, v[162:163]
	global_store_dwordx4 v[66:67], v[70:73], off
	s_and_saveexec_b64 s[56:57], s[8:9]
	s_cbranch_execz .LBB0_893
	v_ashrrev_i32_e32 v81, 31, v80
	v_lshl_add_u64 v[66:67], v[80:81], 2, s[18:19]
	s_waitcnt lgkmcnt(0)
	v_add_f32_e32 v64, v64, v65
	global_atomic_add_f32 v[66:67], v64, off
; __device__ __forceinline__ unsigned cvt_pk_bf16(float lo, float hi) { unsigned r; asm volatile("v_cvt_pk_bf16_f32 %0, %1, %2" : "=v"(r) : "v"(lo), "v"(hi)); return r; }
; __device__ __forceinline__ float bflo(unsigned w) { return __uint_as_float(w << 16); }
; __device__ __forceinline__ float bfhi(unsigned w) { return __uint_as_float(w & 0xffff0000u); }
;     __device__ __forceinline__ void operator()(const f32x4 (&acc)[2][2][4][2], const Unit& u, int wr, int wc, int fr, int fq) const {
;     ...
;             for (int m = 0; m < 4; ++m) { const int row = row0 + ai * HALF + m * 16; const size_t off = (size_t)row * D + col0; const float ri = __builtin_amdgcn_rsqf(sse[row] * (1.f / D) + EPS); float sq = 0.f; u32x4 w[2];
;                 u32x4 rr[2], ee[2]; load_pair_lines(R, D, row, fr, col0, rr[0], rr[1]); load_pair_lines(E, D, row, fr, col0, ee[0], ee[1]);
; #pragma unroll
;                 for (int bj = 0; bj < 2; ++bj) { const u32x4 rw = rr[bj], ew = ee[bj];
;                     const float r[8] = {bflo(rw.x), bfhi(rw.x), bflo(rw.y), bfhi(rw.y), bflo(rw.z), bfhi(rw.z), bflo(rw.w), bfhi(rw.w)};
;                     const float e[8] = {bflo(ew.x), bfhi(ew.x), bflo(ew.y), bfhi(ew.y), bflo(ew.z), bfhi(ew.z), bflo(ew.w), bfhi(ew.w)};
;                     float o[8];
; #pragma unroll
;                     for (int j = 0; j < 8; ++j) { const float a = acc[ai][bj][m][j >> 2][j & 3]; const float gg = gv[bj][j >> 2][j & 3];
;                         o[j] = r[j] + e[j] * ri * gg * __builtin_amdgcn_rcpf(1.f + __builtin_amdgcn_exp2f(-a * LOG2E)); }
;                     if (OUT) { *(f32x4*)(OUT + off + 8 * bj) = (f32x4){o[0], o[1], o[2], o[3]}; *(f32x4*)(OUT + off + 8 * bj + 4) = (f32x4){o[4], o[5], o[6], o[7]}; }
;                     else { sq += (o[0] * o[0] + o[1] * o[1]) + (o[2] * o[2] + o[3] * o[3]) + (o[4] * o[4] + o[5] * o[5]) + (o[6] * o[6] + o[7] * o[7]);
;                         w[bj].x = cvt_pk_bf16(o[0], o[1]); w[bj].y = cvt_pk_bf16(o[2], o[3]); w[bj].z = cvt_pk_bf16(o[4], o[5]); w[bj].w = cvt_pk_bf16(o[6], o[7]); } }
.LBB0_893:
	s_or_b64 exec, exec, s[56:57]
	v_add_u32_e32 v64, 0x90, v164
	v_sub_u32_e32 v66, v64, v172
	v_add_u32_e32 v66, v66, v174
	v_ashrrev_i32_e32 v67, 31, v66
	v_lshlrev_b64 v[66:67], 12, v[66:67]
	v_lshl_add_u64 v[68:69], s[16:17], 0, v[66:67]
	v_lshl_add_u64 v[68:69], v[68:69], 0, v[162:163]
	s_waitcnt vmcnt(2)
	s_nop 0
	v_mov_b64_e32 v[70:71], v[228:229]
	v_mov_b64_e32 v[72:73], v[230:231]
	v_lshl_add_u64 v[68:69], s[38:39], 0, v[66:67]
	v_lshl_add_u64 v[68:69], v[68:69], 0, v[162:163]
	s_waitcnt lgkmcnt(0)
	v_mov_b32_e32 v65, v226
	v_mov_b64_e32 v[74:75], v[232:233]
	v_mov_b64_e32 v[76:77], v[234:235]
	v_lshl_add_u64 v[68:69], v[66:67], 0, s[44:45]
	v_lshl_add_u64 v[82:83], s[38:39], 0, v[68:69]
	v_lshl_add_u64 v[78:79], s[16:17], 0, v[68:69]
	v_lshl_add_u64 v[82:83], v[82:83], 0, v[162:163]
	v_lshl_add_u64 v[78:79], v[78:79], 0, v[162:163]
	v_mov_b64_e32 v[82:83], v[236:237]
	v_mov_b64_e32 v[84:85], v[238:239]
	v_mul_f32_e32 v60, 0xbfb8aa3b, v60
	v_mov_b64_e32 v[78:79], v[240:241]
	v_mov_b64_e32 v[80:81], v[242:243]
	s_nop 1
	v_add_u32_e32 v216, 0xa0, v164
	v_sub_u32_e32 v218, v216, v172
	v_add_u32_e32 v218, v218, v174
	v_ashrrev_i32_e32 v219, 31, v218
	v_lshlrev_b64 v[218:219], 12, v[218:219]
	v_lshl_add_u64 v[220:221], s[16:17], 0, v[218:219]
	v_lshl_add_u64 v[220:221], v[220:221], 0, v[162:163]
	global_load_dwordx4 v[228:231], v[220:221], off
	v_lshl_add_u64 v[220:221], s[38:39], 0, v[218:219]
	v_lshl_add_u64 v[220:221], v[220:221], 0, v[162:163]
	global_load_dword v226, v[166:167], off offset:640
	global_load_dwordx4 v[232:235], v[220:221], off
	v_lshl_add_u64 v[220:221], v[218:219], 0, s[44:45]
	v_lshl_add_u64 v[222:223], s[16:17], 0, v[220:221]
	v_lshl_add_u64 v[222:223], v[222:223], 0, v[162:163]
	global_load_dwordx4 v[236:239], v[222:223], off
	v_lshl_add_u64 v[222:223], s[38:39], 0, v[220:221]
	v_lshl_add_u64 v[222:223], v[222:223], 0, v[162:163]
	global_load_dwordx4 v[240:243], v[222:223], off
	v_exp_f32_e32 v60, v60
	v_mul_f32_e32 v61, 0xbfb8aa3b, v61
	v_exp_f32_e32 v61, v61
	v_add_f32_e32 v60, 1.0, v60
	v_rcp_f32_e32 v60, v60
	v_add_f32_e32 v61, 1.0, v61
	v_rcp_f32_e32 v61, v61
	v_mul_f32_e32 v56, 0xbfb8aa3b, v56
	v_exp_f32_e32 v56, v56
	v_mul_f32_e32 v57, 0xbfb8aa3b, v57
	v_exp_f32_e32 v57, v57
	v_add_f32_e32 v56, 1.0, v56
	v_rcp_f32_e32 v56, v56
	v_add_f32_e32 v57, 1.0, v57
	v_mul_f32_e32 v44, 0xbfb8aa3b, v44
	v_rcp_f32_e32 v57, v57
	v_exp_f32_e32 v44, v44
	v_mul_f32_e32 v45, 0xbfb8aa3b, v45
	v_exp_f32_e32 v45, v45
	v_add_f32_e32 v44, 1.0, v44
	v_rcp_f32_e32 v44, v44
	v_add_f32_e32 v45, 1.0, v45
	v_rcp_f32_e32 v45, v45
	v_mul_f32_e32 v36, 0xbfb8aa3b, v36
	v_exp_f32_e32 v36, v36
	v_mul_f32_e32 v37, 0xbfb8aa3b, v37
	v_exp_f32_e32 v37, v37
	v_add_f32_e32 v36, 1.0, v36
	v_rcp_f32_e32 v36, v36
	v_add_f32_e32 v37, 1.0, v37
	v_rcp_f32_e32 v37, v37
	v_mov_b32_dpp v86, v70 row_ror:8 row_mask:0xf bank_mask:0xf
	v_mov_b32_dpp v87, v71 row_ror:8 row_mask:0xf bank_mask:0xf
	v_mov_b32_dpp v88, v72 row_ror:8 row_mask:0xf bank_mask:0xf
	v_fmamk_f32 v65, v65, 0x3a000000, v180
	v_rsq_f32_e32 v65, v65
	v_mov_b32_dpp v94, v74 row_ror:8 row_mask:0xf bank_mask:0xf
	v_mov_b32_dpp v95, v75 row_ror:8 row_mask:0xf bank_mask:0xf
	v_mov_b32_dpp v96, v76 row_ror:8 row_mask:0xf bank_mask:0xf
	v_mov_b32_dpp v97, v77 row_ror:8 row_mask:0xf bank_mask:0xf
	v_mov_b32_dpp v89, v73 row_ror:8 row_mask:0xf bank_mask:0xf
	v_mov_b32_dpp v98, v82 row_ror:8 row_mask:0xf bank_mask:0xf
	v_cndmask_b32_e64 v74, v98, v74, s[6:7]
	v_mov_b32_dpp v90, v78 row_ror:8 row_mask:0xf bank_mask:0xf
	v_cndmask_b32_e64 v70, v90, v70, s[6:7]
	v_lshlrev_b32_e32 v90, 16, v74
	v_mul_f32_e32 v90, v65, v90
	v_cndmask_b32_e64 v78, v78, v86, s[6:7]
	v_lshlrev_b32_e32 v86, 16, v70
	v_and_b32_e32 v74, 0xffff0000, v74
	v_mul_f32_e32 v90, v52, v90
	v_fmac_f32_e32 v86, v60, v90
	v_mul_f32_e32 v60, v65, v74
	v_and_b32_e32 v70, 0xffff0000, v70
	v_mul_f32_e32 v60, v53, v60
	v_fmac_f32_e32 v70, v61, v60
	v_mul_f32_e32 v60, 0xbfb8aa3b, v62
	v_exp_f32_e32 v60, v60
	v_mul_f32_e32 v62, 0xbfb8aa3b, v63
	v_exp_f32_e32 v62, v62
	v_mov_b32_dpp v99, v83 row_ror:8 row_mask:0xf bank_mask:0xf
	v_add_f32_e32 v60, 1.0, v60
	v_mov_b32_dpp v91, v79 row_ror:8 row_mask:0xf bank_mask:0xf
	v_cndmask_b32_e64 v75, v99, v75, s[6:7]
	v_rcp_f32_e32 v60, v60
	v_cndmask_b32_e64 v71, v91, v71, s[6:7]
	v_lshlrev_b32_e32 v91, 16, v75
	v_add_f32_e32 v62, 1.0, v62
	v_mul_f32_e32 v61, v65, v91
	v_rcp_f32_e32 v62, v62
	v_cndmask_b32_e64 v79, v79, v87, s[6:7]
	v_mov_b32_dpp v100, v84 row_ror:8 row_mask:0xf bank_mask:0xf
	v_lshlrev_b32_e32 v87, 16, v71
	v_and_b32_e32 v75, 0xffff0000, v75
	v_mul_f32_e32 v61, v54, v61
	v_mov_b32_dpp v92, v80 row_ror:8 row_mask:0xf bank_mask:0xf
	v_cndmask_b32_e64 v76, v100, v76, s[6:7]
	v_fmac_f32_e32 v87, v60, v61
	v_mul_f32_e32 v60, v65, v75
	v_cndmask_b32_e64 v72, v92, v72, s[6:7]
	v_and_b32_e32 v71, 0xffff0000, v71
	v_lshlrev_b32_e32 v92, 16, v76
	v_mul_f32_e32 v60, v55, v60
	v_fmac_f32_e32 v71, v62, v60
	v_mul_f32_e32 v60, v65, v92
	v_cndmask_b32_e64 v80, v80, v88, s[6:7]
	v_lshlrev_b32_e32 v88, 16, v72
	v_and_b32_e32 v76, 0xffff0000, v76
	v_mul_f32_e32 v60, v48, v60
	v_fmac_f32_e32 v88, v56, v60
	v_mul_f32_e32 v56, v65, v76
	v_and_b32_e32 v72, 0xffff0000, v72
	v_mul_f32_e32 v56, v49, v56
	v_fmac_f32_e32 v72, v57, v56
	v_mul_f32_e32 v56, 0xbfb8aa3b, v58
	v_cndmask_b32_e64 v82, v82, v94, s[6:7]
	v_exp_f32_e32 v56, v56
	v_mul_f32_e32 v58, 0xbfb8aa3b, v59
	v_lshlrev_b32_e32 v75, 16, v82
	v_exp_f32_e32 v58, v58
	v_mul_f32_e32 v75, v65, v75
	v_lshlrev_b32_e32 v61, 16, v78
	v_and_b32_e32 v76, 0xffff0000, v82
	v_mul_f32_e32 v75, v40, v75
	v_mov_b32_dpp v101, v85 row_ror:8 row_mask:0xf bank_mask:0xf
; __device__ __forceinline__ unsigned cvt_pk_bf16(float lo, float hi) { unsigned r; asm volatile("v_cvt_pk_bf16_f32 %0, %1, %2" : "=v"(r) : "v"(lo), "v"(hi)); return r; }
;     __device__ __forceinline__ void operator()(const f32x4 (&acc)[2][2][4][2], const Unit& u, int wr, int wc, int fr, int fq) const {
;     ...
;                     for (int j = 0; j < 8; ++j) { const float a = acc[ai][bj][m][j >> 2][j & 3]; const float gg = gv[bj][j >> 2][j & 3];
;                         o[j] = r[j] + e[j] * ri * gg * __builtin_amdgcn_rcpf(1.f + __builtin_amdgcn_exp2f(-a * LOG2E)); }
;                     if (OUT) { *(f32x4*)(OUT + off + 8 * bj) = (f32x4){o[0], o[1], o[2], o[3]}; *(f32x4*)(OUT + off + 8 * bj + 4) = (f32x4){o[4], o[5], o[6], o[7]}; }
;                     else { sq += (o[0] * o[0] + o[1] * o[1]) + (o[2] * o[2] + o[3] * o[3]) + (o[4] * o[4] + o[5] * o[5]) + (o[6] * o[6] + o[7] * o[7]);
;                         w[bj].x = cvt_pk_bf16(o[0], o[1]); w[bj].y = cvt_pk_bf16(o[2], o[3]); w[bj].z = cvt_pk_bf16(o[4], o[5]); w[bj].w = cvt_pk_bf16(o[6], o[7]); } }
;                 if (!OUT) { store_pair_lines(O, D, row, fr, col0, w[0], w[1]);
;                     sq += __shfl_xor(sq, 16); sq += __shfl_xor(sq, 32); if (fq == 0) unsafeAtomicAdd(ssout + row, sq); } }
	v_add_f32_e32 v56, 1.0, v56
	v_fmac_f32_e32 v61, v44, v75
	v_mul_f32_e32 v44, v65, v76
	v_mov_b32_dpp v93, v81 row_ror:8 row_mask:0xf bank_mask:0xf
	v_cndmask_b32_e64 v77, v101, v77, s[6:7]
	v_rcp_f32_e32 v56, v56
	v_and_b32_e32 v62, 0xffff0000, v78
	v_mul_f32_e32 v44, v41, v44
	v_cndmask_b32_e64 v73, v93, v73, s[6:7]
	v_lshlrev_b32_e32 v93, 16, v77
	v_add_f32_e32 v58, 1.0, v58
	v_fmac_f32_e32 v62, v45, v44
	v_mul_f32_e32 v44, 0xbfb8aa3b, v46
	v_mul_f32_e32 v57, v65, v93
	v_rcp_f32_e32 v58, v58
	v_exp_f32_e32 v44, v44
	v_cndmask_b32_e64 v81, v81, v89, s[6:7]
	v_lshlrev_b32_e32 v89, 16, v73
	v_and_b32_e32 v77, 0xffff0000, v77
	v_mul_f32_e32 v57, v50, v57
	v_mul_f32_e32 v46, 0xbfb8aa3b, v47
	v_fmac_f32_e32 v89, v56, v57
	v_mul_f32_e32 v56, v65, v77
	v_exp_f32_e32 v46, v46
	v_and_b32_e32 v73, 0xffff0000, v73
	v_mul_f32_e32 v56, v51, v56
	v_fmac_f32_e32 v73, v58, v56
	v_mul_f32_e32 v56, v70, v70
	v_mul_f32_e32 v57, v71, v71
	v_add_f32_e32 v44, 1.0, v44
	v_cndmask_b32_e64 v83, v83, v95, s[6:7]
	v_fmac_f32_e32 v56, v86, v86
	v_fmac_f32_e32 v57, v87, v87
	v_rcp_f32_e32 v44, v44
	v_add_f32_e32 v56, v56, v57
	v_mul_f32_e32 v57, v72, v72
	v_lshlrev_b32_e32 v77, 16, v83
	v_add_f32_e32 v46, 1.0, v46
	v_fmac_f32_e32 v57, v88, v88
	v_mul_f32_e32 v45, v65, v77
	v_rcp_f32_e32 v46, v46
	v_add_f32_e32 v56, v57, v56
	v_mul_f32_e32 v57, v73, v73
	v_lshlrev_b32_e32 v63, 16, v79
	v_and_b32_e32 v78, 0xffff0000, v83
	v_mul_f32_e32 v45, v42, v45
	v_cndmask_b32_e64 v84, v84, v96, s[6:7]
	v_fmac_f32_e32 v57, v89, v89
	v_fmac_f32_e32 v63, v44, v45
	v_mul_f32_e32 v44, v65, v78
	v_add_f32_e32 v56, v57, v56
	v_cvt_pk_bf16_f32 v57, v86, v70
	v_and_b32_e32 v70, 0xffff0000, v79
	v_lshlrev_b32_e32 v79, 16, v84
	v_mul_f32_e32 v44, v43, v44
	v_fmac_f32_e32 v70, v46, v44
	v_mul_f32_e32 v44, v65, v79
	v_cvt_pk_bf16_f32 v58, v87, v71
	v_cvt_pk_bf16_f32 v59, v88, v72
	v_lshlrev_b32_e32 v71, 16, v80
	v_and_b32_e32 v72, 0xffff0000, v80
	v_and_b32_e32 v80, 0xffff0000, v84
	v_mul_f32_e32 v44, v32, v44
	v_fmac_f32_e32 v71, v36, v44
	v_mul_f32_e32 v36, v65, v80
	v_mul_f32_e32 v36, v33, v36
	v_fmac_f32_e32 v72, v37, v36
	v_mul_f32_e32 v36, 0xbfb8aa3b, v38
	v_exp_f32_e32 v36, v36
	v_mul_f32_e32 v38, 0xbfb8aa3b, v39
	v_exp_f32_e32 v38, v38
	v_cndmask_b32_e64 v85, v85, v97, s[6:7]
	v_add_f32_e32 v36, 1.0, v36
	v_rcp_f32_e32 v36, v36
	v_cvt_pk_bf16_f32 v60, v89, v73
	v_lshlrev_b32_e32 v73, 16, v81
	v_and_b32_e32 v74, 0xffff0000, v81
	v_lshlrev_b32_e32 v81, 16, v85
	v_add_f32_e32 v38, 1.0, v38
	v_mul_f32_e32 v37, v65, v81
	v_rcp_f32_e32 v38, v38
	v_and_b32_e32 v82, 0xffff0000, v85
	v_mul_f32_e32 v37, v34, v37
	v_fmac_f32_e32 v73, v36, v37
	v_mul_f32_e32 v36, v65, v82
	v_mul_f32_e32 v36, v35, v36
	v_fmac_f32_e32 v74, v38, v36
	v_mul_f32_e32 v36, v62, v62
	v_mul_f32_e32 v37, v70, v70
	v_fmac_f32_e32 v36, v61, v61
	v_fmac_f32_e32 v37, v63, v63
	v_add_f32_e32 v36, v36, v37
	v_mul_f32_e32 v37, v72, v72
	v_fmac_f32_e32 v37, v71, v71
	v_add_f32_e32 v36, v37, v36
	v_mul_f32_e32 v37, v74, v74
	v_fmac_f32_e32 v37, v73, v73
	v_add_f32_e32 v36, v37, v36
	v_add_f32_e32 v65, v36, v56
	v_cvt_pk_bf16_f32 v36, v61, v62
	v_cvt_pk_bf16_f32 v37, v63, v70
	v_cvt_pk_bf16_f32 v38, v71, v72
	v_cvt_pk_bf16_f32 v39, v73, v74
	v_mov_b32_e32 v63, 0
	v_mov_b32_e32 v56, 0
	v_mov_b32_dpp v47, v39 row_ror:8 row_mask:0xf bank_mask:0xf
	v_mov_b32_dpp v63, v60 row_ror:8 row_mask:0xf bank_mask:0xf
	v_cndmask_b32_e64 v47, v47, v60, s[6:7]
	v_mov_b32_e32 v60, v65
	s_nop 1
	v_permlane16_swap_b32_e32 v60, v65
	v_mov_b32_dpp v56, v57 row_ror:8 row_mask:0xf bank_mask:0xf
	v_mov_b32_dpp v61, v58 row_ror:8 row_mask:0xf bank_mask:0xf
	v_mov_b32_dpp v44, v36 row_ror:8 row_mask:0xf bank_mask:0xf
	v_mov_b32_dpp v62, v59 row_ror:8 row_mask:0xf bank_mask:0xf
	v_mov_b32_dpp v45, v37 row_ror:8 row_mask:0xf bank_mask:0xf
	v_mov_b32_dpp v46, v38 row_ror:8 row_mask:0xf bank_mask:0xf
	v_cndmask_b32_e64 v44, v44, v57, s[6:7]
	v_cndmask_b32_e64 v56, v36, v56, s[6:7]
	v_cndmask_b32_e64 v57, v37, v61, s[6:7]
	v_lshl_add_u64 v[36:37], s[36:37], 0, v[66:67]
	v_cndmask_b32_e64 v45, v45, v58, s[6:7]
	v_cndmask_b32_e64 v46, v46, v59, s[6:7]
	v_cndmask_b32_e64 v58, v38, v62, s[6:7]
	v_cndmask_b32_e64 v59, v39, v63, s[6:7]
	v_lshl_add_u64 v[38:39], v[36:37], 0, v[162:163]
	s_waitcnt lgkmcnt(0)
	v_add_f32_e32 v36, v65, v60
	v_mov_b32_e32 v37, v36
	s_nop 1
	v_permlane32_swap_b32_e32 v37, v36
	global_store_dwordx4 v[38:39], v[44:47], off
	v_lshl_add_u64 v[38:39], s[36:37], 0, v[68:69]
	v_lshl_add_u64 v[38:39], v[38:39], 0, v[162:163]
	global_store_dwordx4 v[38:39], v[56:59], off
	s_and_saveexec_b64 s[56:57], s[8:9]
	s_cbranch_execz .LBB0_895
	v_ashrrev_i32_e32 v65, 31, v64
	v_lshl_add_u64 v[38:39], v[64:65], 2, s[18:19]
	s_waitcnt lgkmcnt(0)
	v_add_f32_e32 v36, v36, v37
	global_atomic_add_f32 v[38:39], v36, off
; __device__ __forceinline__ unsigned cvt_pk_bf16(float lo, float hi) { unsigned r; asm volatile("v_cvt_pk_bf16_f32 %0, %1, %2" : "=v"(r) : "v"(lo), "v"(hi)); return r; }
; __device__ __forceinline__ float bflo(unsigned w) { return __uint_as_float(w << 16); }
; __device__ __forceinline__ float bfhi(unsigned w) { return __uint_as_float(w & 0xffff0000u); }
;     __device__ __forceinline__ void operator()(const f32x4 (&acc)[2][2][4][2], const Unit& u, int wr, int wc, int fr, int fq) const {
;     ...
;             for (int m = 0; m < 4; ++m) { const int row = row0 + ai * HALF + m * 16; const size_t off = (size_t)row * D + col0; const float ri = __builtin_amdgcn_rsqf(sse[row] * (1.f / D) + EPS); float sq = 0.f; u32x4 w[2];
;                 u32x4 rr[2], ee[2]; load_pair_lines(R, D, row, fr, col0, rr[0], rr[1]); load_pair_lines(E, D, row, fr, col0, ee[0], ee[1]);
; #pragma unroll
;                 for (int bj = 0; bj < 2; ++bj) { const u32x4 rw = rr[bj], ew = ee[bj];
;                     const float r[8] = {bflo(rw.x), bfhi(rw.x), bflo(rw.y), bfhi(rw.y), bflo(rw.z), bfhi(rw.z), bflo(rw.w), bfhi(rw.w)};
;                     const float e[8] = {bflo(ew.x), bfhi(ew.x), bflo(ew.y), bfhi(ew.y), bflo(ew.z), bfhi(ew.z), bflo(ew.w), bfhi(ew.w)};
;                     float o[8];
; #pragma unroll
;                     for (int j = 0; j < 8; ++j) { const float a = acc[ai][bj][m][j >> 2][j & 3]; const float gg = gv[bj][j >> 2][j & 3];
;                         o[j] = r[j] + e[j] * ri * gg * __builtin_amdgcn_rcpf(1.f + __builtin_amdgcn_exp2f(-a * LOG2E)); }
;                     if (OUT) { *(f32x4*)(OUT + off + 8 * bj) = (f32x4){o[0], o[1], o[2], o[3]}; *(f32x4*)(OUT + off + 8 * bj + 4) = (f32x4){o[4], o[5], o[6], o[7]}; }
;                     else { sq += (o[0] * o[0] + o[1] * o[1]) + (o[2] * o[2] + o[3] * o[3]) + (o[4] * o[4] + o[5] * o[5]) + (o[6] * o[6] + o[7] * o[7]);
;                         w[bj].x = cvt_pk_bf16(o[0], o[1]); w[bj].y = cvt_pk_bf16(o[2], o[3]); w[bj].z = cvt_pk_bf16(o[4], o[5]); w[bj].w = cvt_pk_bf16(o[6], o[7]); } }
.LBB0_895:
	s_or_b64 exec, exec, s[56:57]
	v_add_u32_e32 v36, 0xa0, v164
	v_sub_u32_e32 v38, v36, v172
	v_add_u32_e32 v38, v38, v174
	v_ashrrev_i32_e32 v39, 31, v38
	v_lshlrev_b64 v[38:39], 12, v[38:39]
	v_lshl_add_u64 v[44:45], s[16:17], 0, v[38:39]
	v_lshl_add_u64 v[44:45], v[44:45], 0, v[162:163]
	s_waitcnt vmcnt(2)
	s_nop 0
	v_mov_b64_e32 v[56:57], v[228:229]
	v_mov_b64_e32 v[58:59], v[230:231]
	v_lshl_add_u64 v[44:45], s[38:39], 0, v[38:39]
	v_lshl_add_u64 v[44:45], v[44:45], 0, v[162:163]
	s_waitcnt lgkmcnt(0)
	v_mov_b32_e32 v37, v226
	v_mov_b64_e32 v[60:61], v[232:233]
	v_mov_b64_e32 v[62:63], v[234:235]
	v_lshl_add_u64 v[44:45], v[38:39], 0, s[44:45]
	v_lshl_add_u64 v[46:47], s[16:17], 0, v[44:45]
	v_lshl_add_u64 v[46:47], v[46:47], 0, v[162:163]
	v_mov_b64_e32 v[64:65], v[236:237]
	v_mov_b64_e32 v[66:67], v[238:239]
	v_lshl_add_u64 v[46:47], s[38:39], 0, v[44:45]
	v_lshl_add_u64 v[46:47], v[46:47], 0, v[162:163]
	v_mov_b64_e32 v[68:69], v[240:241]
	v_mov_b64_e32 v[70:71], v[242:243]
	s_nop 1
	v_add_u32_e32 v216, 0xb0, v164
	v_sub_u32_e32 v218, v216, v172
	v_add_u32_e32 v218, v218, v174
	v_ashrrev_i32_e32 v219, 31, v218
	v_lshlrev_b64 v[218:219], 12, v[218:219]
	v_lshl_add_u64 v[220:221], s[16:17], 0, v[218:219]
	v_lshl_add_u64 v[220:221], v[220:221], 0, v[162:163]
	global_load_dwordx4 v[228:231], v[220:221], off
	v_lshl_add_u64 v[220:221], s[38:39], 0, v[218:219]
	v_lshl_add_u64 v[220:221], v[220:221], 0, v[162:163]
	global_load_dword v226, v[166:167], off offset:704
	global_load_dwordx4 v[232:235], v[220:221], off
	v_lshl_add_u64 v[220:221], v[218:219], 0, s[44:45]
	v_lshl_add_u64 v[222:223], s[16:17], 0, v[220:221]
	v_lshl_add_u64 v[222:223], v[222:223], 0, v[162:163]
	global_load_dwordx4 v[236:239], v[222:223], off
	v_lshl_add_u64 v[222:223], s[38:39], 0, v[220:221]
	v_lshl_add_u64 v[222:223], v[222:223], 0, v[162:163]
	global_load_dwordx4 v[240:243], v[222:223], off
	v_mul_f32_e32 v28, 0xbfb8aa3b, v28
	v_exp_f32_e32 v28, v28
	v_mul_f32_e32 v29, 0xbfb8aa3b, v29
	v_exp_f32_e32 v29, v29
	v_add_f32_e32 v28, 1.0, v28
	v_rcp_f32_e32 v28, v28
	v_add_f32_e32 v29, 1.0, v29
	v_rcp_f32_e32 v29, v29
	v_mul_f32_e32 v24, 0xbfb8aa3b, v24
	v_exp_f32_e32 v24, v24
	v_mul_f32_e32 v25, 0xbfb8aa3b, v25
	v_exp_f32_e32 v25, v25
	v_add_f32_e32 v24, 1.0, v24
	v_rcp_f32_e32 v24, v24
	v_add_f32_e32 v25, 1.0, v25
	v_rcp_f32_e32 v25, v25
	v_mul_f32_e32 v20, 0xbfb8aa3b, v20
	v_exp_f32_e32 v20, v20
	v_mul_f32_e32 v21, 0xbfb8aa3b, v21
	v_exp_f32_e32 v21, v21
	v_mul_f32_e32 v16, 0xbfb8aa3b, v16
	v_add_f32_e32 v20, 1.0, v20
	v_rcp_f32_e32 v20, v20
	v_add_f32_e32 v21, 1.0, v21
	v_rcp_f32_e32 v21, v21
	v_exp_f32_e32 v16, v16
	v_mul_f32_e32 v17, 0xbfb8aa3b, v17
	v_exp_f32_e32 v17, v17
	v_add_f32_e32 v16, 1.0, v16
	v_rcp_f32_e32 v16, v16
	v_add_f32_e32 v17, 1.0, v17
	v_rcp_f32_e32 v17, v17
	v_mov_b32_dpp v46, v56 row_ror:8 row_mask:0xf bank_mask:0xf
	v_mov_b32_dpp v47, v57 row_ror:8 row_mask:0xf bank_mask:0xf
	v_mov_b32_dpp v72, v58 row_ror:8 row_mask:0xf bank_mask:0xf
	v_fmamk_f32 v37, v37, 0x3a000000, v180
	v_rsq_f32_e32 v37, v37
	v_mov_b32_dpp v78, v60 row_ror:8 row_mask:0xf bank_mask:0xf
	v_mov_b32_dpp v80, v62 row_ror:8 row_mask:0xf bank_mask:0xf
	v_mov_b32_dpp v79, v61 row_ror:8 row_mask:0xf bank_mask:0xf
	v_mov_b32_dpp v74, v64 row_ror:8 row_mask:0xf bank_mask:0xf
	v_cndmask_b32_e64 v56, v74, v56, s[6:7]
	v_mov_b32_dpp v75, v65 row_ror:8 row_mask:0xf bank_mask:0xf
	v_mov_b32_dpp v82, v68 row_ror:8 row_mask:0xf bank_mask:0xf
	v_cndmask_b32_e64 v60, v82, v60, s[6:7]
	v_lshlrev_b32_e32 v74, 16, v60
	v_mul_f32_e32 v74, v37, v74
	v_cndmask_b32_e64 v47, v65, v47, s[6:7]
	v_mov_b32_dpp v84, v70 row_ror:8 row_mask:0xf bank_mask:0xf
	v_cndmask_b32_e64 v65, v70, v80, s[6:7]
	v_lshlrev_b32_e32 v70, 16, v56
	v_and_b32_e32 v60, 0xffff0000, v60
	v_mul_f32_e32 v74, v52, v74
	v_fmac_f32_e32 v70, v28, v74
	v_mul_f32_e32 v28, v37, v60
	v_and_b32_e32 v56, 0xffff0000, v56
	v_mul_f32_e32 v28, v53, v28
	v_fmac_f32_e32 v56, v29, v28
	v_mul_f32_e32 v28, 0xbfb8aa3b, v30
	v_exp_f32_e32 v28, v28
	v_mul_f32_e32 v30, 0xbfb8aa3b, v31
	v_exp_f32_e32 v30, v30
	v_mov_b32_dpp v83, v69 row_ror:8 row_mask:0xf bank_mask:0xf
	v_add_f32_e32 v28, 1.0, v28
	v_cndmask_b32_e64 v61, v83, v61, s[6:7]
	v_rcp_f32_e32 v28, v28
	v_cndmask_b32_e64 v57, v75, v57, s[6:7]
	v_lshlrev_b32_e32 v75, 16, v61
	v_add_f32_e32 v30, 1.0, v30
	v_mov_b32_dpp v81, v63 row_ror:8 row_mask:0xf bank_mask:0xf
	v_mul_f32_e32 v29, v37, v75
	v_rcp_f32_e32 v30, v30
	v_cndmask_b32_e64 v46, v64, v46, s[6:7]
	v_mov_b32_dpp v85, v71 row_ror:8 row_mask:0xf bank_mask:0xf
	v_cndmask_b32_e64 v64, v71, v81, s[6:7]
	v_lshlrev_b32_e32 v71, 16, v57
	v_and_b32_e32 v61, 0xffff0000, v61
	v_mul_f32_e32 v29, v54, v29
	v_mov_b32_dpp v76, v66 row_ror:8 row_mask:0xf bank_mask:0xf
	v_cndmask_b32_e64 v62, v84, v62, s[6:7]
	v_fmac_f32_e32 v71, v28, v29
	v_mul_f32_e32 v28, v37, v61
	v_cndmask_b32_e64 v58, v76, v58, s[6:7]
	v_and_b32_e32 v57, 0xffff0000, v57
	v_lshlrev_b32_e32 v76, 16, v62
	v_mul_f32_e32 v28, v55, v28
	v_fmac_f32_e32 v57, v30, v28
	v_mul_f32_e32 v28, v37, v76
	v_cndmask_b32_e64 v66, v66, v72, s[6:7]
	v_lshlrev_b32_e32 v72, 16, v58
	v_and_b32_e32 v62, 0xffff0000, v62
	v_mul_f32_e32 v28, v48, v28
	v_fmac_f32_e32 v72, v24, v28
	v_mul_f32_e32 v24, v37, v62
	v_and_b32_e32 v58, 0xffff0000, v58
	v_mul_f32_e32 v24, v49, v24
	v_fmac_f32_e32 v58, v25, v24
	v_mul_f32_e32 v24, 0xbfb8aa3b, v26
	v_exp_f32_e32 v24, v24
	v_mul_f32_e32 v26, 0xbfb8aa3b, v27
	v_exp_f32_e32 v26, v26
	v_mov_b32_dpp v77, v67 row_ror:8 row_mask:0xf bank_mask:0xf
	v_add_f32_e32 v24, 1.0, v24
	v_cndmask_b32_e64 v63, v85, v63, s[6:7]
	v_rcp_f32_e32 v24, v24
; __device__ __forceinline__ unsigned cvt_pk_bf16(float lo, float hi) { unsigned r; asm volatile("v_cvt_pk_bf16_f32 %0, %1, %2" : "=v"(r) : "v"(lo), "v"(hi)); return r; }
; __device__ __forceinline__ float bflo(unsigned w) { return __uint_as_float(w << 16); }
; __device__ __forceinline__ float bfhi(unsigned w) { return __uint_as_float(w & 0xffff0000u); }
;     __device__ __forceinline__ void operator()(const f32x4 (&acc)[2][2][4][2], const Unit& u, int wr, int wc, int fr, int fq) const {
;     ...
;             for (int m = 0; m < 4; ++m) { const int row = row0 + ai * HALF + m * 16; const size_t off = (size_t)row * D + col0; const float ri = __builtin_amdgcn_rsqf(sse[row] * (1.f / D) + EPS); float sq = 0.f; u32x4 w[2];
;                 u32x4 rr[2], ee[2]; load_pair_lines(R, D, row, fr, col0, rr[0], rr[1]); load_pair_lines(E, D, row, fr, col0, ee[0], ee[1]);
; #pragma unroll
;                 for (int bj = 0; bj < 2; ++bj) { const u32x4 rw = rr[bj], ew = ee[bj];
;                     const float r[8] = {bflo(rw.x), bfhi(rw.x), bflo(rw.y), bfhi(rw.y), bflo(rw.z), bfhi(rw.z), bflo(rw.w), bfhi(rw.w)};
;                     const float e[8] = {bflo(ew.x), bfhi(ew.x), bflo(ew.y), bfhi(ew.y), bflo(ew.z), bfhi(ew.z), bflo(ew.w), bfhi(ew.w)};
;                     float o[8];
; #pragma unroll
;                     for (int j = 0; j < 8; ++j) { const float a = acc[ai][bj][m][j >> 2][j & 3]; const float gg = gv[bj][j >> 2][j & 3];
;                         o[j] = r[j] + e[j] * ri * gg * __builtin_amdgcn_rcpf(1.f + __builtin_amdgcn_exp2f(-a * LOG2E)); }
;                     if (OUT) { *(f32x4*)(OUT + off + 8 * bj) = (f32x4){o[0], o[1], o[2], o[3]}; *(f32x4*)(OUT + off + 8 * bj + 4) = (f32x4){o[4], o[5], o[6], o[7]}; }
;                     else { sq += (o[0] * o[0] + o[1] * o[1]) + (o[2] * o[2] + o[3] * o[3]) + (o[4] * o[4] + o[5] * o[5]) + (o[6] * o[6] + o[7] * o[7]);
;                         w[bj].x = cvt_pk_bf16(o[0], o[1]); w[bj].y = cvt_pk_bf16(o[2], o[3]); w[bj].z = cvt_pk_bf16(o[4], o[5]); w[bj].w = cvt_pk_bf16(o[6], o[7]); } }
;                 if (!OUT) { store_pair_lines(O, D, row, fr, col0, w[0], w[1]);
;                     sq += __shfl_xor(sq, 16); sq += __shfl_xor(sq, 32); if (fq == 0) unsafeAtomicAdd(ssout + row, sq); } }
	v_mov_b32_dpp v73, v59 row_ror:8 row_mask:0xf bank_mask:0xf
	v_cndmask_b32_e64 v59, v77, v59, s[6:7]
	v_lshlrev_b32_e32 v77, 16, v63
	v_add_f32_e32 v26, 1.0, v26
	v_mul_f32_e32 v25, v37, v77
	v_rcp_f32_e32 v26, v26
	v_cndmask_b32_e64 v67, v67, v73, s[6:7]
	v_lshlrev_b32_e32 v73, 16, v59
	v_and_b32_e32 v63, 0xffff0000, v63
	v_mul_f32_e32 v25, v50, v25
	v_fmac_f32_e32 v73, v24, v25
	v_mul_f32_e32 v24, v37, v63
	v_and_b32_e32 v59, 0xffff0000, v59
	v_mul_f32_e32 v24, v51, v24
	v_fmac_f32_e32 v59, v26, v24
	v_mul_f32_e32 v24, v56, v56
	v_mul_f32_e32 v25, v57, v57
	v_fmac_f32_e32 v24, v70, v70
	v_fmac_f32_e32 v25, v71, v71
	v_add_f32_e32 v24, v24, v25
	v_mul_f32_e32 v25, v58, v58
	v_fmac_f32_e32 v25, v72, v72
	v_add_f32_e32 v24, v25, v24
	v_mul_f32_e32 v25, v59, v59
	v_cndmask_b32_e64 v68, v68, v78, s[6:7]
	v_fmac_f32_e32 v25, v73, v73
	v_add_f32_e32 v24, v25, v24
	v_cvt_pk_bf16_f32 v25, v70, v56
	v_cvt_pk_bf16_f32 v26, v71, v57
	v_cvt_pk_bf16_f32 v27, v72, v58
	v_cvt_pk_bf16_f32 v28, v73, v59
	v_lshlrev_b32_e32 v59, 16, v68
	v_mul_f32_e32 v59, v37, v59
	v_lshlrev_b32_e32 v29, 16, v46
	v_and_b32_e32 v60, 0xffff0000, v68
	v_mul_f32_e32 v59, v40, v59
	v_fmac_f32_e32 v29, v20, v59
	v_mul_f32_e32 v20, v37, v60
	v_and_b32_e32 v30, 0xffff0000, v46
	v_mul_f32_e32 v20, v41, v20
	v_fmac_f32_e32 v30, v21, v20
	v_mul_f32_e32 v20, 0xbfb8aa3b, v22
	v_exp_f32_e32 v20, v20
	v_mul_f32_e32 v22, 0xbfb8aa3b, v23
	v_exp_f32_e32 v22, v22
	v_cndmask_b32_e64 v69, v69, v79, s[6:7]
	v_add_f32_e32 v20, 1.0, v20
	v_rcp_f32_e32 v20, v20
	v_lshlrev_b32_e32 v61, 16, v69
	v_add_f32_e32 v22, 1.0, v22
	v_mul_f32_e32 v21, v37, v61
	v_rcp_f32_e32 v22, v22
	v_lshlrev_b32_e32 v31, 16, v47
	v_and_b32_e32 v62, 0xffff0000, v69
	v_mul_f32_e32 v21, v42, v21
	v_fmac_f32_e32 v31, v20, v21
	v_mul_f32_e32 v20, v37, v62
	v_and_b32_e32 v46, 0xffff0000, v47
	v_lshlrev_b32_e32 v63, 16, v65
	v_mul_f32_e32 v20, v43, v20
	v_fmac_f32_e32 v46, v22, v20
	v_mul_f32_e32 v20, v37, v63
	v_lshlrev_b32_e32 v47, 16, v66
	v_and_b32_e32 v65, 0xffff0000, v65
	v_mul_f32_e32 v20, v32, v20
	v_fmac_f32_e32 v47, v16, v20
	v_mul_f32_e32 v16, v37, v65
	v_and_b32_e32 v56, 0xffff0000, v66
	v_mul_f32_e32 v16, v33, v16
	v_fmac_f32_e32 v56, v17, v16
	v_mul_f32_e32 v16, 0xbfb8aa3b, v18
	v_exp_f32_e32 v16, v16
	v_mul_f32_e32 v18, 0xbfb8aa3b, v19
	v_exp_f32_e32 v18, v18
	v_lshlrev_b32_e32 v66, 16, v64
	v_add_f32_e32 v16, 1.0, v16
	v_rcp_f32_e32 v16, v16
	v_add_f32_e32 v18, 1.0, v18
	v_mul_f32_e32 v17, v37, v66
	v_rcp_f32_e32 v18, v18
	v_lshlrev_b32_e32 v57, 16, v67
	v_and_b32_e32 v64, 0xffff0000, v64
	v_mul_f32_e32 v17, v34, v17
	v_fmac_f32_e32 v57, v16, v17
	v_mul_f32_e32 v16, v37, v64
	v_and_b32_e32 v58, 0xffff0000, v67
	v_mul_f32_e32 v16, v35, v16
	v_fmac_f32_e32 v58, v18, v16
	v_mul_f32_e32 v16, v30, v30
	v_mul_f32_e32 v17, v46, v46
	v_fmac_f32_e32 v16, v29, v29
	v_fmac_f32_e32 v17, v31, v31
	v_add_f32_e32 v16, v16, v17
	v_mul_f32_e32 v17, v56, v56
	v_fmac_f32_e32 v17, v47, v47
	v_add_f32_e32 v16, v17, v16
	v_mul_f32_e32 v17, v58, v58
	v_fmac_f32_e32 v17, v57, v57
	v_add_f32_e32 v16, v17, v16
	v_add_f32_e32 v37, v16, v24
	v_cvt_pk_bf16_f32 v16, v29, v30
	v_cvt_pk_bf16_f32 v17, v31, v46
	v_cvt_pk_bf16_f32 v24, v47, v56
	v_cvt_pk_bf16_f32 v29, v57, v58
	v_mov_b32_e32 v31, 0
	v_mov_b32_e32 v22, 0
	v_mov_b32_dpp v21, v29 row_ror:8 row_mask:0xf bank_mask:0xf
	v_mov_b32_dpp v31, v28 row_ror:8 row_mask:0xf bank_mask:0xf
	v_cndmask_b32_e64 v21, v21, v28, s[6:7]
	v_mov_b32_e32 v28, v37
	s_nop 1
	v_permlane16_swap_b32_e32 v28, v37
	v_mov_b32_dpp v22, v25 row_ror:8 row_mask:0xf bank_mask:0xf
	v_mov_b32_dpp v23, v26 row_ror:8 row_mask:0xf bank_mask:0xf
	v_mov_b32_dpp v18, v16 row_ror:8 row_mask:0xf bank_mask:0xf
	v_mov_b32_dpp v19, v17 row_ror:8 row_mask:0xf bank_mask:0xf
	v_mov_b32_dpp v20, v24 row_ror:8 row_mask:0xf bank_mask:0xf
	v_cndmask_b32_e64 v22, v16, v22, s[6:7]
	v_cndmask_b32_e64 v23, v17, v23, s[6:7]
	v_lshl_add_u64 v[16:17], s[36:37], 0, v[38:39]
	v_mov_b32_dpp v30, v27 row_ror:8 row_mask:0xf bank_mask:0xf
	v_cndmask_b32_e64 v19, v19, v26, s[6:7]
	v_cndmask_b32_e64 v20, v20, v27, s[6:7]
	v_lshl_add_u64 v[26:27], v[16:17], 0, v[162:163]
	s_waitcnt lgkmcnt(0)
	v_add_f32_e32 v16, v37, v28
	v_mov_b32_e32 v17, v16
	s_nop 1
	v_permlane32_swap_b32_e32 v17, v16
	v_cndmask_b32_e64 v18, v18, v25, s[6:7]
	global_store_dwordx4 v[26:27], v[18:21], off
	v_cndmask_b32_e64 v24, v24, v30, s[6:7]
	v_cndmask_b32_e64 v25, v29, v31, s[6:7]
	v_lshl_add_u64 v[18:19], s[36:37], 0, v[44:45]
	v_lshl_add_u64 v[18:19], v[18:19], 0, v[162:163]
	global_store_dwordx4 v[18:19], v[22:25], off
	s_and_saveexec_b64 s[56:57], s[8:9]
	s_cbranch_execz .LBB0_897
	v_ashrrev_i32_e32 v37, 31, v36
	v_lshl_add_u64 v[18:19], v[36:37], 2, s[18:19]
	s_waitcnt lgkmcnt(0)
	v_add_f32_e32 v16, v16, v17
	global_atomic_add_f32 v[18:19], v16, off
; __device__ __forceinline__ unsigned cvt_pk_bf16(float lo, float hi) { unsigned r; asm volatile("v_cvt_pk_bf16_f32 %0, %1, %2" : "=v"(r) : "v"(lo), "v"(hi)); return r; }
; __device__ __forceinline__ float bflo(unsigned w) { return __uint_as_float(w << 16); }
; __device__ __forceinline__ float bfhi(unsigned w) { return __uint_as_float(w & 0xffff0000u); }
;     __device__ __forceinline__ void operator()(const f32x4 (&acc)[2][2][4][2], const Unit& u, int wr, int wc, int fr, int fq) const {
;     ...
;             for (int m = 0; m < 4; ++m) { const int row = row0 + ai * HALF + m * 16; const size_t off = (size_t)row * D + col0; const float ri = __builtin_amdgcn_rsqf(sse[row] * (1.f / D) + EPS); float sq = 0.f; u32x4 w[2];
;                 u32x4 rr[2], ee[2]; load_pair_lines(R, D, row, fr, col0, rr[0], rr[1]); load_pair_lines(E, D, row, fr, col0, ee[0], ee[1]);
; #pragma unroll
;                 for (int bj = 0; bj < 2; ++bj) { const u32x4 rw = rr[bj], ew = ee[bj];
;                     const float r[8] = {bflo(rw.x), bfhi(rw.x), bflo(rw.y), bfhi(rw.y), bflo(rw.z), bfhi(rw.z), bflo(rw.w), bfhi(rw.w)};
;                     const float e[8] = {bflo(ew.x), bfhi(ew.x), bflo(ew.y), bfhi(ew.y), bflo(ew.z), bfhi(ew.z), bflo(ew.w), bfhi(ew.w)};
;                     float o[8];
; #pragma unroll
;                     for (int j = 0; j < 8; ++j) { const float a = acc[ai][bj][m][j >> 2][j & 3]; const float gg = gv[bj][j >> 2][j & 3];
;                         o[j] = r[j] + e[j] * ri * gg * __builtin_amdgcn_rcpf(1.f + __builtin_amdgcn_exp2f(-a * LOG2E)); }
;                     if (OUT) { *(f32x4*)(OUT + off + 8 * bj) = (f32x4){o[0], o[1], o[2], o[3]}; *(f32x4*)(OUT + off + 8 * bj + 4) = (f32x4){o[4], o[5], o[6], o[7]}; }
;                     else { sq += (o[0] * o[0] + o[1] * o[1]) + (o[2] * o[2] + o[3] * o[3]) + (o[4] * o[4] + o[5] * o[5]) + (o[6] * o[6] + o[7] * o[7]);
;                         w[bj].x = cvt_pk_bf16(o[0], o[1]); w[bj].y = cvt_pk_bf16(o[2], o[3]); w[bj].z = cvt_pk_bf16(o[4], o[5]); w[bj].w = cvt_pk_bf16(o[6], o[7]); } }
.LBB0_897:
	s_or_b64 exec, exec, s[56:57]
	v_add_u32_e32 v16, 0xb0, v164
	v_sub_u32_e32 v18, v16, v172
	v_add_u32_e32 v18, v18, v174
	v_ashrrev_i32_e32 v19, 31, v18
	v_lshlrev_b64 v[18:19], 12, v[18:19]
	v_lshl_add_u64 v[20:21], s[16:17], 0, v[18:19]
	v_lshl_add_u64 v[20:21], v[20:21], 0, v[162:163]
	s_waitcnt vmcnt(2)
	s_nop 0
	v_mov_b64_e32 v[22:23], v[228:229]
	v_mov_b64_e32 v[24:25], v[230:231]
	v_lshl_add_u64 v[20:21], s[38:39], 0, v[18:19]
	v_lshl_add_u64 v[20:21], v[20:21], 0, v[162:163]
	s_waitcnt lgkmcnt(0)
	v_mov_b32_e32 v17, v226
	v_mov_b64_e32 v[26:27], v[232:233]
	v_mov_b64_e32 v[28:29], v[234:235]
	v_lshl_add_u64 v[20:21], v[18:19], 0, s[44:45]
	v_lshl_add_u64 v[30:31], s[16:17], 0, v[20:21]
	v_lshl_add_u64 v[30:31], v[30:31], 0, v[162:163]
	v_mov_b64_e32 v[36:37], v[236:237]
	v_mov_b64_e32 v[38:39], v[238:239]
	v_lshl_add_u64 v[30:31], s[38:39], 0, v[20:21]
	v_lshl_add_u64 v[30:31], v[30:31], 0, v[162:163]
	v_mov_b64_e32 v[44:45], v[240:241]
	v_mov_b64_e32 v[46:47], v[242:243]
	s_nop 1
	v_mul_f32_e32 v12, 0xbfb8aa3b, v12
	v_exp_f32_e32 v12, v12
	v_mul_f32_e32 v13, 0xbfb8aa3b, v13
	v_exp_f32_e32 v13, v13
	v_add_f32_e32 v12, 1.0, v12
	v_rcp_f32_e32 v12, v12
	v_add_f32_e32 v13, 1.0, v13
	v_rcp_f32_e32 v13, v13
	v_mul_f32_e32 v8, 0xbfb8aa3b, v8
	v_exp_f32_e32 v8, v8
	v_mul_f32_e32 v9, 0xbfb8aa3b, v9
	v_exp_f32_e32 v9, v9
	v_add_f32_e32 v8, 1.0, v8
	v_rcp_f32_e32 v8, v8
	v_add_f32_e32 v9, 1.0, v9
	v_mul_f32_e32 v4, 0xbfb8aa3b, v4
	v_rcp_f32_e32 v9, v9
	v_exp_f32_e32 v4, v4
	v_mul_f32_e32 v5, 0xbfb8aa3b, v5
	v_exp_f32_e32 v5, v5
	v_add_f32_e32 v4, 1.0, v4
	v_rcp_f32_e32 v4, v4
	v_add_f32_e32 v5, 1.0, v5
	v_rcp_f32_e32 v5, v5
	v_mul_f32_e32 v0, 0xbfb8aa3b, v0
	v_exp_f32_e32 v0, v0
	v_mul_f32_e32 v1, 0xbfb8aa3b, v1
	v_exp_f32_e32 v1, v1
	v_add_f32_e32 v0, 1.0, v0
	v_rcp_f32_e32 v0, v0
	v_add_f32_e32 v1, 1.0, v1
	v_rcp_f32_e32 v1, v1
	v_mov_b32_dpp v30, v22 row_ror:8 row_mask:0xf bank_mask:0xf
	v_mov_b32_dpp v31, v23 row_ror:8 row_mask:0xf bank_mask:0xf
	v_mov_b32_dpp v56, v24 row_ror:8 row_mask:0xf bank_mask:0xf
	v_fmamk_f32 v17, v17, 0x3a000000, v180
	v_rsq_f32_e32 v17, v17
	v_mov_b32_dpp v62, v26 row_ror:8 row_mask:0xf bank_mask:0xf
	v_mov_b32_dpp v64, v28 row_ror:8 row_mask:0xf bank_mask:0xf
	v_mov_b32_dpp v63, v27 row_ror:8 row_mask:0xf bank_mask:0xf
	v_mov_b32_dpp v58, v36 row_ror:8 row_mask:0xf bank_mask:0xf
	v_cndmask_b32_e64 v22, v58, v22, s[6:7]
	v_mov_b32_dpp v59, v37 row_ror:8 row_mask:0xf bank_mask:0xf
	v_mov_b32_dpp v66, v44 row_ror:8 row_mask:0xf bank_mask:0xf
	v_cndmask_b32_e64 v26, v66, v26, s[6:7]
	v_lshlrev_b32_e32 v58, 16, v26
	v_mul_f32_e32 v58, v17, v58
	v_cndmask_b32_e64 v31, v37, v31, s[6:7]
	v_mov_b32_dpp v68, v46 row_ror:8 row_mask:0xf bank_mask:0xf
	v_cndmask_b32_e64 v37, v46, v64, s[6:7]
	v_lshlrev_b32_e32 v46, 16, v22
	v_and_b32_e32 v26, 0xffff0000, v26
	v_mul_f32_e32 v52, v52, v58
	v_fmac_f32_e32 v46, v12, v52
	v_mul_f32_e32 v12, v17, v26
	v_and_b32_e32 v22, 0xffff0000, v22
	v_mul_f32_e32 v12, v53, v12
	v_fmac_f32_e32 v22, v13, v12
	v_mul_f32_e32 v12, 0xbfb8aa3b, v14
	v_exp_f32_e32 v12, v12
	v_mul_f32_e32 v14, 0xbfb8aa3b, v15
	v_exp_f32_e32 v14, v14
	v_mov_b32_dpp v67, v45 row_ror:8 row_mask:0xf bank_mask:0xf
	v_add_f32_e32 v12, 1.0, v12
	v_cndmask_b32_e64 v27, v67, v27, s[6:7]
	v_rcp_f32_e32 v12, v12
	v_cndmask_b32_e64 v23, v59, v23, s[6:7]
	v_lshlrev_b32_e32 v59, 16, v27
	v_add_f32_e32 v14, 1.0, v14
	v_mov_b32_dpp v65, v29 row_ror:8 row_mask:0xf bank_mask:0xf
	v_mul_f32_e32 v13, v17, v59
	v_rcp_f32_e32 v14, v14
	v_cndmask_b32_e64 v30, v36, v30, s[6:7]
	v_mov_b32_dpp v69, v47 row_ror:8 row_mask:0xf bank_mask:0xf
	v_cndmask_b32_e64 v36, v47, v65, s[6:7]
	v_lshlrev_b32_e32 v47, 16, v23
	v_and_b32_e32 v27, 0xffff0000, v27
	v_mul_f32_e32 v13, v54, v13
	v_mov_b32_dpp v60, v38 row_ror:8 row_mask:0xf bank_mask:0xf
	v_cndmask_b32_e64 v28, v68, v28, s[6:7]
	v_fmac_f32_e32 v47, v12, v13
	v_mul_f32_e32 v12, v17, v27
	v_cndmask_b32_e64 v24, v60, v24, s[6:7]
	v_and_b32_e32 v23, 0xffff0000, v23
	v_lshlrev_b32_e32 v60, 16, v28
	v_mul_f32_e32 v12, v55, v12
	v_fmac_f32_e32 v23, v14, v12
	v_mul_f32_e32 v12, v17, v60
	v_cndmask_b32_e64 v38, v38, v56, s[6:7]
	v_lshlrev_b32_e32 v56, 16, v24
	v_and_b32_e32 v28, 0xffff0000, v28
	v_mul_f32_e32 v12, v48, v12
	v_fmac_f32_e32 v56, v8, v12
	v_mul_f32_e32 v8, v17, v28
	v_and_b32_e32 v24, 0xffff0000, v24
	v_mul_f32_e32 v8, v49, v8
	v_fmac_f32_e32 v24, v9, v8
	v_mul_f32_e32 v8, 0xbfb8aa3b, v10
	v_cndmask_b32_e64 v44, v44, v62, s[6:7]
	v_exp_f32_e32 v8, v8
	v_mul_f32_e32 v10, 0xbfb8aa3b, v11
	v_lshlrev_b32_e32 v27, 16, v44
	v_exp_f32_e32 v10, v10
	v_mul_f32_e32 v27, v17, v27
	v_lshlrev_b32_e32 v13, 16, v30
; __device__ __forceinline__ unsigned cvt_pk_bf16(float lo, float hi) { unsigned r; asm volatile("v_cvt_pk_bf16_f32 %0, %1, %2" : "=v"(r) : "v"(lo), "v"(hi)); return r; }
; __device__ __forceinline__ float bflo(unsigned w) { return __uint_as_float(w << 16); }
; __device__ __forceinline__ float bfhi(unsigned w) { return __uint_as_float(w & 0xffff0000u); }
;     __device__ __forceinline__ void operator()(const f32x4 (&acc)[2][2][4][2], const Unit& u, int wr, int wc, int fr, int fq) const {
;     ...
;             for (int m = 0; m < 4; ++m) { const int row = row0 + ai * HALF + m * 16; const size_t off = (size_t)row * D + col0; const float ri = __builtin_amdgcn_rsqf(sse[row] * (1.f / D) + EPS); float sq = 0.f; u32x4 w[2];
;                 u32x4 rr[2], ee[2]; load_pair_lines(R, D, row, fr, col0, rr[0], rr[1]); load_pair_lines(E, D, row, fr, col0, ee[0], ee[1]);
; #pragma unroll
;                 for (int bj = 0; bj < 2; ++bj) { const u32x4 rw = rr[bj], ew = ee[bj];
;                     const float r[8] = {bflo(rw.x), bfhi(rw.x), bflo(rw.y), bfhi(rw.y), bflo(rw.z), bfhi(rw.z), bflo(rw.w), bfhi(rw.w)};
;                     const float e[8] = {bflo(ew.x), bfhi(ew.x), bflo(ew.y), bfhi(ew.y), bflo(ew.z), bfhi(ew.z), bflo(ew.w), bfhi(ew.w)};
;                     float o[8];
; #pragma unroll
;                     for (int j = 0; j < 8; ++j) { const float a = acc[ai][bj][m][j >> 2][j & 3]; const float gg = gv[bj][j >> 2][j & 3];
;                         o[j] = r[j] + e[j] * ri * gg * __builtin_amdgcn_rcpf(1.f + __builtin_amdgcn_exp2f(-a * LOG2E)); }
;                     if (OUT) { *(f32x4*)(OUT + off + 8 * bj) = (f32x4){o[0], o[1], o[2], o[3]}; *(f32x4*)(OUT + off + 8 * bj + 4) = (f32x4){o[4], o[5], o[6], o[7]}; }
;                     else { sq += (o[0] * o[0] + o[1] * o[1]) + (o[2] * o[2] + o[3] * o[3]) + (o[4] * o[4] + o[5] * o[5]) + (o[6] * o[6] + o[7] * o[7]);
;                         w[bj].x = cvt_pk_bf16(o[0], o[1]); w[bj].y = cvt_pk_bf16(o[2], o[3]); w[bj].z = cvt_pk_bf16(o[4], o[5]); w[bj].w = cvt_pk_bf16(o[6], o[7]); } }
;                 if (!OUT) { store_pair_lines(O, D, row, fr, col0, w[0], w[1]);
;                     sq += __shfl_xor(sq, 16); sq += __shfl_xor(sq, 32); if (fq == 0) unsafeAtomicAdd(ssout + row, sq); } }
	v_and_b32_e32 v28, 0xffff0000, v44
	v_mul_f32_e32 v27, v40, v27
	v_add_f32_e32 v8, 1.0, v8
	v_fmac_f32_e32 v13, v4, v27
	v_mul_f32_e32 v4, v17, v28
	v_mov_b32_dpp v61, v39 row_ror:8 row_mask:0xf bank_mask:0xf
	v_cndmask_b32_e64 v29, v69, v29, s[6:7]
	v_rcp_f32_e32 v8, v8
	v_and_b32_e32 v14, 0xffff0000, v30
	v_mul_f32_e32 v4, v41, v4
	v_mov_b32_dpp v57, v25 row_ror:8 row_mask:0xf bank_mask:0xf
	v_cndmask_b32_e64 v25, v61, v25, s[6:7]
	v_lshlrev_b32_e32 v61, 16, v29
	v_add_f32_e32 v10, 1.0, v10
	v_fmac_f32_e32 v14, v5, v4
	v_mul_f32_e32 v4, 0xbfb8aa3b, v6
	v_mul_f32_e32 v9, v17, v61
	v_rcp_f32_e32 v10, v10
	v_exp_f32_e32 v4, v4
	v_cndmask_b32_e64 v39, v39, v57, s[6:7]
	v_lshlrev_b32_e32 v57, 16, v25
	v_and_b32_e32 v29, 0xffff0000, v29
	v_mul_f32_e32 v9, v50, v9
	v_mul_f32_e32 v6, 0xbfb8aa3b, v7
	v_fmac_f32_e32 v57, v8, v9
	v_mul_f32_e32 v8, v17, v29
	v_exp_f32_e32 v6, v6
	v_and_b32_e32 v25, 0xffff0000, v25
	v_mul_f32_e32 v8, v51, v8
	v_fmac_f32_e32 v25, v10, v8
	v_mul_f32_e32 v8, v22, v22
	v_mul_f32_e32 v9, v23, v23
	v_add_f32_e32 v4, 1.0, v4
	v_cndmask_b32_e64 v45, v45, v63, s[6:7]
	v_fmac_f32_e32 v8, v46, v46
	v_fmac_f32_e32 v9, v47, v47
	v_rcp_f32_e32 v4, v4
	v_add_f32_e32 v8, v8, v9
	v_mul_f32_e32 v9, v24, v24
	v_lshlrev_b32_e32 v29, 16, v45
	v_add_f32_e32 v6, 1.0, v6
	v_fmac_f32_e32 v9, v56, v56
	v_mul_f32_e32 v5, v17, v29
	v_rcp_f32_e32 v6, v6
	v_add_f32_e32 v8, v9, v8
	v_mul_f32_e32 v9, v25, v25
	v_lshlrev_b32_e32 v15, 16, v31
	v_and_b32_e32 v30, 0xffff0000, v45
	v_mul_f32_e32 v5, v42, v5
	v_fmac_f32_e32 v9, v57, v57
	v_fmac_f32_e32 v15, v4, v5
	v_mul_f32_e32 v4, v17, v30
	v_add_f32_e32 v8, v9, v8
	v_cvt_pk_bf16_f32 v9, v46, v22
	v_and_b32_e32 v22, 0xffff0000, v31
	v_lshlrev_b32_e32 v31, 16, v37
	v_mul_f32_e32 v4, v43, v4
	v_fmac_f32_e32 v22, v6, v4
	v_mul_f32_e32 v4, v17, v31
	v_cvt_pk_bf16_f32 v10, v47, v23
	v_lshlrev_b32_e32 v23, 16, v38
	v_and_b32_e32 v37, 0xffff0000, v37
	v_mul_f32_e32 v4, v32, v4
	v_fmac_f32_e32 v23, v0, v4
	v_mul_f32_e32 v0, v17, v37
	v_cvt_pk_bf16_f32 v11, v56, v24
	v_and_b32_e32 v24, 0xffff0000, v38
	v_mul_f32_e32 v0, v33, v0
	v_fmac_f32_e32 v24, v1, v0
	v_mul_f32_e32 v0, 0xbfb8aa3b, v2
	v_exp_f32_e32 v0, v0
	v_mul_f32_e32 v2, 0xbfb8aa3b, v3
	v_exp_f32_e32 v2, v2
	v_lshlrev_b32_e32 v38, 16, v36
	v_add_f32_e32 v0, 1.0, v0
	v_rcp_f32_e32 v0, v0
	v_add_f32_e32 v2, 1.0, v2
	v_mul_f32_e32 v1, v17, v38
	v_rcp_f32_e32 v2, v2
	v_cvt_pk_bf16_f32 v12, v57, v25
	v_lshlrev_b32_e32 v25, 16, v39
	v_and_b32_e32 v36, 0xffff0000, v36
	v_mul_f32_e32 v1, v34, v1
	v_fmac_f32_e32 v25, v0, v1
	v_mul_f32_e32 v0, v17, v36
	v_and_b32_e32 v26, 0xffff0000, v39
	v_mul_f32_e32 v0, v35, v0
	v_fmac_f32_e32 v26, v2, v0
	v_mul_f32_e32 v0, v14, v14
	v_mul_f32_e32 v1, v22, v22
	v_fmac_f32_e32 v0, v13, v13
	v_fmac_f32_e32 v1, v15, v15
	v_add_f32_e32 v0, v0, v1
	v_mul_f32_e32 v1, v24, v24
	v_fmac_f32_e32 v1, v23, v23
	v_add_f32_e32 v0, v1, v0
	v_mul_f32_e32 v1, v26, v26
	v_fmac_f32_e32 v1, v25, v25
	v_add_f32_e32 v0, v1, v0
	v_add_f32_e32 v17, v0, v8
	v_cvt_pk_bf16_f32 v0, v13, v14
	v_cvt_pk_bf16_f32 v1, v15, v22
	v_cvt_pk_bf16_f32 v8, v23, v24
	v_cvt_pk_bf16_f32 v13, v25, v26
	v_mov_b32_e32 v15, 0
	v_mov_b32_e32 v6, 0
	v_mov_b32_dpp v5, v13 row_ror:8 row_mask:0xf bank_mask:0xf
	v_mov_b32_dpp v15, v12 row_ror:8 row_mask:0xf bank_mask:0xf
	v_cndmask_b32_e64 v5, v5, v12, s[6:7]
	v_mov_b32_e32 v12, v17
	s_nop 1
	v_permlane16_swap_b32_e32 v12, v17
	v_mov_b32_dpp v6, v9 row_ror:8 row_mask:0xf bank_mask:0xf
	v_mov_b32_dpp v7, v10 row_ror:8 row_mask:0xf bank_mask:0xf
	v_mov_b32_dpp v2, v0 row_ror:8 row_mask:0xf bank_mask:0xf
	v_mov_b32_dpp v3, v1 row_ror:8 row_mask:0xf bank_mask:0xf
	v_mov_b32_dpp v4, v8 row_ror:8 row_mask:0xf bank_mask:0xf
	v_cndmask_b32_e64 v6, v0, v6, s[6:7]
	v_cndmask_b32_e64 v7, v1, v7, s[6:7]
	v_lshl_add_u64 v[0:1], s[36:37], 0, v[18:19]
	v_mov_b32_dpp v14, v11 row_ror:8 row_mask:0xf bank_mask:0xf
	v_cndmask_b32_e64 v3, v3, v10, s[6:7]
	v_cndmask_b32_e64 v4, v4, v11, s[6:7]
	v_lshl_add_u64 v[10:11], v[0:1], 0, v[162:163]
	s_waitcnt lgkmcnt(0)
	v_add_f32_e32 v0, v17, v12
	v_mov_b32_e32 v1, v0
	s_nop 1
	v_permlane32_swap_b32_e32 v1, v0
	v_cndmask_b32_e64 v2, v2, v9, s[6:7]
	global_store_dwordx4 v[10:11], v[2:5], off
	v_cndmask_b32_e64 v8, v8, v14, s[6:7]
	v_cndmask_b32_e64 v9, v13, v15, s[6:7]
	v_lshl_add_u64 v[2:3], s[36:37], 0, v[20:21]
	v_lshl_add_u64 v[2:3], v[2:3], 0, v[162:163]
	global_store_dwordx4 v[2:3], v[6:9], off
	s_and_saveexec_b64 s[56:57], s[8:9]
	s_cbranch_execz .LBB0_873
	v_ashrrev_i32_e32 v17, 31, v16
	v_lshl_add_u64 v[2:3], v[16:17], 2, s[18:19]
	s_waitcnt lgkmcnt(0)
	v_add_f32_e32 v0, v0, v1
	global_atomic_add_f32 v[2:3], v0, off
	s_branch .LBB0_873

; __device__ __forceinline__ float bflo(unsigned w) { return __uint_as_float(w << 16); }
; __device__ __forceinline__ float bfhi(unsigned w) { return __uint_as_float(w & 0xffff0000u); }
; __global__ void __launch_bounds__(NTHREADS, 2) fwd_megakernel(Params P) {
;     ...
;                     const int pos = tok_pos(tok);
;                     const f32x4 c0 = *(const f32x4*)(ROPE128 + pos * 64 + j8), c1 = *(const f32x4*)(ROPE128 + pos * 64 + j8 + 4);
;                     const f32x4 s0 = *(const f32x4*)(ROPE128 + 4096 * 64 + pos * 64 + j8), s1 = *(const f32x4*)(ROPE128 + 4096 * 64 + pos * 64 + j8 + 4);
;                     const float cc[8] = {c0[0], c0[1], c0[2], c0[3], c1[0], c1[1], c1[2], c1[3]}, sn[8] = {s0[0], s0[1], s0[2], s0[3], s1[0], s1[1], s1[2], s1[3]};
;                     const bf16_t* z = Z3 + (size_t)tok * OD_IN;
; #pragma unroll
;                     for (int p = 0; p < 3; ++p) {
;                         const int head = 8 * p + hs; const bool act = head < 20; const int hc = act ? head : 19;
;                         const bf16_t* src = z + hc * 128;
;                         const u32x4 w1 = *(const u32x4*)(src + j8), w2 = *(const u32x4*)(src + 64 + j8);
;                         const float a[8] = {bflo(w1.x), bfhi(w1.x), bflo(w1.y), bfhi(w1.y), bflo(w1.z), bfhi(w1.z), bflo(w1.w), bfhi(w1.w)};
;                         const float b[8] = {bflo(w2.x), bfhi(w2.x), bflo(w2.y), bfhi(w2.y), bflo(w2.z), bfhi(w2.z), bflo(w2.w), bfhi(w2.w)};
;                         float ss = 0.f;
; #pragma unroll
;                         for (int j = 0; j < 8; ++j) ss += a[j] * a[j] + b[j] * b[j];
;                         const bool isq = hc < 16;
;                         const float ri = (isq ? CS : 1.0f) / sqrtf(group_sum<8>(ss) * (1.f / 128.f) + EPS);
;                         float o1[8], o2[8];
; #pragma unroll
;                         for (int j = 0; j < 8; ++j) { const float y1 = a[j] * ri * (isq ? gq[j] : gk[j]), y2 = b[j] * ri * (isq ? gq[8 + j] : gk[8 + j]); o1[j] = y1 * cc[j] - y2 * sn[j]; o2[j] = y2 * cc[j] + y1 * sn[j]; }
.LBB0_1029:
	v_lshl_add_u64 v[150:151], v[70:71], 0, v[42:43]
	global_load_dwordx4 v[152:155], v[150:151], off offset:-1920
	global_load_dwordx4 v[156:159], v[150:151], off offset:-2048
	s_cmpk_lt_i32 s59, 0x2000
	s_nop 0
	s_cselect_b32 s8, s55, 0x7ff
	s_nop 0
	s_and_b32 s8, s8, s59
	s_nop 0
	s_lshl_b32 s16, s8, 8
	s_nop 0
	v_lshl_add_u64 v[142:143], v[44:45], 0, s[16:17]
	v_lshl_add_u64 v[144:145], v[46:47], 0, s[16:17]
	global_load_dwordx4 v[160:163], v[142:143], off offset:16
	global_load_dwordx4 v[164:167], v[144:145], off offset:16
	global_load_dwordx4 v[168:171], v[142:143], off
	global_load_dwordx4 v[172:175], v[144:145], off
	global_load_dwordx4 v[176:179], v[150:151], off offset:128
	global_load_dwordx4 v[180:183], v[150:151], off
	v_lshl_add_u64 v[146:147], v[68:69], 0, v[42:43]
	v_add_co_u32_e32 v148, vcc, s58, v146
	s_nop 1
	v_addc_co_u32_e32 v149, vcc, 0, v147, vcc
	s_nop 1
	global_load_dwordx4 v[184:187], v[148:149], off
	global_load_dwordx4 v[188:191], v[148:149], off offset:128
	v_lshl_add_u64 v[80:81], v[70:71], 0, v[42:43]
	s_waitcnt vmcnt(9)
	s_nop 0
	v_mov_b64_e32 v[72:73], v[152:153]
	v_mov_b64_e32 v[74:75], v[154:155]
	s_nop 1
	s_waitcnt vmcnt(8)
	s_nop 0
	v_mov_b64_e32 v[76:77], v[156:157]
	v_mov_b64_e32 v[78:79], v[158:159]
	s_nop 1
	s_cmpk_lt_i32 s59, 0x2000
	s_cselect_b32 s8, s55, 0x7ff
	s_and_b32 s8, s8, s59
	s_lshl_b32 s16, s8, 8
	v_lshl_add_u64 v[32:33], v[44:45], 0, s[16:17]
	v_lshl_add_u64 v[36:37], v[46:47], 0, s[16:17]
	s_waitcnt vmcnt(7)
	s_nop 0
	v_mov_b64_e32 v[24:25], v[160:161]
	v_mov_b64_e32 v[26:27], v[162:163]
	s_nop 1
	s_waitcnt vmcnt(6)
	s_nop 0
	v_mov_b64_e32 v[28:29], v[164:165]
	v_mov_b64_e32 v[30:31], v[166:167]
	s_nop 1
	s_nop 0
	s_waitcnt vmcnt(5)
	s_nop 0
	v_mov_b64_e32 v[32:33], v[168:169]
	v_mov_b64_e32 v[34:35], v[170:171]
	s_nop 1
	s_nop 0
	s_waitcnt vmcnt(4)
	s_nop 0
	v_mov_b64_e32 v[36:37], v[172:173]
	v_mov_b64_e32 v[38:39], v[174:175]
	s_nop 1
	v_lshlrev_b32_e32 v103, 16, v74
	v_and_b32_e32 v105, 0xffff0000, v74
	v_and_b32_e32 v109, 0xffff0000, v73
	v_and_b32_e32 v108, 0xffff0000, v77
	v_lshlrev_b32_e32 v111, 16, v72
	v_lshlrev_b32_e32 v110, 16, v76
	v_and_b32_e32 v113, 0xffff0000, v72
	v_and_b32_e32 v112, 0xffff0000, v76
	v_lshlrev_b32_e32 v98, 16, v79
	v_and_b32_e32 v100, 0xffff0000, v79
	v_lshlrev_b32_e32 v102, 16, v78
	v_and_b32_e32 v104, 0xffff0000, v78
	v_lshlrev_b32_e32 v107, 16, v73
	v_lshlrev_b32_e32 v106, 16, v77
	v_mov_b32_e32 v78, v103
	v_mov_b32_e32 v79, v105
	v_pk_mul_f32 v[84:85], v[108:109], v[108:109]
	v_pk_mul_f32 v[86:87], v[110:111], v[110:111]
	v_pk_mul_f32 v[88:89], v[112:113], v[112:113]
	v_mov_b32_e32 v76, v102
	v_mov_b32_e32 v77, v104
	v_pk_mul_f32 v[82:83], v[106:107], v[106:107]
	v_pk_mul_f32 v[78:79], v[78:79], v[78:79]
	v_add_f32_e32 v84, v84, v85
	v_add_f32_e32 v85, v88, v89
	v_add_f32_e32 v86, v86, v87
	v_add_f32_e32 v87, v82, v83
	v_pk_fma_f32 v[76:77], v[76:77], v[76:77], v[78:79]
	v_add_f32_e32 v78, v86, v85
	v_lshlrev_b32_e32 v99, 16, v75
	v_and_b32_e32 v101, 0xffff0000, v75
	v_add_f32_e32 v78, v78, v87
	v_mov_b32_e32 v74, v99
	v_mov_b32_e32 v75, v101
	v_add_f32_e32 v78, v78, v84
	v_mov_b32_e32 v72, v98
	v_mov_b32_e32 v73, v100
	v_pk_mul_f32 v[74:75], v[74:75], v[74:75]
	v_add_f32_e32 v76, v78, v76
	v_pk_fma_f32 v[82:83], v[72:73], v[72:73], v[74:75]
	v_add_f32_e32 v76, v76, v77
	v_add_f32_e32 v76, v76, v82
	v_add_f32_e32 v82, v76, v83
	s_nop 1
	v_mov_b32_dpp v83, v82 quad_perm:[1,0,3,2] row_mask:0xf bank_mask:0xf
	v_mov_b32_e32 v76, v34
	v_mov_b32_e32 v77, v38
	v_mov_b32_e32 v88, v38
	v_mov_b32_e32 v89, v34
	s_waitcnt lgkmcnt(0)
	v_add_f32_e32 v86, v82, v83
	s_nop 1
	v_mov_b32_dpp v87, v86 quad_perm:[2,3,0,1] row_mask:0xf bank_mask:0xf
	v_mov_b32_e32 v74, v24
	v_mov_b32_e32 v75, v28
	v_mov_b32_e32 v78, v32
	v_mov_b32_e32 v79, v36
	s_waitcnt lgkmcnt(0)
	v_add_f32_e32 v90, v86, v87
	s_nop 1
	v_mov_b32_dpp v91, v90 row_shl:4 row_mask:0xf bank_mask:0x5
	s_nop 1
	v_mov_b32_dpp v91, v90 row_shr:4 row_mask:0xf bank_mask:0xa
	v_mov_b32_e32 v82, v36
	v_mov_b32_e32 v83, v32
	v_mov_b32_e32 v92, v39
	v_mov_b32_e32 v84, v33
	s_waitcnt lgkmcnt(0)
	v_add_f32_e32 v90, v90, v91
	v_fmamk_f32 v90, v90, 0x3c000000, v94
	v_mul_f32_e32 v91, 0x4f800000, v90
	v_cmp_gt_f32_e32 vcc, s56, v90
	v_mov_b32_e32 v85, v37
	v_mov_b32_e32 v86, v37
	v_cndmask_b32_e32 v93, v90, v91, vcc
	v_sqrt_f32_e32 v114, v93
	v_mov_b32_e32 v90, v35
	v_mov_b32_e32 v91, v39
	v_mov_b32_e32 v87, v33
	v_add_u32_e32 v115, -1, v114
	v_add_u32_e32 v116, 1, v114
	v_fma_f32 v117, -v115, v114, v93
	v_fma_f32 v118, -v116, v114, v93
	v_cmp_ge_f32_e64 s[8:9], 0, v117
	v_mov_b32_e32 v72, v26
	v_mov_b32_e32 v73, v30
	v_cndmask_b32_e64 v114, v114, v115, s[8:9]
	v_cmp_lt_f32_e64 s[8:9], 0, v118
	s_nop 1
	v_cndmask_b32_e64 v114, v114, v116, s[8:9]
	v_mul_f32_e32 v115, 0x37800000, v114
	v_cndmask_b32_e32 v114, v114, v115, vcc
	v_cmp_class_f32_e32 vcc, v93, v95
	s_nop 1
	v_cndmask_b32_e32 v114, v114, v93, vcc
	v_div_scale_f32 v115, s[8:9], v114, v114, s57
	v_rcp_f32_e32 v116, v115
	v_div_scale_f32 v117, vcc, s57, v114, s57
	v_mov_b32_e32 v93, v35
	v_fma_f32 v118, -v115, v116, 1.0
	v_fmac_f32_e32 v116, v118, v116
	v_mul_f32_e32 v118, v117, v116
	v_fma_f32 v119, -v115, v118, v117
	v_fmac_f32_e32 v118, v119, v116
	v_fma_f32 v115, -v115, v118, v117
	v_div_fmas_f32 v115, v115, v116, v118
	v_div_fixup_f32 v114, v115, v114, s57
	v_pk_mul_f32 v[106:107], v[114:115], v[106:107] op_sel_hi:[0,1]
	v_pk_mul_f32 v[106:107], v[106:107], v[56:57]
	v_pk_mul_f32 v[102:103], v[114:115], v[102:103] op_sel_hi:[0,1]
	v_pk_mul_f32 v[120:121], v[106:107], v[76:77]
	v_pk_mul_f32 v[106:107], v[106:107], v[88:89]
; __device__ __forceinline__ unsigned cvt_pk_bf16(float lo, float hi) { unsigned r; asm volatile("v_cvt_pk_bf16_f32 %0, %1, %2" : "=v"(r) : "v"(lo), "v"(hi)); return r; }
; __device__ __forceinline__ float bflo(unsigned w) { return __uint_as_float(w << 16); }
; __device__ __forceinline__ float bfhi(unsigned w) { return __uint_as_float(w & 0xffff0000u); }
; __global__ void __launch_bounds__(NTHREADS, 2) fwd_megakernel(Params P) {
;     ...
;                     for (int p = 0; p < 3; ++p) {
;                         const int head = 8 * p + hs; const bool act = head < 20; const int hc = act ? head : 19;
;                         const bf16_t* src = z + hc * 128;
;                         const u32x4 w1 = *(const u32x4*)(src + j8), w2 = *(const u32x4*)(src + 64 + j8);
;                         const float a[8] = {bflo(w1.x), bfhi(w1.x), bflo(w1.y), bfhi(w1.y), bflo(w1.z), bfhi(w1.z), bflo(w1.w), bfhi(w1.w)};
;                         const float b[8] = {bflo(w2.x), bfhi(w2.x), bflo(w2.y), bfhi(w2.y), bflo(w2.z), bfhi(w2.z), bflo(w2.w), bfhi(w2.w)};
;                         float ss = 0.f;
; #pragma unroll
;                         for (int j = 0; j < 8; ++j) ss += a[j] * a[j] + b[j] * b[j];
;                         const bool isq = hc < 16;
;                         const float ri = (isq ? CS : 1.0f) / sqrtf(group_sum<8>(ss) * (1.f / 128.f) + EPS);
;                         float o1[8], o2[8];
; #pragma unroll
;                         for (int j = 0; j < 8; ++j) { const float y1 = a[j] * ri * (isq ? gq[j] : gk[j]), y2 = b[j] * ri * (isq ? gq[8 + j] : gk[8 + j]); o1[j] = y1 * cc[j] - y2 * sn[j]; o2[j] = y2 * cc[j] + y1 * sn[j]; }
;                         u32x4 v1, v2;
;                         v1.x = cvt_pk_bf16(o1[0], o1[1]); v1.y = cvt_pk_bf16(o1[2], o1[3]); v1.z = cvt_pk_bf16(o1[4], o1[5]); v1.w = cvt_pk_bf16(o1[6], o1[7]);
;                         v2.x = cvt_pk_bf16(o2[0], o2[1]); v2.y = cvt_pk_bf16(o2[2], o2[3]); v2.z = cvt_pk_bf16(o2[4], o2[5]); v2.w = cvt_pk_bf16(o2[6], o2[7]);
;                         bf16_t* dst = isq ? SQ + (size_t)tok * 2048 + hc * 128 : SK + (size_t)tok * 512 + (hc - 16) * 128;
;                         if (act) { *(u32x4*)(dst + j8) = v1; *(u32x4*)(dst + 64 + j8) = v2; }
	v_pk_mul_f32 v[110:111], v[114:115], v[110:111] op_sel_hi:[0,1]
	v_pk_mul_f32 v[108:109], v[114:115], v[108:109] op_sel_hi:[0,1]
	v_pk_mul_f32 v[102:103], v[102:103], v[54:55]
	v_sub_f32_e32 v120, v120, v121
	v_add_f32_e32 v121, v107, v106
	v_mov_b32_e32 v106, v28
	v_mov_b32_e32 v107, v24
	v_pk_mul_f32 v[112:113], v[114:115], v[112:113] op_sel_hi:[0,1]
	v_pk_mul_f32 v[110:111], v[110:111], v[58:59]
	v_pk_mul_f32 v[108:109], v[108:109], v[6:7]
	v_pk_mul_f32 v[124:125], v[102:103], v[74:75]
	v_pk_mul_f32 v[102:103], v[102:103], v[106:107]
	v_pk_mul_f32 v[112:113], v[112:113], v[4:5]
	v_pk_mul_f32 v[116:117], v[110:111], v[78:79]
	v_pk_mul_f32 v[110:111], v[110:111], v[82:83]
	v_pk_mul_f32 v[122:123], v[108:109], v[90:91]
	v_pk_mul_f32 v[108:109], v[108:109], v[92:93]
	v_sub_f32_e32 v124, v124, v125
	v_add_f32_e32 v125, v103, v102
	v_pk_mul_f32 v[102:103], v[114:115], v[104:105] op_sel_hi:[0,1]
	v_pk_mul_f32 v[118:119], v[112:113], v[84:85]
	v_pk_mul_f32 v[112:113], v[112:113], v[86:87]
	v_add_f32_e32 v127, v111, v110
	v_sub_f32_e32 v122, v122, v123
	v_add_f32_e32 v123, v109, v108
	v_pk_mul_f32 v[102:103], v[102:103], v[0:1]
	v_mov_b32_e32 v108, v25
	v_mov_b32_e32 v109, v29
	v_mov_b32_e32 v110, v29
	v_mov_b32_e32 v111, v25
	v_pk_mul_f32 v[98:99], v[114:115], v[98:99] op_sel_hi:[0,1]
	v_sub_f32_e32 v118, v118, v119
	v_add_f32_e32 v119, v113, v112
	v_pk_mul_f32 v[104:105], v[102:103], v[108:109]
	v_pk_mul_f32 v[102:103], v[102:103], v[110:111]
	v_pk_mul_f32 v[98:99], v[98:99], v[52:53]
	v_mov_b32_e32 v112, v30
	v_mov_b32_e32 v113, v26
	v_sub_f32_e32 v104, v104, v105
	v_add_f32_e32 v105, v103, v102
	v_pk_mul_f32 v[102:103], v[98:99], v[72:73]
	v_pk_mul_f32 v[98:99], v[98:99], v[112:113]
	v_sub_f32_e32 v126, v116, v117
	v_add_f32_e32 v128, v99, v98
	v_pk_mul_f32 v[98:99], v[114:115], v[100:101] op_sel_hi:[0,1]
	v_pk_mul_f32 v[98:99], v[98:99], v[2:3]
	v_mov_b32_e32 v114, v27
	v_mov_b32_e32 v115, v31
	v_pk_mul_f32 v[100:101], v[98:99], v[114:115]
	v_mov_b32_e32 v116, v31
	v_mov_b32_e32 v117, v27
	v_sub_f32_e32 v102, v102, v103
	v_sub_f32_e32 v101, v100, v101
	v_pk_mul_f32 v[98:99], v[98:99], v[116:117]
	s_nop 0
	v_add_f32_e32 v129, v99, v98
	v_cvt_pk_bf16_f32 v98, v126, v118
	v_cvt_pk_bf16_f32 v99, v120, v122
	v_cvt_pk_bf16_f32 v100, v124, v104
	v_cvt_pk_bf16_f32 v101, v102, v101
	v_cvt_pk_bf16_f32 v102, v127, v119
	v_lshl_add_u64 v[118:119], v[66:67], 0, v[42:43]
	v_cvt_pk_bf16_f32 v103, v121, v123
	v_cvt_pk_bf16_f32 v104, v125, v105
	v_cvt_pk_bf16_f32 v105, v128, v129
	global_store_dwordx4 v[118:119], v[98:101], off offset:-2048
	global_store_dwordx4 v[118:119], v[102:105], off offset:-1920
	s_waitcnt vmcnt(5)
	s_nop 0
	v_mov_b64_e32 v[98:99], v[176:177]
	v_mov_b64_e32 v[100:101], v[178:179]
	s_nop 1
	s_nop 0
	s_waitcnt vmcnt(4)
	s_nop 0
	v_mov_b64_e32 v[102:103], v[180:181]
	v_mov_b64_e32 v[104:105], v[182:183]
	s_nop 1
	v_lshlrev_b32_e32 v81, 16, v101
	v_lshlrev_b32_e32 v80, 16, v105
	v_and_b32_e32 v121, 0xffff0000, v101
	v_and_b32_e32 v120, 0xffff0000, v105
	v_lshlrev_b32_e32 v123, 16, v100
	v_and_b32_e32 v101, 0xffff0000, v100
	v_lshlrev_b32_e32 v105, 16, v99
	v_and_b32_e32 v125, 0xffff0000, v99
	v_and_b32_e32 v124, 0xffff0000, v103
	v_lshlrev_b32_e32 v127, 16, v98
	v_lshlrev_b32_e32 v126, 16, v102
	v_and_b32_e32 v99, 0xffff0000, v98
	v_and_b32_e32 v98, 0xffff0000, v102
	v_lshlrev_b32_e32 v122, 16, v104
	v_and_b32_e32 v100, 0xffff0000, v104
	v_lshlrev_b32_e32 v104, 16, v103
	v_mov_b32_e32 v128, v81
	v_mov_b32_e32 v129, v121
	v_mov_b32_e32 v132, v123
	v_mov_b32_e32 v133, v101
	v_pk_mul_f32 v[136:137], v[124:125], v[124:125]
	v_pk_mul_f32 v[138:139], v[126:127], v[126:127]
	v_pk_mul_f32 v[140:141], v[98:99], v[98:99]
	v_mov_b32_e32 v102, v80
	v_mov_b32_e32 v103, v120
	v_mov_b32_e32 v130, v122
	v_mov_b32_e32 v131, v100
	v_pk_mul_f32 v[134:135], v[104:105], v[104:105]
	v_pk_mul_f32 v[128:129], v[128:129], v[128:129]
	v_pk_mul_f32 v[132:133], v[132:133], v[132:133]
	v_add_f32_e32 v136, v136, v137
	v_add_f32_e32 v137, v140, v141
	v_add_f32_e32 v138, v138, v139
	v_add_f32_e32 v134, v134, v135
	v_pk_fma_f32 v[102:103], v[102:103], v[102:103], v[128:129]
	v_pk_fma_f32 v[128:129], v[130:131], v[130:131], v[132:133]
	v_add_f32_e32 v130, v138, v137
	v_add_f32_e32 v130, v130, v134
	v_add_f32_e32 v130, v130, v136
	v_add_f32_e32 v128, v130, v128
	v_add_f32_e32 v128, v128, v129
	v_add_f32_e32 v102, v128, v102
	v_add_f32_e32 v102, v102, v103
	s_nop 1
	v_mov_b32_dpp v103, v102 quad_perm:[1,0,3,2] row_mask:0xf bank_mask:0xf
	s_waitcnt lgkmcnt(0)
	v_add_f32_e32 v102, v102, v103
	s_nop 1
	v_mov_b32_dpp v103, v102 quad_perm:[2,3,0,1] row_mask:0xf bank_mask:0xf
	s_waitcnt lgkmcnt(0)
	v_add_f32_e32 v102, v102, v103
	s_nop 1
	v_mov_b32_dpp v103, v102 row_shl:4 row_mask:0xf bank_mask:0x5
	s_nop 1
	v_mov_b32_dpp v103, v102 row_shr:4 row_mask:0xf bank_mask:0xa
	s_waitcnt lgkmcnt(0)
; __device__ __forceinline__ unsigned cvt_pk_bf16(float lo, float hi) { unsigned r; asm volatile("v_cvt_pk_bf16_f32 %0, %1, %2" : "=v"(r) : "v"(lo), "v"(hi)); return r; }
; __device__ __forceinline__ float bflo(unsigned w) { return __uint_as_float(w << 16); }
; __device__ __forceinline__ float bfhi(unsigned w) { return __uint_as_float(w & 0xffff0000u); }
; __global__ void __launch_bounds__(NTHREADS, 2) fwd_megakernel(Params P) {
;     ...
;                     for (int p = 0; p < 3; ++p) {
;                         const int head = 8 * p + hs; const bool act = head < 20; const int hc = act ? head : 19;
;                         const bf16_t* src = z + hc * 128;
;                         const u32x4 w1 = *(const u32x4*)(src + j8), w2 = *(const u32x4*)(src + 64 + j8);
;                         const float a[8] = {bflo(w1.x), bfhi(w1.x), bflo(w1.y), bfhi(w1.y), bflo(w1.z), bfhi(w1.z), bflo(w1.w), bfhi(w1.w)};
;                         const float b[8] = {bflo(w2.x), bfhi(w2.x), bflo(w2.y), bfhi(w2.y), bflo(w2.z), bfhi(w2.z), bflo(w2.w), bfhi(w2.w)};
;                         float ss = 0.f;
; #pragma unroll
;                         for (int j = 0; j < 8; ++j) ss += a[j] * a[j] + b[j] * b[j];
;                         const bool isq = hc < 16;
;                         const float ri = (isq ? CS : 1.0f) / sqrtf(group_sum<8>(ss) * (1.f / 128.f) + EPS);
;                         float o1[8], o2[8];
; #pragma unroll
;                         for (int j = 0; j < 8; ++j) { const float y1 = a[j] * ri * (isq ? gq[j] : gk[j]), y2 = b[j] * ri * (isq ? gq[8 + j] : gk[8 + j]); o1[j] = y1 * cc[j] - y2 * sn[j]; o2[j] = y2 * cc[j] + y1 * sn[j]; }
;                         u32x4 v1, v2;
;                         v1.x = cvt_pk_bf16(o1[0], o1[1]); v1.y = cvt_pk_bf16(o1[2], o1[3]); v1.z = cvt_pk_bf16(o1[4], o1[5]); v1.w = cvt_pk_bf16(o1[6], o1[7]);
;                         v2.x = cvt_pk_bf16(o2[0], o2[1]); v2.y = cvt_pk_bf16(o2[2], o2[3]); v2.z = cvt_pk_bf16(o2[4], o2[5]); v2.w = cvt_pk_bf16(o2[6], o2[7]);
;                         bf16_t* dst = isq ? SQ + (size_t)tok * 2048 + hc * 128 : SK + (size_t)tok * 512 + (hc - 16) * 128;
;                         if (act) { *(u32x4*)(dst + j8) = v1; *(u32x4*)(dst + 64 + j8) = v2; }
	v_add_f32_e32 v102, v102, v103
	v_fmamk_f32 v102, v102, 0x3c000000, v94
	v_mul_f32_e32 v103, 0x4f800000, v102
	v_cmp_gt_f32_e32 vcc, s56, v102
	s_nop 1
	v_cndmask_b32_e32 v102, v102, v103, vcc
	v_sqrt_f32_e32 v103, v102
	s_nop 0
	v_add_u32_e32 v128, -1, v103
	v_add_u32_e32 v129, 1, v103
	v_fma_f32 v130, -v128, v103, v102
	v_fma_f32 v131, -v129, v103, v102
	v_cmp_ge_f32_e64 s[8:9], 0, v130
	s_nop 1
	v_cndmask_b32_e64 v103, v103, v128, s[8:9]
	v_cmp_lt_f32_e64 s[8:9], 0, v131
	s_nop 1
	v_cndmask_b32_e64 v103, v103, v129, s[8:9]
	v_mul_f32_e32 v128, 0x37800000, v103
	v_cndmask_b32_e32 v103, v103, v128, vcc
	v_cmp_class_f32_e32 vcc, v102, v95
	s_nop 1
	v_cndmask_b32_e32 v102, v103, v102, vcc
	v_div_scale_f32 v103, s[8:9], v102, v102, s57
	v_rcp_f32_e32 v128, v103
	v_div_scale_f32 v129, vcc, s57, v102, s57
	v_fma_f32 v130, -v103, v128, 1.0
	v_fmac_f32_e32 v128, v130, v128
	v_mul_f32_e32 v130, v129, v128
	v_fma_f32 v131, -v103, v130, v129
	v_fmac_f32_e32 v130, v131, v128
	v_fma_f32 v103, -v103, v130, v129
	v_div_fmas_f32 v103, v103, v128, v130
	v_div_fixup_f32 v102, v103, v102, s57
	v_pk_mul_f32 v[126:127], v[102:103], v[126:127] op_sel_hi:[0,1]
	v_pk_mul_f32 v[98:99], v[102:103], v[98:99] op_sel_hi:[0,1]
	v_pk_mul_f32 v[104:105], v[102:103], v[104:105] op_sel_hi:[0,1]
	v_pk_mul_f32 v[126:127], v[126:127], v[58:59]
	v_pk_mul_f32 v[98:99], v[98:99], v[4:5]
	v_pk_mul_f32 v[104:105], v[104:105], v[56:57]
	v_pk_mul_f32 v[82:83], v[126:127], v[82:83]
	v_pk_mul_f32 v[84:85], v[98:99], v[84:85]
	v_pk_mul_f32 v[76:77], v[104:105], v[76:77]
	v_pk_mul_f32 v[86:87], v[98:99], v[86:87]
	v_add_f32_e32 v82, v83, v82
	v_sub_f32_e32 v83, v84, v85
	v_sub_f32_e32 v85, v76, v77
	v_pk_mul_f32 v[76:77], v[104:105], v[88:89]
	v_add_f32_e32 v84, v87, v86
	v_add_f32_e32 v86, v77, v76
	v_pk_mul_f32 v[76:77], v[102:103], v[124:125] op_sel_hi:[0,1]
	v_pk_mul_f32 v[78:79], v[126:127], v[78:79]
	v_pk_mul_f32 v[76:77], v[76:77], v[6:7]
	v_sub_f32_e32 v98, v78, v79
	v_pk_mul_f32 v[78:79], v[76:77], v[90:91]
	v_pk_mul_f32 v[76:77], v[76:77], v[92:93]
	v_sub_f32_e32 v78, v78, v79
	v_add_f32_e32 v79, v77, v76
	v_pk_mul_f32 v[76:77], v[102:103], v[122:123] op_sel_hi:[0,1]
	v_pk_mul_f32 v[76:77], v[76:77], v[54:55]
	s_nop 0
	v_pk_mul_f32 v[74:75], v[76:77], v[74:75]
	s_nop 0
	v_sub_f32_e32 v87, v74, v75
	v_pk_mul_f32 v[74:75], v[76:77], v[106:107]
	s_nop 0
	v_add_f32_e32 v88, v75, v74
	v_pk_mul_f32 v[74:75], v[102:103], v[100:101] op_sel_hi:[0,1]
	v_pk_mul_f32 v[74:75], v[74:75], v[0:1]
	s_nop 0
	v_pk_mul_f32 v[76:77], v[74:75], v[108:109]
	v_pk_mul_f32 v[74:75], v[74:75], v[110:111]
	v_sub_f32_e32 v76, v76, v77
	v_add_f32_e32 v89, v75, v74
	v_pk_mul_f32 v[74:75], v[102:103], v[80:81] op_sel_hi:[0,1]
	v_pk_mul_f32 v[74:75], v[74:75], v[52:53]
	s_nop 0
	v_pk_mul_f32 v[72:73], v[74:75], v[72:73]
	s_nop 0
	v_sub_f32_e32 v77, v72, v73
	v_pk_mul_f32 v[72:73], v[74:75], v[112:113]
	s_nop 0
	v_add_f32_e32 v80, v73, v72
	v_pk_mul_f32 v[72:73], v[102:103], v[120:121] op_sel_hi:[0,1]
	v_pk_mul_f32 v[72:73], v[72:73], v[2:3]
	s_nop 0
	v_pk_mul_f32 v[74:75], v[72:73], v[114:115]
	v_pk_mul_f32 v[72:73], v[72:73], v[116:117]
	v_sub_f32_e32 v75, v74, v75
	v_add_f32_e32 v81, v73, v72
	v_cvt_pk_bf16_f32 v72, v98, v83
	v_cvt_pk_bf16_f32 v73, v85, v78
	v_cvt_pk_bf16_f32 v74, v87, v76
	v_cvt_pk_bf16_f32 v75, v77, v75
	v_cvt_pk_bf16_f32 v76, v82, v84
	v_cvt_pk_bf16_f32 v77, v86, v79
	v_cvt_pk_bf16_f32 v78, v88, v89
	v_cvt_pk_bf16_f32 v79, v80, v81
	global_store_dwordx4 v[118:119], v[72:75], off
	global_store_dwordx4 v[118:119], v[76:79], off offset:128
	s_nop 0
	v_lshl_add_u64 v[72:73], v[68:69], 0, v[42:43]
	v_add_co_u32_e32 v76, vcc, s58, v72
	s_nop 1
	v_addc_co_u32_e32 v77, vcc, 0, v73, vcc
	s_waitcnt vmcnt(5)
	s_nop 0
	v_mov_b64_e32 v[72:73], v[184:185]
	v_mov_b64_e32 v[74:75], v[186:187]
	s_nop 1
	s_nop 0
	s_waitcnt vmcnt(4)
; __device__ __forceinline__ unsigned cvt_pk_bf16(float lo, float hi) { unsigned r; asm volatile("v_cvt_pk_bf16_f32 %0, %1, %2" : "=v"(r) : "v"(lo), "v"(hi)); return r; }
; __device__ __forceinline__ float bflo(unsigned w) { return __uint_as_float(w << 16); }
; __device__ __forceinline__ float bfhi(unsigned w) { return __uint_as_float(w & 0xffff0000u); }
; __global__ void __launch_bounds__(NTHREADS, 2) fwd_megakernel(Params P) {
;     ...
;                     for (int p = 0; p < 3; ++p) {
;                         const int head = 8 * p + hs; const bool act = head < 20; const int hc = act ? head : 19;
;                         const bf16_t* src = z + hc * 128;
;                         const u32x4 w1 = *(const u32x4*)(src + j8), w2 = *(const u32x4*)(src + 64 + j8);
;                         const float a[8] = {bflo(w1.x), bfhi(w1.x), bflo(w1.y), bfhi(w1.y), bflo(w1.z), bfhi(w1.z), bflo(w1.w), bfhi(w1.w)};
;                         const float b[8] = {bflo(w2.x), bfhi(w2.x), bflo(w2.y), bfhi(w2.y), bflo(w2.z), bfhi(w2.z), bflo(w2.w), bfhi(w2.w)};
;                         float ss = 0.f;
; #pragma unroll
;                         for (int j = 0; j < 8; ++j) ss += a[j] * a[j] + b[j] * b[j];
;                         const bool isq = hc < 16;
;                         const float ri = (isq ? CS : 1.0f) / sqrtf(group_sum<8>(ss) * (1.f / 128.f) + EPS);
;                         float o1[8], o2[8];
; #pragma unroll
;                         for (int j = 0; j < 8; ++j) { const float y1 = a[j] * ri * (isq ? gq[j] : gk[j]), y2 = b[j] * ri * (isq ? gq[8 + j] : gk[8 + j]); o1[j] = y1 * cc[j] - y2 * sn[j]; o2[j] = y2 * cc[j] + y1 * sn[j]; }
;                         u32x4 v1, v2;
;                         v1.x = cvt_pk_bf16(o1[0], o1[1]); v1.y = cvt_pk_bf16(o1[2], o1[3]); v1.z = cvt_pk_bf16(o1[4], o1[5]); v1.w = cvt_pk_bf16(o1[6], o1[7]);
;                         v2.x = cvt_pk_bf16(o2[0], o2[1]); v2.y = cvt_pk_bf16(o2[2], o2[3]); v2.z = cvt_pk_bf16(o2[4], o2[5]); v2.w = cvt_pk_bf16(o2[6], o2[7]);
;                         bf16_t* dst = isq ? SQ + (size_t)tok * 2048 + hc * 128 : SK + (size_t)tok * 512 + (hc - 16) * 128;
;                         if (act) { *(u32x4*)(dst + j8) = v1; *(u32x4*)(dst + 64 + j8) = v2; }
	s_nop 0
	v_mov_b64_e32 v[76:77], v[188:189]
	v_mov_b64_e32 v[78:79], v[190:191]
	s_nop 1
	v_lshlrev_b32_e32 v80, 16, v72
	v_lshlrev_b32_e32 v84, 16, v76
	v_and_b32_e32 v76, 0xffff0000, v76
	v_and_b32_e32 v72, 0xffff0000, v72
	v_lshlrev_b32_e32 v85, 16, v77
	v_mul_f32_e32 v88, v84, v84
	v_mul_f32_e32 v89, v76, v76
	v_lshlrev_b32_e32 v81, 16, v73
	v_and_b32_e32 v77, 0xffff0000, v77
	v_mul_f32_e32 v90, v85, v85
	v_fmac_f32_e32 v88, v80, v80
	v_fmac_f32_e32 v89, v72, v72
	v_and_b32_e32 v73, 0xffff0000, v73
	v_lshlrev_b32_e32 v86, 16, v78
	v_mul_f32_e32 v91, v77, v77
	v_fmac_f32_e32 v90, v81, v81
	v_add_f32_e32 v88, v88, v89
	v_lshlrev_b32_e32 v82, 16, v74
	v_and_b32_e32 v78, 0xffff0000, v78
	v_mul_f32_e32 v92, v86, v86
	v_fmac_f32_e32 v91, v73, v73
	v_add_f32_e32 v88, v88, v90
	v_and_b32_e32 v74, 0xffff0000, v74
	v_lshlrev_b32_e32 v87, 16, v79
	v_mul_f32_e32 v93, v78, v78
	v_fmac_f32_e32 v92, v82, v82
	v_add_f32_e32 v88, v88, v91
	v_lshlrev_b32_e32 v83, 16, v75
	v_and_b32_e32 v79, 0xffff0000, v79
	v_mul_f32_e32 v98, v87, v87
	v_fmac_f32_e32 v93, v74, v74
	v_add_f32_e32 v88, v88, v92
	v_and_b32_e32 v75, 0xffff0000, v75
	v_mul_f32_e32 v99, v79, v79
	v_fmac_f32_e32 v98, v83, v83
	v_add_f32_e32 v88, v88, v93
	v_fmac_f32_e32 v99, v75, v75
	v_add_f32_e32 v88, v88, v98
	v_add_f32_e32 v88, v88, v99
	s_nop 1
	v_mov_b32_dpp v89, v88 quad_perm:[1,0,3,2] row_mask:0xf bank_mask:0xf
	s_waitcnt lgkmcnt(0)
	v_add_f32_e32 v88, v88, v89
	s_nop 1
	v_mov_b32_dpp v89, v88 quad_perm:[2,3,0,1] row_mask:0xf bank_mask:0xf
	s_waitcnt lgkmcnt(0)
	v_add_f32_e32 v88, v88, v89
	s_nop 1
	v_mov_b32_dpp v89, v88 row_shl:4 row_mask:0xf bank_mask:0x5
	s_nop 1
	v_mov_b32_dpp v89, v88 row_shr:4 row_mask:0xf bank_mask:0xa
	s_waitcnt lgkmcnt(0)
	v_add_f32_e32 v88, v88, v89
	v_fmamk_f32 v88, v88, 0x3c000000, v94
	v_mul_f32_e32 v89, 0x4f800000, v88
	v_cmp_gt_f32_e32 vcc, s56, v88
	s_nop 1
	v_cndmask_b32_e32 v88, v88, v89, vcc
	v_sqrt_f32_e32 v89, v88
	s_nop 0
	v_add_u32_e32 v90, -1, v89
	v_add_u32_e32 v91, 1, v89
	v_fma_f32 v92, -v90, v89, v88
	v_fma_f32 v93, -v91, v89, v88
	v_cmp_ge_f32_e64 s[8:9], 0, v92
	s_nop 1
	v_cndmask_b32_e64 v89, v89, v90, s[8:9]
	v_cmp_lt_f32_e64 s[8:9], 0, v93
	s_nop 1
	v_cndmask_b32_e64 v89, v89, v91, s[8:9]
	v_mul_f32_e32 v90, 0x37800000, v89
	v_cndmask_b32_e32 v89, v89, v90, vcc
	v_cmp_class_f32_e32 vcc, v88, v95
	s_nop 1
	v_cndmask_b32_e32 v88, v89, v88, vcc
	v_div_scale_f32 v89, s[8:9], v88, v88, 1.0
	v_rcp_f32_e32 v90, v89
	v_div_scale_f32 v91, vcc, 1.0, v88, 1.0
	v_fma_f32 v92, -v89, v90, 1.0
	v_fmac_f32_e32 v90, v92, v90
	v_mul_f32_e32 v92, v91, v90
	v_fma_f32 v93, -v89, v92, v91
	v_fmac_f32_e32 v92, v93, v90
	v_fma_f32 v89, -v89, v92, v91
	v_div_fmas_f32 v89, v89, v90, v92
	v_div_fixup_f32 v88, v89, v88, 1.0
	v_mul_f32_e32 v80, v88, v80
	v_mul_f32_e32 v84, v88, v84
	v_mul_f32_e32 v76, v88, v76
	v_mul_f32_e32 v72, v88, v72
	v_mul_f32_e32 v80, v80, v8
	v_mul_f32_e32 v84, v84, v16
	v_mul_f32_e32 v76, v76, v17
	v_mul_f32_e32 v72, v72, v9
	v_mul_f32_e32 v89, v84, v36
	v_mul_f32_e32 v36, v80, v36
	v_mul_f32_e32 v90, v76, v37
	v_mul_f32_e32 v37, v72, v37
	v_fma_f32 v80, v80, v32, -v89
	v_fmac_f32_e32 v36, v84, v32
	v_fma_f32 v32, v72, v33, -v90
	v_mul_f32_e32 v72, v88, v85
	v_fmac_f32_e32 v37, v76, v33
	v_mul_f32_e32 v33, v88, v81
	v_mul_f32_e32 v72, v72, v18
	v_mul_f32_e32 v33, v33, v10
	v_mul_f32_e32 v76, v72, v38
	v_fma_f32 v76, v33, v34, -v76
	v_mul_f32_e32 v33, v33, v38
	v_mul_f32_e32 v38, v88, v77
	v_fmac_f32_e32 v33, v72, v34
	v_mul_f32_e32 v34, v88, v73
	v_mul_f32_e32 v38, v38, v19
	v_mul_f32_e32 v34, v34, v11
	v_mul_f32_e32 v72, v38, v39
	v_fma_f32 v72, v34, v35, -v72
	v_mul_f32_e32 v34, v34, v39
	v_fmac_f32_e32 v34, v38, v35
	v_mul_f32_e32 v38, v88, v86
	v_mul_f32_e32 v35, v88, v82
	v_mul_f32_e32 v38, v38, v20
	v_mul_f32_e32 v35, v35, v12
	v_mul_f32_e32 v39, v38, v28
	v_fma_f32 v39, v35, v24, -v39
	v_mul_f32_e32 v35, v35, v28
	v_fmac_f32_e32 v35, v38, v24
	v_mul_f32_e32 v24, v88, v74
	v_mul_f32_e32 v28, v88, v78
	v_mul_f32_e32 v24, v24, v13
	v_mul_f32_e32 v28, v28, v21
	v_mul_f32_e32 v38, v28, v29
	v_mul_f32_e32 v73, v24, v29
	v_fma_f32 v38, v24, v25, -v38
	v_fmac_f32_e32 v73, v28, v25
	v_mul_f32_e32 v24, v88, v83
	v_mul_f32_e32 v25, v88, v87
	v_mul_f32_e32 v24, v24, v14
	v_mul_f32_e32 v25, v25, v22
	v_mul_f32_e32 v28, v25, v30
	v_mul_f32_e32 v74, v24, v30
	v_fma_f32 v28, v24, v26, -v28
	v_fmac_f32_e32 v74, v25, v26
	v_mul_f32_e32 v24, v88, v75
	v_mul_f32_e32 v25, v88, v79
	v_mul_f32_e32 v24, v24, v15
	v_mul_f32_e32 v25, v25, v23
	v_mul_f32_e32 v26, v25, v31
	v_mul_f32_e32 v31, v24, v31
	v_fma_f32 v29, v24, v27, -v26
	v_fmac_f32_e32 v31, v25, v27
	v_cvt_pk_bf16_f32 v24, v80, v32
	v_cvt_pk_bf16_f32 v25, v76, v72
	v_cvt_pk_bf16_f32 v26, v39, v38
	v_cvt_pk_bf16_f32 v27, v28, v29
	v_cvt_pk_bf16_f32 v28, v36, v37
	v_cvt_pk_bf16_f32 v29, v33, v34
	v_cvt_pk_bf16_f32 v30, v35, v73
	v_cvt_pk_bf16_f32 v31, v74, v31
	s_and_saveexec_b64 s[8:9], s[6:7]
	s_cbranch_execz .LBB0_1028
	v_lshl_add_u64 v[32:33], v[64:65], 0, v[42:43]
	v_add_co_u32_e32 v32, vcc, 0x18bff000, v32
	s_nop 1
	v_addc_co_u32_e32 v33, vcc, 0, v33, vcc
	global_store_dwordx4 v[32:33], v[24:27], off
	global_store_dwordx4 v[32:33], v[28:31], off offset:128
	s_branch .LBB0_1028

; #define PG8_STAGE(bufoff, gbase, voff) do { _Pragma("unroll") for (int _i = 0; _i < 2; ++_i) \
;         __builtin_amdgcn_global_load_lds((const unsigned*)((const char*)(gbase) + (voff)[_i]), (LAS unsigned*)(lds + (bufoff) + ldsw + _i * 8192), 16, 0, 0); } while (0)
; #define PG8_LDA(dst, b, h) do { _Pragma("unroll") for (int m = 0; m < 4; ++m) _Pragma("unroll") for (int k = 0; k < 2; ++k) dst[m][k] = *(const LAS bf16x8*)(lds + PG8_SA(b, h) + aoff + m * 2048 + k * 1024); } while (0)
; #define PG8_WAIT_V(n) asm volatile("s_waitcnt vmcnt(" #n ")" ::: "memory")
; #define PG8_WAIT_L(n) asm volatile("s_waitcnt lgkmcnt(" #n ")" ::: "memory")
; template <class Epi>
; __device__ __forceinline__ void gemm_phase(LAS unsigned char* lds, const Gemm g, const StaticOrder& S, const Epi& E) {
;     ...
;         for (int t = 0; t < nt; t += 2) {
;             const bool last = (t == nt - 2);
;             const char* a1 = cA + (size_t)(t + 1) * kstep;
;             const char* a2 = last ? nA : cA + (size_t)(t + 2) * kstep; const char* b2 = last ? nB : cB + (size_t)(t + 2) * kstep;
;             const char* a3 = a2 + kstep; const char* b3 = b2 + kstep;
;             PG8_LDB(B0, 0, 0); PG8_SCHED; PG8_LDA(At, 0, 0); PG8_STAGE(PG8_SA(1, 1), a1 + hstep, voffA);
;             PG8_WAIT_L(8); PG8_BAR; PG8_WAIT_L(0); PG8_MMA(0, 0, At, B0); PG8_BAR; PG8_SCHED;
;             PG8_LDB(B1, 0, 1); PG8_STAGE(PG8_SB(0, 0), b2, voffB0);
;             PG8_BAR; PG8_WAIT_L(0); PG8_MMA(0, 1, At, B1); PG8_BAR;
;             PG8_LDA(At, 0, 1); PG8_STAGE(PG8_SA(0, 0), a2, voffA);
;             PG8_BAR; PG8_WAIT_L(0); PG8_MMA(1, 0, At, B0); PG8_BAR; PG8_SCHED;
;             PG8_STAGE(PG8_SB(0, 1), b2, voffB1);
;             PG8_WAIT_V(6); PG8_BAR; PG8_MMA(1, 1, At, B1); PG8_BAR;
;             PG8_LDB(B0, 1, 0); PG8_SCHED; PG8_LDA(At, 1, 0); PG8_STAGE(PG8_SA(0, 1), a2 + hstep, voffA);
;             PG8_WAIT_L(8); PG8_BAR; PG8_WAIT_L(0); PG8_MMA(0, 0, At, B0); PG8_BAR; PG8_SCHED;
;             PG8_LDB(B1, 1, 1); PG8_STAGE(PG8_SB(1, 0), b3, voffB0);
;             PG8_BAR; PG8_WAIT_L(0); PG8_MMA(0, 1, At, B1); PG8_BAR;
;             PG8_LDA(At, 1, 1); PG8_STAGE(PG8_SA(1, 0), a3, voffA);
;             PG8_BAR; PG8_WAIT_L(0); PG8_MMA(1, 0, At, B0); PG8_BAR; PG8_SCHED;
;             PG8_STAGE(PG8_SB(1, 1), b3, voffB1);
;             PG8_WAIT_V(6); PG8_BAR; PG8_MMA(1, 1, At, B1); PG8_BAR;
.LBB0_1245:
	ds_read_b128 v[146:149], v154
	ds_read_b128 v[158:161], v154 offset:1024
	ds_read_b128 v[162:165], v154 offset:2048
	ds_read_b128 v[166:169], v154 offset:3072
	s_add_u32 s33, s46, 0xfff80080
	s_addc_u32 s48, s47, -1
	s_cmp_eq_u32 s73, 28
	s_cselect_b32 s49, s35, s48
	s_cselect_b32 s48, s43, s33
	s_cselect_b32 s51, s31, s72
	s_cselect_b32 s50, s70, s71
	v_lshl_add_u64 v[204:205], s[46:47], 0, v[140:141]
	s_add_i32 m0, s45, 0xc000
	ds_read_b128 v[170:173], v155
	ds_read_b128 v[174:177], v155 offset:1024
	ds_read_b128 v[178:181], v155 offset:2048
	ds_read_b128 v[182:185], v155 offset:3072
	ds_read_b128 v[186:189], v155 offset:4096
	ds_read_b128 v[190:193], v155 offset:5120
	ds_read_b128 v[194:197], v155 offset:6144
	ds_read_b128 v[198:201], v155 offset:7168
	global_load_lds_dwordx4 v[204:205], off
	v_lshl_add_u64 v[204:205], s[46:47], 0, v[142:143]
	s_add_i32 m0, s45, 0xe000
	s_nop 0
	global_load_lds_dwordx4 v[204:205], off
	s_waitcnt lgkmcnt(8)
	s_barrier
	s_waitcnt lgkmcnt(0)
	v_mfma_f32_16x16x32_bf16 v[124:127], v[146:149], v[170:173], v[124:127]
	v_mfma_f32_16x16x32_bf16 v[120:123], v[162:165], v[170:173], v[120:123]
	v_mfma_f32_16x16x32_bf16 v[108:111], v[146:149], v[178:181], v[108:111]
	v_mfma_f32_16x16x32_bf16 v[104:107], v[162:165], v[178:181], v[104:107]
	v_mfma_f32_16x16x32_bf16 v[92:95], v[146:149], v[186:189], v[92:95]
	v_mfma_f32_16x16x32_bf16 v[88:91], v[162:165], v[186:189], v[88:91]
	v_mfma_f32_16x16x32_bf16 v[76:79], v[146:149], v[194:197], v[76:79]
	v_mfma_f32_16x16x32_bf16 v[72:75], v[162:165], v[194:197], v[72:75]
	v_mfma_f32_16x16x32_bf16 v[124:127], v[158:161], v[174:177], v[124:127]
	v_mfma_f32_16x16x32_bf16 v[120:123], v[166:169], v[174:177], v[120:123]
	v_mfma_f32_16x16x32_bf16 v[108:111], v[158:161], v[182:185], v[108:111]
	v_mfma_f32_16x16x32_bf16 v[104:107], v[166:169], v[182:185], v[104:107]
	v_mfma_f32_16x16x32_bf16 v[92:95], v[158:161], v[190:193], v[92:95]
	v_mfma_f32_16x16x32_bf16 v[88:91], v[166:169], v[190:193], v[88:91]
	v_mfma_f32_16x16x32_bf16 v[76:79], v[158:161], v[198:201], v[76:79]
	v_mfma_f32_16x16x32_bf16 v[72:75], v[166:169], v[198:201], v[72:75]
	s_barrier
	s_add_i32 s33, s68, s57
	v_lshl_add_u64 v[220:221], s[50:51], 0, v[130:131]
	s_mov_b32 m0, s33
	ds_read_b128 v[204:207], v156
	ds_read_b128 v[208:211], v156 offset:1024
	ds_read_b128 v[212:215], v156 offset:2048
	ds_read_b128 v[216:219], v156 offset:3072
	global_load_lds_dwordx4 v[220:221], off
	v_lshl_add_u64 v[222:223], s[50:51], 0, v[136:137]
	s_add_i32 m0, s33, 0x2000
	s_nop 0
	global_load_lds_dwordx4 v[222:223], off
	s_barrier
	s_waitcnt lgkmcnt(0)
	v_mfma_f32_16x16x32_bf16 v[116:119], v[204:207], v[170:173], v[116:119]
	v_mfma_f32_16x16x32_bf16 v[112:115], v[212:215], v[170:173], v[112:115]
	v_mfma_f32_16x16x32_bf16 v[100:103], v[204:207], v[178:181], v[100:103]
	v_mfma_f32_16x16x32_bf16 v[96:99], v[212:215], v[178:181], v[96:99]
	v_mfma_f32_16x16x32_bf16 v[84:87], v[204:207], v[186:189], v[84:87]
	v_mfma_f32_16x16x32_bf16 v[80:83], v[212:215], v[186:189], v[80:83]
	v_mfma_f32_16x16x32_bf16 v[68:71], v[204:207], v[194:197], v[68:71]
	v_mfma_f32_16x16x32_bf16 v[64:67], v[212:215], v[194:197], v[64:67]
	v_mfma_f32_16x16x32_bf16 v[116:119], v[208:211], v[174:177], v[116:119]
	v_mfma_f32_16x16x32_bf16 v[112:115], v[216:219], v[174:177], v[112:115]
	v_mfma_f32_16x16x32_bf16 v[100:103], v[208:211], v[182:185], v[100:103]
	v_mfma_f32_16x16x32_bf16 v[96:99], v[216:219], v[182:185], v[96:99]
	v_mfma_f32_16x16x32_bf16 v[84:87], v[208:211], v[190:193], v[84:87]
	v_mfma_f32_16x16x32_bf16 v[80:83], v[216:219], v[190:193], v[80:83]
	v_mfma_f32_16x16x32_bf16 v[68:71], v[208:211], v[198:201], v[68:71]
	v_mfma_f32_16x16x32_bf16 v[64:67], v[216:219], v[198:201], v[64:67]
	s_mov_b32 m0, s45
	v_lshl_add_u64 v[224:225], s[48:49], 0, v[128:129]
	s_barrier
	ds_read_b128 v[170:173], v155 offset:16384
	ds_read_b128 v[174:177], v155 offset:17408
	ds_read_b128 v[178:181], v155 offset:18432
	ds_read_b128 v[182:185], v155 offset:19456
	ds_read_b128 v[186:189], v155 offset:20480
	ds_read_b128 v[190:193], v155 offset:21504
	ds_read_b128 v[194:197], v155 offset:22528
	ds_read_b128 v[198:201], v155 offset:23552
	global_load_lds_dwordx4 v[224:225], off
	v_lshl_add_u64 v[226:227], s[48:49], 0, v[134:135]
	s_mov_b32 m0, s58
	s_nop 0
	global_load_lds_dwordx4 v[226:227], off
	s_barrier
	s_waitcnt lgkmcnt(0)
	v_mfma_f32_16x16x32_bf16 v[60:63], v[146:149], v[170:173], v[60:63]
	v_mfma_f32_16x16x32_bf16 v[56:59], v[162:165], v[170:173], v[56:59]
	v_mfma_f32_16x16x32_bf16 v[44:47], v[146:149], v[178:181], v[44:47]
	v_mfma_f32_16x16x32_bf16 v[40:43], v[162:165], v[178:181], v[40:43]
	v_mfma_f32_16x16x32_bf16 v[28:31], v[146:149], v[186:189], v[28:31]
	v_mfma_f32_16x16x32_bf16 v[24:27], v[162:165], v[186:189], v[24:27]
	v_mfma_f32_16x16x32_bf16 v[12:15], v[146:149], v[194:197], v[12:15]
	v_mfma_f32_16x16x32_bf16 v[8:11], v[162:165], v[194:197], v[8:11]
	v_mfma_f32_16x16x32_bf16 v[60:63], v[158:161], v[174:177], v[60:63]
	v_mfma_f32_16x16x32_bf16 v[56:59], v[166:169], v[174:177], v[56:59]
	v_mfma_f32_16x16x32_bf16 v[44:47], v[158:161], v[182:185], v[44:47]
	v_mfma_f32_16x16x32_bf16 v[40:43], v[166:169], v[182:185], v[40:43]
	v_mfma_f32_16x16x32_bf16 v[28:31], v[158:161], v[190:193], v[28:31]
	v_mfma_f32_16x16x32_bf16 v[24:27], v[166:169], v[190:193], v[24:27]
	v_mfma_f32_16x16x32_bf16 v[12:15], v[158:161], v[198:201], v[12:15]
	v_mfma_f32_16x16x32_bf16 v[8:11], v[166:169], v[198:201], v[8:11]
	s_barrier
	s_add_i32 s33, s69, s57
	v_lshl_add_u64 v[228:229], s[50:51], 0, v[132:133]
	s_mov_b32 m0, s33
	v_lshl_add_u64 v[230:231], s[50:51], 0, v[138:139]
	global_load_lds_dwordx4 v[228:229], off
	s_add_i32 m0, s33, 0x2000
	s_nop 0
	global_load_lds_dwordx4 v[230:231], off
	s_waitcnt vmcnt(6)
	s_barrier
; #define PG8_STAGE(bufoff, gbase, voff) do { _Pragma("unroll") for (int _i = 0; _i < 2; ++_i) \
;         __builtin_amdgcn_global_load_lds((const unsigned*)((const char*)(gbase) + (voff)[_i]), (LAS unsigned*)(lds + (bufoff) + ldsw + _i * 8192), 16, 0, 0); } while (0)
; #define PG8_LDA(dst, b, h) do { _Pragma("unroll") for (int m = 0; m < 4; ++m) _Pragma("unroll") for (int k = 0; k < 2; ++k) dst[m][k] = *(const LAS bf16x8*)(lds + PG8_SA(b, h) + aoff + m * 2048 + k * 1024); } while (0)
; #define PG8_WAIT_V(n) asm volatile("s_waitcnt vmcnt(" #n ")" ::: "memory")
; #define PG8_WAIT_L(n) asm volatile("s_waitcnt lgkmcnt(" #n ")" ::: "memory")
; template <class Epi>
; __device__ __forceinline__ void gemm_phase(LAS unsigned char* lds, const Gemm g, const StaticOrder& S, const Epi& E) {
;     ...
;         for (int t = 0; t < nt; t += 2) {
;             const bool last = (t == nt - 2);
;             const char* a1 = cA + (size_t)(t + 1) * kstep;
;             const char* a2 = last ? nA : cA + (size_t)(t + 2) * kstep; const char* b2 = last ? nB : cB + (size_t)(t + 2) * kstep;
;             const char* a3 = a2 + kstep; const char* b3 = b2 + kstep;
;             PG8_LDB(B0, 0, 0); PG8_SCHED; PG8_LDA(At, 0, 0); PG8_STAGE(PG8_SA(1, 1), a1 + hstep, voffA);
;             PG8_WAIT_L(8); PG8_BAR; PG8_WAIT_L(0); PG8_MMA(0, 0, At, B0); PG8_BAR; PG8_SCHED;
;             PG8_LDB(B1, 0, 1); PG8_STAGE(PG8_SB(0, 0), b2, voffB0);
;             PG8_BAR; PG8_WAIT_L(0); PG8_MMA(0, 1, At, B1); PG8_BAR;
;             PG8_LDA(At, 0, 1); PG8_STAGE(PG8_SA(0, 0), a2, voffA);
;             PG8_BAR; PG8_WAIT_L(0); PG8_MMA(1, 0, At, B0); PG8_BAR; PG8_SCHED;
;             PG8_STAGE(PG8_SB(0, 1), b2, voffB1);
;             PG8_WAIT_V(6); PG8_BAR; PG8_MMA(1, 1, At, B1); PG8_BAR;
;             PG8_LDB(B0, 1, 0); PG8_SCHED; PG8_LDA(At, 1, 0); PG8_STAGE(PG8_SA(0, 1), a2 + hstep, voffA);
;             PG8_WAIT_L(8); PG8_BAR; PG8_WAIT_L(0); PG8_MMA(0, 0, At, B0); PG8_BAR; PG8_SCHED;
;             PG8_LDB(B1, 1, 1); PG8_STAGE(PG8_SB(1, 0), b3, voffB0);
;             PG8_BAR; PG8_WAIT_L(0); PG8_MMA(0, 1, At, B1); PG8_BAR;
;             PG8_LDA(At, 1, 1); PG8_STAGE(PG8_SA(1, 0), a3, voffA);
;             PG8_BAR; PG8_WAIT_L(0); PG8_MMA(1, 0, At, B0); PG8_BAR; PG8_SCHED;
;             PG8_STAGE(PG8_SB(1, 1), b3, voffB1);
;             PG8_WAIT_V(6); PG8_BAR; PG8_MMA(1, 1, At, B1); PG8_BAR;
	v_mfma_f32_16x16x32_bf16 v[52:55], v[204:207], v[170:173], v[52:55]
	v_mfma_f32_16x16x32_bf16 v[48:51], v[212:215], v[170:173], v[48:51]
	v_mfma_f32_16x16x32_bf16 v[36:39], v[204:207], v[178:181], v[36:39]
	v_mfma_f32_16x16x32_bf16 v[32:35], v[212:215], v[178:181], v[32:35]
	v_mfma_f32_16x16x32_bf16 v[20:23], v[204:207], v[186:189], v[20:23]
	v_mfma_f32_16x16x32_bf16 v[16:19], v[212:215], v[186:189], v[16:19]
	v_mfma_f32_16x16x32_bf16 v[4:7], v[204:207], v[194:197], v[4:7]
	v_mfma_f32_16x16x32_bf16 v[0:3], v[212:215], v[194:197], v[0:3]
	v_mfma_f32_16x16x32_bf16 v[52:55], v[208:211], v[174:177], v[52:55]
	v_mfma_f32_16x16x32_bf16 v[48:51], v[216:219], v[174:177], v[48:51]
	v_mfma_f32_16x16x32_bf16 v[36:39], v[208:211], v[182:185], v[36:39]
	v_mfma_f32_16x16x32_bf16 v[32:35], v[216:219], v[182:185], v[32:35]
	v_mfma_f32_16x16x32_bf16 v[20:23], v[208:211], v[190:193], v[20:23]
	v_mfma_f32_16x16x32_bf16 v[16:19], v[216:219], v[190:193], v[16:19]
	v_mfma_f32_16x16x32_bf16 v[4:7], v[208:211], v[198:201], v[4:7]
	v_mfma_f32_16x16x32_bf16 v[0:3], v[216:219], v[198:201], v[0:3]
	s_add_i32 s33, 0, 0x18000
	v_add_u32_e32 v157, s33, v151
	s_barrier
	ds_read_b128 v[146:149], v157
	ds_read_b128 v[158:161], v157 offset:1024
	ds_read_b128 v[162:165], v157 offset:2048
	ds_read_b128 v[166:169], v157 offset:3072
	s_add_u32 s48, s48, 0x80000
	s_addc_u32 s49, s49, 0
	s_mov_b32 m0, s59
	v_lshl_add_u64 v[204:205], s[48:49], 0, v[128:129]
	ds_read_b128 v[170:173], v155 offset:32768
	ds_read_b128 v[174:177], v155 offset:33792
	ds_read_b128 v[178:181], v155 offset:34816
	ds_read_b128 v[182:185], v155 offset:35840
	ds_read_b128 v[186:189], v155 offset:36864
	ds_read_b128 v[190:193], v155 offset:37888
	ds_read_b128 v[194:197], v155 offset:38912
	ds_read_b128 v[198:201], v155 offset:39936
	global_load_lds_dwordx4 v[204:205], off
	v_lshl_add_u64 v[204:205], s[48:49], 0, v[134:135]
	s_mov_b32 m0, s60
	s_nop 0
	global_load_lds_dwordx4 v[204:205], off
	s_waitcnt lgkmcnt(8)
	s_barrier
	s_waitcnt lgkmcnt(0)
	v_mfma_f32_16x16x32_bf16 v[124:127], v[146:149], v[170:173], v[124:127]
	v_mfma_f32_16x16x32_bf16 v[120:123], v[162:165], v[170:173], v[120:123]
	v_mfma_f32_16x16x32_bf16 v[108:111], v[146:149], v[178:181], v[108:111]
	v_mfma_f32_16x16x32_bf16 v[104:107], v[162:165], v[178:181], v[104:107]
	v_mfma_f32_16x16x32_bf16 v[92:95], v[146:149], v[186:189], v[92:95]
	v_mfma_f32_16x16x32_bf16 v[88:91], v[162:165], v[186:189], v[88:91]
	v_mfma_f32_16x16x32_bf16 v[76:79], v[146:149], v[194:197], v[76:79]
	v_mfma_f32_16x16x32_bf16 v[72:75], v[162:165], v[194:197], v[72:75]
	v_mfma_f32_16x16x32_bf16 v[124:127], v[158:161], v[174:177], v[124:127]
	v_mfma_f32_16x16x32_bf16 v[120:123], v[166:169], v[174:177], v[120:123]
	v_mfma_f32_16x16x32_bf16 v[108:111], v[158:161], v[182:185], v[108:111]
	v_mfma_f32_16x16x32_bf16 v[104:107], v[166:169], v[182:185], v[104:107]
	v_mfma_f32_16x16x32_bf16 v[92:95], v[158:161], v[190:193], v[92:95]
	v_mfma_f32_16x16x32_bf16 v[88:91], v[166:169], v[190:193], v[88:91]
	v_mfma_f32_16x16x32_bf16 v[76:79], v[158:161], v[198:201], v[76:79]
	v_mfma_f32_16x16x32_bf16 v[72:75], v[166:169], v[198:201], v[72:75]
	s_barrier
	s_add_i32 s48, 0, 0x1c000
	s_add_i32 s33, s33, s57
	v_add_u32_e32 v157, s48, v151
	v_lshl_add_u64 v[220:221], v[220:221], 0, s[26:27]
	s_mov_b32 m0, s33
	ds_read_b128 v[204:207], v157
	ds_read_b128 v[208:211], v157 offset:1024
	ds_read_b128 v[212:215], v157 offset:2048
	ds_read_b128 v[216:219], v157 offset:3072
	global_load_lds_dwordx4 v[220:221], off
	v_lshl_add_u64 v[220:221], v[222:223], 0, s[26:27]
	s_add_i32 m0, s33, 0x2000
	s_nop 0
	global_load_lds_dwordx4 v[220:221], off
	s_barrier
	s_waitcnt lgkmcnt(0)
	v_mfma_f32_16x16x32_bf16 v[116:119], v[204:207], v[170:173], v[116:119]
	v_mfma_f32_16x16x32_bf16 v[112:115], v[212:215], v[170:173], v[112:115]
	v_mfma_f32_16x16x32_bf16 v[100:103], v[204:207], v[178:181], v[100:103]
	v_mfma_f32_16x16x32_bf16 v[96:99], v[212:215], v[178:181], v[96:99]
	v_mfma_f32_16x16x32_bf16 v[84:87], v[204:207], v[186:189], v[84:87]
	v_mfma_f32_16x16x32_bf16 v[80:83], v[212:215], v[186:189], v[80:83]
	v_mfma_f32_16x16x32_bf16 v[68:71], v[204:207], v[194:197], v[68:71]
	v_mfma_f32_16x16x32_bf16 v[64:67], v[212:215], v[194:197], v[64:67]
	v_mfma_f32_16x16x32_bf16 v[116:119], v[208:211], v[174:177], v[116:119]
	v_mfma_f32_16x16x32_bf16 v[112:115], v[216:219], v[174:177], v[112:115]
	v_mfma_f32_16x16x32_bf16 v[100:103], v[208:211], v[182:185], v[100:103]
	v_mfma_f32_16x16x32_bf16 v[96:99], v[216:219], v[182:185], v[96:99]
	v_mfma_f32_16x16x32_bf16 v[84:87], v[208:211], v[190:193], v[84:87]
	v_mfma_f32_16x16x32_bf16 v[80:83], v[216:219], v[190:193], v[80:83]
	v_mfma_f32_16x16x32_bf16 v[68:71], v[208:211], v[198:201], v[68:71]
	v_mfma_f32_16x16x32_bf16 v[64:67], v[216:219], v[198:201], v[64:67]
	s_mov_b32 m0, s62
	v_lshl_add_u64 v[220:221], v[224:225], 0, s[26:27]
	s_barrier
	ds_read_b128 v[170:173], v155 offset:49152
	ds_read_b128 v[174:177], v155 offset:50176
	ds_read_b128 v[178:181], v155 offset:51200
	ds_read_b128 v[182:185], v155 offset:52224
	ds_read_b128 v[186:189], v155 offset:53248
	ds_read_b128 v[190:193], v155 offset:54272
	ds_read_b128 v[194:197], v155 offset:55296
	ds_read_b128 v[198:201], v155 offset:56320
	global_load_lds_dwordx4 v[220:221], off
	v_lshl_add_u64 v[220:221], v[226:227], 0, s[26:27]
	s_mov_b32 m0, s63
	s_nop 0
	global_load_lds_dwordx4 v[220:221], off
	s_barrier
; #define PG8_STAGE(bufoff, gbase, voff) do { _Pragma("unroll") for (int _i = 0; _i < 2; ++_i) \
;         __builtin_amdgcn_global_load_lds((const unsigned*)((const char*)(gbase) + (voff)[_i]), (LAS unsigned*)(lds + (bufoff) + ldsw + _i * 8192), 16, 0, 0); } while (0)
; #define PG8_LDA(dst, b, h) do { _Pragma("unroll") for (int m = 0; m < 4; ++m) _Pragma("unroll") for (int k = 0; k < 2; ++k) dst[m][k] = *(const LAS bf16x8*)(lds + PG8_SA(b, h) + aoff + m * 2048 + k * 1024); } while (0)
; #define PG8_LDB(dst, b, h) do { _Pragma("unroll") for (int n = 0; n < 2; ++n) _Pragma("unroll") for (int k = 0; k < 2; ++k) dst[n][k] = *(const LAS bf16x8*)(lds + PG8_SB(b, h) + boff + n * 2048 + k * 1024); } while (0)
; #define PG8_WAIT_V(n) asm volatile("s_waitcnt vmcnt(" #n ")" ::: "memory")
; #define PG8_WAIT_L(n) asm volatile("s_waitcnt lgkmcnt(" #n ")" ::: "memory")
; #define PG8_BAR __builtin_amdgcn_s_barrier()
; #define PG8_SCHED __builtin_amdgcn_sched_barrier(0)
;     __device__ __forceinline__ void operator()(const f32x4 (&acc)[2][2][4][2], const Unit& u, int wr, int wc, int fr, int fq) const {
;     ...
;             for (int m = 0; m < 4; ++m) { const int row = row0 + ai * HALF + m * 16; const size_t off = (size_t)row * D + col0; float sq = 0.f; u32x4 w[2];
;                 const float sc = rsin ? __builtin_amdgcn_rcpf(rsin[row] * (1.f / D) + EPS) : 1.0f;
;                 u32x4 rr[2]; if (R) load_pair_lines(R, D, row, fr, col0, rr[0], rr[1]);
; template <class Epi>
; __device__ __forceinline__ void gemm_phase(LAS unsigned char* lds, const Gemm g, const StaticOrder& S, const Epi& E) {
;     ...
;             PG8_WAIT_V(6); PG8_BAR; PG8_MMA(1, 1, At, B1); PG8_BAR;
;             PG8_LDB(B0, 1, 0); PG8_SCHED; PG8_LDA(At, 1, 0); PG8_STAGE(PG8_SA(0, 1), a2 + hstep, voffA);
;             PG8_WAIT_L(8); PG8_BAR; PG8_WAIT_L(0); PG8_MMA(0, 0, At, B0); PG8_BAR; PG8_SCHED;
;             PG8_LDB(B1, 1, 1); PG8_STAGE(PG8_SB(1, 0), b3, voffB0);
;             PG8_BAR; PG8_WAIT_L(0); PG8_MMA(0, 1, At, B1); PG8_BAR;
;             PG8_LDA(At, 1, 1); PG8_STAGE(PG8_SA(1, 0), a3, voffA);
;             PG8_BAR; PG8_WAIT_L(0); PG8_MMA(1, 0, At, B0); PG8_BAR; PG8_SCHED;
;             PG8_STAGE(PG8_SB(1, 1), b3, voffB1);
;             PG8_WAIT_V(6); PG8_BAR; PG8_MMA(1, 1, At, B1); PG8_BAR;
;         }
;         E(acc, cur, wr, wc, fr, fq);
	s_waitcnt lgkmcnt(0)
	v_mfma_f32_16x16x32_bf16 v[60:63], v[146:149], v[170:173], v[60:63]
	v_mfma_f32_16x16x32_bf16 v[56:59], v[162:165], v[170:173], v[56:59]
	v_mfma_f32_16x16x32_bf16 v[44:47], v[146:149], v[178:181], v[44:47]
	v_mfma_f32_16x16x32_bf16 v[40:43], v[162:165], v[178:181], v[40:43]
	v_mfma_f32_16x16x32_bf16 v[28:31], v[146:149], v[186:189], v[28:31]
	v_mfma_f32_16x16x32_bf16 v[24:27], v[162:165], v[186:189], v[24:27]
	v_mfma_f32_16x16x32_bf16 v[12:15], v[146:149], v[194:197], v[12:15]
	v_mfma_f32_16x16x32_bf16 v[8:11], v[162:165], v[194:197], v[8:11]
	v_mfma_f32_16x16x32_bf16 v[60:63], v[158:161], v[174:177], v[60:63]
	v_mfma_f32_16x16x32_bf16 v[56:59], v[166:169], v[174:177], v[56:59]
	v_mfma_f32_16x16x32_bf16 v[44:47], v[158:161], v[182:185], v[44:47]
	v_mfma_f32_16x16x32_bf16 v[40:43], v[166:169], v[182:185], v[40:43]
	v_mfma_f32_16x16x32_bf16 v[28:31], v[158:161], v[190:193], v[28:31]
	v_mfma_f32_16x16x32_bf16 v[24:27], v[166:169], v[190:193], v[24:27]
	v_mfma_f32_16x16x32_bf16 v[12:15], v[158:161], v[198:201], v[12:15]
	v_mfma_f32_16x16x32_bf16 v[8:11], v[166:169], v[198:201], v[8:11]
	s_barrier
	s_add_i32 s33, s48, s57
	v_lshl_add_u64 v[146:147], v[228:229], 0, s[26:27]
	s_mov_b32 m0, s33
	s_nop 0
	global_load_lds_dwordx4 v[146:147], off
	v_lshl_add_u64 v[146:147], v[230:231], 0, s[26:27]
	s_add_i32 m0, s33, 0x2000
	s_nop 0
	global_load_lds_dwordx4 v[146:147], off
	s_waitcnt vmcnt(6)
	s_barrier
	v_mfma_f32_16x16x32_bf16 v[52:55], v[204:207], v[170:173], v[52:55]
	v_mfma_f32_16x16x32_bf16 v[48:51], v[212:215], v[170:173], v[48:51]
	v_mfma_f32_16x16x32_bf16 v[36:39], v[204:207], v[178:181], v[36:39]
	v_mfma_f32_16x16x32_bf16 v[32:35], v[212:215], v[178:181], v[32:35]
	v_mfma_f32_16x16x32_bf16 v[20:23], v[204:207], v[186:189], v[20:23]
	v_mfma_f32_16x16x32_bf16 v[16:19], v[212:215], v[186:189], v[16:19]
	v_mfma_f32_16x16x32_bf16 v[4:7], v[204:207], v[194:197], v[4:7]
	v_mfma_f32_16x16x32_bf16 v[0:3], v[212:215], v[194:197], v[0:3]
	v_mfma_f32_16x16x32_bf16 v[52:55], v[208:211], v[174:177], v[52:55]
	v_mfma_f32_16x16x32_bf16 v[48:51], v[216:219], v[174:177], v[48:51]
	v_mfma_f32_16x16x32_bf16 v[36:39], v[208:211], v[182:185], v[36:39]
	v_mfma_f32_16x16x32_bf16 v[32:35], v[216:219], v[182:185], v[32:35]
	v_mfma_f32_16x16x32_bf16 v[20:23], v[208:211], v[190:193], v[20:23]
	v_mfma_f32_16x16x32_bf16 v[16:19], v[216:219], v[190:193], v[16:19]
	v_mfma_f32_16x16x32_bf16 v[4:7], v[208:211], v[198:201], v[4:7]
	v_mfma_f32_16x16x32_bf16 v[0:3], v[216:219], v[198:201], v[0:3]
	s_add_i32 s73, s73, 2
	s_add_u32 s46, s46, 0x100
	s_addc_u32 s47, s47, 0
	s_add_u32 s71, s71, 0x100
	s_addc_u32 s72, s72, 0
	s_cmp_gt_u32 s73, 29
	s_barrier
	s_cbranch_scc0 .LBB0_1245
	s_lshl_b32 s31, s44, 8
	s_add_i32 s31, s31, s64
	v_or_b32_e32 v148, s31, v152
	v_ashrrev_i32_e32 v149, 31, v148
	v_lshlrev_b64 v[166:167], 12, v[148:149]
	v_or_b32_e32 v148, 8, v148
	v_lshl_or_b32 v146, s42, 8, v153
	v_ashrrev_i32_e32 v149, 31, v148
	v_ashrrev_i32_e32 v147, 31, v146
	v_lshlrev_b64 v[168:169], 12, v[148:149]
	v_lshl_add_u64 v[158:159], s[10:11], 0, v[166:167]
	v_lshlrev_b64 v[146:147], 1, v[146:147]
	v_lshl_add_u64 v[148:149], s[10:11], 0, v[168:169]
	v_lshl_add_u64 v[158:159], v[158:159], 0, v[146:147]
	v_lshl_add_u64 v[148:149], v[148:149], 0, v[146:147]
	global_load_dwordx4 v[158:161], v[158:159], off
	global_load_dwordx4 v[162:165], v[148:149], off
	v_or_b32_e32 v194, s31, v150
	v_or_b32_e32 v184, 16, v194
	v_sub_u32_e32 v185, v184, v150
	v_add_u32_e32 v186, v185, v152
	v_ashrrev_i32_e32 v187, 31, v186
	v_lshlrev_b64 v[190:191], 12, v[186:187]
	v_lshl_add_u64 v[192:193], v[190:191], 0, s[28:29]
	v_lshl_add_u64 v[186:187], s[10:11], 0, v[190:191]
	v_lshl_add_u64 v[188:189], s[10:11], 0, v[192:193]
	v_lshl_add_u64 v[186:187], v[186:187], 0, v[146:147]
	v_lshl_add_u64 v[188:189], v[188:189], 0, v[146:147]
	global_load_dwordx4 v[196:199], v[186:187], off
	global_load_dwordx4 v[204:207], v[188:189], off
	v_or_b32_e32 v194, s31, v150
	v_or_b32_e32 v184, 32, v194
	v_sub_u32_e32 v185, v184, v150
	v_add_u32_e32 v186, v185, v152
	v_ashrrev_i32_e32 v187, 31, v186
	v_lshlrev_b64 v[190:191], 12, v[186:187]
	v_lshl_add_u64 v[192:193], v[190:191], 0, s[28:29]
	v_lshl_add_u64 v[186:187], s[10:11], 0, v[190:191]
	v_lshl_add_u64 v[188:189], s[10:11], 0, v[192:193]
	v_lshl_add_u64 v[186:187], v[186:187], 0, v[146:147]
	v_lshl_add_u64 v[188:189], v[188:189], 0, v[146:147]
	global_load_dwordx4 v[208:211], v[186:187], off
	global_load_dwordx4 v[212:215], v[188:189], off
	v_or_b32_e32 v194, s31, v150
	v_or_b32_e32 v184, 48, v194
	v_sub_u32_e32 v185, v184, v150
	v_add_u32_e32 v186, v185, v152
	v_ashrrev_i32_e32 v187, 31, v186
	v_lshlrev_b64 v[190:191], 12, v[186:187]
	v_lshl_add_u64 v[192:193], v[190:191], 0, s[28:29]
	v_lshl_add_u64 v[186:187], s[10:11], 0, v[190:191]
	v_lshl_add_u64 v[188:189], s[10:11], 0, v[192:193]
	v_lshl_add_u64 v[186:187], v[186:187], 0, v[146:147]
	v_lshl_add_u64 v[188:189], v[188:189], 0, v[146:147]
	global_load_dwordx4 v[216:219], v[186:187], off
	global_load_dwordx4 v[220:223], v[188:189], off
	v_or_b32_e32 v194, s31, v150
	v_add_u32_e32 v184, 0x80, v194
	v_sub_u32_e32 v185, v184, v150
	v_add_u32_e32 v186, v185, v152
	v_ashrrev_i32_e32 v187, 31, v186
	v_lshlrev_b64 v[190:191], 12, v[186:187]
	v_lshl_add_u64 v[192:193], v[190:191], 0, s[28:29]
	v_lshl_add_u64 v[186:187], s[10:11], 0, v[190:191]
	v_lshl_add_u64 v[188:189], s[10:11], 0, v[192:193]
	v_lshl_add_u64 v[186:187], v[186:187], 0, v[146:147]
	v_lshl_add_u64 v[188:189], v[188:189], 0, v[146:147]
	global_load_dwordx4 v[224:227], v[186:187], off
	global_load_dwordx4 v[228:231], v[188:189], off
	v_or_b32_e32 v194, s31, v150
	v_add_u32_e32 v184, 0x90, v194
	v_sub_u32_e32 v185, v184, v150
	v_add_u32_e32 v186, v185, v152
	v_ashrrev_i32_e32 v187, 31, v186
	v_lshlrev_b64 v[190:191], 12, v[186:187]
	v_lshl_add_u64 v[192:193], v[190:191], 0, s[28:29]
	v_lshl_add_u64 v[186:187], s[10:11], 0, v[190:191]
	v_lshl_add_u64 v[188:189], s[10:11], 0, v[192:193]
	v_lshl_add_u64 v[186:187], v[186:187], 0, v[146:147]
	v_lshl_add_u64 v[188:189], v[188:189], 0, v[146:147]
	global_load_dwordx4 v[232:235], v[186:187], off
	global_load_dwordx4 v[236:239], v[188:189], off
	v_or_b32_e32 v194, s31, v150
	v_add_u32_e32 v184, 0xa0, v194
	v_sub_u32_e32 v185, v184, v150
	v_add_u32_e32 v186, v185, v152
	v_ashrrev_i32_e32 v187, 31, v186
	v_lshlrev_b64 v[190:191], 12, v[186:187]
	v_lshl_add_u64 v[192:193], v[190:191], 0, s[28:29]
	v_lshl_add_u64 v[186:187], s[10:11], 0, v[190:191]
	v_lshl_add_u64 v[188:189], s[10:11], 0, v[192:193]
	v_lshl_add_u64 v[186:187], v[186:187], 0, v[146:147]
	v_lshl_add_u64 v[188:189], v[188:189], 0, v[146:147]
	global_load_dwordx4 v[240:243], v[186:187], off
	global_load_dwordx4 v[244:247], v[188:189], off
	v_or_b32_e32 v148, s31, v150
	s_waitcnt vmcnt(12)
; __device__ __forceinline__ unsigned cvt_pk_bf16(float lo, float hi) { unsigned r; asm volatile("v_cvt_pk_bf16_f32 %0, %1, %2" : "=v"(r) : "v"(lo), "v"(hi)); return r; }
; __device__ __forceinline__ float bflo(unsigned w) { return __uint_as_float(w << 16); }
; __device__ __forceinline__ float bfhi(unsigned w) { return __uint_as_float(w & 0xffff0000u); }
;     __device__ __forceinline__ void operator()(const f32x4 (&acc)[2][2][4][2], const Unit& u, int wr, int wc, int fr, int fq) const {
;     ...
;             for (int m = 0; m < 4; ++m) { const int row = row0 + ai * HALF + m * 16; const size_t off = (size_t)row * D + col0; float sq = 0.f; u32x4 w[2];
;                 const float sc = rsin ? __builtin_amdgcn_rcpf(rsin[row] * (1.f / D) + EPS) : 1.0f;
;                 u32x4 rr[2]; if (R) load_pair_lines(R, D, row, fr, col0, rr[0], rr[1]);
; #pragma unroll
;                 for (int bj = 0; bj < 2; ++bj) { f32x4 r0, r1;
;                     if (R) { const u32x4 rw = rr[bj]; r0 = (f32x4){bflo(rw.x), bfhi(rw.x), bflo(rw.y), bfhi(rw.y)}; r1 = (f32x4){bflo(rw.z), bfhi(rw.z), bflo(rw.w), bfhi(rw.w)}; }
;                     else { const float* rp = (row < 8192 ? src_p + off : src_s + (off - (size_t)8192 * D)) + 8 * bj; r0 = *(const f32x4*)rp; r1 = *(const f32x4*)(rp + 4); }
;                     const f32x4 o0 = r0 + acc[ai][bj][m][0] * sc, o1 = r1 + acc[ai][bj][m][1] * sc;
;                     sq += (o0[0] * o0[0] + o0[1] * o0[1]) + (o0[2] * o0[2] + o0[3] * o0[3]) + (o1[0] * o1[0] + o1[1] * o1[1]) + (o1[2] * o1[2] + o1[3] * o1[3]);
;                     w[bj].x = cvt_pk_bf16(o0[0], o0[1]); w[bj].y = cvt_pk_bf16(o0[2], o0[3]); w[bj].z = cvt_pk_bf16(o1[0], o1[1]); w[bj].w = cvt_pk_bf16(o1[2], o1[3]); }
;                 store_pair_lines(O, D, row, fr, col0, w[0], w[1]);
;                 if (ssout) { sq += __shfl_xor(sq, 16); sq += __shfl_xor(sq, 32); if (fq == 0) unsafeAtomicAdd(ssout + row, sq); } }
	v_mov_b32_dpp v149, v158 row_ror:8 row_mask:0xf bank_mask:0xf
	v_mov_b32_dpp v157, v159 row_ror:8 row_mask:0xf bank_mask:0xf
	v_mov_b32_dpp v171, v161 row_ror:8 row_mask:0xf bank_mask:0xf
	v_mov_b32_dpp v172, v162 row_ror:8 row_mask:0xf bank_mask:0xf
	v_mov_b32_dpp v173, v163 row_ror:8 row_mask:0xf bank_mask:0xf
	v_mov_b32_dpp v170, v160 row_ror:8 row_mask:0xf bank_mask:0xf
	v_mov_b32_dpp v174, v164 row_ror:8 row_mask:0xf bank_mask:0xf
	v_mov_b32_dpp v175, v165 row_ror:8 row_mask:0xf bank_mask:0xf
	v_cndmask_b32_e64 v165, v165, v171, s[6:7]
	v_cndmask_b32_e64 v157, v163, v157, s[6:7]
	v_cndmask_b32_e64 v149, v162, v149, s[6:7]
	v_cndmask_b32_e64 v173, v173, v159, s[6:7]
	v_cndmask_b32_e64 v171, v172, v158, s[6:7]
	v_cndmask_b32_e64 v164, v164, v170, s[6:7]
	v_cndmask_b32_e64 v177, v175, v161, s[6:7]
	v_cndmask_b32_e64 v175, v174, v160, s[6:7]
	v_lshlrev_b32_e32 v158, 16, v149
	v_and_b32_e32 v159, 0xffff0000, v149
	v_lshlrev_b32_e32 v160, 16, v157
	v_and_b32_e32 v161, 0xffff0000, v157
	v_lshlrev_b32_e32 v170, 16, v171
	v_and_b32_e32 v171, 0xffff0000, v171
	v_lshlrev_b32_e32 v172, 16, v173
	v_and_b32_e32 v173, 0xffff0000, v173
	v_lshlrev_b32_e32 v174, 16, v175
	v_and_b32_e32 v175, 0xffff0000, v175
	v_pk_add_f32 v[160:161], v[118:119], v[160:161]
	v_pk_add_f32 v[158:159], v[116:117], v[158:159]
	v_pk_add_f32 v[116:117], v[126:127], v[172:173]
	v_pk_add_f32 v[118:119], v[124:125], v[170:171]
	v_lshlrev_b32_e32 v176, 16, v177
	v_and_b32_e32 v177, 0xffff0000, v177
	v_pk_add_f32 v[120:121], v[120:121], v[174:175]
	v_mul_f32_e32 v124, v119, v119
	v_mul_f32_e32 v125, v117, v117
	v_lshlrev_b32_e32 v162, 16, v164
	v_and_b32_e32 v163, 0xffff0000, v164
	v_lshlrev_b32_e32 v164, 16, v165
	v_and_b32_e32 v165, 0xffff0000, v165
	v_pk_add_f32 v[122:123], v[122:123], v[176:177]
	v_mul_f32_e32 v126, v121, v121
	v_fmac_f32_e32 v124, v118, v118
	v_fmac_f32_e32 v125, v116, v116
	v_pk_add_f32 v[114:115], v[114:115], v[164:165]
	v_mul_f32_e32 v127, v123, v123
	v_cvt_pk_bf16_f32 v119, v118, v119
	v_cvt_pk_bf16_f32 v117, v116, v117
	v_cvt_pk_bf16_f32 v121, v120, v121
	v_fmac_f32_e32 v126, v120, v120
	v_add_f32_e32 v116, v124, v125
	v_pk_add_f32 v[112:113], v[112:113], v[162:163]
	v_cvt_pk_bf16_f32 v123, v122, v123
	v_cvt_pk_bf16_f32 v149, v158, v159
	v_cvt_pk_bf16_f32 v157, v160, v161
	v_fmac_f32_e32 v127, v122, v122
	v_cvt_pk_bf16_f32 v162, v112, v113
	v_cvt_pk_bf16_f32 v163, v114, v115
	v_add_f32_e32 v116, v126, v116
	v_mov_b32_dpp v182, v149 row_ror:8 row_mask:0xf bank_mask:0xf
	v_mov_b32_dpp v120, v163 row_ror:8 row_mask:0xf bank_mask:0xf
	v_mul_f32_e32 v115, v115, v115
	v_mov_b32_dpp v178, v119 row_ror:8 row_mask:0xf bank_mask:0xf
	v_mov_b32_dpp v181, v123 row_ror:8 row_mask:0xf bank_mask:0xf
	v_add_f32_e32 v122, v127, v116
	v_cndmask_b32_e64 v116, v182, v119, s[6:7]
	v_cndmask_b32_e64 v119, v120, v123, s[6:7]
	v_fmac_f32_e32 v115, v114, v114
	v_mul_f32_e32 v114, v159, v159
	v_mul_f32_e32 v123, v161, v161
	v_fmac_f32_e32 v114, v158, v158
	v_fmac_f32_e32 v123, v160, v160
	v_mul_f32_e32 v113, v113, v113
	v_add_f32_e32 v114, v114, v123
	v_fmac_f32_e32 v113, v112, v112
	v_add_f32_e32 v112, v113, v114
	v_add_f32_e32 v112, v115, v112
	v_and_b32_e32 v113, 64, v203
	v_add_f32_e32 v115, v112, v122
	v_xor_b32_e32 v112, 16, v203
	v_add_u32_e32 v126, 64, v113
	v_cmp_lt_i32_e32 vcc, v112, v126
	v_mov_b32_e32 v118, 0
	v_mov_b32_dpp v183, v157 row_ror:8 row_mask:0xf bank_mask:0xf
	v_cndmask_b32_e32 v112, v203, v112, vcc
	v_lshlrev_b32_e32 v114, 2, v112
	v_mov_b32_e32 v127, v115
	s_nop 1
	v_permlane16_swap_b32_e32 v127, v115
	v_lshl_add_u64 v[112:113], s[16:17], 0, v[166:167]
	v_lshl_add_u64 v[124:125], v[112:113], 0, v[146:147]
	v_xor_b32_e32 v113, 32, v203
	v_cmp_lt_i32_e32 vcc, v113, v126
	s_waitcnt lgkmcnt(0)
	v_add_f32_e32 v112, v115, v127
	v_mov_b32_dpp v118, v162 row_ror:8 row_mask:0xf bank_mask:0xf
	v_cndmask_b32_e32 v113, v203, v113, vcc
	v_lshlrev_b32_e32 v115, 2, v113
	v_mov_b32_e32 v113, v112
	s_nop 1
	v_permlane32_swap_b32_e32 v113, v112
	v_mov_b32_dpp v179, v117 row_ror:8 row_mask:0xf bank_mask:0xf
	v_cndmask_b32_e64 v117, v183, v117, s[6:7]
	v_cndmask_b32_e64 v118, v118, v121, s[6:7]
	v_mov_b32_dpp v180, v121 row_ror:8 row_mask:0xf bank_mask:0xf
	global_store_dwordx4 v[124:125], v[116:119], off
	v_cndmask_b32_e64 v120, v149, v178, s[6:7]
	v_cndmask_b32_e64 v121, v157, v179, s[6:7]
	v_lshl_add_u64 v[116:117], s[16:17], 0, v[168:169]
	v_cndmask_b32_e64 v122, v162, v180, s[6:7]
	v_cndmask_b32_e64 v123, v163, v181, s[6:7]
	v_lshl_add_u64 v[116:117], v[116:117], 0, v[146:147]
	global_store_dwordx4 v[116:117], v[120:123], off
	s_and_saveexec_b64 s[42:43], s[8:9]
	s_cbranch_execz .LBB0_1248
	v_ashrrev_i32_e32 v149, 31, v148
	s_waitcnt lgkmcnt(0)
	v_add_f32_e32 v116, v112, v113
	v_lshl_add_u64 v[112:113], v[148:149], 2, s[18:19]
	global_atomic_add_f32 v[112:113], v116, off
; __device__ __forceinline__ unsigned cvt_pk_bf16(float lo, float hi) { unsigned r; asm volatile("v_cvt_pk_bf16_f32 %0, %1, %2" : "=v"(r) : "v"(lo), "v"(hi)); return r; }
; __device__ __forceinline__ float bflo(unsigned w) { return __uint_as_float(w << 16); }
; __device__ __forceinline__ float bfhi(unsigned w) { return __uint_as_float(w & 0xffff0000u); }
;     __device__ __forceinline__ void operator()(const f32x4 (&acc)[2][2][4][2], const Unit& u, int wr, int wc, int fr, int fq) const {
;     ...
;             for (int m = 0; m < 4; ++m) { const int row = row0 + ai * HALF + m * 16; const size_t off = (size_t)row * D + col0; float sq = 0.f; u32x4 w[2];
;                 const float sc = rsin ? __builtin_amdgcn_rcpf(rsin[row] * (1.f / D) + EPS) : 1.0f;
;                 u32x4 rr[2]; if (R) load_pair_lines(R, D, row, fr, col0, rr[0], rr[1]);
; #pragma unroll
;                 for (int bj = 0; bj < 2; ++bj) { f32x4 r0, r1;
;                     if (R) { const u32x4 rw = rr[bj]; r0 = (f32x4){bflo(rw.x), bfhi(rw.x), bflo(rw.y), bfhi(rw.y)}; r1 = (f32x4){bflo(rw.z), bfhi(rw.z), bflo(rw.w), bfhi(rw.w)}; }
;                     else { const float* rp = (row < 8192 ? src_p + off : src_s + (off - (size_t)8192 * D)) + 8 * bj; r0 = *(const f32x4*)rp; r1 = *(const f32x4*)(rp + 4); }
;                     const f32x4 o0 = r0 + acc[ai][bj][m][0] * sc, o1 = r1 + acc[ai][bj][m][1] * sc;
;                     sq += (o0[0] * o0[0] + o0[1] * o0[1]) + (o0[2] * o0[2] + o0[3] * o0[3]) + (o1[0] * o1[0] + o1[1] * o1[1]) + (o1[2] * o1[2] + o1[3] * o1[3]);
;                     w[bj].x = cvt_pk_bf16(o0[0], o0[1]); w[bj].y = cvt_pk_bf16(o0[2], o0[3]); w[bj].z = cvt_pk_bf16(o1[0], o1[1]); w[bj].w = cvt_pk_bf16(o1[2], o1[3]); }
;                 store_pair_lines(O, D, row, fr, col0, w[0], w[1]);
;                 if (ssout) { sq += __shfl_xor(sq, 16); sq += __shfl_xor(sq, 32); if (fq == 0) unsafeAtomicAdd(ssout + row, sq); } }
.LBB0_1248:
	s_or_b64 exec, exec, s[42:43]
	v_or_b32_e32 v112, 16, v148
	s_waitcnt lgkmcnt(0)
	v_sub_u32_e32 v113, v112, v150
	v_add_u32_e32 v116, v113, v152
	v_ashrrev_i32_e32 v117, 31, v116
	v_lshlrev_b64 v[124:125], 12, v[116:117]
	v_lshl_add_u64 v[126:127], v[124:125], 0, s[28:29]
	v_lshl_add_u64 v[116:117], s[10:11], 0, v[124:125]
	v_lshl_add_u64 v[120:121], s[10:11], 0, v[126:127]
	v_lshl_add_u64 v[116:117], v[116:117], 0, v[146:147]
	v_lshl_add_u64 v[120:121], v[120:121], 0, v[146:147]
	s_waitcnt vmcnt(12)
	s_nop 0
	v_mov_b64_e32 v[116:117], v[196:197]
	v_mov_b64_e32 v[118:119], v[198:199]
	v_mov_b64_e32 v[120:121], v[204:205]
	v_mov_b64_e32 v[122:123], v[206:207]
	s_nop 1
	v_add_u32_e32 v184, 0xb0, v148
	v_sub_u32_e32 v185, v184, v150
	v_add_u32_e32 v186, v185, v152
	v_ashrrev_i32_e32 v187, 31, v186
	v_lshlrev_b64 v[190:191], 12, v[186:187]
	v_lshl_add_u64 v[192:193], v[190:191], 0, s[28:29]
	v_lshl_add_u64 v[186:187], s[10:11], 0, v[190:191]
	v_lshl_add_u64 v[188:189], s[10:11], 0, v[192:193]
	v_lshl_add_u64 v[186:187], v[186:187], 0, v[146:147]
	v_lshl_add_u64 v[188:189], v[188:189], 0, v[146:147]
	global_load_dwordx4 v[196:199], v[186:187], off
	global_load_dwordx4 v[204:207], v[188:189], off
	v_mov_b32_dpp v113, v116 row_ror:8 row_mask:0xf bank_mask:0xf
	v_mov_b32_dpp v149, v117 row_ror:8 row_mask:0xf bank_mask:0xf
	v_mov_b32_dpp v157, v118 row_ror:8 row_mask:0xf bank_mask:0xf
	v_mov_b32_dpp v158, v119 row_ror:8 row_mask:0xf bank_mask:0xf
	v_mov_b32_dpp v159, v120 row_ror:8 row_mask:0xf bank_mask:0xf
	v_mov_b32_dpp v160, v121 row_ror:8 row_mask:0xf bank_mask:0xf
	v_mov_b32_dpp v161, v122 row_ror:8 row_mask:0xf bank_mask:0xf
	v_mov_b32_dpp v162, v123 row_ror:8 row_mask:0xf bank_mask:0xf
	v_cndmask_b32_e64 v123, v123, v158, s[6:7]
	v_cndmask_b32_e64 v122, v122, v157, s[6:7]
	v_cndmask_b32_e64 v121, v121, v149, s[6:7]
	v_cndmask_b32_e64 v113, v120, v113, s[6:7]
	v_cndmask_b32_e64 v157, v161, v118, s[6:7]
	v_cndmask_b32_e64 v161, v160, v117, s[6:7]
	v_cndmask_b32_e64 v159, v159, v116, s[6:7]
	v_cndmask_b32_e64 v149, v162, v119, s[6:7]
	v_lshlrev_b32_e32 v116, 16, v113
	v_and_b32_e32 v117, 0xffff0000, v113
	v_lshlrev_b32_e32 v118, 16, v121
	v_and_b32_e32 v119, 0xffff0000, v121
	v_lshlrev_b32_e32 v120, 16, v122
	v_and_b32_e32 v121, 0xffff0000, v122
	v_lshlrev_b32_e32 v122, 16, v123
	v_and_b32_e32 v123, 0xffff0000, v123
	v_lshlrev_b32_e32 v158, 16, v159
	v_and_b32_e32 v159, 0xffff0000, v159
	v_lshlrev_b32_e32 v160, 16, v161
	v_and_b32_e32 v161, 0xffff0000, v161
	v_lshlrev_b32_e32 v162, 16, v157
	v_and_b32_e32 v163, 0xffff0000, v157
	v_lshlrev_b32_e32 v164, 16, v149
	v_and_b32_e32 v165, 0xffff0000, v149
	v_pk_add_f32 v[116:117], v[100:101], v[116:117]
	v_pk_add_f32 v[122:123], v[98:99], v[122:123]
	v_pk_add_f32 v[98:99], v[110:111], v[160:161]
	v_pk_add_f32 v[100:101], v[108:109], v[158:159]
	v_pk_add_f32 v[118:119], v[102:103], v[118:119]
	v_pk_add_f32 v[102:103], v[106:107], v[164:165]
	v_pk_add_f32 v[104:105], v[104:105], v[162:163]
	v_mul_f32_e32 v106, v101, v101
	v_mul_f32_e32 v107, v99, v99
	v_mul_f32_e32 v108, v105, v105
	v_fmac_f32_e32 v106, v100, v100
	v_fmac_f32_e32 v107, v98, v98
	v_pk_add_f32 v[96:97], v[96:97], v[120:121]
	v_mul_f32_e32 v109, v103, v103
	v_cvt_pk_bf16_f32 v101, v100, v101
	v_fmac_f32_e32 v108, v104, v104
	v_add_f32_e32 v100, v106, v107
	v_mul_f32_e32 v106, v117, v117
	v_mul_f32_e32 v107, v119, v119
	v_cvt_pk_bf16_f32 v99, v98, v99
	v_cvt_pk_bf16_f32 v105, v104, v105
	v_cvt_pk_bf16_f32 v103, v102, v103
	v_cvt_pk_bf16_f32 v110, v116, v117
	v_cvt_pk_bf16_f32 v111, v118, v119
	v_cvt_pk_bf16_f32 v113, v96, v97
	v_fmac_f32_e32 v109, v102, v102
	v_add_f32_e32 v100, v108, v100
	v_mov_b32_dpp v172, v113 row_ror:8 row_mask:0xf bank_mask:0xf
	v_fmac_f32_e32 v106, v116, v116
	v_fmac_f32_e32 v107, v118, v118
	v_mul_f32_e32 v97, v97, v97
	v_mov_b32_dpp v168, v105 row_ror:8 row_mask:0xf bank_mask:0xf
	v_add_f32_e32 v104, v109, v100
	v_cndmask_b32_e64 v100, v172, v105, s[6:7]
	v_mul_f32_e32 v105, v123, v123
	v_add_f32_e32 v106, v106, v107
	v_fmac_f32_e32 v97, v96, v96
	v_fmac_f32_e32 v105, v122, v122
	v_add_f32_e32 v96, v97, v106
	v_add_f32_e32 v96, v105, v96
	v_add_f32_e32 v108, v96, v104
	v_mov_b32_e32 v109, v108
	s_nop 1
	v_permlane16_swap_b32_e32 v109, v108
	v_lshl_add_u64 v[96:97], s[16:17], 0, v[124:125]
	v_lshl_add_u64 v[106:107], v[96:97], 0, v[146:147]
	v_cvt_pk_bf16_f32 v120, v122, v123
	v_mov_b32_dpp v170, v110 row_ror:8 row_mask:0xf bank_mask:0xf
	s_waitcnt lgkmcnt(0)
	v_add_f32_e32 v96, v108, v109
	v_mov_b32_e32 v97, v96
	s_nop 1
	v_permlane32_swap_b32_e32 v97, v96
	v_mov_b32_dpp v171, v111 row_ror:8 row_mask:0xf bank_mask:0xf
	v_mov_b32_dpp v173, v120 row_ror:8 row_mask:0xf bank_mask:0xf
	v_mov_b32_dpp v166, v101 row_ror:8 row_mask:0xf bank_mask:0xf
	v_mov_b32_dpp v167, v99 row_ror:8 row_mask:0xf bank_mask:0xf
	v_cndmask_b32_e64 v98, v170, v101, s[6:7]
	v_cndmask_b32_e64 v99, v171, v99, s[6:7]
	v_cndmask_b32_e64 v101, v173, v103, s[6:7]
	v_mov_b32_dpp v169, v103 row_ror:8 row_mask:0xf bank_mask:0xf
	global_store_dwordx4 v[106:107], v[98:101], off
	v_cndmask_b32_e64 v102, v110, v166, s[6:7]
	v_cndmask_b32_e64 v103, v111, v167, s[6:7]
	v_lshl_add_u64 v[98:99], s[16:17], 0, v[126:127]
	v_cndmask_b32_e64 v104, v113, v168, s[6:7]
	v_cndmask_b32_e64 v105, v120, v169, s[6:7]
	v_lshl_add_u64 v[98:99], v[98:99], 0, v[146:147]
	global_store_dwordx4 v[98:99], v[102:105], off
	s_and_saveexec_b64 s[42:43], s[8:9]
	s_cbranch_execz .LBB0_1250
	v_ashrrev_i32_e32 v113, 31, v112
	s_waitcnt lgkmcnt(0)
	v_add_f32_e32 v98, v96, v97
	v_lshl_add_u64 v[96:97], v[112:113], 2, s[18:19]
	global_atomic_add_f32 v[96:97], v98, off
; __device__ __forceinline__ unsigned cvt_pk_bf16(float lo, float hi) { unsigned r; asm volatile("v_cvt_pk_bf16_f32 %0, %1, %2" : "=v"(r) : "v"(lo), "v"(hi)); return r; }
; __device__ __forceinline__ float bflo(unsigned w) { return __uint_as_float(w << 16); }
; __device__ __forceinline__ float bfhi(unsigned w) { return __uint_as_float(w & 0xffff0000u); }
;     __device__ __forceinline__ void operator()(const f32x4 (&acc)[2][2][4][2], const Unit& u, int wr, int wc, int fr, int fq) const {
;     ...
;             for (int m = 0; m < 4; ++m) { const int row = row0 + ai * HALF + m * 16; const size_t off = (size_t)row * D + col0; float sq = 0.f; u32x4 w[2];
;                 const float sc = rsin ? __builtin_amdgcn_rcpf(rsin[row] * (1.f / D) + EPS) : 1.0f;
;                 u32x4 rr[2]; if (R) load_pair_lines(R, D, row, fr, col0, rr[0], rr[1]);
; #pragma unroll
;                 for (int bj = 0; bj < 2; ++bj) { f32x4 r0, r1;
;                     if (R) { const u32x4 rw = rr[bj]; r0 = (f32x4){bflo(rw.x), bfhi(rw.x), bflo(rw.y), bfhi(rw.y)}; r1 = (f32x4){bflo(rw.z), bfhi(rw.z), bflo(rw.w), bfhi(rw.w)}; }
;                     else { const float* rp = (row < 8192 ? src_p + off : src_s + (off - (size_t)8192 * D)) + 8 * bj; r0 = *(const f32x4*)rp; r1 = *(const f32x4*)(rp + 4); }
;                     const f32x4 o0 = r0 + acc[ai][bj][m][0] * sc, o1 = r1 + acc[ai][bj][m][1] * sc;
;                     sq += (o0[0] * o0[0] + o0[1] * o0[1]) + (o0[2] * o0[2] + o0[3] * o0[3]) + (o1[0] * o1[0] + o1[1] * o1[1]) + (o1[2] * o1[2] + o1[3] * o1[3]);
;                     w[bj].x = cvt_pk_bf16(o0[0], o0[1]); w[bj].y = cvt_pk_bf16(o0[2], o0[3]); w[bj].z = cvt_pk_bf16(o1[0], o1[1]); w[bj].w = cvt_pk_bf16(o1[2], o1[3]); }
;                 store_pair_lines(O, D, row, fr, col0, w[0], w[1]);
;                 if (ssout) { sq += __shfl_xor(sq, 16); sq += __shfl_xor(sq, 32); if (fq == 0) unsafeAtomicAdd(ssout + row, sq); } }
.LBB0_1250:
	s_or_b64 exec, exec, s[42:43]
	v_or_b32_e32 v96, 32, v148
	s_waitcnt lgkmcnt(0)
	v_sub_u32_e32 v97, v96, v150
	v_add_u32_e32 v98, v97, v152
	v_ashrrev_i32_e32 v99, 31, v98
	v_lshlrev_b64 v[106:107], 12, v[98:99]
	v_lshl_add_u64 v[108:109], v[106:107], 0, s[28:29]
	v_lshl_add_u64 v[98:99], s[10:11], 0, v[106:107]
	v_lshl_add_u64 v[102:103], s[10:11], 0, v[108:109]
	v_lshl_add_u64 v[98:99], v[98:99], 0, v[146:147]
	v_lshl_add_u64 v[102:103], v[102:103], 0, v[146:147]
	s_waitcnt vmcnt(14)
	s_nop 0
	v_mov_b64_e32 v[98:99], v[208:209]
	v_mov_b64_e32 v[100:101], v[210:211]
	v_mov_b64_e32 v[102:103], v[212:213]
	v_mov_b64_e32 v[104:105], v[214:215]
	s_nop 1
	v_mov_b32_dpp v97, v98 row_ror:8 row_mask:0xf bank_mask:0xf
	v_mov_b32_dpp v110, v99 row_ror:8 row_mask:0xf bank_mask:0xf
	v_mov_b32_dpp v111, v100 row_ror:8 row_mask:0xf bank_mask:0xf
	v_mov_b32_dpp v112, v101 row_ror:8 row_mask:0xf bank_mask:0xf
	v_mov_b32_dpp v113, v102 row_ror:8 row_mask:0xf bank_mask:0xf
	v_mov_b32_dpp v116, v103 row_ror:8 row_mask:0xf bank_mask:0xf
	v_mov_b32_dpp v117, v104 row_ror:8 row_mask:0xf bank_mask:0xf
	v_mov_b32_dpp v118, v105 row_ror:8 row_mask:0xf bank_mask:0xf
	v_cndmask_b32_e64 v105, v105, v112, s[6:7]
	v_cndmask_b32_e64 v104, v104, v111, s[6:7]
	v_cndmask_b32_e64 v103, v103, v110, s[6:7]
	v_cndmask_b32_e64 v97, v102, v97, s[6:7]
	v_cndmask_b32_e64 v116, v116, v99, s[6:7]
	v_cndmask_b32_e64 v111, v113, v98, s[6:7]
	v_cndmask_b32_e64 v119, v118, v101, s[6:7]
	v_cndmask_b32_e64 v117, v117, v100, s[6:7]
	v_lshlrev_b32_e32 v98, 16, v97
	v_and_b32_e32 v99, 0xffff0000, v97
	v_lshlrev_b32_e32 v100, 16, v103
	v_and_b32_e32 v101, 0xffff0000, v103
	v_lshlrev_b32_e32 v102, 16, v104
	v_and_b32_e32 v103, 0xffff0000, v104
	v_lshlrev_b32_e32 v104, 16, v105
	v_and_b32_e32 v105, 0xffff0000, v105
	v_lshlrev_b32_e32 v110, 16, v111
	v_and_b32_e32 v111, 0xffff0000, v111
	v_lshlrev_b32_e32 v112, 16, v116
	v_and_b32_e32 v113, 0xffff0000, v116
	v_lshlrev_b32_e32 v116, 16, v117
	v_and_b32_e32 v117, 0xffff0000, v117
	v_lshlrev_b32_e32 v118, 16, v119
	v_and_b32_e32 v119, 0xffff0000, v119
	v_pk_add_f32 v[98:99], v[84:85], v[98:99]
	v_pk_add_f32 v[104:105], v[82:83], v[104:105]
	v_pk_add_f32 v[82:83], v[94:95], v[112:113]
	v_pk_add_f32 v[84:85], v[92:93], v[110:111]
	v_pk_add_f32 v[100:101], v[86:87], v[100:101]
	v_pk_add_f32 v[86:87], v[90:91], v[118:119]
	v_pk_add_f32 v[88:89], v[88:89], v[116:117]
	v_mul_f32_e32 v90, v85, v85
	v_mul_f32_e32 v91, v83, v83
	v_mul_f32_e32 v92, v89, v89
	v_fmac_f32_e32 v90, v84, v84
	v_fmac_f32_e32 v91, v82, v82
	v_pk_add_f32 v[80:81], v[80:81], v[102:103]
	v_mul_f32_e32 v93, v87, v87
	v_cvt_pk_bf16_f32 v85, v84, v85
	v_fmac_f32_e32 v92, v88, v88
	v_add_f32_e32 v84, v90, v91
	v_mul_f32_e32 v90, v99, v99
	v_mul_f32_e32 v91, v101, v101
	v_cvt_pk_bf16_f32 v83, v82, v83
	v_cvt_pk_bf16_f32 v89, v88, v89
	v_cvt_pk_bf16_f32 v87, v86, v87
	v_cvt_pk_bf16_f32 v94, v98, v99
	v_cvt_pk_bf16_f32 v95, v100, v101
	v_cvt_pk_bf16_f32 v97, v80, v81
	v_fmac_f32_e32 v93, v86, v86
	v_add_f32_e32 v84, v92, v84
	v_mov_b32_dpp v126, v97 row_ror:8 row_mask:0xf bank_mask:0xf
	v_fmac_f32_e32 v90, v98, v98
	v_fmac_f32_e32 v91, v100, v100
	v_mul_f32_e32 v81, v81, v81
	v_mov_b32_dpp v122, v89 row_ror:8 row_mask:0xf bank_mask:0xf
	v_add_f32_e32 v88, v93, v84
	v_cndmask_b32_e64 v84, v126, v89, s[6:7]
	v_mul_f32_e32 v89, v105, v105
	v_add_f32_e32 v90, v90, v91
	v_fmac_f32_e32 v81, v80, v80
	v_fmac_f32_e32 v89, v104, v104
	v_add_f32_e32 v80, v81, v90
	v_add_f32_e32 v80, v89, v80
	v_add_f32_e32 v92, v80, v88
	v_mov_b32_e32 v93, v92
	s_nop 1
	v_permlane16_swap_b32_e32 v93, v92
	v_lshl_add_u64 v[80:81], s[16:17], 0, v[106:107]
	v_lshl_add_u64 v[90:91], v[80:81], 0, v[146:147]
	v_cvt_pk_bf16_f32 v102, v104, v105
	v_mov_b32_dpp v124, v94 row_ror:8 row_mask:0xf bank_mask:0xf
	s_waitcnt lgkmcnt(0)
	v_add_f32_e32 v80, v92, v93
	v_mov_b32_e32 v81, v80
	s_nop 1
	v_permlane32_swap_b32_e32 v81, v80
	v_mov_b32_dpp v125, v95 row_ror:8 row_mask:0xf bank_mask:0xf
	v_mov_b32_dpp v127, v102 row_ror:8 row_mask:0xf bank_mask:0xf
	v_mov_b32_dpp v120, v85 row_ror:8 row_mask:0xf bank_mask:0xf
	v_mov_b32_dpp v121, v83 row_ror:8 row_mask:0xf bank_mask:0xf
	v_cndmask_b32_e64 v82, v124, v85, s[6:7]
	v_cndmask_b32_e64 v83, v125, v83, s[6:7]
	v_cndmask_b32_e64 v85, v127, v87, s[6:7]
	v_mov_b32_dpp v123, v87 row_ror:8 row_mask:0xf bank_mask:0xf
	global_store_dwordx4 v[90:91], v[82:85], off
	v_cndmask_b32_e64 v86, v94, v120, s[6:7]
	v_cndmask_b32_e64 v87, v95, v121, s[6:7]
	v_lshl_add_u64 v[82:83], s[16:17], 0, v[108:109]
	v_cndmask_b32_e64 v88, v97, v122, s[6:7]
	v_cndmask_b32_e64 v89, v102, v123, s[6:7]
	v_lshl_add_u64 v[82:83], v[82:83], 0, v[146:147]
	global_store_dwordx4 v[82:83], v[86:89], off
	s_and_saveexec_b64 s[42:43], s[8:9]
	s_cbranch_execz .LBB0_1252
	v_ashrrev_i32_e32 v97, 31, v96
	s_waitcnt lgkmcnt(0)
	v_add_f32_e32 v82, v80, v81
	v_lshl_add_u64 v[80:81], v[96:97], 2, s[18:19]
	global_atomic_add_f32 v[80:81], v82, off
; __device__ __forceinline__ unsigned cvt_pk_bf16(float lo, float hi) { unsigned r; asm volatile("v_cvt_pk_bf16_f32 %0, %1, %2" : "=v"(r) : "v"(lo), "v"(hi)); return r; }
; __device__ __forceinline__ float bflo(unsigned w) { return __uint_as_float(w << 16); }
; __device__ __forceinline__ float bfhi(unsigned w) { return __uint_as_float(w & 0xffff0000u); }
;     __device__ __forceinline__ void operator()(const f32x4 (&acc)[2][2][4][2], const Unit& u, int wr, int wc, int fr, int fq) const {
;     ...
;             for (int m = 0; m < 4; ++m) { const int row = row0 + ai * HALF + m * 16; const size_t off = (size_t)row * D + col0; float sq = 0.f; u32x4 w[2];
;                 const float sc = rsin ? __builtin_amdgcn_rcpf(rsin[row] * (1.f / D) + EPS) : 1.0f;
;                 u32x4 rr[2]; if (R) load_pair_lines(R, D, row, fr, col0, rr[0], rr[1]);
; #pragma unroll
;                 for (int bj = 0; bj < 2; ++bj) { f32x4 r0, r1;
;                     if (R) { const u32x4 rw = rr[bj]; r0 = (f32x4){bflo(rw.x), bfhi(rw.x), bflo(rw.y), bfhi(rw.y)}; r1 = (f32x4){bflo(rw.z), bfhi(rw.z), bflo(rw.w), bfhi(rw.w)}; }
;                     else { const float* rp = (row < 8192 ? src_p + off : src_s + (off - (size_t)8192 * D)) + 8 * bj; r0 = *(const f32x4*)rp; r1 = *(const f32x4*)(rp + 4); }
;                     const f32x4 o0 = r0 + acc[ai][bj][m][0] * sc, o1 = r1 + acc[ai][bj][m][1] * sc;
;                     sq += (o0[0] * o0[0] + o0[1] * o0[1]) + (o0[2] * o0[2] + o0[3] * o0[3]) + (o1[0] * o1[0] + o1[1] * o1[1]) + (o1[2] * o1[2] + o1[3] * o1[3]);
;                     w[bj].x = cvt_pk_bf16(o0[0], o0[1]); w[bj].y = cvt_pk_bf16(o0[2], o0[3]); w[bj].z = cvt_pk_bf16(o1[0], o1[1]); w[bj].w = cvt_pk_bf16(o1[2], o1[3]); }
;                 store_pair_lines(O, D, row, fr, col0, w[0], w[1]);
;                 if (ssout) { sq += __shfl_xor(sq, 16); sq += __shfl_xor(sq, 32); if (fq == 0) unsafeAtomicAdd(ssout + row, sq); } }
.LBB0_1252:
	s_or_b64 exec, exec, s[42:43]
	v_or_b32_e32 v80, 48, v148
	s_waitcnt lgkmcnt(0)
	v_sub_u32_e32 v81, v80, v150
	v_add_u32_e32 v82, v81, v152
	v_ashrrev_i32_e32 v83, 31, v82
	v_lshlrev_b64 v[90:91], 12, v[82:83]
	v_lshl_add_u64 v[92:93], v[90:91], 0, s[28:29]
	v_lshl_add_u64 v[82:83], s[10:11], 0, v[90:91]
	v_lshl_add_u64 v[86:87], s[10:11], 0, v[92:93]
	v_lshl_add_u64 v[82:83], v[82:83], 0, v[146:147]
	v_lshl_add_u64 v[86:87], v[86:87], 0, v[146:147]
	s_waitcnt vmcnt(14)
	s_nop 0
	v_mov_b64_e32 v[82:83], v[216:217]
	v_mov_b64_e32 v[84:85], v[218:219]
	v_mov_b64_e32 v[86:87], v[220:221]
	v_mov_b64_e32 v[88:89], v[222:223]
	s_nop 1
	v_mov_b32_dpp v81, v82 row_ror:8 row_mask:0xf bank_mask:0xf
	v_mov_b32_dpp v94, v83 row_ror:8 row_mask:0xf bank_mask:0xf
	v_mov_b32_dpp v95, v84 row_ror:8 row_mask:0xf bank_mask:0xf
	v_mov_b32_dpp v96, v85 row_ror:8 row_mask:0xf bank_mask:0xf
	v_mov_b32_dpp v97, v86 row_ror:8 row_mask:0xf bank_mask:0xf
	v_mov_b32_dpp v98, v87 row_ror:8 row_mask:0xf bank_mask:0xf
	v_mov_b32_dpp v99, v88 row_ror:8 row_mask:0xf bank_mask:0xf
	v_mov_b32_dpp v100, v89 row_ror:8 row_mask:0xf bank_mask:0xf
	v_cndmask_b32_e64 v89, v89, v96, s[6:7]
	v_cndmask_b32_e64 v88, v88, v95, s[6:7]
	v_cndmask_b32_e64 v87, v87, v94, s[6:7]
	v_cndmask_b32_e64 v81, v86, v81, s[6:7]
	v_cndmask_b32_e64 v98, v98, v83, s[6:7]
	v_cndmask_b32_e64 v95, v97, v82, s[6:7]
	v_cndmask_b32_e64 v101, v100, v85, s[6:7]
	v_cndmask_b32_e64 v99, v99, v84, s[6:7]
	v_lshlrev_b32_e32 v82, 16, v81
	v_and_b32_e32 v83, 0xffff0000, v81
	v_lshlrev_b32_e32 v84, 16, v87
	v_and_b32_e32 v85, 0xffff0000, v87
	v_lshlrev_b32_e32 v86, 16, v88
	v_and_b32_e32 v87, 0xffff0000, v88
	v_lshlrev_b32_e32 v88, 16, v89
	v_and_b32_e32 v89, 0xffff0000, v89
	v_lshlrev_b32_e32 v94, 16, v95
	v_and_b32_e32 v95, 0xffff0000, v95
	v_lshlrev_b32_e32 v96, 16, v98
	v_and_b32_e32 v97, 0xffff0000, v98
	v_lshlrev_b32_e32 v98, 16, v99
	v_and_b32_e32 v99, 0xffff0000, v99
	v_lshlrev_b32_e32 v100, 16, v101
	v_and_b32_e32 v101, 0xffff0000, v101
	v_pk_add_f32 v[82:83], v[68:69], v[82:83]
	v_pk_add_f32 v[88:89], v[66:67], v[88:89]
	v_pk_add_f32 v[66:67], v[78:79], v[96:97]
	v_pk_add_f32 v[68:69], v[76:77], v[94:95]
	v_pk_add_f32 v[84:85], v[70:71], v[84:85]
	v_pk_add_f32 v[70:71], v[74:75], v[100:101]
	v_pk_add_f32 v[72:73], v[72:73], v[98:99]
	v_mul_f32_e32 v74, v69, v69
	v_mul_f32_e32 v75, v67, v67
	v_mul_f32_e32 v76, v73, v73
	v_fmac_f32_e32 v74, v68, v68
	v_fmac_f32_e32 v75, v66, v66
	v_pk_add_f32 v[64:65], v[64:65], v[86:87]
	v_mul_f32_e32 v77, v71, v71
	v_cvt_pk_bf16_f32 v69, v68, v69
	v_fmac_f32_e32 v76, v72, v72
	v_add_f32_e32 v68, v74, v75
	v_mul_f32_e32 v74, v83, v83
	v_mul_f32_e32 v75, v85, v85
	v_cvt_pk_bf16_f32 v67, v66, v67
	v_cvt_pk_bf16_f32 v73, v72, v73
	v_cvt_pk_bf16_f32 v71, v70, v71
	v_cvt_pk_bf16_f32 v78, v82, v83
	v_cvt_pk_bf16_f32 v79, v84, v85
	v_cvt_pk_bf16_f32 v81, v64, v65
	v_fmac_f32_e32 v77, v70, v70
	v_add_f32_e32 v68, v76, v68
	v_mov_b32_dpp v108, v81 row_ror:8 row_mask:0xf bank_mask:0xf
	v_fmac_f32_e32 v74, v82, v82
	v_fmac_f32_e32 v75, v84, v84
	v_mul_f32_e32 v65, v65, v65
	v_mov_b32_dpp v104, v73 row_ror:8 row_mask:0xf bank_mask:0xf
	v_add_f32_e32 v72, v77, v68
	v_cndmask_b32_e64 v68, v108, v73, s[6:7]
	v_mul_f32_e32 v73, v89, v89
	v_add_f32_e32 v74, v74, v75
	v_fmac_f32_e32 v65, v64, v64
	v_fmac_f32_e32 v73, v88, v88
	v_add_f32_e32 v64, v65, v74
	v_add_f32_e32 v64, v73, v64
	v_add_f32_e32 v76, v64, v72
	v_mov_b32_e32 v77, v76
	s_nop 1
	v_permlane16_swap_b32_e32 v77, v76
	v_lshl_add_u64 v[64:65], s[16:17], 0, v[90:91]
	v_lshl_add_u64 v[74:75], v[64:65], 0, v[146:147]
	v_cvt_pk_bf16_f32 v86, v88, v89
	v_mov_b32_dpp v106, v78 row_ror:8 row_mask:0xf bank_mask:0xf
	s_waitcnt lgkmcnt(0)
	v_add_f32_e32 v64, v76, v77
	v_mov_b32_e32 v65, v64
	s_nop 1
	v_permlane32_swap_b32_e32 v65, v64
	v_mov_b32_dpp v107, v79 row_ror:8 row_mask:0xf bank_mask:0xf
	v_mov_b32_dpp v109, v86 row_ror:8 row_mask:0xf bank_mask:0xf
	v_mov_b32_dpp v102, v69 row_ror:8 row_mask:0xf bank_mask:0xf
	v_mov_b32_dpp v103, v67 row_ror:8 row_mask:0xf bank_mask:0xf
	v_cndmask_b32_e64 v66, v106, v69, s[6:7]
	v_cndmask_b32_e64 v67, v107, v67, s[6:7]
	v_cndmask_b32_e64 v69, v109, v71, s[6:7]
	v_mov_b32_dpp v105, v71 row_ror:8 row_mask:0xf bank_mask:0xf
	global_store_dwordx4 v[74:75], v[66:69], off
	v_cndmask_b32_e64 v70, v78, v102, s[6:7]
	v_cndmask_b32_e64 v71, v79, v103, s[6:7]
	v_lshl_add_u64 v[66:67], s[16:17], 0, v[92:93]
	v_cndmask_b32_e64 v72, v81, v104, s[6:7]
	v_cndmask_b32_e64 v73, v86, v105, s[6:7]
	v_lshl_add_u64 v[66:67], v[66:67], 0, v[146:147]
	global_store_dwordx4 v[66:67], v[70:73], off
	s_and_saveexec_b64 s[42:43], s[8:9]
	s_cbranch_execz .LBB0_1254
	v_ashrrev_i32_e32 v81, 31, v80
	s_waitcnt lgkmcnt(0)
	v_add_f32_e32 v66, v64, v65
	v_lshl_add_u64 v[64:65], v[80:81], 2, s[18:19]
	global_atomic_add_f32 v[64:65], v66, off
; __device__ __forceinline__ unsigned cvt_pk_bf16(float lo, float hi) { unsigned r; asm volatile("v_cvt_pk_bf16_f32 %0, %1, %2" : "=v"(r) : "v"(lo), "v"(hi)); return r; }
; __device__ __forceinline__ float bflo(unsigned w) { return __uint_as_float(w << 16); }
; __device__ __forceinline__ float bfhi(unsigned w) { return __uint_as_float(w & 0xffff0000u); }
;     __device__ __forceinline__ void operator()(const f32x4 (&acc)[2][2][4][2], const Unit& u, int wr, int wc, int fr, int fq) const {
;     ...
;             for (int m = 0; m < 4; ++m) { const int row = row0 + ai * HALF + m * 16; const size_t off = (size_t)row * D + col0; float sq = 0.f; u32x4 w[2];
;                 const float sc = rsin ? __builtin_amdgcn_rcpf(rsin[row] * (1.f / D) + EPS) : 1.0f;
;                 u32x4 rr[2]; if (R) load_pair_lines(R, D, row, fr, col0, rr[0], rr[1]);
; #pragma unroll
;                 for (int bj = 0; bj < 2; ++bj) { f32x4 r0, r1;
;                     if (R) { const u32x4 rw = rr[bj]; r0 = (f32x4){bflo(rw.x), bfhi(rw.x), bflo(rw.y), bfhi(rw.y)}; r1 = (f32x4){bflo(rw.z), bfhi(rw.z), bflo(rw.w), bfhi(rw.w)}; }
;                     else { const float* rp = (row < 8192 ? src_p + off : src_s + (off - (size_t)8192 * D)) + 8 * bj; r0 = *(const f32x4*)rp; r1 = *(const f32x4*)(rp + 4); }
;                     const f32x4 o0 = r0 + acc[ai][bj][m][0] * sc, o1 = r1 + acc[ai][bj][m][1] * sc;
;                     sq += (o0[0] * o0[0] + o0[1] * o0[1]) + (o0[2] * o0[2] + o0[3] * o0[3]) + (o1[0] * o1[0] + o1[1] * o1[1]) + (o1[2] * o1[2] + o1[3] * o1[3]);
;                     w[bj].x = cvt_pk_bf16(o0[0], o0[1]); w[bj].y = cvt_pk_bf16(o0[2], o0[3]); w[bj].z = cvt_pk_bf16(o1[0], o1[1]); w[bj].w = cvt_pk_bf16(o1[2], o1[3]); }
;                 store_pair_lines(O, D, row, fr, col0, w[0], w[1]);
;                 if (ssout) { sq += __shfl_xor(sq, 16); sq += __shfl_xor(sq, 32); if (fq == 0) unsafeAtomicAdd(ssout + row, sq); } }
.LBB0_1254:
	s_or_b64 exec, exec, s[42:43]
	v_add_u32_e32 v64, 0x80, v148
	s_waitcnt lgkmcnt(0)
	v_sub_u32_e32 v65, v64, v150
	v_add_u32_e32 v66, v65, v152
	v_ashrrev_i32_e32 v67, 31, v66
	v_lshlrev_b64 v[74:75], 12, v[66:67]
	v_lshl_add_u64 v[76:77], v[74:75], 0, s[28:29]
	v_lshl_add_u64 v[66:67], s[10:11], 0, v[74:75]
	v_lshl_add_u64 v[70:71], s[10:11], 0, v[76:77]
	v_lshl_add_u64 v[66:67], v[66:67], 0, v[146:147]
	v_lshl_add_u64 v[70:71], v[70:71], 0, v[146:147]
	s_waitcnt vmcnt(14)
	s_nop 0
	v_mov_b64_e32 v[66:67], v[224:225]
	v_mov_b64_e32 v[68:69], v[226:227]
	v_mov_b64_e32 v[70:71], v[228:229]
	v_mov_b64_e32 v[72:73], v[230:231]
	s_nop 1
	v_mov_b32_dpp v65, v66 row_ror:8 row_mask:0xf bank_mask:0xf
	v_mov_b32_dpp v78, v67 row_ror:8 row_mask:0xf bank_mask:0xf
	v_mov_b32_dpp v79, v68 row_ror:8 row_mask:0xf bank_mask:0xf
	v_mov_b32_dpp v80, v69 row_ror:8 row_mask:0xf bank_mask:0xf
	v_mov_b32_dpp v81, v70 row_ror:8 row_mask:0xf bank_mask:0xf
	v_mov_b32_dpp v82, v71 row_ror:8 row_mask:0xf bank_mask:0xf
	v_mov_b32_dpp v83, v72 row_ror:8 row_mask:0xf bank_mask:0xf
	v_mov_b32_dpp v84, v73 row_ror:8 row_mask:0xf bank_mask:0xf
	v_cndmask_b32_e64 v73, v73, v80, s[6:7]
	v_cndmask_b32_e64 v72, v72, v79, s[6:7]
	v_cndmask_b32_e64 v71, v71, v78, s[6:7]
	v_cndmask_b32_e64 v65, v70, v65, s[6:7]
	v_cndmask_b32_e64 v82, v82, v67, s[6:7]
	v_cndmask_b32_e64 v79, v81, v66, s[6:7]
	v_cndmask_b32_e64 v85, v84, v69, s[6:7]
	v_cndmask_b32_e64 v83, v83, v68, s[6:7]
	v_lshlrev_b32_e32 v66, 16, v65
	v_and_b32_e32 v67, 0xffff0000, v65
	v_lshlrev_b32_e32 v68, 16, v71
	v_and_b32_e32 v69, 0xffff0000, v71
	v_lshlrev_b32_e32 v70, 16, v72
	v_and_b32_e32 v71, 0xffff0000, v72
	v_lshlrev_b32_e32 v72, 16, v73
	v_and_b32_e32 v73, 0xffff0000, v73
	v_lshlrev_b32_e32 v78, 16, v79
	v_and_b32_e32 v79, 0xffff0000, v79
	v_lshlrev_b32_e32 v80, 16, v82
	v_and_b32_e32 v81, 0xffff0000, v82
	v_lshlrev_b32_e32 v82, 16, v83
	v_and_b32_e32 v83, 0xffff0000, v83
	v_lshlrev_b32_e32 v84, 16, v85
	v_and_b32_e32 v85, 0xffff0000, v85
	v_pk_add_f32 v[66:67], v[52:53], v[66:67]
	v_pk_add_f32 v[72:73], v[50:51], v[72:73]
	v_pk_add_f32 v[50:51], v[62:63], v[80:81]
	v_pk_add_f32 v[52:53], v[60:61], v[78:79]
	v_pk_add_f32 v[68:69], v[54:55], v[68:69]
	v_pk_add_f32 v[54:55], v[58:59], v[84:85]
	v_pk_add_f32 v[56:57], v[56:57], v[82:83]
	v_mul_f32_e32 v58, v53, v53
	v_mul_f32_e32 v59, v51, v51
	v_mul_f32_e32 v60, v57, v57
	v_fmac_f32_e32 v58, v52, v52
	v_fmac_f32_e32 v59, v50, v50
	v_pk_add_f32 v[48:49], v[48:49], v[70:71]
	v_mul_f32_e32 v61, v55, v55
	v_cvt_pk_bf16_f32 v53, v52, v53
	v_fmac_f32_e32 v60, v56, v56
	v_add_f32_e32 v52, v58, v59
	v_mul_f32_e32 v58, v67, v67
	v_mul_f32_e32 v59, v69, v69
	v_cvt_pk_bf16_f32 v51, v50, v51
	v_cvt_pk_bf16_f32 v57, v56, v57
	v_cvt_pk_bf16_f32 v55, v54, v55
	v_cvt_pk_bf16_f32 v62, v66, v67
	v_cvt_pk_bf16_f32 v63, v68, v69
	v_cvt_pk_bf16_f32 v65, v48, v49
	v_fmac_f32_e32 v61, v54, v54
	v_add_f32_e32 v52, v60, v52
	v_mov_b32_dpp v92, v65 row_ror:8 row_mask:0xf bank_mask:0xf
	v_fmac_f32_e32 v58, v66, v66
	v_fmac_f32_e32 v59, v68, v68
	v_mul_f32_e32 v49, v49, v49
	v_mov_b32_dpp v88, v57 row_ror:8 row_mask:0xf bank_mask:0xf
	v_add_f32_e32 v56, v61, v52
	v_cndmask_b32_e64 v52, v92, v57, s[6:7]
	v_mul_f32_e32 v57, v73, v73
	v_add_f32_e32 v58, v58, v59
	v_fmac_f32_e32 v49, v48, v48
	v_fmac_f32_e32 v57, v72, v72
	v_add_f32_e32 v48, v49, v58
	v_add_f32_e32 v48, v57, v48
	v_add_f32_e32 v60, v48, v56
	v_mov_b32_e32 v61, v60
	s_nop 1
	v_permlane16_swap_b32_e32 v61, v60
	v_lshl_add_u64 v[48:49], s[16:17], 0, v[74:75]
	v_lshl_add_u64 v[58:59], v[48:49], 0, v[146:147]
	v_cvt_pk_bf16_f32 v70, v72, v73
	v_mov_b32_dpp v90, v62 row_ror:8 row_mask:0xf bank_mask:0xf
	s_waitcnt lgkmcnt(0)
	v_add_f32_e32 v48, v60, v61
	v_mov_b32_e32 v49, v48
	s_nop 1
	v_permlane32_swap_b32_e32 v49, v48
	v_mov_b32_dpp v91, v63 row_ror:8 row_mask:0xf bank_mask:0xf
	v_mov_b32_dpp v93, v70 row_ror:8 row_mask:0xf bank_mask:0xf
	v_mov_b32_dpp v86, v53 row_ror:8 row_mask:0xf bank_mask:0xf
	v_mov_b32_dpp v87, v51 row_ror:8 row_mask:0xf bank_mask:0xf
	v_cndmask_b32_e64 v50, v90, v53, s[6:7]
	v_cndmask_b32_e64 v51, v91, v51, s[6:7]
	v_cndmask_b32_e64 v53, v93, v55, s[6:7]
	v_mov_b32_dpp v89, v55 row_ror:8 row_mask:0xf bank_mask:0xf
	global_store_dwordx4 v[58:59], v[50:53], off
	v_cndmask_b32_e64 v54, v62, v86, s[6:7]
	v_cndmask_b32_e64 v55, v63, v87, s[6:7]
	v_lshl_add_u64 v[50:51], s[16:17], 0, v[76:77]
	v_cndmask_b32_e64 v56, v65, v88, s[6:7]
	v_cndmask_b32_e64 v57, v70, v89, s[6:7]
	v_lshl_add_u64 v[50:51], v[50:51], 0, v[146:147]
	global_store_dwordx4 v[50:51], v[54:57], off
	s_and_saveexec_b64 s[42:43], s[8:9]
	s_cbranch_execz .LBB0_1256
	v_ashrrev_i32_e32 v65, 31, v64
	s_waitcnt lgkmcnt(0)
	v_add_f32_e32 v50, v48, v49
	v_lshl_add_u64 v[48:49], v[64:65], 2, s[18:19]
	global_atomic_add_f32 v[48:49], v50, off
; __device__ __forceinline__ unsigned cvt_pk_bf16(float lo, float hi) { unsigned r; asm volatile("v_cvt_pk_bf16_f32 %0, %1, %2" : "=v"(r) : "v"(lo), "v"(hi)); return r; }
; __device__ __forceinline__ float bflo(unsigned w) { return __uint_as_float(w << 16); }
; __device__ __forceinline__ float bfhi(unsigned w) { return __uint_as_float(w & 0xffff0000u); }
;     __device__ __forceinline__ void operator()(const f32x4 (&acc)[2][2][4][2], const Unit& u, int wr, int wc, int fr, int fq) const {
;     ...
;             for (int m = 0; m < 4; ++m) { const int row = row0 + ai * HALF + m * 16; const size_t off = (size_t)row * D + col0; float sq = 0.f; u32x4 w[2];
;                 const float sc = rsin ? __builtin_amdgcn_rcpf(rsin[row] * (1.f / D) + EPS) : 1.0f;
;                 u32x4 rr[2]; if (R) load_pair_lines(R, D, row, fr, col0, rr[0], rr[1]);
; #pragma unroll
;                 for (int bj = 0; bj < 2; ++bj) { f32x4 r0, r1;
;                     if (R) { const u32x4 rw = rr[bj]; r0 = (f32x4){bflo(rw.x), bfhi(rw.x), bflo(rw.y), bfhi(rw.y)}; r1 = (f32x4){bflo(rw.z), bfhi(rw.z), bflo(rw.w), bfhi(rw.w)}; }
;                     else { const float* rp = (row < 8192 ? src_p + off : src_s + (off - (size_t)8192 * D)) + 8 * bj; r0 = *(const f32x4*)rp; r1 = *(const f32x4*)(rp + 4); }
;                     const f32x4 o0 = r0 + acc[ai][bj][m][0] * sc, o1 = r1 + acc[ai][bj][m][1] * sc;
;                     sq += (o0[0] * o0[0] + o0[1] * o0[1]) + (o0[2] * o0[2] + o0[3] * o0[3]) + (o1[0] * o1[0] + o1[1] * o1[1]) + (o1[2] * o1[2] + o1[3] * o1[3]);
;                     w[bj].x = cvt_pk_bf16(o0[0], o0[1]); w[bj].y = cvt_pk_bf16(o0[2], o0[3]); w[bj].z = cvt_pk_bf16(o1[0], o1[1]); w[bj].w = cvt_pk_bf16(o1[2], o1[3]); }
;                 store_pair_lines(O, D, row, fr, col0, w[0], w[1]);
;                 if (ssout) { sq += __shfl_xor(sq, 16); sq += __shfl_xor(sq, 32); if (fq == 0) unsafeAtomicAdd(ssout + row, sq); } }
.LBB0_1256:
	s_or_b64 exec, exec, s[42:43]
	v_add_u32_e32 v48, 0x90, v148
	s_waitcnt lgkmcnt(0)
	v_sub_u32_e32 v49, v48, v150
	v_add_u32_e32 v50, v49, v152
	v_ashrrev_i32_e32 v51, 31, v50
	v_lshlrev_b64 v[58:59], 12, v[50:51]
	v_lshl_add_u64 v[60:61], v[58:59], 0, s[28:29]
	v_lshl_add_u64 v[50:51], s[10:11], 0, v[58:59]
	v_lshl_add_u64 v[54:55], s[10:11], 0, v[60:61]
	v_lshl_add_u64 v[50:51], v[50:51], 0, v[146:147]
	v_lshl_add_u64 v[54:55], v[54:55], 0, v[146:147]
	s_waitcnt vmcnt(14)
	s_nop 0
	v_mov_b64_e32 v[50:51], v[232:233]
	v_mov_b64_e32 v[52:53], v[234:235]
	v_mov_b64_e32 v[54:55], v[236:237]
	v_mov_b64_e32 v[56:57], v[238:239]
	s_nop 1
	v_mov_b32_dpp v49, v50 row_ror:8 row_mask:0xf bank_mask:0xf
	v_mov_b32_dpp v62, v51 row_ror:8 row_mask:0xf bank_mask:0xf
	v_mov_b32_dpp v63, v52 row_ror:8 row_mask:0xf bank_mask:0xf
	v_mov_b32_dpp v64, v53 row_ror:8 row_mask:0xf bank_mask:0xf
	v_mov_b32_dpp v65, v54 row_ror:8 row_mask:0xf bank_mask:0xf
	v_mov_b32_dpp v66, v55 row_ror:8 row_mask:0xf bank_mask:0xf
	v_mov_b32_dpp v67, v56 row_ror:8 row_mask:0xf bank_mask:0xf
	v_mov_b32_dpp v68, v57 row_ror:8 row_mask:0xf bank_mask:0xf
	v_cndmask_b32_e64 v57, v57, v64, s[6:7]
	v_cndmask_b32_e64 v56, v56, v63, s[6:7]
	v_cndmask_b32_e64 v55, v55, v62, s[6:7]
	v_cndmask_b32_e64 v49, v54, v49, s[6:7]
	v_cndmask_b32_e64 v66, v66, v51, s[6:7]
	v_cndmask_b32_e64 v63, v65, v50, s[6:7]
	v_cndmask_b32_e64 v69, v68, v53, s[6:7]
	v_cndmask_b32_e64 v67, v67, v52, s[6:7]
	v_lshlrev_b32_e32 v50, 16, v49
	v_and_b32_e32 v51, 0xffff0000, v49
	v_lshlrev_b32_e32 v52, 16, v55
	v_and_b32_e32 v53, 0xffff0000, v55
	v_lshlrev_b32_e32 v54, 16, v56
	v_and_b32_e32 v55, 0xffff0000, v56
	v_lshlrev_b32_e32 v56, 16, v57
	v_and_b32_e32 v57, 0xffff0000, v57
	v_lshlrev_b32_e32 v62, 16, v63
	v_and_b32_e32 v63, 0xffff0000, v63
	v_lshlrev_b32_e32 v64, 16, v66
	v_and_b32_e32 v65, 0xffff0000, v66
	v_lshlrev_b32_e32 v66, 16, v67
	v_and_b32_e32 v67, 0xffff0000, v67
	v_lshlrev_b32_e32 v68, 16, v69
	v_and_b32_e32 v69, 0xffff0000, v69
	v_pk_add_f32 v[50:51], v[36:37], v[50:51]
	v_pk_add_f32 v[56:57], v[34:35], v[56:57]
	v_pk_add_f32 v[34:35], v[46:47], v[64:65]
	v_pk_add_f32 v[36:37], v[44:45], v[62:63]
	v_pk_add_f32 v[52:53], v[38:39], v[52:53]
	v_pk_add_f32 v[38:39], v[42:43], v[68:69]
	v_pk_add_f32 v[40:41], v[40:41], v[66:67]
	v_mul_f32_e32 v42, v37, v37
	v_mul_f32_e32 v43, v35, v35
	v_mul_f32_e32 v44, v41, v41
	v_fmac_f32_e32 v42, v36, v36
	v_fmac_f32_e32 v43, v34, v34
	v_pk_add_f32 v[32:33], v[32:33], v[54:55]
	v_mul_f32_e32 v45, v39, v39
	v_cvt_pk_bf16_f32 v37, v36, v37
	v_fmac_f32_e32 v44, v40, v40
	v_add_f32_e32 v36, v42, v43
	v_mul_f32_e32 v42, v51, v51
	v_mul_f32_e32 v43, v53, v53
	v_cvt_pk_bf16_f32 v35, v34, v35
	v_cvt_pk_bf16_f32 v41, v40, v41
	v_cvt_pk_bf16_f32 v39, v38, v39
	v_cvt_pk_bf16_f32 v46, v50, v51
	v_cvt_pk_bf16_f32 v47, v52, v53
	v_cvt_pk_bf16_f32 v49, v32, v33
	v_fmac_f32_e32 v45, v38, v38
	v_add_f32_e32 v36, v44, v36
	v_mov_b32_dpp v76, v49 row_ror:8 row_mask:0xf bank_mask:0xf
	v_fmac_f32_e32 v42, v50, v50
	v_fmac_f32_e32 v43, v52, v52
	v_mul_f32_e32 v33, v33, v33
	v_mov_b32_dpp v72, v41 row_ror:8 row_mask:0xf bank_mask:0xf
	v_add_f32_e32 v40, v45, v36
	v_cndmask_b32_e64 v36, v76, v41, s[6:7]
	v_mul_f32_e32 v41, v57, v57
	v_add_f32_e32 v42, v42, v43
	v_fmac_f32_e32 v33, v32, v32
	v_fmac_f32_e32 v41, v56, v56
	v_add_f32_e32 v32, v33, v42
	v_add_f32_e32 v32, v41, v32
	v_add_f32_e32 v44, v32, v40
	v_mov_b32_e32 v45, v44
	s_nop 1
	v_permlane16_swap_b32_e32 v45, v44
	v_lshl_add_u64 v[32:33], s[16:17], 0, v[58:59]
	v_lshl_add_u64 v[42:43], v[32:33], 0, v[146:147]
	v_cvt_pk_bf16_f32 v54, v56, v57
	v_mov_b32_dpp v74, v46 row_ror:8 row_mask:0xf bank_mask:0xf
	s_waitcnt lgkmcnt(0)
	v_add_f32_e32 v32, v44, v45
	v_mov_b32_e32 v33, v32
	s_nop 1
	v_permlane32_swap_b32_e32 v33, v32
	v_mov_b32_dpp v75, v47 row_ror:8 row_mask:0xf bank_mask:0xf
	v_mov_b32_dpp v77, v54 row_ror:8 row_mask:0xf bank_mask:0xf
	v_mov_b32_dpp v70, v37 row_ror:8 row_mask:0xf bank_mask:0xf
	v_mov_b32_dpp v71, v35 row_ror:8 row_mask:0xf bank_mask:0xf
	v_cndmask_b32_e64 v34, v74, v37, s[6:7]
	v_cndmask_b32_e64 v35, v75, v35, s[6:7]
	v_cndmask_b32_e64 v37, v77, v39, s[6:7]
	v_mov_b32_dpp v73, v39 row_ror:8 row_mask:0xf bank_mask:0xf
	global_store_dwordx4 v[42:43], v[34:37], off
	v_cndmask_b32_e64 v38, v46, v70, s[6:7]
	v_cndmask_b32_e64 v39, v47, v71, s[6:7]
	v_lshl_add_u64 v[34:35], s[16:17], 0, v[60:61]
	v_cndmask_b32_e64 v40, v49, v72, s[6:7]
	v_cndmask_b32_e64 v41, v54, v73, s[6:7]
	v_lshl_add_u64 v[34:35], v[34:35], 0, v[146:147]
	global_store_dwordx4 v[34:35], v[38:41], off
	s_and_saveexec_b64 s[42:43], s[8:9]
	s_cbranch_execz .LBB0_1258
	v_ashrrev_i32_e32 v49, 31, v48
	s_waitcnt lgkmcnt(0)
	v_add_f32_e32 v34, v32, v33
	v_lshl_add_u64 v[32:33], v[48:49], 2, s[18:19]
	global_atomic_add_f32 v[32:33], v34, off
; __device__ __forceinline__ unsigned cvt_pk_bf16(float lo, float hi) { unsigned r; asm volatile("v_cvt_pk_bf16_f32 %0, %1, %2" : "=v"(r) : "v"(lo), "v"(hi)); return r; }
; __device__ __forceinline__ float bflo(unsigned w) { return __uint_as_float(w << 16); }
; __device__ __forceinline__ float bfhi(unsigned w) { return __uint_as_float(w & 0xffff0000u); }
;     __device__ __forceinline__ void operator()(const f32x4 (&acc)[2][2][4][2], const Unit& u, int wr, int wc, int fr, int fq) const {
;     ...
;             for (int m = 0; m < 4; ++m) { const int row = row0 + ai * HALF + m * 16; const size_t off = (size_t)row * D + col0; float sq = 0.f; u32x4 w[2];
;                 const float sc = rsin ? __builtin_amdgcn_rcpf(rsin[row] * (1.f / D) + EPS) : 1.0f;
;                 u32x4 rr[2]; if (R) load_pair_lines(R, D, row, fr, col0, rr[0], rr[1]);
; #pragma unroll
;                 for (int bj = 0; bj < 2; ++bj) { f32x4 r0, r1;
;                     if (R) { const u32x4 rw = rr[bj]; r0 = (f32x4){bflo(rw.x), bfhi(rw.x), bflo(rw.y), bfhi(rw.y)}; r1 = (f32x4){bflo(rw.z), bfhi(rw.z), bflo(rw.w), bfhi(rw.w)}; }
;                     else { const float* rp = (row < 8192 ? src_p + off : src_s + (off - (size_t)8192 * D)) + 8 * bj; r0 = *(const f32x4*)rp; r1 = *(const f32x4*)(rp + 4); }
;                     const f32x4 o0 = r0 + acc[ai][bj][m][0] * sc, o1 = r1 + acc[ai][bj][m][1] * sc;
;                     sq += (o0[0] * o0[0] + o0[1] * o0[1]) + (o0[2] * o0[2] + o0[3] * o0[3]) + (o1[0] * o1[0] + o1[1] * o1[1]) + (o1[2] * o1[2] + o1[3] * o1[3]);
;                     w[bj].x = cvt_pk_bf16(o0[0], o0[1]); w[bj].y = cvt_pk_bf16(o0[2], o0[3]); w[bj].z = cvt_pk_bf16(o1[0], o1[1]); w[bj].w = cvt_pk_bf16(o1[2], o1[3]); }
;                 store_pair_lines(O, D, row, fr, col0, w[0], w[1]);
;                 if (ssout) { sq += __shfl_xor(sq, 16); sq += __shfl_xor(sq, 32); if (fq == 0) unsafeAtomicAdd(ssout + row, sq); } }
.LBB0_1258:
	s_or_b64 exec, exec, s[42:43]
	v_add_u32_e32 v32, 0xa0, v148
	s_waitcnt lgkmcnt(0)
	v_sub_u32_e32 v33, v32, v150
	v_add_u32_e32 v34, v33, v152
	v_ashrrev_i32_e32 v35, 31, v34
	v_lshlrev_b64 v[42:43], 12, v[34:35]
	v_lshl_add_u64 v[44:45], v[42:43], 0, s[28:29]
	v_lshl_add_u64 v[34:35], s[10:11], 0, v[42:43]
	v_lshl_add_u64 v[38:39], s[10:11], 0, v[44:45]
	v_lshl_add_u64 v[34:35], v[34:35], 0, v[146:147]
	v_lshl_add_u64 v[38:39], v[38:39], 0, v[146:147]
	s_waitcnt vmcnt(14)
	s_nop 0
	v_mov_b64_e32 v[34:35], v[240:241]
	v_mov_b64_e32 v[36:37], v[242:243]
	v_mov_b64_e32 v[38:39], v[244:245]
	v_mov_b64_e32 v[40:41], v[246:247]
	s_nop 1
	v_mov_b32_dpp v33, v34 row_ror:8 row_mask:0xf bank_mask:0xf
	v_mov_b32_dpp v46, v35 row_ror:8 row_mask:0xf bank_mask:0xf
	v_mov_b32_dpp v47, v36 row_ror:8 row_mask:0xf bank_mask:0xf
	v_mov_b32_dpp v48, v37 row_ror:8 row_mask:0xf bank_mask:0xf
	v_mov_b32_dpp v49, v38 row_ror:8 row_mask:0xf bank_mask:0xf
	v_mov_b32_dpp v50, v39 row_ror:8 row_mask:0xf bank_mask:0xf
	v_mov_b32_dpp v51, v40 row_ror:8 row_mask:0xf bank_mask:0xf
	v_mov_b32_dpp v52, v41 row_ror:8 row_mask:0xf bank_mask:0xf
	v_cndmask_b32_e64 v41, v41, v48, s[6:7]
	v_cndmask_b32_e64 v40, v40, v47, s[6:7]
	v_cndmask_b32_e64 v39, v39, v46, s[6:7]
	v_cndmask_b32_e64 v33, v38, v33, s[6:7]
	v_cndmask_b32_e64 v50, v50, v35, s[6:7]
	v_cndmask_b32_e64 v47, v49, v34, s[6:7]
	v_cndmask_b32_e64 v53, v52, v37, s[6:7]
	v_cndmask_b32_e64 v51, v51, v36, s[6:7]
	v_lshlrev_b32_e32 v34, 16, v33
	v_and_b32_e32 v35, 0xffff0000, v33
	v_lshlrev_b32_e32 v36, 16, v39
	v_and_b32_e32 v37, 0xffff0000, v39
	v_lshlrev_b32_e32 v38, 16, v40
	v_and_b32_e32 v39, 0xffff0000, v40
	v_lshlrev_b32_e32 v40, 16, v41
	v_and_b32_e32 v41, 0xffff0000, v41
	v_lshlrev_b32_e32 v46, 16, v47
	v_and_b32_e32 v47, 0xffff0000, v47
	v_lshlrev_b32_e32 v48, 16, v50
	v_and_b32_e32 v49, 0xffff0000, v50
	v_lshlrev_b32_e32 v50, 16, v51
	v_and_b32_e32 v51, 0xffff0000, v51
	v_lshlrev_b32_e32 v52, 16, v53
	v_and_b32_e32 v53, 0xffff0000, v53
	v_pk_add_f32 v[34:35], v[20:21], v[34:35]
	v_pk_add_f32 v[40:41], v[18:19], v[40:41]
	v_pk_add_f32 v[18:19], v[30:31], v[48:49]
	v_pk_add_f32 v[20:21], v[28:29], v[46:47]
	v_pk_add_f32 v[36:37], v[22:23], v[36:37]
	v_pk_add_f32 v[22:23], v[26:27], v[52:53]
	v_pk_add_f32 v[24:25], v[24:25], v[50:51]
	v_mul_f32_e32 v26, v21, v21
	v_mul_f32_e32 v27, v19, v19
	v_mul_f32_e32 v28, v25, v25
	v_fmac_f32_e32 v26, v20, v20
	v_fmac_f32_e32 v27, v18, v18
	v_pk_add_f32 v[16:17], v[16:17], v[38:39]
	v_mul_f32_e32 v29, v23, v23
	v_cvt_pk_bf16_f32 v21, v20, v21
	v_fmac_f32_e32 v28, v24, v24
	v_add_f32_e32 v20, v26, v27
	v_mul_f32_e32 v26, v35, v35
	v_mul_f32_e32 v27, v37, v37
	v_cvt_pk_bf16_f32 v19, v18, v19
	v_cvt_pk_bf16_f32 v25, v24, v25
	v_cvt_pk_bf16_f32 v23, v22, v23
	v_cvt_pk_bf16_f32 v30, v34, v35
	v_cvt_pk_bf16_f32 v31, v36, v37
	v_cvt_pk_bf16_f32 v33, v16, v17
	v_fmac_f32_e32 v29, v22, v22
	v_add_f32_e32 v20, v28, v20
	v_mov_b32_dpp v60, v33 row_ror:8 row_mask:0xf bank_mask:0xf
	v_fmac_f32_e32 v26, v34, v34
	v_fmac_f32_e32 v27, v36, v36
	v_mul_f32_e32 v17, v17, v17
	v_mov_b32_dpp v56, v25 row_ror:8 row_mask:0xf bank_mask:0xf
	v_add_f32_e32 v24, v29, v20
	v_cndmask_b32_e64 v20, v60, v25, s[6:7]
	v_mul_f32_e32 v25, v41, v41
	v_add_f32_e32 v26, v26, v27
	v_fmac_f32_e32 v17, v16, v16
	v_fmac_f32_e32 v25, v40, v40
	v_add_f32_e32 v16, v17, v26
	v_add_f32_e32 v16, v25, v16
	v_add_f32_e32 v28, v16, v24
	v_mov_b32_e32 v29, v28
	s_nop 1
	v_permlane16_swap_b32_e32 v29, v28
	v_lshl_add_u64 v[16:17], s[16:17], 0, v[42:43]
	v_lshl_add_u64 v[26:27], v[16:17], 0, v[146:147]
	v_cvt_pk_bf16_f32 v38, v40, v41
	v_mov_b32_dpp v58, v30 row_ror:8 row_mask:0xf bank_mask:0xf
	s_waitcnt lgkmcnt(0)
	v_add_f32_e32 v16, v28, v29
	v_mov_b32_e32 v17, v16
	s_nop 1
	v_permlane32_swap_b32_e32 v17, v16
	v_mov_b32_dpp v59, v31 row_ror:8 row_mask:0xf bank_mask:0xf
	v_mov_b32_dpp v61, v38 row_ror:8 row_mask:0xf bank_mask:0xf
	v_mov_b32_dpp v54, v21 row_ror:8 row_mask:0xf bank_mask:0xf
	v_mov_b32_dpp v55, v19 row_ror:8 row_mask:0xf bank_mask:0xf
	v_cndmask_b32_e64 v18, v58, v21, s[6:7]
	v_cndmask_b32_e64 v19, v59, v19, s[6:7]
	v_cndmask_b32_e64 v21, v61, v23, s[6:7]
	v_mov_b32_dpp v57, v23 row_ror:8 row_mask:0xf bank_mask:0xf
	global_store_dwordx4 v[26:27], v[18:21], off
	v_cndmask_b32_e64 v22, v30, v54, s[6:7]
	v_cndmask_b32_e64 v23, v31, v55, s[6:7]
	v_lshl_add_u64 v[18:19], s[16:17], 0, v[44:45]
	v_cndmask_b32_e64 v24, v33, v56, s[6:7]
	v_cndmask_b32_e64 v25, v38, v57, s[6:7]
	v_lshl_add_u64 v[18:19], v[18:19], 0, v[146:147]
	global_store_dwordx4 v[18:19], v[22:25], off
	s_and_saveexec_b64 s[42:43], s[8:9]
	s_cbranch_execz .LBB0_1260
	v_ashrrev_i32_e32 v33, 31, v32
	s_waitcnt lgkmcnt(0)
	v_add_f32_e32 v18, v16, v17
	v_lshl_add_u64 v[16:17], v[32:33], 2, s[18:19]
	global_atomic_add_f32 v[16:17], v18, off
; __device__ __forceinline__ unsigned cvt_pk_bf16(float lo, float hi) { unsigned r; asm volatile("v_cvt_pk_bf16_f32 %0, %1, %2" : "=v"(r) : "v"(lo), "v"(hi)); return r; }
; __device__ __forceinline__ float bflo(unsigned w) { return __uint_as_float(w << 16); }
; __device__ __forceinline__ float bfhi(unsigned w) { return __uint_as_float(w & 0xffff0000u); }
;     __device__ __forceinline__ void operator()(const f32x4 (&acc)[2][2][4][2], const Unit& u, int wr, int wc, int fr, int fq) const {
;     ...
;             for (int m = 0; m < 4; ++m) { const int row = row0 + ai * HALF + m * 16; const size_t off = (size_t)row * D + col0; float sq = 0.f; u32x4 w[2];
;                 const float sc = rsin ? __builtin_amdgcn_rcpf(rsin[row] * (1.f / D) + EPS) : 1.0f;
;                 u32x4 rr[2]; if (R) load_pair_lines(R, D, row, fr, col0, rr[0], rr[1]);
; #pragma unroll
;                 for (int bj = 0; bj < 2; ++bj) { f32x4 r0, r1;
;                     if (R) { const u32x4 rw = rr[bj]; r0 = (f32x4){bflo(rw.x), bfhi(rw.x), bflo(rw.y), bfhi(rw.y)}; r1 = (f32x4){bflo(rw.z), bfhi(rw.z), bflo(rw.w), bfhi(rw.w)}; }
;                     else { const float* rp = (row < 8192 ? src_p + off : src_s + (off - (size_t)8192 * D)) + 8 * bj; r0 = *(const f32x4*)rp; r1 = *(const f32x4*)(rp + 4); }
;                     const f32x4 o0 = r0 + acc[ai][bj][m][0] * sc, o1 = r1 + acc[ai][bj][m][1] * sc;
;                     sq += (o0[0] * o0[0] + o0[1] * o0[1]) + (o0[2] * o0[2] + o0[3] * o0[3]) + (o1[0] * o1[0] + o1[1] * o1[1]) + (o1[2] * o1[2] + o1[3] * o1[3]);
;                     w[bj].x = cvt_pk_bf16(o0[0], o0[1]); w[bj].y = cvt_pk_bf16(o0[2], o0[3]); w[bj].z = cvt_pk_bf16(o1[0], o1[1]); w[bj].w = cvt_pk_bf16(o1[2], o1[3]); }
;                 store_pair_lines(O, D, row, fr, col0, w[0], w[1]);
;                 if (ssout) { sq += __shfl_xor(sq, 16); sq += __shfl_xor(sq, 32); if (fq == 0) unsafeAtomicAdd(ssout + row, sq); } }
.LBB0_1260:
	s_or_b64 exec, exec, s[42:43]
	v_add_u32_e32 v16, 0xb0, v148
	s_waitcnt lgkmcnt(0)
	v_sub_u32_e32 v17, v16, v150
	v_add_u32_e32 v18, v17, v152
	v_ashrrev_i32_e32 v19, 31, v18
	v_lshlrev_b64 v[26:27], 12, v[18:19]
	v_lshl_add_u64 v[28:29], v[26:27], 0, s[28:29]
	v_lshl_add_u64 v[18:19], s[10:11], 0, v[26:27]
	v_lshl_add_u64 v[22:23], s[10:11], 0, v[28:29]
	v_lshl_add_u64 v[18:19], v[18:19], 0, v[146:147]
	v_lshl_add_u64 v[22:23], v[22:23], 0, v[146:147]
	s_waitcnt vmcnt(12)
	s_nop 0
	v_mov_b64_e32 v[18:19], v[196:197]
	v_mov_b64_e32 v[20:21], v[198:199]
	v_mov_b64_e32 v[22:23], v[204:205]
	v_mov_b64_e32 v[24:25], v[206:207]
	s_nop 1
	v_mov_b32_dpp v17, v18 row_ror:8 row_mask:0xf bank_mask:0xf
	v_mov_b32_dpp v30, v19 row_ror:8 row_mask:0xf bank_mask:0xf
	v_mov_b32_dpp v31, v20 row_ror:8 row_mask:0xf bank_mask:0xf
	v_mov_b32_dpp v32, v21 row_ror:8 row_mask:0xf bank_mask:0xf
	v_mov_b32_dpp v33, v22 row_ror:8 row_mask:0xf bank_mask:0xf
	v_mov_b32_dpp v34, v23 row_ror:8 row_mask:0xf bank_mask:0xf
	v_mov_b32_dpp v35, v24 row_ror:8 row_mask:0xf bank_mask:0xf
	v_mov_b32_dpp v36, v25 row_ror:8 row_mask:0xf bank_mask:0xf
	v_cndmask_b32_e64 v25, v25, v32, s[6:7]
	v_cndmask_b32_e64 v24, v24, v31, s[6:7]
	v_cndmask_b32_e64 v23, v23, v30, s[6:7]
	v_cndmask_b32_e64 v17, v22, v17, s[6:7]
	v_cndmask_b32_e64 v34, v34, v19, s[6:7]
	v_cndmask_b32_e64 v31, v33, v18, s[6:7]
	v_cndmask_b32_e64 v37, v36, v21, s[6:7]
	v_cndmask_b32_e64 v35, v35, v20, s[6:7]
	v_lshlrev_b32_e32 v18, 16, v17
	v_and_b32_e32 v19, 0xffff0000, v17
	v_lshlrev_b32_e32 v20, 16, v23
	v_and_b32_e32 v21, 0xffff0000, v23
	v_lshlrev_b32_e32 v22, 16, v24
	v_and_b32_e32 v23, 0xffff0000, v24
	v_lshlrev_b32_e32 v24, 16, v25
	v_and_b32_e32 v25, 0xffff0000, v25
	v_lshlrev_b32_e32 v30, 16, v31
	v_and_b32_e32 v31, 0xffff0000, v31
	v_lshlrev_b32_e32 v32, 16, v34
	v_and_b32_e32 v33, 0xffff0000, v34
	v_lshlrev_b32_e32 v34, 16, v35
	v_and_b32_e32 v35, 0xffff0000, v35
	v_lshlrev_b32_e32 v36, 16, v37
	v_and_b32_e32 v37, 0xffff0000, v37
	v_pk_add_f32 v[18:19], v[4:5], v[18:19]
	v_pk_add_f32 v[24:25], v[2:3], v[24:25]
	v_pk_add_f32 v[2:3], v[14:15], v[32:33]
	v_pk_add_f32 v[4:5], v[12:13], v[30:31]
	v_pk_add_f32 v[20:21], v[6:7], v[20:21]
	v_pk_add_f32 v[6:7], v[10:11], v[36:37]
	v_pk_add_f32 v[8:9], v[8:9], v[34:35]
	v_mul_f32_e32 v10, v5, v5
	v_mul_f32_e32 v11, v3, v3
	v_mul_f32_e32 v12, v9, v9
	v_fmac_f32_e32 v10, v4, v4
	v_fmac_f32_e32 v11, v2, v2
	v_pk_add_f32 v[0:1], v[0:1], v[22:23]
	v_mul_f32_e32 v13, v7, v7
	v_cvt_pk_bf16_f32 v5, v4, v5
	v_fmac_f32_e32 v12, v8, v8
	v_add_f32_e32 v4, v10, v11
	v_mul_f32_e32 v10, v19, v19
	v_mul_f32_e32 v11, v21, v21
	v_cvt_pk_bf16_f32 v3, v2, v3
	v_cvt_pk_bf16_f32 v9, v8, v9
	v_cvt_pk_bf16_f32 v7, v6, v7
	v_cvt_pk_bf16_f32 v14, v18, v19
	v_cvt_pk_bf16_f32 v15, v20, v21
	v_cvt_pk_bf16_f32 v17, v0, v1
	v_fmac_f32_e32 v13, v6, v6
	v_add_f32_e32 v4, v12, v4
	v_mov_b32_dpp v44, v17 row_ror:8 row_mask:0xf bank_mask:0xf
	v_fmac_f32_e32 v10, v18, v18
	v_fmac_f32_e32 v11, v20, v20
	v_mul_f32_e32 v1, v1, v1
	v_mov_b32_dpp v40, v9 row_ror:8 row_mask:0xf bank_mask:0xf
	v_add_f32_e32 v8, v13, v4
	v_cndmask_b32_e64 v4, v44, v9, s[6:7]
	v_mul_f32_e32 v9, v25, v25
	v_add_f32_e32 v10, v10, v11
	v_fmac_f32_e32 v1, v0, v0
	v_fmac_f32_e32 v9, v24, v24
	v_add_f32_e32 v0, v1, v10
	v_add_f32_e32 v0, v9, v0
	v_add_f32_e32 v12, v0, v8
	v_mov_b32_e32 v13, v12
	s_nop 1
	v_permlane16_swap_b32_e32 v13, v12
	v_lshl_add_u64 v[0:1], s[16:17], 0, v[26:27]
	v_lshl_add_u64 v[10:11], v[0:1], 0, v[146:147]
	v_cvt_pk_bf16_f32 v22, v24, v25
	v_mov_b32_dpp v42, v14 row_ror:8 row_mask:0xf bank_mask:0xf
	s_waitcnt lgkmcnt(0)
	v_add_f32_e32 v0, v12, v13
	v_mov_b32_e32 v1, v0
	s_nop 1
	v_permlane32_swap_b32_e32 v1, v0
	v_mov_b32_dpp v43, v15 row_ror:8 row_mask:0xf bank_mask:0xf
	v_mov_b32_dpp v45, v22 row_ror:8 row_mask:0xf bank_mask:0xf
	v_mov_b32_dpp v38, v5 row_ror:8 row_mask:0xf bank_mask:0xf
	v_mov_b32_dpp v39, v3 row_ror:8 row_mask:0xf bank_mask:0xf
	v_cndmask_b32_e64 v2, v42, v5, s[6:7]
	v_cndmask_b32_e64 v3, v43, v3, s[6:7]
	v_cndmask_b32_e64 v5, v45, v7, s[6:7]
	v_mov_b32_dpp v41, v7 row_ror:8 row_mask:0xf bank_mask:0xf
	global_store_dwordx4 v[10:11], v[2:5], off
	v_cndmask_b32_e64 v6, v14, v38, s[6:7]
	v_cndmask_b32_e64 v7, v15, v39, s[6:7]
	v_lshl_add_u64 v[2:3], s[16:17], 0, v[28:29]
	v_cndmask_b32_e64 v8, v17, v40, s[6:7]
	v_cndmask_b32_e64 v9, v22, v41, s[6:7]
	v_lshl_add_u64 v[2:3], v[2:3], 0, v[146:147]
	global_store_dwordx4 v[2:3], v[6:9], off
	s_and_saveexec_b64 s[42:43], s[8:9]
	s_cbranch_execz .LBB0_1236
	v_ashrrev_i32_e32 v17, 31, v16
	s_waitcnt lgkmcnt(0)
	v_add_f32_e32 v2, v0, v1
	v_lshl_add_u64 v[0:1], v[16:17], 2, s[18:19]
	global_atomic_add_f32 v[0:1], v2, off
	s_branch .LBB0_1236

; #define PG8_STAGE(bufoff, gbase, voff) do { _Pragma("unroll") for (int _i = 0; _i < 2; ++_i) \
;         __builtin_amdgcn_global_load_lds((const unsigned*)((const char*)(gbase) + (voff)[_i]), (LAS unsigned*)(lds + (bufoff) + ldsw + _i * 8192), 16, 0, 0); } while (0)
; #define PG8_LDA(dst, b, h) do { _Pragma("unroll") for (int m = 0; m < 4; ++m) _Pragma("unroll") for (int k = 0; k < 2; ++k) dst[m][k] = *(const LAS bf16x8*)(lds + PG8_SA(b, h) + aoff + m * 2048 + k * 1024); } while (0)
; #define PG8_WAIT_V(n) asm volatile("s_waitcnt vmcnt(" #n ")" ::: "memory")
; #define PG8_WAIT_L(n) asm volatile("s_waitcnt lgkmcnt(" #n ")" ::: "memory")
; template <class Epi>
; __device__ __forceinline__ void gemm_phase(LAS unsigned char* lds, const Gemm g, const StaticOrder& S, const Epi& E) {
;     ...
;         for (int t = 0; t < nt; t += 2) {
;             const bool last = (t == nt - 2);
;             const char* a1 = cA + (size_t)(t + 1) * kstep;
;             const char* a2 = last ? nA : cA + (size_t)(t + 2) * kstep; const char* b2 = last ? nB : cB + (size_t)(t + 2) * kstep;
;             const char* a3 = a2 + kstep; const char* b3 = b2 + kstep;
;             PG8_LDB(B0, 0, 0); PG8_SCHED; PG8_LDA(At, 0, 0); PG8_STAGE(PG8_SA(1, 1), a1 + hstep, voffA);
;             PG8_WAIT_L(8); PG8_BAR; PG8_WAIT_L(0); PG8_MMA(0, 0, At, B0); PG8_BAR; PG8_SCHED;
;             PG8_LDB(B1, 0, 1); PG8_STAGE(PG8_SB(0, 0), b2, voffB0);
;             PG8_BAR; PG8_WAIT_L(0); PG8_MMA(0, 1, At, B1); PG8_BAR;
;             PG8_LDA(At, 0, 1); PG8_STAGE(PG8_SA(0, 0), a2, voffA);
;             PG8_BAR; PG8_WAIT_L(0); PG8_MMA(1, 0, At, B0); PG8_BAR; PG8_SCHED;
;             PG8_STAGE(PG8_SB(0, 1), b2, voffB1);
;             PG8_WAIT_V(6); PG8_BAR; PG8_MMA(1, 1, At, B1); PG8_BAR;
;             PG8_LDB(B0, 1, 0); PG8_SCHED; PG8_LDA(At, 1, 0); PG8_STAGE(PG8_SA(0, 1), a2 + hstep, voffA);
;             PG8_WAIT_L(8); PG8_BAR; PG8_WAIT_L(0); PG8_MMA(0, 0, At, B0); PG8_BAR; PG8_SCHED;
;             PG8_LDB(B1, 1, 1); PG8_STAGE(PG8_SB(1, 0), b3, voffB0);
;             PG8_BAR; PG8_WAIT_L(0); PG8_MMA(0, 1, At, B1); PG8_BAR;
;             PG8_LDA(At, 1, 1); PG8_STAGE(PG8_SA(1, 0), a3, voffA);
;             PG8_BAR; PG8_WAIT_L(0); PG8_MMA(1, 0, At, B0); PG8_BAR; PG8_SCHED;
;             PG8_STAGE(PG8_SB(1, 1), b3, voffB1);
;             PG8_WAIT_V(6); PG8_BAR; PG8_MMA(1, 1, At, B1); PG8_BAR;
.LBB0_1277:
	s_add_u32 s33, s44, s52
	s_addc_u32 s53, s45, 0
	s_add_u32 s50, s33, 0x100
	s_addc_u32 s51, s53, 0
	v_cndmask_b32_e64 v153, 0, 1, s[48:49]
	s_and_b64 s[48:49], s[46:47], exec
	s_cselect_b32 s51, s29, s51
	s_cselect_b32 s50, s39, s50
	s_add_u32 s48, s42, s52
	s_addc_u32 s49, s43, 0
	s_add_u32 s48, s48, 0x100
	s_addc_u32 s49, s49, 0
	s_and_b64 s[46:47], s[46:47], exec
	ds_read_b128 v[142:145], v150
	ds_read_b128 v[154:157], v150 offset:1024
	ds_read_b128 v[158:161], v150 offset:2048
	ds_read_b128 v[162:165], v150 offset:3072
	s_cselect_b32 s48, s73, s48
	s_cselect_b32 s49, s27, s49
	s_add_u32 s52, s33, 0x10080
	s_addc_u32 s53, s53, 0
	s_add_i32 s82, s71, s59
	s_add_i32 s78, s72, s59
	s_add_i32 m0, s41, 0xc000
	s_add_i32 s33, s41, 0xe000
	s_add_i32 s81, s82, 0x2000
	s_add_i32 s77, s78, 0x2000
	s_add_i32 s76, 0, 0x18000
	s_add_u32 s46, s50, 0x10000
	s_addc_u32 s47, s51, 0
	s_add_i32 s74, 0, 0x1c000
	s_add_i32 s75, s76, s59
	s_add_i32 s80, s74, s59
	s_add_i32 s83, s75, 0x2000
	s_add_i32 s79, s80, 0x2000
	v_cmp_ne_u32_e32 vcc, 1, v153
	v_lshl_add_u64 v[198:199], s[52:53], 0, v[128:129]
	ds_read_b128 v[166:169], v151
	ds_read_b128 v[170:173], v151 offset:1024
	ds_read_b128 v[174:177], v151 offset:2048
	ds_read_b128 v[178:181], v151 offset:3072
	ds_read_b128 v[182:185], v151 offset:4096
	ds_read_b128 v[186:189], v151 offset:5120
	ds_read_b128 v[190:193], v151 offset:6144
	ds_read_b128 v[194:197], v151 offset:7168
	global_load_lds_dwordx4 v[198:199], off
	v_lshl_add_u64 v[198:199], s[52:53], 0, v[134:135]
	s_mov_b32 m0, s33
	s_nop 0
	global_load_lds_dwordx4 v[198:199], off
	s_waitcnt lgkmcnt(8)
	s_barrier
	s_waitcnt lgkmcnt(0)
	v_mfma_f32_16x16x32_bf16 v[124:127], v[142:145], v[166:169], v[124:127]
	v_mfma_f32_16x16x32_bf16 v[120:123], v[158:161], v[166:169], v[120:123]
	v_mfma_f32_16x16x32_bf16 v[108:111], v[142:145], v[174:177], v[108:111]
	v_mfma_f32_16x16x32_bf16 v[104:107], v[158:161], v[174:177], v[104:107]
	v_mfma_f32_16x16x32_bf16 v[92:95], v[142:145], v[182:185], v[92:95]
	v_mfma_f32_16x16x32_bf16 v[88:91], v[158:161], v[182:185], v[88:91]
	v_mfma_f32_16x16x32_bf16 v[76:79], v[142:145], v[190:193], v[76:79]
	v_mfma_f32_16x16x32_bf16 v[72:75], v[158:161], v[190:193], v[72:75]
	v_mfma_f32_16x16x32_bf16 v[124:127], v[154:157], v[170:173], v[124:127]
	v_mfma_f32_16x16x32_bf16 v[120:123], v[162:165], v[170:173], v[120:123]
	v_mfma_f32_16x16x32_bf16 v[108:111], v[154:157], v[178:181], v[108:111]
	v_mfma_f32_16x16x32_bf16 v[104:107], v[162:165], v[178:181], v[104:107]
	v_mfma_f32_16x16x32_bf16 v[92:95], v[154:157], v[186:189], v[92:95]
	v_mfma_f32_16x16x32_bf16 v[88:91], v[162:165], v[186:189], v[88:91]
	v_mfma_f32_16x16x32_bf16 v[76:79], v[154:157], v[194:197], v[76:79]
	v_mfma_f32_16x16x32_bf16 v[72:75], v[162:165], v[194:197], v[72:75]
	s_barrier
	s_mov_b32 m0, s82
	v_lshl_add_u64 v[216:217], s[48:49], 0, v[130:131]
	ds_read_b128 v[198:201], v152
	ds_read_b128 v[204:207], v152 offset:1024
	ds_read_b128 v[208:211], v152 offset:2048
	ds_read_b128 v[212:215], v152 offset:3072
	global_load_lds_dwordx4 v[216:217], off
	v_lshl_add_u64 v[218:219], s[48:49], 0, v[136:137]
	s_mov_b32 m0, s81
	s_nop 0
	global_load_lds_dwordx4 v[218:219], off
	s_barrier
	s_waitcnt lgkmcnt(0)
	v_mfma_f32_16x16x32_bf16 v[116:119], v[198:201], v[166:169], v[116:119]
	v_mfma_f32_16x16x32_bf16 v[112:115], v[208:211], v[166:169], v[112:115]
	v_mfma_f32_16x16x32_bf16 v[100:103], v[198:201], v[174:177], v[100:103]
	v_mfma_f32_16x16x32_bf16 v[96:99], v[208:211], v[174:177], v[96:99]
	v_mfma_f32_16x16x32_bf16 v[84:87], v[198:201], v[182:185], v[84:87]
	v_mfma_f32_16x16x32_bf16 v[80:83], v[208:211], v[182:185], v[80:83]
	v_mfma_f32_16x16x32_bf16 v[68:71], v[198:201], v[190:193], v[68:71]
	v_mfma_f32_16x16x32_bf16 v[64:67], v[208:211], v[190:193], v[64:67]
	v_mfma_f32_16x16x32_bf16 v[116:119], v[204:207], v[170:173], v[116:119]
	v_mfma_f32_16x16x32_bf16 v[112:115], v[212:215], v[170:173], v[112:115]
	v_mfma_f32_16x16x32_bf16 v[100:103], v[204:207], v[178:181], v[100:103]
	v_mfma_f32_16x16x32_bf16 v[96:99], v[212:215], v[178:181], v[96:99]
	v_mfma_f32_16x16x32_bf16 v[84:87], v[204:207], v[186:189], v[84:87]
	v_mfma_f32_16x16x32_bf16 v[80:83], v[212:215], v[186:189], v[80:83]
	v_mfma_f32_16x16x32_bf16 v[68:71], v[204:207], v[194:197], v[68:71]
	v_mfma_f32_16x16x32_bf16 v[64:67], v[212:215], v[194:197], v[64:67]
	s_mov_b32 m0, s41
	v_lshl_add_u64 v[220:221], s[50:51], 0, v[128:129]
	s_barrier
	ds_read_b128 v[166:169], v151 offset:16384
	ds_read_b128 v[170:173], v151 offset:17408
	ds_read_b128 v[174:177], v151 offset:18432
	ds_read_b128 v[178:181], v151 offset:19456
	ds_read_b128 v[182:185], v151 offset:20480
	ds_read_b128 v[186:189], v151 offset:21504
	ds_read_b128 v[190:193], v151 offset:22528
	ds_read_b128 v[194:197], v151 offset:23552
	global_load_lds_dwordx4 v[220:221], off
	v_lshl_add_u64 v[222:223], s[50:51], 0, v[134:135]
	s_mov_b32 m0, s60
	s_nop 0
	global_load_lds_dwordx4 v[222:223], off
	s_barrier
	s_waitcnt lgkmcnt(0)
	v_mfma_f32_16x16x32_bf16 v[60:63], v[142:145], v[166:169], v[60:63]
	v_mfma_f32_16x16x32_bf16 v[56:59], v[158:161], v[166:169], v[56:59]
	v_mfma_f32_16x16x32_bf16 v[44:47], v[142:145], v[174:177], v[44:47]
	v_mfma_f32_16x16x32_bf16 v[40:43], v[158:161], v[174:177], v[40:43]
	v_mfma_f32_16x16x32_bf16 v[28:31], v[142:145], v[182:185], v[28:31]
	v_mfma_f32_16x16x32_bf16 v[24:27], v[158:161], v[182:185], v[24:27]
	v_mfma_f32_16x16x32_bf16 v[12:15], v[142:145], v[190:193], v[12:15]
	v_mfma_f32_16x16x32_bf16 v[8:11], v[158:161], v[190:193], v[8:11]
	v_mfma_f32_16x16x32_bf16 v[60:63], v[154:157], v[170:173], v[60:63]
	v_mfma_f32_16x16x32_bf16 v[56:59], v[162:165], v[170:173], v[56:59]
	v_mfma_f32_16x16x32_bf16 v[44:47], v[154:157], v[178:181], v[44:47]
	v_mfma_f32_16x16x32_bf16 v[40:43], v[162:165], v[178:181], v[40:43]
	v_mfma_f32_16x16x32_bf16 v[28:31], v[154:157], v[186:189], v[28:31]
	v_mfma_f32_16x16x32_bf16 v[24:27], v[162:165], v[186:189], v[24:27]
	v_mfma_f32_16x16x32_bf16 v[12:15], v[154:157], v[194:197], v[12:15]
	v_mfma_f32_16x16x32_bf16 v[8:11], v[162:165], v[194:197], v[8:11]
	s_barrier
; #define PG8_STAGE(bufoff, gbase, voff) do { _Pragma("unroll") for (int _i = 0; _i < 2; ++_i) \
;         __builtin_amdgcn_global_load_lds((const unsigned*)((const char*)(gbase) + (voff)[_i]), (LAS unsigned*)(lds + (bufoff) + ldsw + _i * 8192), 16, 0, 0); } while (0)
; #define PG8_LDA(dst, b, h) do { _Pragma("unroll") for (int m = 0; m < 4; ++m) _Pragma("unroll") for (int k = 0; k < 2; ++k) dst[m][k] = *(const LAS bf16x8*)(lds + PG8_SA(b, h) + aoff + m * 2048 + k * 1024); } while (0)
; #define PG8_WAIT_V(n) asm volatile("s_waitcnt vmcnt(" #n ")" ::: "memory")
; #define PG8_WAIT_L(n) asm volatile("s_waitcnt lgkmcnt(" #n ")" ::: "memory")
; template <class Epi>
; __device__ __forceinline__ void gemm_phase(LAS unsigned char* lds, const Gemm g, const StaticOrder& S, const Epi& E) {
;     ...
;         for (int t = 0; t < nt; t += 2) {
;             const bool last = (t == nt - 2);
;             const char* a1 = cA + (size_t)(t + 1) * kstep;
;             const char* a2 = last ? nA : cA + (size_t)(t + 2) * kstep; const char* b2 = last ? nB : cB + (size_t)(t + 2) * kstep;
;             const char* a3 = a2 + kstep; const char* b3 = b2 + kstep;
;             PG8_LDB(B0, 0, 0); PG8_SCHED; PG8_LDA(At, 0, 0); PG8_STAGE(PG8_SA(1, 1), a1 + hstep, voffA);
;             PG8_WAIT_L(8); PG8_BAR; PG8_WAIT_L(0); PG8_MMA(0, 0, At, B0); PG8_BAR; PG8_SCHED;
;             PG8_LDB(B1, 0, 1); PG8_STAGE(PG8_SB(0, 0), b2, voffB0);
;             PG8_BAR; PG8_WAIT_L(0); PG8_MMA(0, 1, At, B1); PG8_BAR;
;             PG8_LDA(At, 0, 1); PG8_STAGE(PG8_SA(0, 0), a2, voffA);
;             PG8_BAR; PG8_WAIT_L(0); PG8_MMA(1, 0, At, B0); PG8_BAR; PG8_SCHED;
;             PG8_STAGE(PG8_SB(0, 1), b2, voffB1);
;             PG8_WAIT_V(6); PG8_BAR; PG8_MMA(1, 1, At, B1); PG8_BAR;
;             PG8_LDB(B0, 1, 0); PG8_SCHED; PG8_LDA(At, 1, 0); PG8_STAGE(PG8_SA(0, 1), a2 + hstep, voffA);
;             PG8_WAIT_L(8); PG8_BAR; PG8_WAIT_L(0); PG8_MMA(0, 0, At, B0); PG8_BAR; PG8_SCHED;
;             PG8_LDB(B1, 1, 1); PG8_STAGE(PG8_SB(1, 0), b3, voffB0);
;             PG8_BAR; PG8_WAIT_L(0); PG8_MMA(0, 1, At, B1); PG8_BAR;
;             PG8_LDA(At, 1, 1); PG8_STAGE(PG8_SA(1, 0), a3, voffA);
;             PG8_BAR; PG8_WAIT_L(0); PG8_MMA(1, 0, At, B0); PG8_BAR; PG8_SCHED;
;             PG8_STAGE(PG8_SB(1, 1), b3, voffB1);
;             PG8_WAIT_V(6); PG8_BAR; PG8_MMA(1, 1, At, B1); PG8_BAR;
	s_mov_b32 m0, s78
	v_lshl_add_u64 v[224:225], s[48:49], 0, v[132:133]
	global_load_lds_dwordx4 v[224:225], off
	v_lshl_add_u64 v[226:227], s[48:49], 0, v[138:139]
	s_mov_b32 m0, s77
	s_nop 0
	global_load_lds_dwordx4 v[226:227], off
	s_waitcnt vmcnt(6)
	s_barrier
	v_mfma_f32_16x16x32_bf16 v[52:55], v[198:201], v[166:169], v[52:55]
	v_mfma_f32_16x16x32_bf16 v[48:51], v[208:211], v[166:169], v[48:51]
	v_mfma_f32_16x16x32_bf16 v[36:39], v[198:201], v[174:177], v[36:39]
	v_mfma_f32_16x16x32_bf16 v[32:35], v[208:211], v[174:177], v[32:35]
	v_mfma_f32_16x16x32_bf16 v[20:23], v[198:201], v[182:185], v[20:23]
	v_mfma_f32_16x16x32_bf16 v[16:19], v[208:211], v[182:185], v[16:19]
	v_mfma_f32_16x16x32_bf16 v[4:7], v[198:201], v[190:193], v[4:7]
	v_mfma_f32_16x16x32_bf16 v[0:3], v[208:211], v[190:193], v[0:3]
	v_mfma_f32_16x16x32_bf16 v[52:55], v[204:207], v[170:173], v[52:55]
	v_mfma_f32_16x16x32_bf16 v[48:51], v[212:215], v[170:173], v[48:51]
	v_mfma_f32_16x16x32_bf16 v[36:39], v[204:207], v[178:181], v[36:39]
	v_mfma_f32_16x16x32_bf16 v[32:35], v[212:215], v[178:181], v[32:35]
	v_mfma_f32_16x16x32_bf16 v[20:23], v[204:207], v[186:189], v[20:23]
	v_mfma_f32_16x16x32_bf16 v[16:19], v[212:215], v[186:189], v[16:19]
	v_mfma_f32_16x16x32_bf16 v[4:7], v[204:207], v[194:197], v[4:7]
	v_mfma_f32_16x16x32_bf16 v[0:3], v[212:215], v[194:197], v[0:3]
	v_add_u32_e32 v153, s76, v147
	s_barrier
	ds_read_b128 v[142:145], v153
	ds_read_b128 v[154:157], v153 offset:1024
	ds_read_b128 v[158:161], v153 offset:2048
	ds_read_b128 v[162:165], v153 offset:3072
	s_mov_b32 m0, s61
	v_lshl_add_u64 v[198:199], s[46:47], 0, v[128:129]
	ds_read_b128 v[166:169], v151 offset:32768
	ds_read_b128 v[170:173], v151 offset:33792
	ds_read_b128 v[174:177], v151 offset:34816
	ds_read_b128 v[178:181], v151 offset:35840
	ds_read_b128 v[182:185], v151 offset:36864
	ds_read_b128 v[186:189], v151 offset:37888
	ds_read_b128 v[190:193], v151 offset:38912
	ds_read_b128 v[194:197], v151 offset:39936
	global_load_lds_dwordx4 v[198:199], off
	v_lshl_add_u64 v[198:199], s[46:47], 0, v[134:135]
	s_mov_b32 m0, s62
	s_nop 0
	global_load_lds_dwordx4 v[198:199], off
	s_waitcnt lgkmcnt(8)
	s_barrier
	s_waitcnt lgkmcnt(0)
	v_mfma_f32_16x16x32_bf16 v[124:127], v[142:145], v[166:169], v[124:127]
	v_mfma_f32_16x16x32_bf16 v[120:123], v[158:161], v[166:169], v[120:123]
	v_mfma_f32_16x16x32_bf16 v[108:111], v[142:145], v[174:177], v[108:111]
	v_mfma_f32_16x16x32_bf16 v[104:107], v[158:161], v[174:177], v[104:107]
	v_mfma_f32_16x16x32_bf16 v[92:95], v[142:145], v[182:185], v[92:95]
	v_mfma_f32_16x16x32_bf16 v[88:91], v[158:161], v[182:185], v[88:91]
	v_mfma_f32_16x16x32_bf16 v[76:79], v[142:145], v[190:193], v[76:79]
	v_mfma_f32_16x16x32_bf16 v[72:75], v[158:161], v[190:193], v[72:75]
	v_mfma_f32_16x16x32_bf16 v[124:127], v[154:157], v[170:173], v[124:127]
	v_mfma_f32_16x16x32_bf16 v[120:123], v[162:165], v[170:173], v[120:123]
	v_mfma_f32_16x16x32_bf16 v[108:111], v[154:157], v[178:181], v[108:111]
	v_mfma_f32_16x16x32_bf16 v[104:107], v[162:165], v[178:181], v[104:107]
	v_mfma_f32_16x16x32_bf16 v[92:95], v[154:157], v[186:189], v[92:95]
	v_mfma_f32_16x16x32_bf16 v[88:91], v[162:165], v[186:189], v[88:91]
	v_mfma_f32_16x16x32_bf16 v[76:79], v[154:157], v[194:197], v[76:79]
	v_mfma_f32_16x16x32_bf16 v[72:75], v[162:165], v[194:197], v[72:75]
	s_barrier
	s_mov_b32 m0, s75
	v_add_u32_e32 v153, s74, v147
	v_lshl_add_u64 v[216:217], v[216:217], 0, s[18:19]
	ds_read_b128 v[198:201], v153
	ds_read_b128 v[204:207], v153 offset:1024
	ds_read_b128 v[208:211], v153 offset:2048
	ds_read_b128 v[212:215], v153 offset:3072
	global_load_lds_dwordx4 v[216:217], off
	v_lshl_add_u64 v[216:217], v[218:219], 0, s[18:19]
	s_mov_b32 m0, s83
	s_nop 0
	global_load_lds_dwordx4 v[216:217], off
	s_barrier
	s_waitcnt lgkmcnt(0)
	v_mfma_f32_16x16x32_bf16 v[116:119], v[198:201], v[166:169], v[116:119]
	v_mfma_f32_16x16x32_bf16 v[112:115], v[208:211], v[166:169], v[112:115]
	v_mfma_f32_16x16x32_bf16 v[100:103], v[198:201], v[174:177], v[100:103]
	v_mfma_f32_16x16x32_bf16 v[96:99], v[208:211], v[174:177], v[96:99]
	v_mfma_f32_16x16x32_bf16 v[84:87], v[198:201], v[182:185], v[84:87]
	v_mfma_f32_16x16x32_bf16 v[80:83], v[208:211], v[182:185], v[80:83]
	v_mfma_f32_16x16x32_bf16 v[68:71], v[198:201], v[190:193], v[68:71]
	v_mfma_f32_16x16x32_bf16 v[64:67], v[208:211], v[190:193], v[64:67]
	v_mfma_f32_16x16x32_bf16 v[116:119], v[204:207], v[170:173], v[116:119]
	v_mfma_f32_16x16x32_bf16 v[112:115], v[212:215], v[170:173], v[112:115]
	v_mfma_f32_16x16x32_bf16 v[100:103], v[204:207], v[178:181], v[100:103]
	v_mfma_f32_16x16x32_bf16 v[96:99], v[212:215], v[178:181], v[96:99]
	v_mfma_f32_16x16x32_bf16 v[84:87], v[204:207], v[186:189], v[84:87]
	v_mfma_f32_16x16x32_bf16 v[80:83], v[212:215], v[186:189], v[80:83]
	v_mfma_f32_16x16x32_bf16 v[68:71], v[204:207], v[194:197], v[68:71]
	v_mfma_f32_16x16x32_bf16 v[64:67], v[212:215], v[194:197], v[64:67]
	s_mov_b32 m0, s64
	v_lshl_add_u64 v[216:217], v[220:221], 0, s[18:19]
	s_barrier
	ds_read_b128 v[166:169], v151 offset:49152
	ds_read_b128 v[170:173], v151 offset:50176
	ds_read_b128 v[174:177], v151 offset:51200
	ds_read_b128 v[178:181], v151 offset:52224
	ds_read_b128 v[182:185], v151 offset:53248
	ds_read_b128 v[186:189], v151 offset:54272
	ds_read_b128 v[190:193], v151 offset:55296
	ds_read_b128 v[194:197], v151 offset:56320
	global_load_lds_dwordx4 v[216:217], off
	v_lshl_add_u64 v[216:217], v[222:223], 0, s[18:19]
	s_mov_b32 m0, s65
	s_nop 0
	global_load_lds_dwordx4 v[216:217], off
	s_barrier
; __device__ __forceinline__ unsigned cvt_pk_bf16(float lo, float hi) { unsigned r; asm volatile("v_cvt_pk_bf16_f32 %0, %1, %2" : "=v"(r) : "v"(lo), "v"(hi)); return r; }
; #define PG8_WAIT_V(n) asm volatile("s_waitcnt vmcnt(" #n ")" ::: "memory")
;     __device__ __forceinline__ void operator()(const f32x4 (&acc)[2][2][4][2], const Unit& u, int wr, int wc, int fr, int fq) const {
;     ...
;             for (int m = 0; m < 4; ++m) { const int row = row0 + ai * HALF + m * 16;
;                 const float rs = ssin ? __builtin_amdgcn_rsqf(ssin[row] * (1.f / D) + EPS) : 1.0f; float sq = 0.f; u32x4 w[2];
; #pragma unroll
;                 for (int bj = 0; bj < 2; ++bj) { f32x4 v0 = acc[ai][bj][m][0] * rs, v1 = acc[ai][bj][m][1] * rs;
;                     if (ACT == 1) {
; #pragma unroll
;                         for (int j = 0; j < 4; ++j) { const float a = fmaxf(v0[j], 0.f), b = fmaxf(v1[j], 0.f); v0[j] = a * a; v1[j] = b * b; } }
;                     sq += (v0[0] * v0[0] + v0[1] * v0[1]) + (v0[2] * v0[2] + v0[3] * v0[3]) + (v1[0] * v1[0] + v1[1] * v1[1]) + (v1[2] * v1[2] + v1[3] * v1[3]);
;                     w[bj].x = cvt_pk_bf16(v0[0], v0[1]); w[bj].y = cvt_pk_bf16(v0[2], v0[3]); w[bj].z = cvt_pk_bf16(v1[0], v1[1]); w[bj].w = cvt_pk_bf16(v1[2], v1[3]); }
;                 store_pair_lines(O, ldc, row, fr, col0, w[0], w[1]);
;                 if (ssout) { sq += __shfl_xor(sq, 16); sq += __shfl_xor(sq, 32); if (fq == 0) unsafeAtomicAdd(ssout + row, sq); } }
; template <class Epi>
; __device__ __forceinline__ void gemm_phase(LAS unsigned char* lds, const Gemm g, const StaticOrder& S, const Epi& E) {
;     ...
;             PG8_WAIT_V(6); PG8_BAR; PG8_MMA(1, 1, At, B1); PG8_BAR;
;             PG8_LDB(B0, 1, 0); PG8_SCHED; PG8_LDA(At, 1, 0); PG8_STAGE(PG8_SA(0, 1), a2 + hstep, voffA);
;             PG8_WAIT_L(8); PG8_BAR; PG8_WAIT_L(0); PG8_MMA(0, 0, At, B0); PG8_BAR; PG8_SCHED;
;             PG8_LDB(B1, 1, 1); PG8_STAGE(PG8_SB(1, 0), b3, voffB0);
;             PG8_BAR; PG8_WAIT_L(0); PG8_MMA(0, 1, At, B1); PG8_BAR;
;             PG8_LDA(At, 1, 1); PG8_STAGE(PG8_SA(1, 0), a3, voffA);
;             PG8_BAR; PG8_WAIT_L(0); PG8_MMA(1, 0, At, B0); PG8_BAR; PG8_SCHED;
;             PG8_STAGE(PG8_SB(1, 1), b3, voffB1);
;             PG8_WAIT_V(6); PG8_BAR; PG8_MMA(1, 1, At, B1); PG8_BAR;
;         }
;         E(acc, cur, wr, wc, fr, fq);
	s_waitcnt lgkmcnt(0)
	v_mfma_f32_16x16x32_bf16 v[60:63], v[142:145], v[166:169], v[60:63]
	v_mfma_f32_16x16x32_bf16 v[56:59], v[158:161], v[166:169], v[56:59]
	v_mfma_f32_16x16x32_bf16 v[44:47], v[142:145], v[174:177], v[44:47]
	v_mfma_f32_16x16x32_bf16 v[40:43], v[158:161], v[174:177], v[40:43]
	v_mfma_f32_16x16x32_bf16 v[28:31], v[142:145], v[182:185], v[28:31]
	v_mfma_f32_16x16x32_bf16 v[24:27], v[158:161], v[182:185], v[24:27]
	v_mfma_f32_16x16x32_bf16 v[12:15], v[142:145], v[190:193], v[12:15]
	v_mfma_f32_16x16x32_bf16 v[8:11], v[158:161], v[190:193], v[8:11]
	v_mfma_f32_16x16x32_bf16 v[60:63], v[154:157], v[170:173], v[60:63]
	v_mfma_f32_16x16x32_bf16 v[56:59], v[162:165], v[170:173], v[56:59]
	v_mfma_f32_16x16x32_bf16 v[44:47], v[154:157], v[178:181], v[44:47]
	v_mfma_f32_16x16x32_bf16 v[40:43], v[162:165], v[178:181], v[40:43]
	v_mfma_f32_16x16x32_bf16 v[28:31], v[154:157], v[186:189], v[28:31]
	v_mfma_f32_16x16x32_bf16 v[24:27], v[162:165], v[186:189], v[24:27]
	v_mfma_f32_16x16x32_bf16 v[12:15], v[154:157], v[194:197], v[12:15]
	v_mfma_f32_16x16x32_bf16 v[8:11], v[162:165], v[194:197], v[8:11]
	s_barrier
	s_mov_b32 m0, s80
	v_lshl_add_u64 v[142:143], v[224:225], 0, s[18:19]
	global_load_lds_dwordx4 v[142:143], off
	v_lshl_add_u64 v[142:143], v[226:227], 0, s[18:19]
	s_mov_b32 m0, s79
	s_nop 0
	global_load_lds_dwordx4 v[142:143], off
	s_waitcnt vmcnt(6)
	s_barrier
	v_mfma_f32_16x16x32_bf16 v[52:55], v[198:201], v[166:169], v[52:55]
	v_mfma_f32_16x16x32_bf16 v[48:51], v[208:211], v[166:169], v[48:51]
	v_mfma_f32_16x16x32_bf16 v[36:39], v[198:201], v[174:177], v[36:39]
	v_mfma_f32_16x16x32_bf16 v[32:35], v[208:211], v[174:177], v[32:35]
	v_mfma_f32_16x16x32_bf16 v[20:23], v[198:201], v[182:185], v[20:23]
	v_mfma_f32_16x16x32_bf16 v[16:19], v[208:211], v[182:185], v[16:19]
	v_mfma_f32_16x16x32_bf16 v[4:7], v[198:201], v[190:193], v[4:7]
	v_mfma_f32_16x16x32_bf16 v[0:3], v[208:211], v[190:193], v[0:3]
	v_mfma_f32_16x16x32_bf16 v[52:55], v[204:207], v[170:173], v[52:55]
	v_mfma_f32_16x16x32_bf16 v[48:51], v[212:215], v[170:173], v[48:51]
	v_mfma_f32_16x16x32_bf16 v[36:39], v[204:207], v[178:181], v[36:39]
	v_mfma_f32_16x16x32_bf16 v[32:35], v[212:215], v[178:181], v[32:35]
	v_mfma_f32_16x16x32_bf16 v[20:23], v[204:207], v[186:189], v[20:23]
	v_mfma_f32_16x16x32_bf16 v[16:19], v[212:215], v[186:189], v[16:19]
	v_mfma_f32_16x16x32_bf16 v[4:7], v[204:207], v[194:197], v[4:7]
	v_mfma_f32_16x16x32_bf16 v[0:3], v[212:215], v[194:197], v[0:3]
	s_movk_i32 s52, 0x100
	s_mov_b64 s[48:49], 0
	s_mov_b64 s[46:47], -1
	s_barrier
	s_cbranch_vccz .LBB0_1277
	v_cvt_pk_bf16_f32 v145, v124, v125
	v_cvt_pk_bf16_f32 v153, v126, v127
	v_cvt_pk_bf16_f32 v156, v120, v121
	v_cvt_pk_bf16_f32 v157, v122, v123
	v_cvt_pk_bf16_f32 v158, v116, v117
	v_cvt_pk_bf16_f32 v159, v118, v119
	v_cvt_pk_bf16_f32 v160, v112, v113
	v_cvt_pk_bf16_f32 v161, v114, v115
	v_mul_f32_e32 v123, v123, v123
	v_mul_f32_e32 v115, v115, v115
	v_fmac_f32_e32 v123, v122, v122
	v_mul_f32_e32 v122, v125, v125
	v_fmac_f32_e32 v115, v114, v114
	v_mul_f32_e32 v114, v117, v117
	v_fmac_f32_e32 v122, v124, v124
	v_mul_f32_e32 v124, v127, v127
	v_fmac_f32_e32 v114, v116, v116
	v_mul_f32_e32 v116, v119, v119
	v_fmac_f32_e32 v124, v126, v126
	v_mul_f32_e32 v121, v121, v121
	v_fmac_f32_e32 v116, v118, v118
	v_mul_f32_e32 v113, v113, v113
	v_add_f32_e32 v122, v122, v124
	v_fmac_f32_e32 v121, v120, v120
	v_add_f32_e32 v114, v114, v116
	v_fmac_f32_e32 v113, v112, v112
	v_add_f32_e32 v120, v122, v121
	v_add_f32_e32 v112, v114, v113
	s_lshl_b32 s27, s40, 8
	v_add_f32_e32 v120, v123, v120
	v_add_f32_e32 v112, v115, v112
	v_and_b32_e32 v113, 64, v203
	s_add_i32 s27, s27, s66
	v_mov_b32_dpp v162, v145 row_ror:8 row_mask:0xf bank_mask:0xf
	v_add_f32_e32 v115, v120, v112
	v_xor_b32_e32 v112, 16, v203
	v_add_u32_e32 v118, 64, v113
	v_mov_b32_dpp v163, v153 row_ror:8 row_mask:0xf bank_mask:0xf
	v_mov_b32_dpp v154, v158 row_ror:8 row_mask:0xf bank_mask:0xf
	v_cndmask_b32_e64 v158, v158, v162, s[6:7]
	v_or_b32_e32 v162, s27, v148
	v_cmp_lt_i32_e32 vcc, v112, v118
	v_lshl_or_b32 v142, s38, 8, v149
	v_mov_b32_dpp v164, v156 row_ror:8 row_mask:0xf bank_mask:0xf
	v_mov_b32_dpp v165, v157 row_ror:8 row_mask:0xf bank_mask:0xf
	v_mov_b32_dpp v155, v159 row_ror:8 row_mask:0xf bank_mask:0xf
	v_cndmask_b32_e64 v159, v159, v163, s[6:7]
	v_ashrrev_i32_e32 v163, 31, v162
	v_cndmask_b32_e32 v112, v203, v112, vcc
	v_ashrrev_i32_e32 v143, 31, v142
	v_mov_b32_dpp v166, v160 row_ror:8 row_mask:0xf bank_mask:0xf
	v_mov_b32_dpp v167, v161 row_ror:8 row_mask:0xf bank_mask:0xf
	v_cndmask_b32_e64 v160, v160, v164, s[6:7]
	v_cndmask_b32_e64 v161, v161, v165, s[6:7]
	v_lshlrev_b64 v[164:165], 12, v[162:163]
	v_lshlrev_b32_e32 v114, 2, v112
	v_cndmask_b32_e64 v156, v166, v156, s[6:7]
	v_cndmask_b32_e64 v157, v167, v157, s[6:7]
	v_lshl_add_u64 v[164:165], s[10:11], 0, v[164:165]
	v_lshlrev_b64 v[166:167], 1, v[142:143]
	v_mov_b32_e32 v119, v115
	s_nop 1
	v_permlane16_swap_b32_e32 v119, v115
	v_cndmask_b32_e64 v154, v154, v145, s[6:7]
	v_cndmask_b32_e64 v155, v155, v153, s[6:7]
	v_lshl_add_u64 v[112:113], v[164:165], 0, v[166:167]
	global_store_dwordx4 v[112:113], v[154:157], off
	v_xor_b32_e32 v113, 32, v203
	v_cmp_lt_i32_e32 vcc, v113, v118
	s_waitcnt lgkmcnt(0)
	v_add_f32_e32 v112, v115, v119
	v_or_b32_e32 v116, 8, v162
	v_cndmask_b32_e32 v113, v203, v113, vcc
	v_lshlrev_b32_e32 v115, 2, v113
	v_mov_b32_e32 v113, v112
	s_nop 1
	v_permlane32_swap_b32_e32 v113, v112
	v_ashrrev_i32_e32 v117, 31, v116
	v_lshlrev_b64 v[116:117], 12, v[116:117]
	v_lshl_add_u64 v[116:117], s[10:11], 0, v[116:117]
	v_or_b32_e32 v144, s27, v146
	v_lshl_add_u64 v[116:117], v[116:117], 0, v[166:167]
	global_store_dwordx4 v[116:117], v[158:161], off
	s_and_saveexec_b64 s[38:39], s[8:9]
	s_cbranch_execz .LBB0_1280
	v_ashrrev_i32_e32 v145, 31, v144
	s_waitcnt lgkmcnt(0)
	v_add_f32_e32 v116, v112, v113
	v_lshl_add_u64 v[112:113], v[144:145], 2, s[16:17]
	global_atomic_add_f32 v[112:113], v116, off
; __device__ __forceinline__ unsigned cvt_pk_bf16(float lo, float hi) { unsigned r; asm volatile("v_cvt_pk_bf16_f32 %0, %1, %2" : "=v"(r) : "v"(lo), "v"(hi)); return r; }
;     __device__ __forceinline__ void operator()(const f32x4 (&acc)[2][2][4][2], const Unit& u, int wr, int wc, int fr, int fq) const {
;     ...
;             for (int m = 0; m < 4; ++m) { const int row = row0 + ai * HALF + m * 16;
;                 const float rs = ssin ? __builtin_amdgcn_rsqf(ssin[row] * (1.f / D) + EPS) : 1.0f; float sq = 0.f; u32x4 w[2];
; #pragma unroll
;                 for (int bj = 0; bj < 2; ++bj) { f32x4 v0 = acc[ai][bj][m][0] * rs, v1 = acc[ai][bj][m][1] * rs;
;                     if (ACT == 1) {
; #pragma unroll
;                         for (int j = 0; j < 4; ++j) { const float a = fmaxf(v0[j], 0.f), b = fmaxf(v1[j], 0.f); v0[j] = a * a; v1[j] = b * b; } }
;                     sq += (v0[0] * v0[0] + v0[1] * v0[1]) + (v0[2] * v0[2] + v0[3] * v0[3]) + (v1[0] * v1[0] + v1[1] * v1[1]) + (v1[2] * v1[2] + v1[3] * v1[3]);
;                     w[bj].x = cvt_pk_bf16(v0[0], v0[1]); w[bj].y = cvt_pk_bf16(v0[2], v0[3]); w[bj].z = cvt_pk_bf16(v1[0], v1[1]); w[bj].w = cvt_pk_bf16(v1[2], v1[3]); }
;                 store_pair_lines(O, ldc, row, fr, col0, w[0], w[1]);
;                 if (ssout) { sq += __shfl_xor(sq, 16); sq += __shfl_xor(sq, 32); if (fq == 0) unsafeAtomicAdd(ssout + row, sq); } }
.LBB0_1280:
	s_or_b64 exec, exec, s[38:39]
	s_waitcnt lgkmcnt(0)
	v_cvt_pk_bf16_f32 v113, v108, v109
	v_cvt_pk_bf16_f32 v117, v110, v111
	v_cvt_pk_bf16_f32 v118, v104, v105
	v_cvt_pk_bf16_f32 v119, v106, v107
	v_cvt_pk_bf16_f32 v120, v100, v101
	v_cvt_pk_bf16_f32 v121, v102, v103
	v_cvt_pk_bf16_f32 v122, v96, v97
	v_cvt_pk_bf16_f32 v123, v98, v99
	v_mul_f32_e32 v107, v107, v107
	v_mul_f32_e32 v99, v99, v99
	v_fmac_f32_e32 v107, v106, v106
	v_mul_f32_e32 v106, v109, v109
	v_fmac_f32_e32 v99, v98, v98
	v_mul_f32_e32 v98, v101, v101
	v_fmac_f32_e32 v106, v108, v108
	v_mul_f32_e32 v108, v111, v111
	v_fmac_f32_e32 v98, v100, v100
	v_mul_f32_e32 v100, v103, v103
	v_fmac_f32_e32 v108, v110, v110
	v_mul_f32_e32 v105, v105, v105
	v_fmac_f32_e32 v100, v102, v102
	v_mul_f32_e32 v97, v97, v97
	v_add_f32_e32 v106, v106, v108
	v_fmac_f32_e32 v105, v104, v104
	v_add_f32_e32 v98, v98, v100
	v_fmac_f32_e32 v97, v96, v96
	v_add_f32_e32 v104, v106, v105
	v_add_f32_e32 v96, v98, v97
	v_add_f32_e32 v104, v107, v104
	v_add_f32_e32 v96, v99, v96
	v_or_b32_e32 v112, 16, v144
	v_mov_b32_dpp v116, v120 row_ror:8 row_mask:0xf bank_mask:0xf
	v_add_f32_e32 v100, v104, v96
	v_mov_b32_dpp v124, v113 row_ror:8 row_mask:0xf bank_mask:0xf
	v_cndmask_b32_e64 v116, v116, v113, s[6:7]
	v_sub_u32_e32 v113, v112, v146
	v_mov_b32_e32 v101, v100
	s_nop 1
	v_permlane16_swap_b32_e32 v101, v100
	v_mov_b32_dpp v125, v117 row_ror:8 row_mask:0xf bank_mask:0xf
	v_cndmask_b32_e64 v120, v120, v124, s[6:7]
	v_add_u32_e32 v124, v113, v148
	v_mov_b32_dpp v145, v121 row_ror:8 row_mask:0xf bank_mask:0xf
	v_cndmask_b32_e64 v121, v121, v125, s[6:7]
	v_ashrrev_i32_e32 v125, 31, v124
	v_lshlrev_b64 v[96:97], 12, v[124:125]
	v_lshl_add_u64 v[96:97], s[10:11], 0, v[96:97]
	v_lshl_add_u64 v[98:99], v[142:143], 1, v[96:97]
	s_waitcnt lgkmcnt(0)
	v_add_f32_e32 v96, v100, v101
	v_mov_b32_e32 v97, v96
	s_nop 1
	v_permlane32_swap_b32_e32 v97, v96
	v_mov_b32_dpp v153, v122 row_ror:8 row_mask:0xf bank_mask:0xf
	v_mov_b32_dpp v154, v123 row_ror:8 row_mask:0xf bank_mask:0xf
	v_mov_b32_dpp v126, v118 row_ror:8 row_mask:0xf bank_mask:0xf
	v_mov_b32_dpp v127, v119 row_ror:8 row_mask:0xf bank_mask:0xf
	v_cndmask_b32_e64 v117, v145, v117, s[6:7]
	v_cndmask_b32_e64 v118, v153, v118, s[6:7]
	v_cndmask_b32_e64 v119, v154, v119, s[6:7]
	global_store_dwordx4 v[98:99], v[116:119], off
	v_add_co_u32_e32 v98, vcc, s67, v98
	v_cndmask_b32_e64 v122, v122, v126, s[6:7]
	v_cndmask_b32_e64 v123, v123, v127, s[6:7]
	v_addc_co_u32_e32 v99, vcc, 0, v99, vcc
	global_store_dwordx4 v[98:99], v[120:123], off
	s_and_saveexec_b64 s[38:39], s[8:9]
	s_cbranch_execz .LBB0_1282
	v_ashrrev_i32_e32 v113, 31, v112
	s_waitcnt lgkmcnt(0)
	v_add_f32_e32 v98, v96, v97
	v_lshl_add_u64 v[96:97], v[112:113], 2, s[16:17]
	global_atomic_add_f32 v[96:97], v98, off
.LBB0_1282:
	s_or_b64 exec, exec, s[38:39]
	s_waitcnt lgkmcnt(0)
	v_cvt_pk_bf16_f32 v97, v92, v93
	v_cvt_pk_bf16_f32 v99, v94, v95
	v_cvt_pk_bf16_f32 v100, v88, v89
	v_cvt_pk_bf16_f32 v101, v90, v91
	v_cvt_pk_bf16_f32 v102, v84, v85
	v_cvt_pk_bf16_f32 v103, v86, v87
	v_cvt_pk_bf16_f32 v104, v80, v81
	v_cvt_pk_bf16_f32 v105, v82, v83
	v_mul_f32_e32 v91, v91, v91
	v_mul_f32_e32 v83, v83, v83
	v_fmac_f32_e32 v91, v90, v90
	v_mul_f32_e32 v90, v93, v93
	v_fmac_f32_e32 v83, v82, v82
	v_mul_f32_e32 v82, v85, v85
	v_fmac_f32_e32 v90, v92, v92
	v_mul_f32_e32 v92, v95, v95
	v_fmac_f32_e32 v82, v84, v84
	v_mul_f32_e32 v84, v87, v87
	v_fmac_f32_e32 v92, v94, v94
	v_mul_f32_e32 v89, v89, v89
	v_fmac_f32_e32 v84, v86, v86
	v_mul_f32_e32 v81, v81, v81
	v_add_f32_e32 v90, v90, v92
	v_fmac_f32_e32 v89, v88, v88
	v_add_f32_e32 v82, v82, v84
	v_fmac_f32_e32 v81, v80, v80
	v_add_f32_e32 v88, v90, v89
	v_add_f32_e32 v80, v82, v81
	v_add_f32_e32 v88, v91, v88
	v_add_f32_e32 v80, v83, v80
	v_or_b32_e32 v96, 32, v144
	v_mov_b32_dpp v98, v102 row_ror:8 row_mask:0xf bank_mask:0xf
	v_add_f32_e32 v84, v88, v80
	v_mov_b32_dpp v106, v97 row_ror:8 row_mask:0xf bank_mask:0xf
	v_cndmask_b32_e64 v98, v98, v97, s[6:7]
	v_sub_u32_e32 v97, v96, v146
	v_mov_b32_e32 v85, v84
	s_nop 1
	v_permlane16_swap_b32_e32 v85, v84
	v_mov_b32_dpp v107, v99 row_ror:8 row_mask:0xf bank_mask:0xf
	v_cndmask_b32_e64 v102, v102, v106, s[6:7]
	v_add_u32_e32 v106, v97, v148
	v_mov_b32_dpp v110, v103 row_ror:8 row_mask:0xf bank_mask:0xf
	v_cndmask_b32_e64 v103, v103, v107, s[6:7]
	v_ashrrev_i32_e32 v107, 31, v106
	v_lshlrev_b64 v[80:81], 12, v[106:107]
	v_lshl_add_u64 v[80:81], s[10:11], 0, v[80:81]
	v_lshl_add_u64 v[82:83], v[142:143], 1, v[80:81]
	s_waitcnt lgkmcnt(0)
	v_add_f32_e32 v80, v84, v85
	v_mov_b32_e32 v81, v80
	s_nop 1
	v_permlane32_swap_b32_e32 v81, v80
	v_mov_b32_dpp v111, v104 row_ror:8 row_mask:0xf bank_mask:0xf
	v_mov_b32_dpp v112, v105 row_ror:8 row_mask:0xf bank_mask:0xf
	v_mov_b32_dpp v108, v100 row_ror:8 row_mask:0xf bank_mask:0xf
	v_mov_b32_dpp v109, v101 row_ror:8 row_mask:0xf bank_mask:0xf
	v_cndmask_b32_e64 v99, v110, v99, s[6:7]
	v_cndmask_b32_e64 v100, v111, v100, s[6:7]
	v_cndmask_b32_e64 v101, v112, v101, s[6:7]
	global_store_dwordx4 v[82:83], v[98:101], off
	v_add_co_u32_e32 v82, vcc, s67, v82
	v_cndmask_b32_e64 v104, v104, v108, s[6:7]
	v_cndmask_b32_e64 v105, v105, v109, s[6:7]
	v_addc_co_u32_e32 v83, vcc, 0, v83, vcc
	global_store_dwordx4 v[82:83], v[102:105], off
	s_and_saveexec_b64 s[38:39], s[8:9]
	s_cbranch_execz .LBB0_1284
	v_ashrrev_i32_e32 v97, 31, v96
	s_waitcnt lgkmcnt(0)
	v_add_f32_e32 v82, v80, v81
	v_lshl_add_u64 v[80:81], v[96:97], 2, s[16:17]
	global_atomic_add_f32 v[80:81], v82, off
; __device__ __forceinline__ unsigned cvt_pk_bf16(float lo, float hi) { unsigned r; asm volatile("v_cvt_pk_bf16_f32 %0, %1, %2" : "=v"(r) : "v"(lo), "v"(hi)); return r; }
;     __device__ __forceinline__ void operator()(const f32x4 (&acc)[2][2][4][2], const Unit& u, int wr, int wc, int fr, int fq) const {
;     ...
;             for (int m = 0; m < 4; ++m) { const int row = row0 + ai * HALF + m * 16;
;                 const float rs = ssin ? __builtin_amdgcn_rsqf(ssin[row] * (1.f / D) + EPS) : 1.0f; float sq = 0.f; u32x4 w[2];
; #pragma unroll
;                 for (int bj = 0; bj < 2; ++bj) { f32x4 v0 = acc[ai][bj][m][0] * rs, v1 = acc[ai][bj][m][1] * rs;
;                     if (ACT == 1) {
; #pragma unroll
;                         for (int j = 0; j < 4; ++j) { const float a = fmaxf(v0[j], 0.f), b = fmaxf(v1[j], 0.f); v0[j] = a * a; v1[j] = b * b; } }
;                     sq += (v0[0] * v0[0] + v0[1] * v0[1]) + (v0[2] * v0[2] + v0[3] * v0[3]) + (v1[0] * v1[0] + v1[1] * v1[1]) + (v1[2] * v1[2] + v1[3] * v1[3]);
;                     w[bj].x = cvt_pk_bf16(v0[0], v0[1]); w[bj].y = cvt_pk_bf16(v0[2], v0[3]); w[bj].z = cvt_pk_bf16(v1[0], v1[1]); w[bj].w = cvt_pk_bf16(v1[2], v1[3]); }
;                 store_pair_lines(O, ldc, row, fr, col0, w[0], w[1]);
;                 if (ssout) { sq += __shfl_xor(sq, 16); sq += __shfl_xor(sq, 32); if (fq == 0) unsafeAtomicAdd(ssout + row, sq); } }
.LBB0_1284:
	s_or_b64 exec, exec, s[38:39]
	s_waitcnt lgkmcnt(0)
	v_cvt_pk_bf16_f32 v81, v76, v77
	v_cvt_pk_bf16_f32 v83, v78, v79
	v_cvt_pk_bf16_f32 v84, v72, v73
	v_cvt_pk_bf16_f32 v85, v74, v75
	v_cvt_pk_bf16_f32 v86, v68, v69
	v_cvt_pk_bf16_f32 v87, v70, v71
	v_cvt_pk_bf16_f32 v88, v64, v65
	v_cvt_pk_bf16_f32 v89, v66, v67
	v_mul_f32_e32 v75, v75, v75
	v_mul_f32_e32 v67, v67, v67
	v_fmac_f32_e32 v75, v74, v74
	v_mul_f32_e32 v74, v77, v77
	v_fmac_f32_e32 v67, v66, v66
	v_mul_f32_e32 v66, v69, v69
	v_fmac_f32_e32 v74, v76, v76
	v_mul_f32_e32 v76, v79, v79
	v_fmac_f32_e32 v66, v68, v68
	v_mul_f32_e32 v68, v71, v71
	v_fmac_f32_e32 v76, v78, v78
	v_mul_f32_e32 v73, v73, v73
	v_fmac_f32_e32 v68, v70, v70
	v_mul_f32_e32 v65, v65, v65
	v_add_f32_e32 v74, v74, v76
	v_fmac_f32_e32 v73, v72, v72
	v_add_f32_e32 v66, v66, v68
	v_fmac_f32_e32 v65, v64, v64
	v_add_f32_e32 v72, v74, v73
	v_add_f32_e32 v64, v66, v65
	v_add_f32_e32 v72, v75, v72
	v_add_f32_e32 v64, v67, v64
	v_or_b32_e32 v80, 48, v144
	v_mov_b32_dpp v82, v86 row_ror:8 row_mask:0xf bank_mask:0xf
	v_add_f32_e32 v68, v72, v64
	v_mov_b32_dpp v90, v81 row_ror:8 row_mask:0xf bank_mask:0xf
	v_cndmask_b32_e64 v82, v82, v81, s[6:7]
	v_sub_u32_e32 v81, v80, v146
	v_mov_b32_e32 v69, v68
	s_nop 1
	v_permlane16_swap_b32_e32 v69, v68
	v_mov_b32_dpp v91, v83 row_ror:8 row_mask:0xf bank_mask:0xf
	v_cndmask_b32_e64 v86, v86, v90, s[6:7]
	v_add_u32_e32 v90, v81, v148
	v_mov_b32_dpp v94, v87 row_ror:8 row_mask:0xf bank_mask:0xf
	v_cndmask_b32_e64 v87, v87, v91, s[6:7]
	v_ashrrev_i32_e32 v91, 31, v90
	v_lshlrev_b64 v[64:65], 12, v[90:91]
	v_lshl_add_u64 v[64:65], s[10:11], 0, v[64:65]
	v_lshl_add_u64 v[66:67], v[142:143], 1, v[64:65]
	s_waitcnt lgkmcnt(0)
	v_add_f32_e32 v64, v68, v69
	v_mov_b32_e32 v65, v64
	s_nop 1
	v_permlane32_swap_b32_e32 v65, v64
	v_mov_b32_dpp v95, v88 row_ror:8 row_mask:0xf bank_mask:0xf
	v_mov_b32_dpp v96, v89 row_ror:8 row_mask:0xf bank_mask:0xf
	v_mov_b32_dpp v92, v84 row_ror:8 row_mask:0xf bank_mask:0xf
	v_mov_b32_dpp v93, v85 row_ror:8 row_mask:0xf bank_mask:0xf
	v_cndmask_b32_e64 v83, v94, v83, s[6:7]
	v_cndmask_b32_e64 v84, v95, v84, s[6:7]
	v_cndmask_b32_e64 v85, v96, v85, s[6:7]
	global_store_dwordx4 v[66:67], v[82:85], off
	v_add_co_u32_e32 v66, vcc, s67, v66
	v_cndmask_b32_e64 v88, v88, v92, s[6:7]
	v_cndmask_b32_e64 v89, v89, v93, s[6:7]
	v_addc_co_u32_e32 v67, vcc, 0, v67, vcc
	global_store_dwordx4 v[66:67], v[86:89], off
	s_and_saveexec_b64 s[38:39], s[8:9]
	s_cbranch_execz .LBB0_1286
	v_ashrrev_i32_e32 v81, 31, v80
	s_waitcnt lgkmcnt(0)
	v_add_f32_e32 v66, v64, v65
	v_lshl_add_u64 v[64:65], v[80:81], 2, s[16:17]
	global_atomic_add_f32 v[64:65], v66, off
.LBB0_1286:
	s_or_b64 exec, exec, s[38:39]
	s_waitcnt lgkmcnt(0)
	v_cvt_pk_bf16_f32 v65, v60, v61
	v_cvt_pk_bf16_f32 v67, v62, v63
	v_cvt_pk_bf16_f32 v68, v56, v57
	v_cvt_pk_bf16_f32 v69, v58, v59
	v_cvt_pk_bf16_f32 v70, v52, v53
	v_cvt_pk_bf16_f32 v71, v54, v55
	v_cvt_pk_bf16_f32 v72, v48, v49
	v_cvt_pk_bf16_f32 v73, v50, v51
	v_mul_f32_e32 v59, v59, v59
	v_mul_f32_e32 v51, v51, v51
	v_fmac_f32_e32 v59, v58, v58
	v_mul_f32_e32 v58, v61, v61
	v_fmac_f32_e32 v51, v50, v50
	v_mul_f32_e32 v50, v53, v53
	v_fmac_f32_e32 v58, v60, v60
	v_mul_f32_e32 v60, v63, v63
	v_fmac_f32_e32 v50, v52, v52
	v_mul_f32_e32 v52, v55, v55
	v_fmac_f32_e32 v60, v62, v62
	v_mul_f32_e32 v57, v57, v57
	v_fmac_f32_e32 v52, v54, v54
	v_mul_f32_e32 v49, v49, v49
	v_add_f32_e32 v58, v58, v60
	v_fmac_f32_e32 v57, v56, v56
	v_add_f32_e32 v50, v50, v52
	v_fmac_f32_e32 v49, v48, v48
	v_add_f32_e32 v56, v58, v57
	v_add_f32_e32 v48, v50, v49
	v_add_f32_e32 v56, v59, v56
	v_add_f32_e32 v48, v51, v48
	v_add_u32_e32 v64, 0x80, v144
	v_mov_b32_dpp v66, v70 row_ror:8 row_mask:0xf bank_mask:0xf
	v_add_f32_e32 v52, v56, v48
	v_mov_b32_dpp v74, v65 row_ror:8 row_mask:0xf bank_mask:0xf
	v_cndmask_b32_e64 v66, v66, v65, s[6:7]
	v_sub_u32_e32 v65, v64, v146
	v_mov_b32_e32 v53, v52
	s_nop 1
	v_permlane16_swap_b32_e32 v53, v52
	v_mov_b32_dpp v75, v67 row_ror:8 row_mask:0xf bank_mask:0xf
	v_cndmask_b32_e64 v70, v70, v74, s[6:7]
	v_add_u32_e32 v74, v65, v148
	v_mov_b32_dpp v78, v71 row_ror:8 row_mask:0xf bank_mask:0xf
	v_cndmask_b32_e64 v71, v71, v75, s[6:7]
	v_ashrrev_i32_e32 v75, 31, v74
	v_lshlrev_b64 v[48:49], 12, v[74:75]
	v_lshl_add_u64 v[48:49], s[10:11], 0, v[48:49]
	v_lshl_add_u64 v[50:51], v[142:143], 1, v[48:49]
	s_waitcnt lgkmcnt(0)
	v_add_f32_e32 v48, v52, v53
	v_mov_b32_e32 v49, v48
	s_nop 1
	v_permlane32_swap_b32_e32 v49, v48
	v_mov_b32_dpp v79, v72 row_ror:8 row_mask:0xf bank_mask:0xf
	v_mov_b32_dpp v80, v73 row_ror:8 row_mask:0xf bank_mask:0xf
	v_mov_b32_dpp v76, v68 row_ror:8 row_mask:0xf bank_mask:0xf
	v_mov_b32_dpp v77, v69 row_ror:8 row_mask:0xf bank_mask:0xf
	v_cndmask_b32_e64 v67, v78, v67, s[6:7]
	v_cndmask_b32_e64 v68, v79, v68, s[6:7]
	v_cndmask_b32_e64 v69, v80, v69, s[6:7]
	global_store_dwordx4 v[50:51], v[66:69], off
	v_add_co_u32_e32 v50, vcc, s67, v50
	v_cndmask_b32_e64 v72, v72, v76, s[6:7]
	v_cndmask_b32_e64 v73, v73, v77, s[6:7]
	v_addc_co_u32_e32 v51, vcc, 0, v51, vcc
	global_store_dwordx4 v[50:51], v[70:73], off
	s_and_saveexec_b64 s[38:39], s[8:9]
	s_cbranch_execz .LBB0_1288
	v_ashrrev_i32_e32 v65, 31, v64
	s_waitcnt lgkmcnt(0)
	v_add_f32_e32 v50, v48, v49
	v_lshl_add_u64 v[48:49], v[64:65], 2, s[16:17]
	global_atomic_add_f32 v[48:49], v50, off
; __device__ __forceinline__ unsigned cvt_pk_bf16(float lo, float hi) { unsigned r; asm volatile("v_cvt_pk_bf16_f32 %0, %1, %2" : "=v"(r) : "v"(lo), "v"(hi)); return r; }
;     __device__ __forceinline__ void operator()(const f32x4 (&acc)[2][2][4][2], const Unit& u, int wr, int wc, int fr, int fq) const {
;     ...
;             for (int m = 0; m < 4; ++m) { const int row = row0 + ai * HALF + m * 16;
;                 const float rs = ssin ? __builtin_amdgcn_rsqf(ssin[row] * (1.f / D) + EPS) : 1.0f; float sq = 0.f; u32x4 w[2];
; #pragma unroll
;                 for (int bj = 0; bj < 2; ++bj) { f32x4 v0 = acc[ai][bj][m][0] * rs, v1 = acc[ai][bj][m][1] * rs;
;                     if (ACT == 1) {
; #pragma unroll
;                         for (int j = 0; j < 4; ++j) { const float a = fmaxf(v0[j], 0.f), b = fmaxf(v1[j], 0.f); v0[j] = a * a; v1[j] = b * b; } }
;                     sq += (v0[0] * v0[0] + v0[1] * v0[1]) + (v0[2] * v0[2] + v0[3] * v0[3]) + (v1[0] * v1[0] + v1[1] * v1[1]) + (v1[2] * v1[2] + v1[3] * v1[3]);
;                     w[bj].x = cvt_pk_bf16(v0[0], v0[1]); w[bj].y = cvt_pk_bf16(v0[2], v0[3]); w[bj].z = cvt_pk_bf16(v1[0], v1[1]); w[bj].w = cvt_pk_bf16(v1[2], v1[3]); }
;                 store_pair_lines(O, ldc, row, fr, col0, w[0], w[1]);
;                 if (ssout) { sq += __shfl_xor(sq, 16); sq += __shfl_xor(sq, 32); if (fq == 0) unsafeAtomicAdd(ssout + row, sq); } }
.LBB0_1288:
	s_or_b64 exec, exec, s[38:39]
	s_waitcnt lgkmcnt(0)
	v_cvt_pk_bf16_f32 v49, v44, v45
	v_cvt_pk_bf16_f32 v51, v46, v47
	v_cvt_pk_bf16_f32 v52, v40, v41
	v_cvt_pk_bf16_f32 v53, v42, v43
	v_cvt_pk_bf16_f32 v54, v36, v37
	v_cvt_pk_bf16_f32 v55, v38, v39
	v_cvt_pk_bf16_f32 v56, v32, v33
	v_cvt_pk_bf16_f32 v57, v34, v35
	v_mul_f32_e32 v43, v43, v43
	v_mul_f32_e32 v35, v35, v35
	v_fmac_f32_e32 v43, v42, v42
	v_mul_f32_e32 v42, v45, v45
	v_fmac_f32_e32 v35, v34, v34
	v_mul_f32_e32 v34, v37, v37
	v_fmac_f32_e32 v42, v44, v44
	v_mul_f32_e32 v44, v47, v47
	v_fmac_f32_e32 v34, v36, v36
	v_mul_f32_e32 v36, v39, v39
	v_fmac_f32_e32 v44, v46, v46
	v_mul_f32_e32 v41, v41, v41
	v_fmac_f32_e32 v36, v38, v38
	v_mul_f32_e32 v33, v33, v33
	v_add_f32_e32 v42, v42, v44
	v_fmac_f32_e32 v41, v40, v40
	v_add_f32_e32 v34, v34, v36
	v_fmac_f32_e32 v33, v32, v32
	v_add_f32_e32 v40, v42, v41
	v_add_f32_e32 v32, v34, v33
	v_add_f32_e32 v40, v43, v40
	v_add_f32_e32 v32, v35, v32
	v_add_u32_e32 v48, 0x90, v144
	v_mov_b32_dpp v50, v54 row_ror:8 row_mask:0xf bank_mask:0xf
	v_add_f32_e32 v36, v40, v32
	v_mov_b32_dpp v58, v49 row_ror:8 row_mask:0xf bank_mask:0xf
	v_cndmask_b32_e64 v50, v50, v49, s[6:7]
	v_sub_u32_e32 v49, v48, v146
	v_mov_b32_e32 v37, v36
	s_nop 1
	v_permlane16_swap_b32_e32 v37, v36
	v_mov_b32_dpp v59, v51 row_ror:8 row_mask:0xf bank_mask:0xf
	v_cndmask_b32_e64 v54, v54, v58, s[6:7]
	v_add_u32_e32 v58, v49, v148
	v_mov_b32_dpp v62, v55 row_ror:8 row_mask:0xf bank_mask:0xf
	v_cndmask_b32_e64 v55, v55, v59, s[6:7]
	v_ashrrev_i32_e32 v59, 31, v58
	v_lshlrev_b64 v[32:33], 12, v[58:59]
	v_lshl_add_u64 v[32:33], s[10:11], 0, v[32:33]
	v_lshl_add_u64 v[34:35], v[142:143], 1, v[32:33]
	s_waitcnt lgkmcnt(0)
	v_add_f32_e32 v32, v36, v37
	v_mov_b32_e32 v33, v32
	s_nop 1
	v_permlane32_swap_b32_e32 v33, v32
	v_mov_b32_dpp v63, v56 row_ror:8 row_mask:0xf bank_mask:0xf
	v_mov_b32_dpp v64, v57 row_ror:8 row_mask:0xf bank_mask:0xf
	v_mov_b32_dpp v60, v52 row_ror:8 row_mask:0xf bank_mask:0xf
	v_mov_b32_dpp v61, v53 row_ror:8 row_mask:0xf bank_mask:0xf
	v_cndmask_b32_e64 v51, v62, v51, s[6:7]
	v_cndmask_b32_e64 v52, v63, v52, s[6:7]
	v_cndmask_b32_e64 v53, v64, v53, s[6:7]
	global_store_dwordx4 v[34:35], v[50:53], off
	v_add_co_u32_e32 v34, vcc, s67, v34
	v_cndmask_b32_e64 v56, v56, v60, s[6:7]
	v_cndmask_b32_e64 v57, v57, v61, s[6:7]
	v_addc_co_u32_e32 v35, vcc, 0, v35, vcc
	global_store_dwordx4 v[34:35], v[54:57], off
	s_and_saveexec_b64 s[38:39], s[8:9]
	s_cbranch_execz .LBB0_1290
	v_ashrrev_i32_e32 v49, 31, v48
	s_waitcnt lgkmcnt(0)
	v_add_f32_e32 v34, v32, v33
	v_lshl_add_u64 v[32:33], v[48:49], 2, s[16:17]
	global_atomic_add_f32 v[32:33], v34, off
; __device__ __forceinline__ unsigned cvt_pk_bf16(float lo, float hi) { unsigned r; asm volatile("v_cvt_pk_bf16_f32 %0, %1, %2" : "=v"(r) : "v"(lo), "v"(hi)); return r; }
;     __device__ __forceinline__ void operator()(const f32x4 (&acc)[2][2][4][2], const Unit& u, int wr, int wc, int fr, int fq) const {
;     ...
;             for (int m = 0; m < 4; ++m) { const int row = row0 + ai * HALF + m * 16;
;                 const float rs = ssin ? __builtin_amdgcn_rsqf(ssin[row] * (1.f / D) + EPS) : 1.0f; float sq = 0.f; u32x4 w[2];
; #pragma unroll
;                 for (int bj = 0; bj < 2; ++bj) { f32x4 v0 = acc[ai][bj][m][0] * rs, v1 = acc[ai][bj][m][1] * rs;
;                     if (ACT == 1) {
; #pragma unroll
;                         for (int j = 0; j < 4; ++j) { const float a = fmaxf(v0[j], 0.f), b = fmaxf(v1[j], 0.f); v0[j] = a * a; v1[j] = b * b; } }
;                     sq += (v0[0] * v0[0] + v0[1] * v0[1]) + (v0[2] * v0[2] + v0[3] * v0[3]) + (v1[0] * v1[0] + v1[1] * v1[1]) + (v1[2] * v1[2] + v1[3] * v1[3]);
;                     w[bj].x = cvt_pk_bf16(v0[0], v0[1]); w[bj].y = cvt_pk_bf16(v0[2], v0[3]); w[bj].z = cvt_pk_bf16(v1[0], v1[1]); w[bj].w = cvt_pk_bf16(v1[2], v1[3]); }
;                 store_pair_lines(O, ldc, row, fr, col0, w[0], w[1]);
;                 if (ssout) { sq += __shfl_xor(sq, 16); sq += __shfl_xor(sq, 32); if (fq == 0) unsafeAtomicAdd(ssout + row, sq); } }
.LBB0_1290:
	s_or_b64 exec, exec, s[38:39]
	s_waitcnt lgkmcnt(0)
	v_cvt_pk_bf16_f32 v33, v28, v29
	v_cvt_pk_bf16_f32 v35, v30, v31
	v_cvt_pk_bf16_f32 v36, v24, v25
	v_cvt_pk_bf16_f32 v37, v26, v27
	v_cvt_pk_bf16_f32 v38, v20, v21
	v_cvt_pk_bf16_f32 v39, v22, v23
	v_cvt_pk_bf16_f32 v40, v16, v17
	v_cvt_pk_bf16_f32 v41, v18, v19
	v_mul_f32_e32 v27, v27, v27
	v_mul_f32_e32 v19, v19, v19
	v_fmac_f32_e32 v27, v26, v26
	v_mul_f32_e32 v26, v29, v29
	v_fmac_f32_e32 v19, v18, v18
	v_mul_f32_e32 v18, v21, v21
	v_fmac_f32_e32 v26, v28, v28
	v_mul_f32_e32 v28, v31, v31
	v_fmac_f32_e32 v18, v20, v20
	v_mul_f32_e32 v20, v23, v23
	v_fmac_f32_e32 v28, v30, v30
	v_mul_f32_e32 v25, v25, v25
	v_fmac_f32_e32 v20, v22, v22
	v_mul_f32_e32 v17, v17, v17
	v_add_f32_e32 v26, v26, v28
	v_fmac_f32_e32 v25, v24, v24
	v_add_f32_e32 v18, v18, v20
	v_fmac_f32_e32 v17, v16, v16
	v_add_f32_e32 v24, v26, v25
	v_add_f32_e32 v16, v18, v17
	v_add_f32_e32 v24, v27, v24
	v_add_f32_e32 v16, v19, v16
	v_add_u32_e32 v32, 0xa0, v144
	v_mov_b32_dpp v34, v38 row_ror:8 row_mask:0xf bank_mask:0xf
	v_add_f32_e32 v20, v24, v16
	v_mov_b32_dpp v42, v33 row_ror:8 row_mask:0xf bank_mask:0xf
	v_cndmask_b32_e64 v34, v34, v33, s[6:7]
	v_sub_u32_e32 v33, v32, v146
	v_mov_b32_e32 v21, v20
	s_nop 1
	v_permlane16_swap_b32_e32 v21, v20
	v_mov_b32_dpp v43, v35 row_ror:8 row_mask:0xf bank_mask:0xf
	v_cndmask_b32_e64 v38, v38, v42, s[6:7]
	v_add_u32_e32 v42, v33, v148
	v_mov_b32_dpp v46, v39 row_ror:8 row_mask:0xf bank_mask:0xf
	v_cndmask_b32_e64 v39, v39, v43, s[6:7]
	v_ashrrev_i32_e32 v43, 31, v42
	v_lshlrev_b64 v[16:17], 12, v[42:43]
	v_lshl_add_u64 v[16:17], s[10:11], 0, v[16:17]
	v_lshl_add_u64 v[18:19], v[142:143], 1, v[16:17]
	s_waitcnt lgkmcnt(0)
	v_add_f32_e32 v16, v20, v21
	v_mov_b32_e32 v17, v16
	s_nop 1
	v_permlane32_swap_b32_e32 v17, v16
	v_mov_b32_dpp v47, v40 row_ror:8 row_mask:0xf bank_mask:0xf
	v_mov_b32_dpp v48, v41 row_ror:8 row_mask:0xf bank_mask:0xf
	v_mov_b32_dpp v44, v36 row_ror:8 row_mask:0xf bank_mask:0xf
	v_mov_b32_dpp v45, v37 row_ror:8 row_mask:0xf bank_mask:0xf
	v_cndmask_b32_e64 v35, v46, v35, s[6:7]
	v_cndmask_b32_e64 v36, v47, v36, s[6:7]
	v_cndmask_b32_e64 v37, v48, v37, s[6:7]
	global_store_dwordx4 v[18:19], v[34:37], off
	v_add_co_u32_e32 v18, vcc, s67, v18
	v_cndmask_b32_e64 v40, v40, v44, s[6:7]
	v_cndmask_b32_e64 v41, v41, v45, s[6:7]
	v_addc_co_u32_e32 v19, vcc, 0, v19, vcc
	global_store_dwordx4 v[18:19], v[38:41], off
	s_and_saveexec_b64 s[38:39], s[8:9]
	s_cbranch_execz .LBB0_1292
	v_ashrrev_i32_e32 v33, 31, v32
	s_waitcnt lgkmcnt(0)
	v_add_f32_e32 v18, v16, v17
	v_lshl_add_u64 v[16:17], v[32:33], 2, s[16:17]
	global_atomic_add_f32 v[16:17], v18, off
.LBB0_1292:
	s_or_b64 exec, exec, s[38:39]
	s_waitcnt lgkmcnt(0)
	v_cvt_pk_bf16_f32 v17, v12, v13
	v_cvt_pk_bf16_f32 v19, v14, v15
	v_cvt_pk_bf16_f32 v20, v8, v9
	v_cvt_pk_bf16_f32 v21, v10, v11
	v_cvt_pk_bf16_f32 v22, v4, v5
	v_cvt_pk_bf16_f32 v23, v6, v7
	v_cvt_pk_bf16_f32 v24, v0, v1
	v_cvt_pk_bf16_f32 v25, v2, v3
	v_mul_f32_e32 v11, v11, v11
	v_mul_f32_e32 v3, v3, v3
	v_fmac_f32_e32 v11, v10, v10
	v_mul_f32_e32 v10, v13, v13
	v_fmac_f32_e32 v3, v2, v2
	v_mul_f32_e32 v2, v5, v5
	v_fmac_f32_e32 v10, v12, v12
	v_mul_f32_e32 v12, v15, v15
	v_fmac_f32_e32 v2, v4, v4
	v_mul_f32_e32 v4, v7, v7
	v_fmac_f32_e32 v12, v14, v14
	v_mul_f32_e32 v9, v9, v9
	v_fmac_f32_e32 v4, v6, v6
	v_mul_f32_e32 v1, v1, v1
	v_add_f32_e32 v10, v10, v12
	v_fmac_f32_e32 v9, v8, v8
	v_add_f32_e32 v2, v2, v4
	v_fmac_f32_e32 v1, v0, v0
	v_add_f32_e32 v8, v10, v9
	v_add_f32_e32 v0, v2, v1
	v_add_f32_e32 v8, v11, v8
	v_add_f32_e32 v0, v3, v0
	v_add_u32_e32 v16, 0xb0, v144
	v_mov_b32_dpp v18, v22 row_ror:8 row_mask:0xf bank_mask:0xf
	v_add_f32_e32 v4, v8, v0
	v_mov_b32_dpp v26, v17 row_ror:8 row_mask:0xf bank_mask:0xf
	v_cndmask_b32_e64 v18, v18, v17, s[6:7]
	v_sub_u32_e32 v17, v16, v146
	v_mov_b32_e32 v5, v4
	s_nop 1
	v_permlane16_swap_b32_e32 v5, v4
	v_mov_b32_dpp v27, v19 row_ror:8 row_mask:0xf bank_mask:0xf
	v_cndmask_b32_e64 v22, v22, v26, s[6:7]
	v_add_u32_e32 v26, v17, v148
	v_mov_b32_dpp v30, v23 row_ror:8 row_mask:0xf bank_mask:0xf
	v_cndmask_b32_e64 v23, v23, v27, s[6:7]
	v_ashrrev_i32_e32 v27, 31, v26
	v_lshlrev_b64 v[0:1], 12, v[26:27]
	v_lshl_add_u64 v[0:1], s[10:11], 0, v[0:1]
	v_lshl_add_u64 v[2:3], v[142:143], 1, v[0:1]
	s_waitcnt lgkmcnt(0)
	v_add_f32_e32 v0, v4, v5
	v_mov_b32_e32 v1, v0
	s_nop 1
	v_permlane32_swap_b32_e32 v1, v0
	v_mov_b32_dpp v31, v24 row_ror:8 row_mask:0xf bank_mask:0xf
	v_mov_b32_dpp v32, v25 row_ror:8 row_mask:0xf bank_mask:0xf
	v_mov_b32_dpp v28, v20 row_ror:8 row_mask:0xf bank_mask:0xf
	v_mov_b32_dpp v29, v21 row_ror:8 row_mask:0xf bank_mask:0xf
	v_cndmask_b32_e64 v19, v30, v19, s[6:7]
	v_cndmask_b32_e64 v20, v31, v20, s[6:7]
	v_cndmask_b32_e64 v21, v32, v21, s[6:7]
	global_store_dwordx4 v[2:3], v[18:21], off
	v_add_co_u32_e32 v2, vcc, s67, v2
	v_cndmask_b32_e64 v24, v24, v28, s[6:7]
	v_cndmask_b32_e64 v25, v25, v29, s[6:7]
	v_addc_co_u32_e32 v3, vcc, 0, v3, vcc
	global_store_dwordx4 v[2:3], v[22:25], off
	s_and_saveexec_b64 s[38:39], s[8:9]
	s_cbranch_execz .LBB0_1271
	v_ashrrev_i32_e32 v17, 31, v16
	s_waitcnt lgkmcnt(0)
	v_add_f32_e32 v2, v0, v1
	v_lshl_add_u64 v[0:1], v[16:17], 2, s[16:17]
	global_atomic_add_f32 v[0:1], v2, off
	s_branch .LBB0_1271
